# K-loop top SALU block (next K-tile pointer selects) computed at the end of the last load part and once in the preheader
# baseline (speedup 1.0000x reference)
.LBB0_286:
	s_ashr_i32 s45, s44, 31
	s_lshl_b64 s[0:1], s[44:45], 19
	v_mov_b64_e32 v[2:3], 0x16b0
	s_add_u32 s48, s20, s0
	v_cmp_lt_i64_e32 vcc, s[26:27], v[2:3]
	s_addc_u32 s49, s21, s1
	s_and_b64 s[0:1], vcc, exec
	s_cselect_b32 s18, s49, s23
	s_cselect_b32 s19, s48, s22
	s_ashr_i32 s47, s46, 31
	s_lshl_b64 s[0:1], s[46:47], 19
	s_add_u32 s50, s36, s0
	s_addc_u32 s51, s37, s1
	s_and_b64 s[0:1], vcc, exec
	s_cselect_b32 s45, s51, s25
	s_cselect_b32 s47, s50, s24
	s_add_u32 s22, s22, 0x40080
	s_addc_u32 s23, s23, 0
	s_add_u32 s59, s24, 0x100
	v_mov_b32_e32 v2, 0
	s_addc_u32 s68, s25, 0
	s_mov_b32 s69, -2
	v_mov_b32_e32 v3, v2
	v_mov_b32_e32 v4, v2
	v_mov_b32_e32 v5, v2
	v_mov_b32_e32 v6, v2
	v_mov_b32_e32 v7, v2
	v_mov_b32_e32 v8, v2
	v_mov_b32_e32 v9, v2
	v_mov_b32_e32 v18, v2
	v_mov_b32_e32 v19, v2
	v_mov_b32_e32 v20, v2
	v_mov_b32_e32 v21, v2
	v_mov_b32_e32 v22, v2
	v_mov_b32_e32 v23, v2
	v_mov_b32_e32 v24, v2
	v_mov_b32_e32 v25, v2
	s_waitcnt vmcnt(0)
	v_mov_b32_e32 v36, v2
	v_mov_b32_e32 v37, v2
	v_mov_b32_e32 v38, v2
	v_mov_b32_e32 v39, v2
	v_mov_b32_e32 v40, v2
	v_mov_b32_e32 v41, v2
	v_mov_b32_e32 v42, v2
	v_mov_b32_e32 v43, v2
	v_mov_b32_e32 v52, v2
	v_mov_b32_e32 v53, v2
	v_mov_b32_e32 v54, v2
	v_mov_b32_e32 v55, v2
	v_mov_b32_e32 v56, v2
	v_mov_b32_e32 v57, v2
	v_mov_b32_e32 v58, v2
	v_mov_b32_e32 v59, v2
	v_mov_b32_e32 v10, v2
	v_mov_b32_e32 v11, v2
	v_mov_b32_e32 v12, v2
	v_mov_b32_e32 v13, v2
	v_mov_b32_e32 v14, v2
	v_mov_b32_e32 v15, v2
	v_mov_b32_e32 v16, v2
	v_mov_b32_e32 v17, v2
	v_mov_b32_e32 v28, v2
	v_mov_b32_e32 v29, v2
	v_mov_b32_e32 v30, v2
	v_mov_b32_e32 v31, v2
	v_mov_b32_e32 v32, v2
	v_mov_b32_e32 v33, v2
	v_mov_b32_e32 v34, v2
	v_mov_b32_e32 v35, v2
	v_mov_b32_e32 v44, v2
	v_mov_b32_e32 v45, v2
	v_mov_b32_e32 v46, v2
	v_mov_b32_e32 v47, v2
	v_mov_b32_e32 v48, v2
	v_mov_b32_e32 v49, v2
	v_mov_b32_e32 v50, v2
	v_mov_b32_e32 v51, v2
	v_mov_b32_e32 v60, v2
	v_mov_b32_e32 v61, v2
	v_mov_b32_e32 v62, v2
	v_mov_b32_e32 v63, v2
	v_mov_b32_e32 v64, v2
	v_mov_b32_e32 v65, v2
	v_mov_b32_e32 v66, v2
	v_mov_b32_e32 v67, v2
	v_mov_b32_e32 v84, v2
	v_mov_b32_e32 v85, v2
	v_mov_b32_e32 v86, v2
	v_mov_b32_e32 v87, v2
	v_mov_b32_e32 v88, v2
	v_mov_b32_e32 v89, v2
	v_mov_b32_e32 v90, v2
	v_mov_b32_e32 v91, v2
	v_mov_b32_e32 v100, v2
	v_mov_b32_e32 v101, v2
	v_mov_b32_e32 v102, v2
	v_mov_b32_e32 v103, v2
	v_mov_b32_e32 v104, v2
	v_mov_b32_e32 v105, v2
	v_mov_b32_e32 v106, v2
	v_mov_b32_e32 v107, v2
	v_mov_b32_e32 v116, v2
	v_mov_b32_e32 v117, v2
	v_mov_b32_e32 v118, v2
	v_mov_b32_e32 v119, v2
	v_mov_b32_e32 v120, v2
	v_mov_b32_e32 v121, v2
	v_mov_b32_e32 v122, v2
	v_mov_b32_e32 v123, v2
	v_mov_b32_e32 v132, v2
	v_mov_b32_e32 v133, v2
	v_mov_b32_e32 v134, v2
	v_mov_b32_e32 v135, v2
	v_mov_b32_e32 v136, v2
	v_mov_b32_e32 v137, v2
	v_mov_b32_e32 v138, v2
	v_mov_b32_e32 v139, v2
	v_mov_b32_e32 v92, v2
	v_mov_b32_e32 v93, v2
	v_mov_b32_e32 v94, v2
	v_mov_b32_e32 v95, v2
	v_mov_b32_e32 v96, v2
	v_mov_b32_e32 v97, v2
	v_mov_b32_e32 v98, v2
	v_mov_b32_e32 v99, v2
	v_mov_b32_e32 v108, v2
	v_mov_b32_e32 v109, v2
	v_mov_b32_e32 v110, v2
	v_mov_b32_e32 v111, v2
	v_mov_b32_e32 v112, v2
	v_mov_b32_e32 v113, v2
	v_mov_b32_e32 v114, v2
	v_mov_b32_e32 v115, v2
	v_mov_b32_e32 v124, v2
	v_mov_b32_e32 v125, v2
	v_mov_b32_e32 v126, v2
	v_mov_b32_e32 v127, v2
	v_mov_b32_e32 v128, v2
	v_mov_b32_e32 v129, v2
	v_mov_b32_e32 v130, v2
	v_mov_b32_e32 v131, v2
	v_mov_b32_e32 v140, v2
	v_mov_b32_e32 v141, v2
	v_mov_b32_e32 v142, v2
	v_mov_b32_e32 v143, v2
	v_mov_b32_e32 v144, v2
	v_mov_b32_e32 v145, v2
	v_mov_b32_e32 v146, v2
	v_mov_b32_e32 v147, v2
	v_add_u32_e32 v80, 0x10000, v163
	ds_read_b128 v[68:71], v80
	ds_read_b128 v[72:75], v80 offset:1024
	ds_read_b128 v[76:79], v80 offset:2048
	ds_read_b128 v[80:83], v80 offset:3072
	s_add_u32 s0, s22, 0xfffc0080
	s_addc_u32 s1, s23, -1
	s_add_i32 s72, 0, 0x10000
	s_cmp_eq_u32 s69, 12
	s_cselect_b32 s27, s18, s1
	s_cselect_b32 s26, s19, s0
	s_cselect_b32 s25, s45, s68
	s_cselect_b32 s24, s47, s59
.LBB0_287:
	s_add_i32 m0, s53, 0xc000
	ds_read_b128 v[158:161], v165
	ds_read_b128 v[174:177], v165 offset:1024
	ds_read_b128 v[178:181], v165 offset:2048
	ds_read_b128 v[182:185], v165 offset:3072
	ds_read_b128 v[186:189], v165 offset:4096
	ds_read_b128 v[190:193], v165 offset:5120
	ds_read_b128 v[194:197], v165 offset:6144
	ds_read_b128 v[198:201], v165 offset:7168
	global_load_lds_dwordx4 v154, s[22:23]
	s_add_i32 m0, s53, 0xe000
	s_nop 0
	global_load_lds_dwordx4 v156, s[22:23]
	s_waitcnt vmcnt(10) lgkmcnt(8)
	s_setprio 1
	s_barrier
	s_waitcnt lgkmcnt(0)
	v_mfma_f32_16x16x32_bf16 v[144:147], v[68:71], v[158:161], v[144:147]
	v_mfma_f32_16x16x32_bf16 v[140:143], v[76:79], v[158:161], v[140:143]
	v_mfma_f32_16x16x32_bf16 v[128:131], v[68:71], v[178:181], v[128:131]
	v_mfma_f32_16x16x32_bf16 v[124:127], v[76:79], v[178:181], v[124:127]
	v_mfma_f32_16x16x32_bf16 v[112:115], v[68:71], v[186:189], v[112:115]
	v_mfma_f32_16x16x32_bf16 v[108:111], v[76:79], v[186:189], v[108:111]
	v_mfma_f32_16x16x32_bf16 v[96:99], v[68:71], v[194:197], v[96:99]
	v_mfma_f32_16x16x32_bf16 v[92:95], v[76:79], v[194:197], v[92:95]
	v_mfma_f32_16x16x32_bf16 v[144:147], v[72:75], v[174:177], v[144:147]
	v_mfma_f32_16x16x32_bf16 v[140:143], v[80:83], v[174:177], v[140:143]
	v_mfma_f32_16x16x32_bf16 v[128:131], v[72:75], v[182:185], v[128:131]
	v_mfma_f32_16x16x32_bf16 v[124:127], v[80:83], v[182:185], v[124:127]
	v_mfma_f32_16x16x32_bf16 v[112:115], v[72:75], v[190:193], v[112:115]
	v_mfma_f32_16x16x32_bf16 v[108:111], v[80:83], v[190:193], v[108:111]
	v_mfma_f32_16x16x32_bf16 v[96:99], v[72:75], v[198:201], v[96:99]
	v_mfma_f32_16x16x32_bf16 v[92:95], v[80:83], v[198:201], v[92:95]
	s_barrier
	s_setprio 0
	s_add_i32 s73, 0, 0x14000
	s_add_i32 s0, s72, s52
	v_add_u32_e32 v166, s73, v163
	v_lshl_add_u64 v[218:219], s[24:25], 0, v[26:27]
	s_mov_b32 m0, s0
	ds_read_b128 v[202:205], v166
	ds_read_b128 v[206:209], v166 offset:1024
	ds_read_b128 v[210:213], v166 offset:2048
	ds_read_b128 v[214:217], v166 offset:3072
	global_load_lds_dwordx4 v[218:219], off
	v_lshl_add_u64 v[220:221], s[24:25], 0, v[148:149]
	s_add_i32 m0, s0, 0x2000
	s_nop 0
	global_load_lds_dwordx4 v[220:221], off
	s_waitcnt vmcnt(10)
	s_setprio 1
	s_barrier
	s_waitcnt lgkmcnt(0)
	v_mfma_f32_16x16x32_bf16 v[136:139], v[202:205], v[158:161], v[136:139]
	v_mfma_f32_16x16x32_bf16 v[132:135], v[210:213], v[158:161], v[132:135]
	v_mfma_f32_16x16x32_bf16 v[120:123], v[202:205], v[178:181], v[120:123]
	v_mfma_f32_16x16x32_bf16 v[116:119], v[210:213], v[178:181], v[116:119]
	v_mfma_f32_16x16x32_bf16 v[104:107], v[202:205], v[186:189], v[104:107]
	v_mfma_f32_16x16x32_bf16 v[100:103], v[210:213], v[186:189], v[100:103]
	v_mfma_f32_16x16x32_bf16 v[88:91], v[202:205], v[194:197], v[88:91]
	v_mfma_f32_16x16x32_bf16 v[84:87], v[210:213], v[194:197], v[84:87]
	v_mfma_f32_16x16x32_bf16 v[136:139], v[206:209], v[174:177], v[136:139]
	v_mfma_f32_16x16x32_bf16 v[132:135], v[214:217], v[174:177], v[132:135]
	v_mfma_f32_16x16x32_bf16 v[120:123], v[206:209], v[182:185], v[120:123]
	v_mfma_f32_16x16x32_bf16 v[116:119], v[214:217], v[182:185], v[116:119]
	v_mfma_f32_16x16x32_bf16 v[104:107], v[206:209], v[190:193], v[104:107]
	v_mfma_f32_16x16x32_bf16 v[100:103], v[214:217], v[190:193], v[100:103]
	v_mfma_f32_16x16x32_bf16 v[88:91], v[206:209], v[198:201], v[88:91]
	v_mfma_f32_16x16x32_bf16 v[84:87], v[214:217], v[198:201], v[84:87]
	s_barrier
	s_setprio 0
	s_mov_b32 m0, s53
	v_lshl_add_u64 v[222:223], s[26:27], 0, v[152:153]
	ds_read_b128 v[158:161], v165 offset:16384
	ds_read_b128 v[174:177], v165 offset:17408
	ds_read_b128 v[178:181], v165 offset:18432
	ds_read_b128 v[182:185], v165 offset:19456
	ds_read_b128 v[186:189], v165 offset:20480
	ds_read_b128 v[190:193], v165 offset:21504
	ds_read_b128 v[194:197], v165 offset:22528
	ds_read_b128 v[198:201], v165 offset:23552
	global_load_lds_dwordx4 v[222:223], off
	v_lshl_add_u64 v[224:225], s[26:27], 0, v[150:151]
	s_mov_b32 m0, s54
	s_nop 0
	global_load_lds_dwordx4 v[224:225], off
	s_waitcnt vmcnt(10)
	s_setprio 1
	s_barrier
	s_waitcnt lgkmcnt(0)
	v_mfma_f32_16x16x32_bf16 v[64:67], v[68:71], v[158:161], v[64:67]
	v_mfma_f32_16x16x32_bf16 v[60:63], v[76:79], v[158:161], v[60:63]
	v_mfma_f32_16x16x32_bf16 v[48:51], v[68:71], v[178:181], v[48:51]
	v_mfma_f32_16x16x32_bf16 v[44:47], v[76:79], v[178:181], v[44:47]
	v_mfma_f32_16x16x32_bf16 v[32:35], v[68:71], v[186:189], v[32:35]
	v_mfma_f32_16x16x32_bf16 v[28:31], v[76:79], v[186:189], v[28:31]
	v_mfma_f32_16x16x32_bf16 v[14:17], v[68:71], v[194:197], v[14:17]
	v_mfma_f32_16x16x32_bf16 v[10:13], v[76:79], v[194:197], v[10:13]
	v_mfma_f32_16x16x32_bf16 v[64:67], v[72:75], v[174:177], v[64:67]
	v_mfma_f32_16x16x32_bf16 v[60:63], v[80:83], v[174:177], v[60:63]
	v_mfma_f32_16x16x32_bf16 v[48:51], v[72:75], v[182:185], v[48:51]
	v_mfma_f32_16x16x32_bf16 v[44:47], v[80:83], v[182:185], v[44:47]
	v_mfma_f32_16x16x32_bf16 v[32:35], v[72:75], v[190:193], v[32:35]
	v_mfma_f32_16x16x32_bf16 v[28:31], v[80:83], v[190:193], v[28:31]
	v_mfma_f32_16x16x32_bf16 v[14:17], v[72:75], v[198:201], v[14:17]
	v_mfma_f32_16x16x32_bf16 v[10:13], v[80:83], v[198:201], v[10:13]
	s_barrier
	s_setprio 0
	s_add_u32 s0, s24, 0x40000
	s_addc_u32 s1, s25, 0
	s_add_i32 s72, s73, s52
	s_mov_b32 m0, s72
	s_nop 0
	global_load_lds_dwordx4 v26, s[0:1]
	s_add_i32 m0, s72, 0x2000
	s_nop 0
	global_load_lds_dwordx4 v148, s[0:1]
	v_add_u32_e32 v80, 0x18000, v163
	ds_read_b128 v[68:71], v80
	ds_read_b128 v[72:75], v80 offset:1024
	ds_read_b128 v[76:79], v80 offset:2048
	ds_read_b128 v[80:83], v80 offset:3072
	s_waitcnt vmcnt(10)
	s_setprio 1
	s_barrier
	v_mfma_f32_16x16x32_bf16 v[56:59], v[202:205], v[158:161], v[56:59]
	v_mfma_f32_16x16x32_bf16 v[52:55], v[210:213], v[158:161], v[52:55]
	v_mfma_f32_16x16x32_bf16 v[40:43], v[202:205], v[178:181], v[40:43]
	v_mfma_f32_16x16x32_bf16 v[36:39], v[210:213], v[178:181], v[36:39]
	v_mfma_f32_16x16x32_bf16 v[22:25], v[202:205], v[186:189], v[22:25]
	v_mfma_f32_16x16x32_bf16 v[18:21], v[210:213], v[186:189], v[18:21]
	v_mfma_f32_16x16x32_bf16 v[6:9], v[202:205], v[194:197], v[6:9]
	v_mfma_f32_16x16x32_bf16 v[2:5], v[210:213], v[194:197], v[2:5]
	v_mfma_f32_16x16x32_bf16 v[56:59], v[206:209], v[174:177], v[56:59]
	v_mfma_f32_16x16x32_bf16 v[52:55], v[214:217], v[174:177], v[52:55]
	v_mfma_f32_16x16x32_bf16 v[40:43], v[206:209], v[182:185], v[40:43]
	v_mfma_f32_16x16x32_bf16 v[36:39], v[214:217], v[182:185], v[36:39]
	v_mfma_f32_16x16x32_bf16 v[22:25], v[206:209], v[190:193], v[22:25]
	v_mfma_f32_16x16x32_bf16 v[18:21], v[214:217], v[190:193], v[18:21]
	v_mfma_f32_16x16x32_bf16 v[6:9], v[206:209], v[198:201], v[6:9]
	v_mfma_f32_16x16x32_bf16 v[2:5], v[214:217], v[198:201], v[2:5]
	s_barrier
	s_setprio 0
	s_add_i32 s72, 0, 0x18000
	s_add_u32 s0, s26, 0x40000
	s_addc_u32 s1, s27, 0
	s_mov_b32 m0, s55
	ds_read_b128 v[158:161], v165 offset:32768
	ds_read_b128 v[174:177], v165 offset:33792
	ds_read_b128 v[178:181], v165 offset:34816
	ds_read_b128 v[182:185], v165 offset:35840
	ds_read_b128 v[186:189], v165 offset:36864
	ds_read_b128 v[190:193], v165 offset:37888
	ds_read_b128 v[194:197], v165 offset:38912
	ds_read_b128 v[198:201], v165 offset:39936
	global_load_lds_dwordx4 v152, s[0:1]
	s_mov_b32 m0, s56
	s_nop 0
	global_load_lds_dwordx4 v150, s[0:1]
	s_waitcnt vmcnt(10) lgkmcnt(8)
	s_setprio 1
	s_barrier
	s_waitcnt lgkmcnt(0)
	v_mfma_f32_16x16x32_bf16 v[144:147], v[68:71], v[158:161], v[144:147]
	v_mfma_f32_16x16x32_bf16 v[140:143], v[76:79], v[158:161], v[140:143]
	v_mfma_f32_16x16x32_bf16 v[128:131], v[68:71], v[178:181], v[128:131]
	v_mfma_f32_16x16x32_bf16 v[124:127], v[76:79], v[178:181], v[124:127]
	v_mfma_f32_16x16x32_bf16 v[112:115], v[68:71], v[186:189], v[112:115]
	v_mfma_f32_16x16x32_bf16 v[108:111], v[76:79], v[186:189], v[108:111]
	v_mfma_f32_16x16x32_bf16 v[96:99], v[68:71], v[194:197], v[96:99]
	v_mfma_f32_16x16x32_bf16 v[92:95], v[76:79], v[194:197], v[92:95]
	v_mfma_f32_16x16x32_bf16 v[144:147], v[72:75], v[174:177], v[144:147]
	v_mfma_f32_16x16x32_bf16 v[140:143], v[80:83], v[174:177], v[140:143]
	v_mfma_f32_16x16x32_bf16 v[128:131], v[72:75], v[182:185], v[128:131]
	v_mfma_f32_16x16x32_bf16 v[124:127], v[80:83], v[182:185], v[124:127]
	v_mfma_f32_16x16x32_bf16 v[112:115], v[72:75], v[190:193], v[112:115]
	v_mfma_f32_16x16x32_bf16 v[108:111], v[80:83], v[190:193], v[108:111]
	v_mfma_f32_16x16x32_bf16 v[96:99], v[72:75], v[198:201], v[96:99]
	v_mfma_f32_16x16x32_bf16 v[92:95], v[80:83], v[198:201], v[92:95]
	s_barrier
	s_setprio 0
	s_add_i32 s26, 0, 0x1c000
	s_add_i32 s0, s72, s52
	v_add_u32_e32 v166, s26, v163
	v_lshl_add_u64 v[218:219], v[218:219], 0, s[12:13]
	s_mov_b32 m0, s0
	ds_read_b128 v[202:205], v166
	ds_read_b128 v[206:209], v166 offset:1024
	ds_read_b128 v[210:213], v166 offset:2048
	ds_read_b128 v[214:217], v166 offset:3072
	global_load_lds_dwordx4 v[218:219], off
	v_lshl_add_u64 v[218:219], v[220:221], 0, s[12:13]
	s_add_i32 m0, s0, 0x2000
	s_nop 0
	global_load_lds_dwordx4 v[218:219], off
	s_waitcnt vmcnt(10)
	s_setprio 1
	s_barrier
	s_waitcnt lgkmcnt(0)
	v_mfma_f32_16x16x32_bf16 v[136:139], v[202:205], v[158:161], v[136:139]
	v_mfma_f32_16x16x32_bf16 v[132:135], v[210:213], v[158:161], v[132:135]
	v_mfma_f32_16x16x32_bf16 v[120:123], v[202:205], v[178:181], v[120:123]
	v_mfma_f32_16x16x32_bf16 v[116:119], v[210:213], v[178:181], v[116:119]
	v_mfma_f32_16x16x32_bf16 v[104:107], v[202:205], v[186:189], v[104:107]
	v_mfma_f32_16x16x32_bf16 v[100:103], v[210:213], v[186:189], v[100:103]
	v_mfma_f32_16x16x32_bf16 v[88:91], v[202:205], v[194:197], v[88:91]
	v_mfma_f32_16x16x32_bf16 v[84:87], v[210:213], v[194:197], v[84:87]
	v_mfma_f32_16x16x32_bf16 v[136:139], v[206:209], v[174:177], v[136:139]
	v_mfma_f32_16x16x32_bf16 v[132:135], v[214:217], v[174:177], v[132:135]
	v_mfma_f32_16x16x32_bf16 v[120:123], v[206:209], v[182:185], v[120:123]
	v_mfma_f32_16x16x32_bf16 v[116:119], v[214:217], v[182:185], v[116:119]
	v_mfma_f32_16x16x32_bf16 v[104:107], v[206:209], v[190:193], v[104:107]
	v_mfma_f32_16x16x32_bf16 v[100:103], v[214:217], v[190:193], v[100:103]
	v_mfma_f32_16x16x32_bf16 v[88:91], v[206:209], v[198:201], v[88:91]
	v_mfma_f32_16x16x32_bf16 v[84:87], v[214:217], v[198:201], v[84:87]
	s_barrier
	s_setprio 0
	s_mov_b32 m0, s30
	v_lshl_add_u64 v[218:219], v[222:223], 0, s[12:13]
	ds_read_b128 v[158:161], v165 offset:49152
	ds_read_b128 v[174:177], v165 offset:50176
	ds_read_b128 v[178:181], v165 offset:51200
	ds_read_b128 v[182:185], v165 offset:52224
	ds_read_b128 v[186:189], v165 offset:53248
	ds_read_b128 v[190:193], v165 offset:54272
	ds_read_b128 v[194:197], v165 offset:55296
	ds_read_b128 v[198:201], v165 offset:56320
	global_load_lds_dwordx4 v[218:219], off
	v_lshl_add_u64 v[218:219], v[224:225], 0, s[12:13]
	s_mov_b32 m0, s31
	s_nop 0
	global_load_lds_dwordx4 v[218:219], off
	s_waitcnt vmcnt(10)
	s_setprio 1
	s_barrier
	s_waitcnt lgkmcnt(0)
	v_mfma_f32_16x16x32_bf16 v[64:67], v[68:71], v[158:161], v[64:67]
	v_mfma_f32_16x16x32_bf16 v[60:63], v[76:79], v[158:161], v[60:63]
	v_mfma_f32_16x16x32_bf16 v[48:51], v[68:71], v[178:181], v[48:51]
	v_mfma_f32_16x16x32_bf16 v[44:47], v[76:79], v[178:181], v[44:47]
	v_mfma_f32_16x16x32_bf16 v[32:35], v[68:71], v[186:189], v[32:35]
	v_mfma_f32_16x16x32_bf16 v[28:31], v[76:79], v[186:189], v[28:31]
	v_mfma_f32_16x16x32_bf16 v[14:17], v[68:71], v[194:197], v[14:17]
	v_mfma_f32_16x16x32_bf16 v[10:13], v[76:79], v[194:197], v[10:13]
	v_mfma_f32_16x16x32_bf16 v[64:67], v[72:75], v[174:177], v[64:67]
	v_mfma_f32_16x16x32_bf16 v[60:63], v[80:83], v[174:177], v[60:63]
	v_mfma_f32_16x16x32_bf16 v[48:51], v[72:75], v[182:185], v[48:51]
	v_mfma_f32_16x16x32_bf16 v[44:47], v[80:83], v[182:185], v[44:47]
	v_mfma_f32_16x16x32_bf16 v[32:35], v[72:75], v[190:193], v[32:35]
	v_mfma_f32_16x16x32_bf16 v[28:31], v[80:83], v[190:193], v[28:31]
	v_mfma_f32_16x16x32_bf16 v[14:17], v[72:75], v[198:201], v[14:17]
	v_mfma_f32_16x16x32_bf16 v[10:13], v[80:83], v[198:201], v[10:13]
	s_barrier
	s_setprio 0
	s_add_u32 s0, s24, 0x40080
	s_addc_u32 s1, s25, 0
	s_add_i32 s24, s26, s52
	s_mov_b32 m0, s24
	s_nop 0
	global_load_lds_dwordx4 v26, s[0:1]
	s_add_i32 m0, s24, 0x2000
	s_nop 0
	global_load_lds_dwordx4 v148, s[0:1]
	v_add_u32_e32 v80, 0x10000, v163
	ds_read_b128 v[68:71], v80
	ds_read_b128 v[72:75], v80 offset:1024
	ds_read_b128 v[76:79], v80 offset:2048
	ds_read_b128 v[80:83], v80 offset:3072
	s_add_i32 s69, s69, 2
	s_add_u32 s22, s22, 0x100
	s_addc_u32 s23, s23, 0
	s_add_u32 s59, s59, 0x100
	s_addc_u32 s68, s68, 0
	s_cmp_gt_u32 s69, 13
	s_cbranch_scc1 .Lth__287
	s_add_u32 s0, s22, 0xfffc0080
	s_addc_u32 s1, s23, -1
	s_add_i32 s72, 0, 0x10000
	s_cmp_eq_u32 s69, 12
	s_cselect_b32 s27, s18, s1
	s_cselect_b32 s26, s19, s0
	s_cselect_b32 s25, s45, s68
	s_cselect_b32 s24, s47, s59
	s_cmp_gt_u32 s69, 13
.Lth__287:
	s_waitcnt vmcnt(10)
	s_setprio 1
	s_barrier
	v_mfma_f32_16x16x32_bf16 v[56:59], v[202:205], v[158:161], v[56:59]
	v_mfma_f32_16x16x32_bf16 v[52:55], v[210:213], v[158:161], v[52:55]
	v_mfma_f32_16x16x32_bf16 v[40:43], v[202:205], v[178:181], v[40:43]
	v_mfma_f32_16x16x32_bf16 v[36:39], v[210:213], v[178:181], v[36:39]
	v_mfma_f32_16x16x32_bf16 v[22:25], v[202:205], v[186:189], v[22:25]
	v_mfma_f32_16x16x32_bf16 v[18:21], v[210:213], v[186:189], v[18:21]
	v_mfma_f32_16x16x32_bf16 v[6:9], v[202:205], v[194:197], v[6:9]
	v_mfma_f32_16x16x32_bf16 v[2:5], v[210:213], v[194:197], v[2:5]
	v_mfma_f32_16x16x32_bf16 v[56:59], v[206:209], v[174:177], v[56:59]
	v_mfma_f32_16x16x32_bf16 v[52:55], v[214:217], v[174:177], v[52:55]
	v_mfma_f32_16x16x32_bf16 v[40:43], v[206:209], v[182:185], v[40:43]
	v_mfma_f32_16x16x32_bf16 v[36:39], v[214:217], v[182:185], v[36:39]
	v_mfma_f32_16x16x32_bf16 v[22:25], v[206:209], v[190:193], v[22:25]
	v_mfma_f32_16x16x32_bf16 v[18:21], v[214:217], v[190:193], v[18:21]
	v_mfma_f32_16x16x32_bf16 v[6:9], v[206:209], v[198:201], v[6:9]
	v_mfma_f32_16x16x32_bf16 v[2:5], v[214:217], v[198:201], v[2:5]
	s_barrier
	s_setprio 0
	s_cbranch_scc0 .LBB0_287
	s_waitcnt lgkmcnt(0)
	s_cmpk_gt_i32 s58, 0xff
	s_mov_b64 s[18:19], 0xb000
	s_cbranch_scc1 .LBB0_283
	s_ashr_i32 s0, s58, 5
	s_mul_hi_i32 s19, s0, 0x1600
	s_mul_i32 s18, s0, 0x1600
	s_branch .LBB0_283

.LBB0_360:
	s_add_u32 s18, s28, 0x100
	v_mov_b32_e32 v2, 0
	s_addc_u32 s19, s29, 0
	s_mov_b32 s46, -2
	v_mov_b32_e32 v3, v2
	v_mov_b32_e32 v4, v2
	v_mov_b32_e32 v5, v2
	v_mov_b32_e32 v6, v2
	v_mov_b32_e32 v7, v2
	v_mov_b32_e32 v8, v2
	v_mov_b32_e32 v9, v2
	v_mov_b32_e32 v10, v2
	v_mov_b32_e32 v11, v2
	v_mov_b32_e32 v12, v2
	v_mov_b32_e32 v13, v2
	v_mov_b32_e32 v14, v2
	v_mov_b32_e32 v15, v2
	v_mov_b32_e32 v16, v2
	v_mov_b32_e32 v17, v2
	v_mov_b32_e32 v18, v2
	v_mov_b32_e32 v19, v2
	v_mov_b32_e32 v20, v2
	v_mov_b32_e32 v21, v2
	v_mov_b32_e32 v22, v2
	v_mov_b32_e32 v23, v2
	v_mov_b32_e32 v24, v2
	v_mov_b32_e32 v25, v2
	v_mov_b32_e32 v28, v2
	v_mov_b32_e32 v29, v2
	v_mov_b32_e32 v30, v2
	v_mov_b32_e32 v31, v2
	v_mov_b32_e32 v32, v2
	v_mov_b32_e32 v33, v2
	v_mov_b32_e32 v34, v2
	v_mov_b32_e32 v35, v2
	v_mov_b32_e32 v68, v2
	v_mov_b32_e32 v69, v2
	v_mov_b32_e32 v70, v2
	v_mov_b32_e32 v71, v2
	v_mov_b32_e32 v72, v2
	v_mov_b32_e32 v73, v2
	v_mov_b32_e32 v74, v2
	v_mov_b32_e32 v75, v2
	v_mov_b32_e32 v76, v2
	v_mov_b32_e32 v77, v2
	v_mov_b32_e32 v78, v2
	v_mov_b32_e32 v79, v2
	v_mov_b32_e32 v80, v2
	v_mov_b32_e32 v81, v2
	v_mov_b32_e32 v82, v2
	v_mov_b32_e32 v83, v2
	v_mov_b32_e32 v84, v2
	v_mov_b32_e32 v85, v2
	v_mov_b32_e32 v86, v2
	v_mov_b32_e32 v87, v2
	v_mov_b32_e32 v88, v2
	v_mov_b32_e32 v89, v2
	v_mov_b32_e32 v90, v2
	v_mov_b32_e32 v91, v2
	v_mov_b32_e32 v92, v2
	v_mov_b32_e32 v93, v2
	v_mov_b32_e32 v94, v2
	v_mov_b32_e32 v95, v2
	v_mov_b32_e32 v96, v2
	v_mov_b32_e32 v97, v2
	v_mov_b32_e32 v98, v2
	v_mov_b32_e32 v99, v2
	s_waitcnt vmcnt(0)
	v_mov_b32_e32 v36, v2
	v_mov_b32_e32 v37, v2
	v_mov_b32_e32 v38, v2
	v_mov_b32_e32 v39, v2
	v_mov_b32_e32 v40, v2
	v_mov_b32_e32 v41, v2
	v_mov_b32_e32 v42, v2
	v_mov_b32_e32 v43, v2
	v_mov_b32_e32 v44, v2
	v_mov_b32_e32 v45, v2
	v_mov_b32_e32 v46, v2
	v_mov_b32_e32 v47, v2
	v_mov_b32_e32 v48, v2
	v_mov_b32_e32 v49, v2
	v_mov_b32_e32 v50, v2
	v_mov_b32_e32 v51, v2
	v_mov_b32_e32 v52, v2
	v_mov_b32_e32 v53, v2
	v_mov_b32_e32 v54, v2
	v_mov_b32_e32 v55, v2
	v_mov_b32_e32 v56, v2
	v_mov_b32_e32 v57, v2
	v_mov_b32_e32 v58, v2
	v_mov_b32_e32 v59, v2
	v_mov_b32_e32 v60, v2
	v_mov_b32_e32 v61, v2
	v_mov_b32_e32 v62, v2
	v_mov_b32_e32 v63, v2
	v_mov_b32_e32 v64, v2
	v_mov_b32_e32 v65, v2
	v_mov_b32_e32 v66, v2
	v_mov_b32_e32 v67, v2
	v_mov_b32_e32 v100, v2
	v_mov_b32_e32 v101, v2
	v_mov_b32_e32 v102, v2
	v_mov_b32_e32 v103, v2
	v_mov_b32_e32 v104, v2
	v_mov_b32_e32 v105, v2
	v_mov_b32_e32 v106, v2
	v_mov_b32_e32 v107, v2
	v_mov_b32_e32 v108, v2
	v_mov_b32_e32 v109, v2
	v_mov_b32_e32 v110, v2
	v_mov_b32_e32 v111, v2
	v_mov_b32_e32 v112, v2
	v_mov_b32_e32 v113, v2
	v_mov_b32_e32 v114, v2
	v_mov_b32_e32 v115, v2
	v_mov_b32_e32 v116, v2
	v_mov_b32_e32 v117, v2
	v_mov_b32_e32 v118, v2
	v_mov_b32_e32 v119, v2
	v_mov_b32_e32 v120, v2
	v_mov_b32_e32 v121, v2
	v_mov_b32_e32 v122, v2
	v_mov_b32_e32 v123, v2
	v_mov_b32_e32 v124, v2
	v_mov_b32_e32 v125, v2
	v_mov_b32_e32 v126, v2
	v_mov_b32_e32 v127, v2
	v_mov_b32_e32 v128, v2
	v_mov_b32_e32 v129, v2
	v_mov_b32_e32 v130, v2
	v_mov_b32_e32 v131, v2
	v_add_u32_e32 v160, 0x10000, v222
	ds_read_b128 v[132:135], v160
	ds_read_b128 v[136:139], v160 offset:1024
	ds_read_b128 v[156:159], v160 offset:2048
	ds_read_b128 v[160:163], v160 offset:3072
	s_add_u32 s28, s26, 0x100
	s_addc_u32 s29, s27, 0
	s_add_i32 s0, 0, 0x10000
	s_cmp_eq_u32 s46, 40
	s_cselect_b32 s35, s45, s29
	s_cselect_b32 s34, s44, s28
	s_cselect_b32 s31, s23, s19
	s_cselect_b32 s30, s22, s18
.LBB0_361:
	s_add_i32 m0, s20, 0xc000
	ds_read_b128 v[172:175], v224
	ds_read_b128 v[176:179], v224 offset:1024
	ds_read_b128 v[180:183], v224 offset:2048
	ds_read_b128 v[184:187], v224 offset:3072
	ds_read_b128 v[188:191], v224 offset:4096
	ds_read_b128 v[192:195], v224 offset:5120
	ds_read_b128 v[196:199], v224 offset:6144
	ds_read_b128 v[200:203], v224 offset:7168
	global_load_lds_dwordx4 v152, s[26:27]
	v_lshl_add_u64 v[164:165], s[26:27], 0, v[154:155]
	s_add_i32 m0, s20, 0xe000
	s_nop 0
	global_load_lds_dwordx4 v[164:165], off
	s_waitcnt vmcnt(10) lgkmcnt(8)
	s_setprio 1
	s_barrier
	s_waitcnt lgkmcnt(0)
	v_mfma_f32_16x16x32_bf16 v[128:131], v[132:135], v[172:175], v[128:131]
	v_mfma_f32_16x16x32_bf16 v[124:127], v[156:159], v[172:175], v[124:127]
	v_mfma_f32_16x16x32_bf16 v[120:123], v[132:135], v[180:183], v[120:123]
	v_mfma_f32_16x16x32_bf16 v[116:119], v[156:159], v[180:183], v[116:119]
	v_mfma_f32_16x16x32_bf16 v[112:115], v[132:135], v[188:191], v[112:115]
	v_mfma_f32_16x16x32_bf16 v[108:111], v[156:159], v[188:191], v[108:111]
	v_mfma_f32_16x16x32_bf16 v[104:107], v[132:135], v[196:199], v[104:107]
	v_mfma_f32_16x16x32_bf16 v[100:103], v[156:159], v[196:199], v[100:103]
	v_mfma_f32_16x16x32_bf16 v[128:131], v[136:139], v[176:179], v[128:131]
	v_mfma_f32_16x16x32_bf16 v[124:127], v[160:163], v[176:179], v[124:127]
	v_mfma_f32_16x16x32_bf16 v[120:123], v[136:139], v[184:187], v[120:123]
	v_mfma_f32_16x16x32_bf16 v[116:119], v[160:163], v[184:187], v[116:119]
	v_mfma_f32_16x16x32_bf16 v[112:115], v[136:139], v[192:195], v[112:115]
	v_mfma_f32_16x16x32_bf16 v[108:111], v[160:163], v[192:195], v[108:111]
	v_mfma_f32_16x16x32_bf16 v[104:107], v[136:139], v[200:203], v[104:107]
	v_mfma_f32_16x16x32_bf16 v[100:103], v[160:163], v[200:203], v[100:103]
	s_barrier
	s_setprio 0
	s_add_i32 s26, 0, 0x14000
	v_add_u32_e32 v164, s26, v222
	s_add_i32 s0, s0, s17
	ds_read_b128 v[204:207], v164
	ds_read_b128 v[208:211], v164 offset:1024
	ds_read_b128 v[212:215], v164 offset:2048
	ds_read_b128 v[216:219], v164 offset:3072
	v_lshl_add_u64 v[164:165], s[30:31], 0, v[26:27]
	s_mov_b32 m0, s0
	v_lshl_add_u64 v[166:167], s[30:31], 0, v[140:141]
	global_load_lds_dwordx4 v[164:165], off
	s_add_i32 m0, s0, 0x2000
	s_nop 0
	global_load_lds_dwordx4 v[166:167], off
	s_waitcnt vmcnt(10)
	s_setprio 1
	s_barrier
	s_waitcnt lgkmcnt(0)
	v_mfma_f32_16x16x32_bf16 v[64:67], v[204:207], v[172:175], v[64:67]
	v_mfma_f32_16x16x32_bf16 v[60:63], v[212:215], v[172:175], v[60:63]
	v_mfma_f32_16x16x32_bf16 v[56:59], v[204:207], v[180:183], v[56:59]
	v_mfma_f32_16x16x32_bf16 v[52:55], v[212:215], v[180:183], v[52:55]
	v_mfma_f32_16x16x32_bf16 v[48:51], v[204:207], v[188:191], v[48:51]
	v_mfma_f32_16x16x32_bf16 v[44:47], v[212:215], v[188:191], v[44:47]
	v_mfma_f32_16x16x32_bf16 v[40:43], v[204:207], v[196:199], v[40:43]
	v_mfma_f32_16x16x32_bf16 v[36:39], v[212:215], v[196:199], v[36:39]
	v_mfma_f32_16x16x32_bf16 v[64:67], v[208:211], v[176:179], v[64:67]
	v_mfma_f32_16x16x32_bf16 v[60:63], v[216:219], v[176:179], v[60:63]
	v_mfma_f32_16x16x32_bf16 v[56:59], v[208:211], v[184:187], v[56:59]
	v_mfma_f32_16x16x32_bf16 v[52:55], v[216:219], v[184:187], v[52:55]
	v_mfma_f32_16x16x32_bf16 v[48:51], v[208:211], v[192:195], v[48:51]
	v_mfma_f32_16x16x32_bf16 v[44:47], v[216:219], v[192:195], v[44:47]
	v_mfma_f32_16x16x32_bf16 v[40:43], v[208:211], v[200:203], v[40:43]
	v_mfma_f32_16x16x32_bf16 v[36:39], v[216:219], v[200:203], v[36:39]
	s_barrier
	s_setprio 0
	s_mov_b32 m0, s20
	v_lshl_add_u64 v[168:169], s[34:35], 0, v[144:145]
	ds_read_b128 v[172:175], v224 offset:16384
	ds_read_b128 v[176:179], v224 offset:17408
	ds_read_b128 v[180:183], v224 offset:18432
	ds_read_b128 v[184:187], v224 offset:19456
	ds_read_b128 v[188:191], v224 offset:20480
	ds_read_b128 v[192:195], v224 offset:21504
	ds_read_b128 v[196:199], v224 offset:22528
	ds_read_b128 v[200:203], v224 offset:23552
	global_load_lds_dwordx4 v[168:169], off
	v_lshl_add_u64 v[220:221], s[34:35], 0, v[142:143]
	s_mov_b32 m0, s21
	s_nop 0
	global_load_lds_dwordx4 v[220:221], off
	s_waitcnt vmcnt(10)
	s_setprio 1
	s_barrier
	s_waitcnt lgkmcnt(0)
	v_mfma_f32_16x16x32_bf16 v[96:99], v[132:135], v[172:175], v[96:99]
	v_mfma_f32_16x16x32_bf16 v[92:95], v[156:159], v[172:175], v[92:95]
	v_mfma_f32_16x16x32_bf16 v[88:91], v[132:135], v[180:183], v[88:91]
	v_mfma_f32_16x16x32_bf16 v[84:87], v[156:159], v[180:183], v[84:87]
	v_mfma_f32_16x16x32_bf16 v[80:83], v[132:135], v[188:191], v[80:83]
	v_mfma_f32_16x16x32_bf16 v[76:79], v[156:159], v[188:191], v[76:79]
	v_mfma_f32_16x16x32_bf16 v[72:75], v[132:135], v[196:199], v[72:75]
	v_mfma_f32_16x16x32_bf16 v[68:71], v[156:159], v[196:199], v[68:71]
	v_mfma_f32_16x16x32_bf16 v[96:99], v[136:139], v[176:179], v[96:99]
	v_mfma_f32_16x16x32_bf16 v[92:95], v[160:163], v[176:179], v[92:95]
	v_mfma_f32_16x16x32_bf16 v[88:91], v[136:139], v[184:187], v[88:91]
	v_mfma_f32_16x16x32_bf16 v[84:87], v[160:163], v[184:187], v[84:87]
	v_mfma_f32_16x16x32_bf16 v[80:83], v[136:139], v[192:195], v[80:83]
	v_mfma_f32_16x16x32_bf16 v[76:79], v[160:163], v[192:195], v[76:79]
	v_mfma_f32_16x16x32_bf16 v[72:75], v[136:139], v[200:203], v[72:75]
	v_mfma_f32_16x16x32_bf16 v[68:71], v[160:163], v[200:203], v[68:71]
	s_barrier
	s_setprio 0
	s_add_u32 s0, s30, 0xb0000
	s_addc_u32 s1, s31, 0
	s_add_i32 s26, s26, s17
	s_mov_b32 m0, s26
	s_nop 0
	global_load_lds_dwordx4 v26, s[0:1]
	s_add_i32 m0, s26, 0x2000
	s_nop 0
	global_load_lds_dwordx4 v140, s[0:1]
	v_add_u32_e32 v160, 0x18000, v222
	ds_read_b128 v[132:135], v160
	ds_read_b128 v[136:139], v160 offset:1024
	ds_read_b128 v[156:159], v160 offset:2048
	ds_read_b128 v[160:163], v160 offset:3072
	s_waitcnt vmcnt(10)
	s_setprio 1
	s_barrier
	v_mfma_f32_16x16x32_bf16 v[32:35], v[204:207], v[172:175], v[32:35]
	v_mfma_f32_16x16x32_bf16 v[28:31], v[212:215], v[172:175], v[28:31]
	v_mfma_f32_16x16x32_bf16 v[22:25], v[204:207], v[180:183], v[22:25]
	v_mfma_f32_16x16x32_bf16 v[18:21], v[212:215], v[180:183], v[18:21]
	v_mfma_f32_16x16x32_bf16 v[14:17], v[204:207], v[188:191], v[14:17]
	v_mfma_f32_16x16x32_bf16 v[10:13], v[212:215], v[188:191], v[10:13]
	v_mfma_f32_16x16x32_bf16 v[6:9], v[204:207], v[196:199], v[6:9]
	v_mfma_f32_16x16x32_bf16 v[2:5], v[212:215], v[196:199], v[2:5]
	v_mfma_f32_16x16x32_bf16 v[32:35], v[208:211], v[176:179], v[32:35]
	v_mfma_f32_16x16x32_bf16 v[28:31], v[216:219], v[176:179], v[28:31]
	v_mfma_f32_16x16x32_bf16 v[22:25], v[208:211], v[184:187], v[22:25]
	v_mfma_f32_16x16x32_bf16 v[18:21], v[216:219], v[184:187], v[18:21]
	v_mfma_f32_16x16x32_bf16 v[14:17], v[208:211], v[192:195], v[14:17]
	v_mfma_f32_16x16x32_bf16 v[10:13], v[216:219], v[192:195], v[10:13]
	v_mfma_f32_16x16x32_bf16 v[6:9], v[208:211], v[200:203], v[6:9]
	v_mfma_f32_16x16x32_bf16 v[2:5], v[216:219], v[200:203], v[2:5]
	s_barrier
	s_setprio 0
	s_add_i32 s26, 0, 0x18000
	s_add_u32 s0, s34, 0xb0000
	s_addc_u32 s1, s35, 0
	s_mov_b32 m0, s36
	ds_read_b128 v[172:175], v224 offset:32768
	ds_read_b128 v[176:179], v224 offset:33792
	ds_read_b128 v[180:183], v224 offset:34816
	ds_read_b128 v[184:187], v224 offset:35840
	ds_read_b128 v[188:191], v224 offset:36864
	ds_read_b128 v[192:195], v224 offset:37888
	ds_read_b128 v[196:199], v224 offset:38912
	ds_read_b128 v[200:203], v224 offset:39936
	global_load_lds_dwordx4 v144, s[0:1]
	s_mov_b32 m0, s37
	s_nop 0
	global_load_lds_dwordx4 v142, s[0:1]
	s_waitcnt vmcnt(10) lgkmcnt(8)
	s_setprio 1
	s_barrier
	s_waitcnt lgkmcnt(0)
	v_mfma_f32_16x16x32_bf16 v[128:131], v[132:135], v[172:175], v[128:131]
	v_mfma_f32_16x16x32_bf16 v[124:127], v[156:159], v[172:175], v[124:127]
	v_mfma_f32_16x16x32_bf16 v[120:123], v[132:135], v[180:183], v[120:123]
	v_mfma_f32_16x16x32_bf16 v[116:119], v[156:159], v[180:183], v[116:119]
	v_mfma_f32_16x16x32_bf16 v[112:115], v[132:135], v[188:191], v[112:115]
	v_mfma_f32_16x16x32_bf16 v[108:111], v[156:159], v[188:191], v[108:111]
	v_mfma_f32_16x16x32_bf16 v[104:107], v[132:135], v[196:199], v[104:107]
	v_mfma_f32_16x16x32_bf16 v[100:103], v[156:159], v[196:199], v[100:103]
	v_mfma_f32_16x16x32_bf16 v[128:131], v[136:139], v[176:179], v[128:131]
	v_mfma_f32_16x16x32_bf16 v[124:127], v[160:163], v[176:179], v[124:127]
	v_mfma_f32_16x16x32_bf16 v[120:123], v[136:139], v[184:187], v[120:123]
	v_mfma_f32_16x16x32_bf16 v[116:119], v[160:163], v[184:187], v[116:119]
	v_mfma_f32_16x16x32_bf16 v[112:115], v[136:139], v[192:195], v[112:115]
	v_mfma_f32_16x16x32_bf16 v[108:111], v[160:163], v[192:195], v[108:111]
	v_mfma_f32_16x16x32_bf16 v[104:107], v[136:139], v[200:203], v[104:107]
	v_mfma_f32_16x16x32_bf16 v[100:103], v[160:163], v[200:203], v[100:103]
	s_barrier
	s_setprio 0
	s_add_i32 s27, 0, 0x1c000
	s_add_i32 s0, s26, s17
	v_add_u32_e32 v216, s27, v222
	v_lshl_add_u64 v[164:165], v[164:165], 0, s[12:13]
	s_mov_b32 m0, s0
	ds_read_b128 v[204:207], v216
	ds_read_b128 v[208:211], v216 offset:1024
	ds_read_b128 v[212:215], v216 offset:2048
	ds_read_b128 v[216:219], v216 offset:3072
	global_load_lds_dwordx4 v[164:165], off
	v_lshl_add_u64 v[164:165], v[166:167], 0, s[12:13]
	s_add_i32 m0, s0, 0x2000
	s_nop 0
	global_load_lds_dwordx4 v[164:165], off
	s_waitcnt vmcnt(10)
	s_setprio 1
	s_barrier
	s_waitcnt lgkmcnt(0)
	v_mfma_f32_16x16x32_bf16 v[64:67], v[204:207], v[172:175], v[64:67]
	v_mfma_f32_16x16x32_bf16 v[60:63], v[212:215], v[172:175], v[60:63]
	v_mfma_f32_16x16x32_bf16 v[56:59], v[204:207], v[180:183], v[56:59]
	v_mfma_f32_16x16x32_bf16 v[52:55], v[212:215], v[180:183], v[52:55]
	v_mfma_f32_16x16x32_bf16 v[48:51], v[204:207], v[188:191], v[48:51]
	v_mfma_f32_16x16x32_bf16 v[44:47], v[212:215], v[188:191], v[44:47]
	v_mfma_f32_16x16x32_bf16 v[40:43], v[204:207], v[196:199], v[40:43]
	v_mfma_f32_16x16x32_bf16 v[36:39], v[212:215], v[196:199], v[36:39]
	v_mfma_f32_16x16x32_bf16 v[64:67], v[208:211], v[176:179], v[64:67]
	v_mfma_f32_16x16x32_bf16 v[60:63], v[216:219], v[176:179], v[60:63]
	v_mfma_f32_16x16x32_bf16 v[56:59], v[208:211], v[184:187], v[56:59]
	v_mfma_f32_16x16x32_bf16 v[52:55], v[216:219], v[184:187], v[52:55]
	v_mfma_f32_16x16x32_bf16 v[48:51], v[208:211], v[192:195], v[48:51]
	v_mfma_f32_16x16x32_bf16 v[44:47], v[216:219], v[192:195], v[44:47]
	v_mfma_f32_16x16x32_bf16 v[40:43], v[208:211], v[200:203], v[40:43]
	v_mfma_f32_16x16x32_bf16 v[36:39], v[216:219], v[200:203], v[36:39]
	s_barrier
	s_setprio 0
	s_mov_b32 m0, s59
	v_lshl_add_u64 v[164:165], v[168:169], 0, s[12:13]
	ds_read_b128 v[172:175], v224 offset:49152
	ds_read_b128 v[176:179], v224 offset:50176
	ds_read_b128 v[180:183], v224 offset:51200
	ds_read_b128 v[184:187], v224 offset:52224
	ds_read_b128 v[188:191], v224 offset:53248
	ds_read_b128 v[192:195], v224 offset:54272
	ds_read_b128 v[196:199], v224 offset:55296
	ds_read_b128 v[200:203], v224 offset:56320
	global_load_lds_dwordx4 v[164:165], off
	v_lshl_add_u64 v[164:165], v[220:221], 0, s[12:13]
	s_mov_b32 m0, s68
	s_nop 0
	global_load_lds_dwordx4 v[164:165], off
	s_waitcnt vmcnt(10)
	s_setprio 1
	s_barrier
	s_waitcnt lgkmcnt(0)
	v_mfma_f32_16x16x32_bf16 v[96:99], v[132:135], v[172:175], v[96:99]
	v_mfma_f32_16x16x32_bf16 v[92:95], v[156:159], v[172:175], v[92:95]
	v_mfma_f32_16x16x32_bf16 v[88:91], v[132:135], v[180:183], v[88:91]
	v_mfma_f32_16x16x32_bf16 v[84:87], v[156:159], v[180:183], v[84:87]
	v_mfma_f32_16x16x32_bf16 v[80:83], v[132:135], v[188:191], v[80:83]
	v_mfma_f32_16x16x32_bf16 v[76:79], v[156:159], v[188:191], v[76:79]
	v_mfma_f32_16x16x32_bf16 v[72:75], v[132:135], v[196:199], v[72:75]
	v_mfma_f32_16x16x32_bf16 v[68:71], v[156:159], v[196:199], v[68:71]
	v_mfma_f32_16x16x32_bf16 v[96:99], v[136:139], v[176:179], v[96:99]
	v_mfma_f32_16x16x32_bf16 v[92:95], v[160:163], v[176:179], v[92:95]
	v_mfma_f32_16x16x32_bf16 v[88:91], v[136:139], v[184:187], v[88:91]
	v_mfma_f32_16x16x32_bf16 v[84:87], v[160:163], v[184:187], v[84:87]
	v_mfma_f32_16x16x32_bf16 v[80:83], v[136:139], v[192:195], v[80:83]
	v_mfma_f32_16x16x32_bf16 v[76:79], v[160:163], v[192:195], v[76:79]
	v_mfma_f32_16x16x32_bf16 v[72:75], v[136:139], v[200:203], v[72:75]
	v_mfma_f32_16x16x32_bf16 v[68:71], v[160:163], v[200:203], v[68:71]
	s_barrier
	s_setprio 0
	s_add_u32 s0, s30, 0xb0080
	s_addc_u32 s1, s31, 0
	s_add_i32 s26, s27, s17
	s_mov_b32 m0, s26
	s_nop 0
	global_load_lds_dwordx4 v26, s[0:1]
	s_add_i32 m0, s26, 0x2000
	s_nop 0
	global_load_lds_dwordx4 v140, s[0:1]
	v_add_u32_e32 v160, 0x10000, v222
	ds_read_b128 v[132:135], v160
	ds_read_b128 v[136:139], v160 offset:1024
	ds_read_b128 v[156:159], v160 offset:2048
	ds_read_b128 v[160:163], v160 offset:3072
	s_add_i32 s46, s46, 2
	s_add_u32 s18, s18, 0x100
	s_addc_u32 s19, s19, 0
	s_mov_b64 s[26:27], s[28:29]
	s_cmp_gt_u32 s46, 41
	s_cbranch_scc1 .Lth__361
	s_add_u32 s28, s26, 0x100
	s_addc_u32 s29, s27, 0
	s_add_i32 s0, 0, 0x10000
	s_cmp_eq_u32 s46, 40
	s_cselect_b32 s35, s45, s29
	s_cselect_b32 s34, s44, s28
	s_cselect_b32 s31, s23, s19
	s_cselect_b32 s30, s22, s18
	s_cmp_gt_u32 s46, 41
.Lth__361:
	s_waitcnt vmcnt(10)
	s_setprio 1
	s_barrier
	v_mfma_f32_16x16x32_bf16 v[32:35], v[204:207], v[172:175], v[32:35]
	v_mfma_f32_16x16x32_bf16 v[28:31], v[212:215], v[172:175], v[28:31]
	v_mfma_f32_16x16x32_bf16 v[22:25], v[204:207], v[180:183], v[22:25]
	v_mfma_f32_16x16x32_bf16 v[18:21], v[212:215], v[180:183], v[18:21]
	v_mfma_f32_16x16x32_bf16 v[14:17], v[204:207], v[188:191], v[14:17]
	v_mfma_f32_16x16x32_bf16 v[10:13], v[212:215], v[188:191], v[10:13]
	v_mfma_f32_16x16x32_bf16 v[6:9], v[204:207], v[196:199], v[6:9]
	v_mfma_f32_16x16x32_bf16 v[2:5], v[212:215], v[196:199], v[2:5]
	v_mfma_f32_16x16x32_bf16 v[32:35], v[208:211], v[176:179], v[32:35]
	v_mfma_f32_16x16x32_bf16 v[28:31], v[216:219], v[176:179], v[28:31]
	v_mfma_f32_16x16x32_bf16 v[22:25], v[208:211], v[184:187], v[22:25]
	v_mfma_f32_16x16x32_bf16 v[18:21], v[216:219], v[184:187], v[18:21]
	v_mfma_f32_16x16x32_bf16 v[14:17], v[208:211], v[192:195], v[14:17]
	v_mfma_f32_16x16x32_bf16 v[10:13], v[216:219], v[192:195], v[10:13]
	v_mfma_f32_16x16x32_bf16 v[6:9], v[208:211], v[200:203], v[6:9]
	v_mfma_f32_16x16x32_bf16 v[2:5], v[216:219], v[200:203], v[2:5]
	s_barrier
	s_setprio 0
	s_cbranch_scc0 .LBB0_361
	s_waitcnt lgkmcnt(0)
	s_min_i32 s0, s24, 0x100
	s_ashr_i32 s0, s0, 5
	s_ashr_i32 s1, s0, 31
	s_add_i32 s18, s24, 0xffffff00
	s_cmpk_lt_i32 s24, 0x100
	s_cselect_b32 s18, s24, s18
	s_cselect_b32 s27, 0, s58
	s_cselect_b32 s26, 0, s57
	s_ashr_i32 s19, s18, 31
	s_lshl_b64 s[18:19], s[18:19], 19
	s_add_u32 s26, s50, s26
	v_lshl_or_b32 v178, s25, 8, v223
	s_addc_u32 s27, s51, s27
	s_ashr_i32 s25, s24, 31
	v_lshl_add_u64 v[132:133], s[18:19], 0, v[146:147]
	s_lshl_b64 s[18:19], s[24:25], 19
	v_lshl_add_u64 v[184:185], v[148:149], 0, s[18:19]
	s_lshl_b64 s[24:25], s[24:25], 10
	s_mul_i32 s18, s0, 0x9000
	v_ashrrev_i32_e32 v179, 31, v178
	s_mul_hi_i32 s19, s0, 0x9000
	s_add_u32 s18, s48, s18
	s_addc_u32 s19, s49, s19
	v_lshlrev_b64 v[186:187], 2, v[178:179]
	v_lshl_add_u64 v[156:157], s[18:19], 0, v[186:187]
	v_lshl_add_u64 v[180:181], v[132:133], 0, v[178:179]
	v_lshl_add_u64 v[182:183], v[132:133], 1, s[26:27]
	global_load_dwordx4 v[132:135], v[156:157], off offset:16
	global_load_dwordx4 v[136:139], v[156:157], off
	s_lshl_b64 s[0:1], s[0:1], 12
	s_add_u32 s28, s52, s0
	s_addc_u32 s29, s53, s1
	v_lshl_add_u64 v[196:197], v[180:181], 1, s[26:27]
	v_lshl_add_u64 v[180:181], s[28:29], 0, v[186:187]
	v_add_co_u32_e32 v210, vcc, s65, v196
	v_lshlrev_b64 v[188:189], 1, v[178:179]
	s_nop 0
	v_addc_co_u32_e32 v211, vcc, 0, v197, vcc
	s_mov_b32 s1, 0x20000
	v_lshl_add_u64 v[178:179], v[184:185], 0, v[188:189]
	v_add_co_u32_e32 v184, vcc, s1, v196
	s_mov_b32 s18, 0x30000
	s_nop 0
	v_addc_co_u32_e32 v185, vcc, 0, v197, vcc
	v_lshl_add_u64 v[182:183], v[182:183], 0, v[188:189]
	v_add_co_u32_e32 v188, vcc, s18, v196
	s_mov_b32 s0, 0x8000
	s_nop 0
	v_addc_co_u32_e32 v189, vcc, 0, v197, vcc
	s_mov_b32 s19, 0x80000
	s_mov_b32 s26, 0x90000
	s_waitcnt vmcnt(0)
	v_pk_mul_f32 v[172:173], v[134:135], 0.5 op_sel_hi:[1,0]
	v_pk_mul_f32 v[176:177], v[138:139], 0.5 op_sel_hi:[1,0]
	v_pk_mul_f32 v[174:175], v[136:137], 0.5 op_sel_hi:[1,0]
	v_pk_mul_f32 v[164:165], v[132:133], 0.5 op_sel_hi:[1,0]
	global_load_dwordx4 v[132:135], v[156:157], off offset:528
	global_load_dwordx4 v[136:139], v[156:157], off offset:512
	s_waitcnt vmcnt(0)
	v_pk_mul_f32 v[158:159], v[134:135], 0.5 op_sel_hi:[1,0]
	v_pk_mul_f32 v[162:163], v[138:139], 0.5 op_sel_hi:[1,0]
	v_pk_mul_f32 v[160:161], v[136:137], 0.5 op_sel_hi:[1,0]
	v_pk_mul_f32 v[156:157], v[132:133], 0.5 op_sel_hi:[1,0]
	global_load_dwordx4 v[132:135], v[180:181], off offset:16
	global_load_dwordx4 v[136:139], v[180:181], off
	global_load_dwordx4 v[190:193], v[196:197], off offset:2048
	global_load_dwordx4 v[198:201], v[210:211], off offset:2048
	global_load_dwordx4 v[202:205], v[184:185], off offset:2048
	global_load_dwordx4 v[206:209], v[188:189], off offset:2048
	s_waitcnt vmcnt(0)
	v_lshlrev_b32_e32 v186, 16, v190
	v_and_b32_e32 v187, 0xffff0000, v190
	v_lshlrev_b32_e32 v190, 16, v191
	v_and_b32_e32 v191, 0xffff0000, v191
	v_lshlrev_b32_e32 v194, 16, v192
	v_and_b32_e32 v195, 0xffff0000, v192
	v_lshlrev_b32_e32 v192, 16, v193
	v_and_b32_e32 v193, 0xffff0000, v193
	v_pk_fma_f32 v[130:131], v[130:131], v[176:177], v[190:191]
	v_pk_fma_f32 v[128:129], v[128:129], v[174:175], v[186:187]
	v_pk_fma_f32 v[126:127], v[126:127], v[172:173], v[192:193]
	v_pk_fma_f32 v[124:125], v[124:125], v[164:165], v[194:195]
	v_cvt_pk_bf16_f32 v190, v128, v129
	v_cvt_pk_bf16_f32 v191, v130, v131
	v_cvt_pk_bf16_f32 v192, v124, v125
	v_cvt_pk_bf16_f32 v193, v126, v127
	v_lshlrev_b32_e32 v130, 16, v190
	v_and_b32_e32 v131, 0xffff0000, v190
	v_lshlrev_b32_e32 v128, 16, v191
	v_and_b32_e32 v129, 0xffff0000, v191
	v_lshlrev_b32_e32 v126, 16, v192
	v_and_b32_e32 v127, 0xffff0000, v192
	v_lshlrev_b32_e32 v124, 16, v193
	v_and_b32_e32 v125, 0xffff0000, v193
	v_lshlrev_b32_e32 v212, 16, v198
	v_and_b32_e32 v213, 0xffff0000, v198
	v_lshlrev_b32_e32 v198, 16, v199
	v_and_b32_e32 v199, 0xffff0000, v199
	global_store_dwordx4 v[182:183], v[190:193], off offset:2048
	v_pk_mul_f32 v[186:187], v[138:139], v[128:129]
	v_pk_mul_f32 v[194:195], v[134:135], v[124:125]
	v_pk_mul_f32 v[190:191], v[136:137], v[130:131]
	v_pk_mul_f32 v[192:193], v[132:133], v[126:127]
	v_lshlrev_b32_e32 v214, 16, v200
	v_and_b32_e32 v215, 0xffff0000, v200
	v_lshlrev_b32_e32 v200, 16, v201
	v_and_b32_e32 v201, 0xffff0000, v201
	v_cvt_pk_bf16_f32 v190, v190, v191
	v_cvt_pk_bf16_f32 v191, v186, v187
	v_cvt_pk_bf16_f32 v192, v192, v193
	v_cvt_pk_bf16_f32 v193, v194, v195
	v_pk_fma_f32 v[122:123], v[122:123], v[176:177], v[198:199]
	v_pk_fma_f32 v[120:121], v[120:121], v[174:175], v[212:213]
	global_store_dwordx4 v[178:179], v[190:193], off
	v_pk_fma_f32 v[118:119], v[118:119], v[172:173], v[200:201]
	v_pk_fma_f32 v[116:117], v[116:117], v[164:165], v[214:215]
	v_cvt_pk_bf16_f32 v190, v120, v121
	v_cvt_pk_bf16_f32 v191, v122, v123
	v_add_co_u32_e32 v186, vcc, s65, v182
	v_cvt_pk_bf16_f32 v192, v116, v117
	v_cvt_pk_bf16_f32 v193, v118, v119
	v_addc_co_u32_e32 v187, vcc, 0, v183, vcc
	v_lshlrev_b32_e32 v122, 16, v190
	v_and_b32_e32 v123, 0xffff0000, v190
	v_lshlrev_b32_e32 v120, 16, v191
	v_and_b32_e32 v121, 0xffff0000, v191
	global_store_dwordx4 v[186:187], v[190:193], off offset:2048
	v_lshlrev_b32_e32 v118, 16, v192
	v_and_b32_e32 v119, 0xffff0000, v192
	v_lshlrev_b32_e32 v116, 16, v193
	v_and_b32_e32 v117, 0xffff0000, v193
	v_pk_mul_f32 v[190:191], v[138:139], v[120:121]
	v_pk_mul_f32 v[192:193], v[136:137], v[122:123]
	v_pk_mul_f32 v[198:199], v[134:135], v[116:117]
	v_pk_mul_f32 v[194:195], v[132:133], v[118:119]
	v_cvt_pk_bf16_f32 v192, v192, v193
	v_cvt_pk_bf16_f32 v193, v190, v191
	v_add_co_u32_e32 v190, vcc, s0, v178
	v_cvt_pk_bf16_f32 v194, v194, v195
	v_cvt_pk_bf16_f32 v195, v198, v199
	v_addc_co_u32_e32 v191, vcc, 0, v179, vcc
	global_store_dwordx4 v[190:191], v[192:195], off
	v_lshlrev_b32_e32 v198, 16, v202
	v_and_b32_e32 v199, 0xffff0000, v202
	v_add_co_u32_e32 v192, vcc, s19, v196
	v_lshlrev_b32_e32 v200, 16, v203
	s_nop 0
	v_addc_co_u32_e32 v193, vcc, 0, v197, vcc
	v_add_co_u32_e32 v194, vcc, s26, v196
	v_and_b32_e32 v201, 0xffff0000, v203
	global_load_dwordx4 v[212:215], v[192:193], off offset:2048
	v_addc_co_u32_e32 v195, vcc, 0, v197, vcc
	v_lshlrev_b32_e32 v202, 16, v204
	v_and_b32_e32 v203, 0xffff0000, v204
	v_lshlrev_b32_e32 v204, 16, v205
	v_and_b32_e32 v205, 0xffff0000, v205
	v_pk_fma_f32 v[114:115], v[114:115], v[176:177], v[200:201]
	v_pk_fma_f32 v[112:113], v[112:113], v[174:175], v[198:199]
	v_pk_fma_f32 v[110:111], v[110:111], v[172:173], v[204:205]
	v_pk_fma_f32 v[108:109], v[108:109], v[164:165], v[202:203]
	v_cvt_pk_bf16_f32 v200, v112, v113
	v_cvt_pk_bf16_f32 v201, v114, v115
	v_add_co_u32_e32 v198, vcc, s1, v182
	v_cvt_pk_bf16_f32 v202, v108, v109
	v_cvt_pk_bf16_f32 v203, v110, v111
	v_addc_co_u32_e32 v199, vcc, 0, v183, vcc
	v_lshlrev_b32_e32 v114, 16, v200
	v_and_b32_e32 v115, 0xffff0000, v200
	v_lshlrev_b32_e32 v112, 16, v201
	v_and_b32_e32 v113, 0xffff0000, v201
	global_load_dwordx4 v[216:219], v[194:195], off offset:2048
	v_lshlrev_b32_e32 v110, 16, v202
	global_store_dwordx4 v[198:199], v[200:203], off offset:2048
	v_and_b32_e32 v111, 0xffff0000, v202
	v_lshlrev_b32_e32 v108, 16, v203
	v_and_b32_e32 v109, 0xffff0000, v203
	v_pk_mul_f32 v[200:201], v[138:139], v[112:113]
	v_pk_mul_f32 v[202:203], v[136:137], v[114:115]
	v_lshlrev_b32_e32 v220, 16, v206
	v_and_b32_e32 v221, 0xffff0000, v206
	v_lshlrev_b32_e32 v206, 16, v207
	v_and_b32_e32 v207, 0xffff0000, v207
	v_pk_mul_f32 v[238:239], v[134:135], v[108:109]
	v_pk_mul_f32 v[204:205], v[132:133], v[110:111]
	v_cvt_pk_bf16_f32 v202, v202, v203
	v_cvt_pk_bf16_f32 v203, v200, v201
	v_add_co_u32_e32 v200, vcc, s65, v178
	v_lshlrev_b32_e32 v234, 16, v208
	v_and_b32_e32 v235, 0xffff0000, v208
	v_lshlrev_b32_e32 v208, 16, v209
	v_and_b32_e32 v209, 0xffff0000, v209
	v_cvt_pk_bf16_f32 v204, v204, v205
	v_cvt_pk_bf16_f32 v205, v238, v239
	v_addc_co_u32_e32 v201, vcc, 0, v179, vcc
	v_pk_fma_f32 v[106:107], v[106:107], v[176:177], v[206:207]
	v_pk_fma_f32 v[104:105], v[104:105], v[174:175], v[220:221]
	global_store_dwordx4 v[200:201], v[202:205], off
	v_pk_fma_f32 v[102:103], v[102:103], v[172:173], v[208:209]
	v_pk_fma_f32 v[100:101], v[100:101], v[164:165], v[234:235]
	v_cvt_pk_bf16_f32 v204, v104, v105
	v_cvt_pk_bf16_f32 v205, v106, v107
	v_add_co_u32_e32 v202, vcc, s18, v182
	v_cvt_pk_bf16_f32 v206, v100, v101
	v_cvt_pk_bf16_f32 v207, v102, v103
	v_addc_co_u32_e32 v203, vcc, 0, v183, vcc
	v_lshlrev_b32_e32 v106, 16, v204
	v_and_b32_e32 v107, 0xffff0000, v204
	v_lshlrev_b32_e32 v104, 16, v205
	v_and_b32_e32 v105, 0xffff0000, v205
	global_store_dwordx4 v[202:203], v[204:207], off offset:2048
	v_lshlrev_b32_e32 v102, 16, v206
	v_and_b32_e32 v103, 0xffff0000, v206
	v_lshlrev_b32_e32 v100, 16, v207
	v_and_b32_e32 v101, 0xffff0000, v207
	v_pk_mul_f32 v[204:205], v[138:139], v[104:105]
	v_pk_mul_f32 v[206:207], v[136:137], v[106:107]
	s_mov_b32 s0, 0x18000
	v_pk_mul_f32 v[220:221], v[134:135], v[100:101]
	v_pk_mul_f32 v[208:209], v[132:133], v[102:103]
	v_cvt_pk_bf16_f32 v206, v206, v207
	v_cvt_pk_bf16_f32 v207, v204, v205
	v_add_co_u32_e32 v204, vcc, s0, v178
	v_cvt_pk_bf16_f32 v208, v208, v209
	v_cvt_pk_bf16_f32 v209, v220, v221
	v_addc_co_u32_e32 v205, vcc, 0, v179, vcc
	global_store_dwordx4 v[204:205], v[206:209], off
	s_mov_b32 s0, 0xb0000
	s_waitcnt vmcnt(0)
	v_lshlrev_b32_e32 v220, 16, v212
	v_add_co_u32_e32 v206, vcc, s76, v196
	v_and_b32_e32 v221, 0xffff0000, v212
	s_nop 0
	v_addc_co_u32_e32 v207, vcc, 0, v197, vcc
	global_load_dwordx4 v[238:241], v[206:207], off offset:2048
	v_add_co_u32_e32 v208, vcc, s0, v196
	v_lshlrev_b32_e32 v212, 16, v213
	s_nop 0
	v_addc_co_u32_e32 v209, vcc, 0, v197, vcc
	global_load_dwordx4 v[242:245], v[208:209], off offset:2048
	v_and_b32_e32 v213, 0xffff0000, v213
	v_lshlrev_b32_e32 v234, 16, v214
	v_and_b32_e32 v235, 0xffff0000, v214
	v_lshlrev_b32_e32 v214, 16, v215
	v_and_b32_e32 v215, 0xffff0000, v215
	v_pk_fma_f32 v[98:99], v[98:99], v[176:177], v[212:213]
	v_pk_fma_f32 v[96:97], v[96:97], v[174:175], v[220:221]
	v_pk_fma_f32 v[94:95], v[94:95], v[172:173], v[214:215]
	v_pk_fma_f32 v[92:93], v[92:93], v[164:165], v[234:235]
	v_cvt_pk_bf16_f32 v214, v96, v97
	v_cvt_pk_bf16_f32 v215, v98, v99
	v_add_co_u32_e32 v212, vcc, s19, v182
	v_lshlrev_b32_e32 v246, 16, v216
	v_and_b32_e32 v247, 0xffff0000, v216
	v_lshlrev_b32_e32 v248, 16, v217
	v_and_b32_e32 v249, 0xffff0000, v217
	v_cvt_pk_bf16_f32 v216, v92, v93
	v_cvt_pk_bf16_f32 v217, v94, v95
	v_addc_co_u32_e32 v213, vcc, 0, v183, vcc
	v_lshlrev_b32_e32 v98, 16, v214
	v_and_b32_e32 v99, 0xffff0000, v214
	v_lshlrev_b32_e32 v96, 16, v215
	v_and_b32_e32 v97, 0xffff0000, v215
	global_store_dwordx4 v[212:213], v[214:217], off offset:2048
	v_lshlrev_b32_e32 v94, 16, v216
	v_and_b32_e32 v95, 0xffff0000, v216
	v_lshlrev_b32_e32 v92, 16, v217
	v_and_b32_e32 v93, 0xffff0000, v217
	v_pk_mul_f32 v[214:215], v[138:139], v[96:97]
	v_pk_mul_f32 v[216:217], v[136:137], v[98:99]
	s_mov_b32 s1, 0x40000
	v_lshlrev_b32_e32 v250, 16, v218
	v_and_b32_e32 v251, 0xffff0000, v218
	v_lshlrev_b32_e32 v252, 16, v219
	v_and_b32_e32 v253, 0xffff0000, v219
	v_pk_mul_f32 v[220:221], v[134:135], v[92:93]
	v_pk_mul_f32 v[218:219], v[132:133], v[94:95]
	v_cvt_pk_bf16_f32 v216, v216, v217
	v_cvt_pk_bf16_f32 v217, v214, v215
	v_add_co_u32_e32 v214, vcc, s1, v178
	v_cvt_pk_bf16_f32 v218, v218, v219
	v_cvt_pk_bf16_f32 v219, v220, v221
	v_addc_co_u32_e32 v215, vcc, 0, v179, vcc
	v_pk_fma_f32 v[90:91], v[90:91], v[176:177], v[248:249]
	global_store_dwordx4 v[214:215], v[216:219], off
	v_pk_fma_f32 v[88:89], v[88:89], v[174:175], v[246:247]
	v_pk_fma_f32 v[86:87], v[86:87], v[172:173], v[252:253]
	v_pk_fma_f32 v[84:85], v[84:85], v[164:165], v[250:251]
	v_cvt_pk_bf16_f32 v219, v90, v91
	v_add_co_u32_e32 v216, vcc, s26, v182
	v_cvt_pk_bf16_f32 v218, v88, v89
	v_cvt_pk_bf16_f32 v220, v84, v85
	v_cvt_pk_bf16_f32 v221, v86, v87
	v_addc_co_u32_e32 v217, vcc, 0, v183, vcc
	v_lshlrev_b32_e32 v88, 16, v219
	v_and_b32_e32 v89, 0xffff0000, v219
	global_store_dwordx4 v[216:217], v[218:221], off offset:2048
	v_lshlrev_b32_e32 v90, 16, v218
	v_and_b32_e32 v91, 0xffff0000, v218
	v_lshlrev_b32_e32 v86, 16, v220
	v_and_b32_e32 v87, 0xffff0000, v220
	v_lshlrev_b32_e32 v84, 16, v221
	v_and_b32_e32 v85, 0xffff0000, v221
	v_pk_mul_f32 v[218:219], v[138:139], v[88:89]
	s_mov_b32 s1, 0x48000
	v_pk_mul_f32 v[220:221], v[136:137], v[90:91]
	v_pk_mul_f32 v[234:235], v[134:135], v[84:85]
	v_pk_mul_f32 v[248:249], v[132:133], v[86:87]
	v_cvt_pk_bf16_f32 v247, v218, v219
	v_add_co_u32_e32 v218, vcc, s1, v178
	v_cvt_pk_bf16_f32 v246, v220, v221
	v_cvt_pk_bf16_f32 v248, v248, v249
	v_cvt_pk_bf16_f32 v249, v234, v235
	v_addc_co_u32_e32 v219, vcc, 0, v179, vcc
	global_store_dwordx4 v[218:219], v[246:249], off
	global_load_dwordx4 v[246:249], v[196:197], off offset:2304
	s_nop 0
	global_load_dwordx4 v[250:253], v[210:211], off offset:2304
	s_waitcnt vmcnt(0)
	v_lshlrev_b32_e32 v210, 16, v239
	v_and_b32_e32 v211, 0xffff0000, v239
	v_lshlrev_b32_e32 v196, 16, v238
	v_and_b32_e32 v197, 0xffff0000, v238
	v_pk_fma_f32 v[82:83], v[82:83], v[176:177], v[210:211]
	v_lshlrev_b32_e32 v220, 16, v240
	v_and_b32_e32 v221, 0xffff0000, v240
	v_lshlrev_b32_e32 v234, 16, v241
	v_and_b32_e32 v235, 0xffff0000, v241
	v_pk_fma_f32 v[80:81], v[80:81], v[174:175], v[196:197]
	v_cvt_pk_bf16_f32 v239, v82, v83
	v_pk_fma_f32 v[78:79], v[78:79], v[172:173], v[234:235]
	v_pk_fma_f32 v[76:77], v[76:77], v[164:165], v[220:221]
	v_cvt_pk_bf16_f32 v238, v80, v81
	v_add_co_u32_e32 v196, vcc, s76, v182
	v_lshlrev_b32_e32 v80, 16, v239
	v_and_b32_e32 v81, 0xffff0000, v239
	v_cvt_pk_bf16_f32 v240, v76, v77
	v_cvt_pk_bf16_f32 v241, v78, v79
	v_addc_co_u32_e32 v197, vcc, 0, v183, vcc
	v_pk_mul_f32 v[210:211], v[138:139], v[80:81]
	v_lshlrev_b32_e32 v166, 16, v242
	v_and_b32_e32 v167, 0xffff0000, v242
	v_lshlrev_b32_e32 v242, 16, v243
	v_and_b32_e32 v243, 0xffff0000, v243
	v_lshlrev_b32_e32 v168, 16, v244
	v_and_b32_e32 v169, 0xffff0000, v244
	v_lshlrev_b32_e32 v244, 16, v245
	v_and_b32_e32 v245, 0xffff0000, v245
	global_store_dwordx4 v[196:197], v[238:241], off offset:2048
	v_lshlrev_b32_e32 v82, 16, v238
	v_and_b32_e32 v83, 0xffff0000, v238
	v_cvt_pk_bf16_f32 v239, v210, v211
	v_add_co_u32_e32 v210, vcc, s77, v178
	v_lshlrev_b32_e32 v78, 16, v240
	v_and_b32_e32 v79, 0xffff0000, v240
	v_lshlrev_b32_e32 v76, 16, v241
	v_and_b32_e32 v77, 0xffff0000, v241
	v_pk_mul_f32 v[220:221], v[136:137], v[82:83]
	v_addc_co_u32_e32 v211, vcc, 0, v179, vcc
	v_pk_fma_f32 v[74:75], v[74:75], v[176:177], v[242:243]
	v_pk_fma_f32 v[72:73], v[72:73], v[174:175], v[166:167]
	v_pk_fma_f32 v[166:167], v[70:71], v[172:173], v[244:245]
	v_pk_fma_f32 v[70:71], v[68:69], v[164:165], v[168:169]
	v_pk_mul_f32 v[234:235], v[134:135], v[76:77]
	v_pk_mul_f32 v[240:241], v[132:133], v[78:79]
	v_cvt_pk_bf16_f32 v238, v220, v221
	v_cvt_pk_bf16_f32 v68, v72, v73
	v_cvt_pk_bf16_f32 v69, v74, v75
	v_cvt_pk_bf16_f32 v70, v70, v71
	v_cvt_pk_bf16_f32 v71, v166, v167
	v_add_co_u32_e32 v220, vcc, s0, v182
	v_cvt_pk_bf16_f32 v240, v240, v241
	v_cvt_pk_bf16_f32 v241, v234, v235
	v_addc_co_u32_e32 v221, vcc, 0, v183, vcc
	v_lshlrev_b32_e32 v176, 16, v68
	v_and_b32_e32 v177, 0xffff0000, v68
	v_lshlrev_b32_e32 v174, 16, v69
	v_and_b32_e32 v175, 0xffff0000, v69
	v_lshlrev_b32_e32 v172, 16, v70
	v_and_b32_e32 v173, 0xffff0000, v70
	v_lshlrev_b32_e32 v164, 16, v71
	v_and_b32_e32 v165, 0xffff0000, v71
	s_mov_b32 s0, 0x58000
	global_store_dwordx4 v[210:211], v[238:241], off
	global_store_dwordx4 v[220:221], v[68:71], off offset:2048
	v_pk_mul_f32 v[72:73], v[134:135], v[164:165]
	v_pk_mul_f32 v[74:75], v[132:133], v[172:173]
	v_pk_mul_f32 v[70:71], v[138:139], v[174:175]
	v_pk_mul_f32 v[68:69], v[136:137], v[176:177]
	v_add_co_u32_e32 v132, vcc, s0, v178
	v_cvt_pk_bf16_f32 v68, v68, v69
	v_cvt_pk_bf16_f32 v69, v70, v71
	v_cvt_pk_bf16_f32 v70, v74, v75
	v_cvt_pk_bf16_f32 v71, v72, v73
	v_addc_co_u32_e32 v133, vcc, 0, v179, vcc
	global_store_dwordx4 v[132:133], v[68:71], off
	global_load_dwordx4 v[134:137], v[184:185], off offset:2304
	global_load_dwordx4 v[238:241], v[188:189], off offset:2304
	s_nop 0
	global_load_dwordx4 v[68:71], v[180:181], off offset:528
	global_load_dwordx4 v[72:75], v[180:181], off offset:512
	v_lshlrev_b32_e32 v138, 16, v246
	v_and_b32_e32 v139, 0xffff0000, v246
	v_lshlrev_b32_e32 v166, 16, v247
	v_and_b32_e32 v167, 0xffff0000, v247
	v_lshlrev_b32_e32 v168, 16, v248
	v_and_b32_e32 v169, 0xffff0000, v248
	v_lshlrev_b32_e32 v180, 16, v249
	v_and_b32_e32 v181, 0xffff0000, v249
	v_pk_fma_f32 v[66:67], v[66:67], v[162:163], v[166:167]
	v_pk_fma_f32 v[64:65], v[64:65], v[160:161], v[138:139]
	v_pk_fma_f32 v[62:63], v[62:63], v[158:159], v[180:181]
	v_pk_fma_f32 v[60:61], v[60:61], v[156:157], v[168:169]
	v_cvt_pk_bf16_f32 v242, v64, v65
	v_cvt_pk_bf16_f32 v243, v66, v67
	v_cvt_pk_bf16_f32 v244, v60, v61
	v_cvt_pk_bf16_f32 v245, v62, v63
	v_lshlrev_b32_e32 v66, 16, v242
	v_and_b32_e32 v67, 0xffff0000, v242
	v_lshlrev_b32_e32 v64, 16, v243
	v_and_b32_e32 v65, 0xffff0000, v243
	v_lshlrev_b32_e32 v62, 16, v244
	v_and_b32_e32 v63, 0xffff0000, v244
	v_lshlrev_b32_e32 v60, 16, v245
	v_and_b32_e32 v61, 0xffff0000, v245
	v_lshlrev_b32_e32 v184, 16, v250
	v_and_b32_e32 v185, 0xffff0000, v250
	v_lshlrev_b32_e32 v188, 16, v251
	v_and_b32_e32 v189, 0xffff0000, v251
	v_lshlrev_b32_e32 v234, 16, v252
	v_and_b32_e32 v235, 0xffff0000, v252
	v_lshlrev_b32_e32 v246, 16, v253
	v_and_b32_e32 v247, 0xffff0000, v253
	global_store_dwordx4 v[182:183], v[242:245], off offset:2304
	v_pk_fma_f32 v[58:59], v[58:59], v[162:163], v[188:189]
	v_pk_fma_f32 v[56:57], v[56:57], v[160:161], v[184:185]
	v_pk_fma_f32 v[54:55], v[54:55], v[158:159], v[246:247]
	v_pk_fma_f32 v[52:53], v[52:53], v[156:157], v[234:235]
	s_waitcnt vmcnt(0)
	v_lshlrev_b32_e32 v188, 16, v240
	v_pk_mul_f32 v[168:169], v[70:71], v[60:61]
	v_pk_mul_f32 v[138:139], v[74:75], v[64:65]
	v_pk_mul_f32 v[166:167], v[72:73], v[66:67]
	v_pk_mul_f32 v[182:183], v[68:69], v[62:63]
	v_cvt_pk_bf16_f32 v180, v166, v167
	v_cvt_pk_bf16_f32 v181, v138, v139
	v_cvt_pk_bf16_f32 v182, v182, v183
	v_cvt_pk_bf16_f32 v183, v168, v169
	global_store_dwordx4 v[178:179], v[180:183], off offset:256
	v_cvt_pk_bf16_f32 v178, v56, v57
	v_cvt_pk_bf16_f32 v179, v58, v59
	v_cvt_pk_bf16_f32 v180, v52, v53
	v_cvt_pk_bf16_f32 v181, v54, v55
	v_lshlrev_b32_e32 v58, 16, v178
	v_and_b32_e32 v59, 0xffff0000, v178
	v_lshlrev_b32_e32 v56, 16, v179
	v_and_b32_e32 v57, 0xffff0000, v179
	v_lshlrev_b32_e32 v54, 16, v180
	v_and_b32_e32 v55, 0xffff0000, v180
	v_lshlrev_b32_e32 v52, 16, v181
	v_and_b32_e32 v53, 0xffff0000, v181
	global_store_dwordx4 v[186:187], v[178:181], off offset:2304
	v_pk_mul_f32 v[138:139], v[74:75], v[56:57]
	v_pk_mul_f32 v[166:167], v[72:73], v[58:59]
	v_pk_mul_f32 v[168:169], v[70:71], v[52:53]
	v_pk_mul_f32 v[180:181], v[68:69], v[54:55]
	v_cvt_pk_bf16_f32 v178, v166, v167
	v_cvt_pk_bf16_f32 v179, v138, v139
	v_cvt_pk_bf16_f32 v180, v180, v181
	v_cvt_pk_bf16_f32 v181, v168, v169
	v_lshlrev_b32_e32 v138, 16, v134
	v_and_b32_e32 v139, 0xffff0000, v134
	v_lshlrev_b32_e32 v134, 16, v135
	v_and_b32_e32 v135, 0xffff0000, v135
	v_lshlrev_b32_e32 v166, 16, v136
	v_and_b32_e32 v167, 0xffff0000, v136
	v_lshlrev_b32_e32 v136, 16, v137
	v_and_b32_e32 v137, 0xffff0000, v137
	global_store_dwordx4 v[190:191], v[178:181], off offset:256
	v_pk_fma_f32 v[50:51], v[50:51], v[162:163], v[134:135]
	v_pk_fma_f32 v[48:49], v[48:49], v[160:161], v[138:139]
	v_pk_fma_f32 v[46:47], v[46:47], v[158:159], v[136:137]
	v_pk_fma_f32 v[44:45], v[44:45], v[156:157], v[166:167]
	global_load_dwordx4 v[178:181], v[192:193], off offset:2304
	global_load_dwordx4 v[182:185], v[194:195], off offset:2304
	v_cvt_pk_bf16_f32 v134, v48, v49
	v_cvt_pk_bf16_f32 v135, v50, v51
	v_cvt_pk_bf16_f32 v136, v44, v45
	v_cvt_pk_bf16_f32 v137, v46, v47
	v_lshlrev_b32_e32 v50, 16, v134
	v_and_b32_e32 v51, 0xffff0000, v134
	v_lshlrev_b32_e32 v48, 16, v135
	v_and_b32_e32 v49, 0xffff0000, v135
	v_lshlrev_b32_e32 v46, 16, v136
	v_and_b32_e32 v47, 0xffff0000, v136
	v_lshlrev_b32_e32 v44, 16, v137
	v_and_b32_e32 v45, 0xffff0000, v137
	v_lshlrev_b32_e32 v168, 16, v238
	v_and_b32_e32 v169, 0xffff0000, v238
	v_lshlrev_b32_e32 v186, 16, v239
	v_and_b32_e32 v187, 0xffff0000, v239
	v_and_b32_e32 v189, 0xffff0000, v240
	v_lshlrev_b32_e32 v190, 16, v241
	v_and_b32_e32 v191, 0xffff0000, v241
	global_store_dwordx4 v[198:199], v[134:137], off offset:2304
	v_pk_mul_f32 v[138:139], v[70:71], v[44:45]
	v_pk_mul_f32 v[166:167], v[68:69], v[46:47]
	v_pk_mul_f32 v[136:137], v[74:75], v[48:49]
	v_pk_mul_f32 v[134:135], v[72:73], v[50:51]
	v_pk_fma_f32 v[42:43], v[42:43], v[162:163], v[186:187]
	v_cvt_pk_bf16_f32 v134, v134, v135
	v_cvt_pk_bf16_f32 v135, v136, v137
	v_cvt_pk_bf16_f32 v136, v166, v167
	v_cvt_pk_bf16_f32 v137, v138, v139
	v_pk_fma_f32 v[40:41], v[40:41], v[160:161], v[168:169]
	v_pk_fma_f32 v[38:39], v[38:39], v[158:159], v[190:191]
	v_pk_fma_f32 v[36:37], v[36:37], v[156:157], v[188:189]
	global_store_dwordx4 v[200:201], v[134:137], off offset:256
	v_mul_f32_e32 v67, v67, v67
	v_mul_f32_e32 v65, v65, v65
	v_cvt_pk_bf16_f32 v134, v40, v41
	v_cvt_pk_bf16_f32 v135, v42, v43
	v_cvt_pk_bf16_f32 v136, v36, v37
	v_cvt_pk_bf16_f32 v137, v38, v39
	v_lshlrev_b32_e32 v42, 16, v134
	v_and_b32_e32 v43, 0xffff0000, v134
	v_lshlrev_b32_e32 v40, 16, v135
	v_and_b32_e32 v41, 0xffff0000, v135
	v_lshlrev_b32_e32 v38, 16, v136
	v_and_b32_e32 v39, 0xffff0000, v136
	v_lshlrev_b32_e32 v36, 16, v137
	v_and_b32_e32 v37, 0xffff0000, v137
	global_store_dwordx4 v[202:203], v[134:137], off offset:2304
	v_pk_mul_f32 v[138:139], v[70:71], v[36:37]
	v_pk_mul_f32 v[166:167], v[68:69], v[38:39]
	v_pk_mul_f32 v[136:137], v[74:75], v[40:41]
	v_pk_mul_f32 v[134:135], v[72:73], v[42:43]
	v_fmac_f32_e32 v67, v66, v66
	v_cvt_pk_bf16_f32 v134, v134, v135
	v_cvt_pk_bf16_f32 v135, v136, v137
	v_cvt_pk_bf16_f32 v136, v166, v167
	v_cvt_pk_bf16_f32 v137, v138, v139
	global_store_dwordx4 v[204:205], v[134:137], off offset:256
	global_load_dwordx4 v[134:137], v[206:207], off offset:2304
	s_nop 0
	global_load_dwordx4 v[186:189], v[208:209], off offset:2304
	v_fmac_f32_e32 v65, v64, v64
	v_mul_f32_e32 v63, v63, v63
	v_mul_f32_e32 v61, v61, v61
	v_add_f32_e32 v64, v67, v65
	v_fmac_f32_e32 v63, v62, v62
	v_fmac_f32_e32 v61, v60, v60
	v_add_f32_e32 v60, v63, v61
	s_waitcnt vmcnt(0)
	v_lshlrev_b32_e32 v138, 16, v178
	v_and_b32_e32 v139, 0xffff0000, v178
	v_lshlrev_b32_e32 v166, 16, v179
	v_and_b32_e32 v167, 0xffff0000, v179
	v_lshlrev_b32_e32 v168, 16, v180
	v_and_b32_e32 v169, 0xffff0000, v180
	v_lshlrev_b32_e32 v178, 16, v181
	v_and_b32_e32 v179, 0xffff0000, v181
	v_pk_fma_f32 v[34:35], v[34:35], v[162:163], v[166:167]
	v_pk_fma_f32 v[32:33], v[32:33], v[160:161], v[138:139]
	v_pk_fma_f32 v[30:31], v[30:31], v[158:159], v[178:179]
	v_pk_fma_f32 v[28:29], v[28:29], v[156:157], v[168:169]
	v_cvt_pk_bf16_f32 v178, v32, v33
	v_cvt_pk_bf16_f32 v179, v34, v35
	v_cvt_pk_bf16_f32 v180, v28, v29
	v_cvt_pk_bf16_f32 v181, v30, v31
	v_lshlrev_b32_e32 v34, 16, v178
	v_and_b32_e32 v35, 0xffff0000, v178
	v_lshlrev_b32_e32 v32, 16, v179
	v_and_b32_e32 v33, 0xffff0000, v179
	v_lshlrev_b32_e32 v30, 16, v180
	v_and_b32_e32 v31, 0xffff0000, v180
	v_lshlrev_b32_e32 v28, 16, v181
	v_and_b32_e32 v29, 0xffff0000, v181
	v_lshlrev_b32_e32 v190, 16, v182
	v_and_b32_e32 v191, 0xffff0000, v182
	v_lshlrev_b32_e32 v182, 16, v183
	v_and_b32_e32 v183, 0xffff0000, v183
	global_store_dwordx4 v[212:213], v[178:181], off offset:2304
	v_pk_mul_f32 v[138:139], v[74:75], v[32:33]
	v_pk_mul_f32 v[166:167], v[72:73], v[34:35]
	v_pk_mul_f32 v[168:169], v[70:71], v[28:29]
	v_pk_mul_f32 v[180:181], v[68:69], v[30:31]
	v_cvt_pk_bf16_f32 v178, v166, v167
	v_cvt_pk_bf16_f32 v179, v138, v139
	v_cvt_pk_bf16_f32 v180, v180, v181
	v_cvt_pk_bf16_f32 v181, v168, v169
	v_pk_fma_f32 v[24:25], v[24:25], v[162:163], v[182:183]
	v_pk_fma_f32 v[22:23], v[22:23], v[160:161], v[190:191]
	v_lshlrev_b32_e32 v192, 16, v184
	v_and_b32_e32 v193, 0xffff0000, v184
	v_lshlrev_b32_e32 v184, 16, v185
	v_and_b32_e32 v185, 0xffff0000, v185
	global_store_dwordx4 v[214:215], v[178:181], off offset:256
	v_pk_fma_f32 v[20:21], v[20:21], v[158:159], v[184:185]
	v_pk_fma_f32 v[18:19], v[18:19], v[156:157], v[192:193]
	v_cvt_pk_bf16_f32 v178, v22, v23
	v_cvt_pk_bf16_f32 v179, v24, v25
	v_lshlrev_b32_e32 v24, 16, v178
	v_and_b32_e32 v25, 0xffff0000, v178
	v_lshlrev_b32_e32 v22, 16, v179
	v_and_b32_e32 v23, 0xffff0000, v179
	v_cvt_pk_bf16_f32 v180, v18, v19
	v_cvt_pk_bf16_f32 v181, v20, v21
	v_pk_mul_f32 v[138:139], v[74:75], v[22:23]
	v_pk_mul_f32 v[166:167], v[72:73], v[24:25]
	global_store_dwordx4 v[216:217], v[178:181], off offset:2304
	v_lshlrev_b32_e32 v20, 16, v180
	v_and_b32_e32 v21, 0xffff0000, v180
	v_cvt_pk_bf16_f32 v178, v166, v167
	v_cvt_pk_bf16_f32 v179, v138, v139
	v_lshlrev_b32_e32 v138, 16, v134
	v_and_b32_e32 v139, 0xffff0000, v134
	v_lshlrev_b32_e32 v134, 16, v135
	v_and_b32_e32 v135, 0xffff0000, v135
	v_lshlrev_b32_e32 v166, 16, v136
	v_and_b32_e32 v167, 0xffff0000, v136
	v_lshlrev_b32_e32 v136, 16, v137
	v_and_b32_e32 v137, 0xffff0000, v137
	v_lshlrev_b32_e32 v18, 16, v181
	v_and_b32_e32 v19, 0xffff0000, v181
	v_pk_fma_f32 v[16:17], v[16:17], v[162:163], v[134:135]
	v_pk_fma_f32 v[14:15], v[14:15], v[160:161], v[138:139]
	v_pk_fma_f32 v[12:13], v[12:13], v[158:159], v[136:137]
	v_pk_fma_f32 v[10:11], v[10:11], v[156:157], v[166:167]
	v_pk_mul_f32 v[168:169], v[70:71], v[18:19]
	v_pk_mul_f32 v[180:181], v[68:69], v[20:21]
	v_cvt_pk_bf16_f32 v134, v14, v15
	v_cvt_pk_bf16_f32 v135, v16, v17
	v_cvt_pk_bf16_f32 v136, v10, v11
	v_cvt_pk_bf16_f32 v137, v12, v13
	v_cvt_pk_bf16_f32 v180, v180, v181
	v_cvt_pk_bf16_f32 v181, v168, v169
	v_lshlrev_b32_e32 v16, 16, v134
	v_and_b32_e32 v17, 0xffff0000, v134
	v_lshlrev_b32_e32 v14, 16, v135
	v_and_b32_e32 v15, 0xffff0000, v135
	v_lshlrev_b32_e32 v12, 16, v136
	v_and_b32_e32 v13, 0xffff0000, v136
	v_lshlrev_b32_e32 v10, 16, v137
	v_and_b32_e32 v11, 0xffff0000, v137
	global_store_dwordx4 v[218:219], v[178:181], off offset:256
	v_lshlrev_b32_e32 v168, 16, v186
	v_and_b32_e32 v169, 0xffff0000, v186
	v_lshlrev_b32_e32 v178, 16, v187
	v_and_b32_e32 v179, 0xffff0000, v187
	v_lshlrev_b32_e32 v180, 16, v188
	v_and_b32_e32 v181, 0xffff0000, v188
	v_lshlrev_b32_e32 v182, 16, v189
	v_and_b32_e32 v183, 0xffff0000, v189
	global_store_dwordx4 v[196:197], v[134:137], off offset:2304
	v_pk_mul_f32 v[138:139], v[70:71], v[10:11]
	v_pk_mul_f32 v[166:167], v[68:69], v[12:13]
	v_pk_mul_f32 v[136:137], v[74:75], v[14:15]
	v_pk_mul_f32 v[134:135], v[72:73], v[16:17]
	v_pk_fma_f32 v[8:9], v[8:9], v[162:163], v[178:179]
	v_cvt_pk_bf16_f32 v134, v134, v135
	v_cvt_pk_bf16_f32 v135, v136, v137
	v_cvt_pk_bf16_f32 v136, v166, v167
	v_cvt_pk_bf16_f32 v137, v138, v139
	v_pk_fma_f32 v[6:7], v[6:7], v[160:161], v[168:169]
	v_pk_fma_f32 v[4:5], v[4:5], v[158:159], v[182:183]
	v_pk_fma_f32 v[2:3], v[2:3], v[156:157], v[180:181]
	global_store_dwordx4 v[210:211], v[134:137], off offset:256
	s_nop 1
	v_cvt_pk_bf16_f32 v134, v6, v7
	v_cvt_pk_bf16_f32 v135, v8, v9
	v_cvt_pk_bf16_f32 v136, v2, v3
	v_cvt_pk_bf16_f32 v137, v4, v5
	v_lshlrev_b32_e32 v8, 16, v134
	v_and_b32_e32 v9, 0xffff0000, v134
	v_lshlrev_b32_e32 v6, 16, v135
	v_and_b32_e32 v7, 0xffff0000, v135
	v_lshlrev_b32_e32 v4, 16, v136
	v_and_b32_e32 v5, 0xffff0000, v136
	v_lshlrev_b32_e32 v2, 16, v137
	v_and_b32_e32 v3, 0xffff0000, v137
	global_store_dwordx4 v[220:221], v[134:137], off offset:2304
	v_pk_mul_f32 v[74:75], v[74:75], v[6:7]
	v_pk_mul_f32 v[72:73], v[72:73], v[8:9]
	v_pk_mul_f32 v[134:135], v[70:71], v[2:3]
	v_pk_mul_f32 v[70:71], v[68:69], v[4:5]
	v_cvt_pk_bf16_f32 v68, v72, v73
	v_cvt_pk_bf16_f32 v69, v74, v75
	v_cvt_pk_bf16_f32 v70, v70, v71
	v_cvt_pk_bf16_f32 v71, v134, v135
	global_store_dwordx4 v[132:133], v[68:71], off offset:256
	v_xor_b32_e32 v72, 32, v227
	v_mul_f32_e32 v73, v129, v129
	v_and_b32_e32 v71, 64, v227
	v_xor_b32_e32 v70, 16, v227
	v_add_u32_e32 v71, 64, v71
	v_cmp_lt_i32_e32 vcc, v70, v71
	v_fmac_f32_e32 v73, v128, v128
	v_mul_f32_e32 v74, v125, v125
	v_cndmask_b32_e32 v70, v227, v70, vcc
	v_cmp_lt_i32_e32 vcc, v72, v71
	v_fmac_f32_e32 v74, v124, v124
	v_lshlrev_b32_e32 v70, 2, v70
	v_cndmask_b32_e32 v71, v227, v72, vcc
	v_mul_f32_e32 v72, v131, v131
	v_fmac_f32_e32 v72, v130, v130
	v_add_f32_e32 v72, v72, v73
	v_mul_f32_e32 v73, v127, v127
	v_fmac_f32_e32 v73, v126, v126
	v_add_f32_e32 v73, v73, v74
	v_add_f32_e32 v72, v72, v73
	v_add_f32_e32 v64, v72, v64
	v_add_f32_e32 v60, v60, v64
	ds_bpermute_b32 v61, v70, v60
	v_lshlrev_b32_e32 v71, 2, v71
	v_lshl_add_u64 v[68:69], v[150:151], 0, s[24:25]
	s_waitcnt lgkmcnt(0)
	v_add_f32_e32 v60, v60, v61
	ds_bpermute_b32 v61, v71, v60
	s_and_saveexec_b64 s[18:19], s[40:41]
	s_cbranch_execz .LBB0_364
	s_waitcnt lgkmcnt(0)
	v_add_f32_e32 v60, v60, v61
	global_atomic_add_f32 v[68:69], v60, off

.LBB0_394:
	s_add_u32 s18, s26, 0x100
	v_mov_b32_e32 v2, 0
	s_addc_u32 s19, s27, 0
	s_mov_b32 s52, -2
	v_mov_b32_e32 v3, v2
	v_mov_b32_e32 v4, v2
	s_waitcnt lgkmcnt(0)
	v_mov_b32_e32 v5, v2
	v_mov_b32_e32 v6, v2
	v_mov_b32_e32 v7, v2
	v_mov_b32_e32 v8, v2
	v_mov_b32_e32 v9, v2
	v_mov_b32_e32 v10, v2
	v_mov_b32_e32 v11, v2
	v_mov_b32_e32 v12, v2
	v_mov_b32_e32 v13, v2
	v_mov_b32_e32 v14, v2
	v_mov_b32_e32 v15, v2
	v_mov_b32_e32 v16, v2
	v_mov_b32_e32 v17, v2
	v_mov_b32_e32 v18, v2
	v_mov_b32_e32 v19, v2
	v_mov_b32_e32 v20, v2
	v_mov_b32_e32 v21, v2
	v_mov_b32_e32 v22, v2
	v_mov_b32_e32 v23, v2
	v_mov_b32_e32 v24, v2
	v_mov_b32_e32 v25, v2
	v_mov_b32_e32 v28, v2
	v_mov_b32_e32 v29, v2
	v_mov_b32_e32 v30, v2
	v_mov_b32_e32 v31, v2
	v_mov_b32_e32 v32, v2
	v_mov_b32_e32 v33, v2
	v_mov_b32_e32 v34, v2
	v_mov_b32_e32 v35, v2
	v_mov_b32_e32 v68, v2
	v_mov_b32_e32 v69, v2
	v_mov_b32_e32 v70, v2
	v_mov_b32_e32 v71, v2
	v_mov_b32_e32 v72, v2
	v_mov_b32_e32 v73, v2
	v_mov_b32_e32 v74, v2
	v_mov_b32_e32 v75, v2
	v_mov_b32_e32 v76, v2
	v_mov_b32_e32 v77, v2
	v_mov_b32_e32 v78, v2
	v_mov_b32_e32 v79, v2
	v_mov_b32_e32 v80, v2
	v_mov_b32_e32 v81, v2
	v_mov_b32_e32 v82, v2
	v_mov_b32_e32 v83, v2
	v_mov_b32_e32 v84, v2
	v_mov_b32_e32 v85, v2
	v_mov_b32_e32 v86, v2
	v_mov_b32_e32 v87, v2
	v_mov_b32_e32 v88, v2
	v_mov_b32_e32 v89, v2
	v_mov_b32_e32 v90, v2
	v_mov_b32_e32 v91, v2
	v_mov_b32_e32 v92, v2
	v_mov_b32_e32 v93, v2
	v_mov_b32_e32 v94, v2
	v_mov_b32_e32 v95, v2
	v_mov_b32_e32 v96, v2
	v_mov_b32_e32 v97, v2
	v_mov_b32_e32 v98, v2
	v_mov_b32_e32 v99, v2
	s_waitcnt vmcnt(0)
	v_mov_b32_e32 v36, v2
	v_mov_b32_e32 v37, v2
	v_mov_b32_e32 v38, v2
	v_mov_b32_e32 v39, v2
	v_mov_b32_e32 v40, v2
	v_mov_b32_e32 v41, v2
	v_mov_b32_e32 v42, v2
	v_mov_b32_e32 v43, v2
	v_mov_b32_e32 v44, v2
	v_mov_b32_e32 v45, v2
	v_mov_b32_e32 v46, v2
	v_mov_b32_e32 v47, v2
	v_mov_b32_e32 v48, v2
	v_mov_b32_e32 v49, v2
	v_mov_b32_e32 v50, v2
	v_mov_b32_e32 v51, v2
	v_mov_b32_e32 v52, v2
	v_mov_b32_e32 v53, v2
	v_mov_b32_e32 v54, v2
	v_mov_b32_e32 v55, v2
	v_mov_b32_e32 v56, v2
	v_mov_b32_e32 v57, v2
	v_mov_b32_e32 v58, v2
	v_mov_b32_e32 v59, v2
	v_mov_b32_e32 v60, v2
	v_mov_b32_e32 v61, v2
	v_mov_b32_e32 v62, v2
	v_mov_b32_e32 v63, v2
	v_mov_b32_e32 v64, v2
	v_mov_b32_e32 v65, v2
	v_mov_b32_e32 v66, v2
	v_mov_b32_e32 v67, v2
	v_mov_b32_e32 v108, v2
	v_mov_b32_e32 v109, v2
	v_mov_b32_e32 v110, v2
	v_mov_b32_e32 v111, v2
	v_mov_b32_e32 v112, v2
	v_mov_b32_e32 v113, v2
	v_mov_b32_e32 v114, v2
	v_mov_b32_e32 v115, v2
	v_mov_b32_e32 v116, v2
	v_mov_b32_e32 v117, v2
	v_mov_b32_e32 v118, v2
	v_mov_b32_e32 v119, v2
	v_mov_b32_e32 v120, v2
	v_mov_b32_e32 v121, v2
	v_mov_b32_e32 v122, v2
	v_mov_b32_e32 v123, v2
	v_mov_b32_e32 v124, v2
	v_mov_b32_e32 v125, v2
	v_mov_b32_e32 v126, v2
	v_mov_b32_e32 v127, v2
	v_mov_b32_e32 v128, v2
	v_mov_b32_e32 v129, v2
	v_mov_b32_e32 v130, v2
	v_mov_b32_e32 v131, v2
	v_mov_b32_e32 v132, v2
	v_mov_b32_e32 v133, v2
	v_mov_b32_e32 v134, v2
	v_mov_b32_e32 v135, v2
	v_mov_b32_e32 v136, v2
	v_mov_b32_e32 v137, v2
	v_mov_b32_e32 v138, v2
	v_mov_b32_e32 v139, v2
	v_add_u32_e32 v160, 0x10000, v233
	ds_read_b128 v[100:103], v160
	ds_read_b128 v[104:107], v160 offset:1024
	ds_read_b128 v[156:159], v160 offset:2048
	ds_read_b128 v[160:163], v160 offset:3072
	s_add_u32 s26, s24, 0x100
	s_addc_u32 s27, s25, 0
	s_add_i32 s0, 0, 0x10000
	s_cmp_eq_u32 s52, 40
	s_cselect_b32 s31, s43, s27
	s_cselect_b32 s30, s42, s26
	s_cselect_b32 s29, s45, s19
	s_cselect_b32 s28, s44, s18
.LBB0_395:
	s_add_i32 m0, s69, 0xc000
	ds_read_b128 v[172:175], v235
	ds_read_b128 v[176:179], v235 offset:1024
	ds_read_b128 v[180:183], v235 offset:2048
	ds_read_b128 v[184:187], v235 offset:3072
	ds_read_b128 v[188:191], v235 offset:4096
	ds_read_b128 v[192:195], v235 offset:5120
	ds_read_b128 v[196:199], v235 offset:6144
	ds_read_b128 v[200:203], v235 offset:7168
	global_load_lds_dwordx4 v152, s[24:25]
	v_lshl_add_u64 v[164:165], s[24:25], 0, v[154:155]
	s_add_i32 m0, s69, 0xe000
	s_nop 0
	global_load_lds_dwordx4 v[164:165], off
	s_waitcnt vmcnt(10) lgkmcnt(8)
	s_setprio 1
	s_barrier
	s_waitcnt lgkmcnt(0)
	v_mfma_f32_16x16x32_bf16 v[136:139], v[100:103], v[172:175], v[136:139]
	v_mfma_f32_16x16x32_bf16 v[132:135], v[156:159], v[172:175], v[132:135]
	v_mfma_f32_16x16x32_bf16 v[128:131], v[100:103], v[180:183], v[128:131]
	v_mfma_f32_16x16x32_bf16 v[124:127], v[156:159], v[180:183], v[124:127]
	v_mfma_f32_16x16x32_bf16 v[120:123], v[100:103], v[188:191], v[120:123]
	v_mfma_f32_16x16x32_bf16 v[116:119], v[156:159], v[188:191], v[116:119]
	v_mfma_f32_16x16x32_bf16 v[112:115], v[100:103], v[196:199], v[112:115]
	v_mfma_f32_16x16x32_bf16 v[108:111], v[156:159], v[196:199], v[108:111]
	v_mfma_f32_16x16x32_bf16 v[136:139], v[104:107], v[176:179], v[136:139]
	v_mfma_f32_16x16x32_bf16 v[132:135], v[160:163], v[176:179], v[132:135]
	v_mfma_f32_16x16x32_bf16 v[128:131], v[104:107], v[184:187], v[128:131]
	v_mfma_f32_16x16x32_bf16 v[124:127], v[160:163], v[184:187], v[124:127]
	v_mfma_f32_16x16x32_bf16 v[120:123], v[104:107], v[192:195], v[120:123]
	v_mfma_f32_16x16x32_bf16 v[116:119], v[160:163], v[192:195], v[116:119]
	v_mfma_f32_16x16x32_bf16 v[112:115], v[104:107], v[200:203], v[112:115]
	v_mfma_f32_16x16x32_bf16 v[108:111], v[160:163], v[200:203], v[108:111]
	s_barrier
	s_setprio 0
	s_add_i32 s24, 0, 0x14000
	v_add_u32_e32 v164, s24, v233
	s_add_i32 s0, s0, s68
	ds_read_b128 v[204:207], v164
	ds_read_b128 v[208:211], v164 offset:1024
	ds_read_b128 v[212:215], v164 offset:2048
	ds_read_b128 v[216:219], v164 offset:3072
	v_lshl_add_u64 v[164:165], s[28:29], 0, v[26:27]
	s_mov_b32 m0, s0
	v_lshl_add_u64 v[220:221], s[28:29], 0, v[140:141]
	global_load_lds_dwordx4 v[164:165], off
	s_add_i32 m0, s0, 0x2000
	s_nop 0
	global_load_lds_dwordx4 v[220:221], off
	s_waitcnt vmcnt(10)
	s_setprio 1
	s_barrier
	s_waitcnt lgkmcnt(0)
	v_mfma_f32_16x16x32_bf16 v[64:67], v[204:207], v[172:175], v[64:67]
	v_mfma_f32_16x16x32_bf16 v[60:63], v[212:215], v[172:175], v[60:63]
	v_mfma_f32_16x16x32_bf16 v[56:59], v[204:207], v[180:183], v[56:59]
	v_mfma_f32_16x16x32_bf16 v[52:55], v[212:215], v[180:183], v[52:55]
	v_mfma_f32_16x16x32_bf16 v[48:51], v[204:207], v[188:191], v[48:51]
	v_mfma_f32_16x16x32_bf16 v[44:47], v[212:215], v[188:191], v[44:47]
	v_mfma_f32_16x16x32_bf16 v[40:43], v[204:207], v[196:199], v[40:43]
	v_mfma_f32_16x16x32_bf16 v[36:39], v[212:215], v[196:199], v[36:39]
	v_mfma_f32_16x16x32_bf16 v[64:67], v[208:211], v[176:179], v[64:67]
	v_mfma_f32_16x16x32_bf16 v[60:63], v[216:219], v[176:179], v[60:63]
	v_mfma_f32_16x16x32_bf16 v[56:59], v[208:211], v[184:187], v[56:59]
	v_mfma_f32_16x16x32_bf16 v[52:55], v[216:219], v[184:187], v[52:55]
	v_mfma_f32_16x16x32_bf16 v[48:51], v[208:211], v[192:195], v[48:51]
	v_mfma_f32_16x16x32_bf16 v[44:47], v[216:219], v[192:195], v[44:47]
	v_mfma_f32_16x16x32_bf16 v[40:43], v[208:211], v[200:203], v[40:43]
	v_mfma_f32_16x16x32_bf16 v[36:39], v[216:219], v[200:203], v[36:39]
	s_barrier
	s_setprio 0
	s_mov_b32 m0, s69
	v_lshl_add_u64 v[222:223], s[30:31], 0, v[144:145]
	ds_read_b128 v[172:175], v235 offset:16384
	ds_read_b128 v[176:179], v235 offset:17408
	ds_read_b128 v[180:183], v235 offset:18432
	ds_read_b128 v[184:187], v235 offset:19456
	ds_read_b128 v[188:191], v235 offset:20480
	ds_read_b128 v[192:195], v235 offset:21504
	ds_read_b128 v[196:199], v235 offset:22528
	ds_read_b128 v[200:203], v235 offset:23552
	global_load_lds_dwordx4 v[222:223], off
	v_lshl_add_u64 v[224:225], s[30:31], 0, v[142:143]
	s_mov_b32 m0, s72
	s_nop 0
	global_load_lds_dwordx4 v[224:225], off
	s_waitcnt vmcnt(10)
	s_setprio 1
	s_barrier
	s_waitcnt lgkmcnt(0)
	v_mfma_f32_16x16x32_bf16 v[96:99], v[100:103], v[172:175], v[96:99]
	v_mfma_f32_16x16x32_bf16 v[92:95], v[156:159], v[172:175], v[92:95]
	v_mfma_f32_16x16x32_bf16 v[88:91], v[100:103], v[180:183], v[88:91]
	v_mfma_f32_16x16x32_bf16 v[84:87], v[156:159], v[180:183], v[84:87]
	v_mfma_f32_16x16x32_bf16 v[80:83], v[100:103], v[188:191], v[80:83]
	v_mfma_f32_16x16x32_bf16 v[76:79], v[156:159], v[188:191], v[76:79]
	v_mfma_f32_16x16x32_bf16 v[72:75], v[100:103], v[196:199], v[72:75]
	v_mfma_f32_16x16x32_bf16 v[68:71], v[156:159], v[196:199], v[68:71]
	v_mfma_f32_16x16x32_bf16 v[96:99], v[104:107], v[176:179], v[96:99]
	v_mfma_f32_16x16x32_bf16 v[92:95], v[160:163], v[176:179], v[92:95]
	v_mfma_f32_16x16x32_bf16 v[88:91], v[104:107], v[184:187], v[88:91]
	v_mfma_f32_16x16x32_bf16 v[84:87], v[160:163], v[184:187], v[84:87]
	v_mfma_f32_16x16x32_bf16 v[80:83], v[104:107], v[192:195], v[80:83]
	v_mfma_f32_16x16x32_bf16 v[76:79], v[160:163], v[192:195], v[76:79]
	v_mfma_f32_16x16x32_bf16 v[72:75], v[104:107], v[200:203], v[72:75]
	v_mfma_f32_16x16x32_bf16 v[68:71], v[160:163], v[200:203], v[68:71]
	s_barrier
	s_setprio 0
	s_add_u32 s0, s28, 0xb0000
	s_addc_u32 s1, s29, 0
	s_add_i32 s24, s24, s68
	s_mov_b32 m0, s24
	s_nop 0
	global_load_lds_dwordx4 v26, s[0:1]
	s_add_i32 m0, s24, 0x2000
	s_nop 0
	global_load_lds_dwordx4 v140, s[0:1]
	v_add_u32_e32 v160, 0x18000, v233
	ds_read_b128 v[100:103], v160
	ds_read_b128 v[104:107], v160 offset:1024
	ds_read_b128 v[156:159], v160 offset:2048
	ds_read_b128 v[160:163], v160 offset:3072
	s_waitcnt vmcnt(10)
	s_setprio 1
	s_barrier
	v_mfma_f32_16x16x32_bf16 v[32:35], v[204:207], v[172:175], v[32:35]
	v_mfma_f32_16x16x32_bf16 v[28:31], v[212:215], v[172:175], v[28:31]
	v_mfma_f32_16x16x32_bf16 v[22:25], v[204:207], v[180:183], v[22:25]
	v_mfma_f32_16x16x32_bf16 v[18:21], v[212:215], v[180:183], v[18:21]
	v_mfma_f32_16x16x32_bf16 v[14:17], v[204:207], v[188:191], v[14:17]
	v_mfma_f32_16x16x32_bf16 v[10:13], v[212:215], v[188:191], v[10:13]
	v_mfma_f32_16x16x32_bf16 v[6:9], v[204:207], v[196:199], v[6:9]
	v_mfma_f32_16x16x32_bf16 v[2:5], v[212:215], v[196:199], v[2:5]
	v_mfma_f32_16x16x32_bf16 v[32:35], v[208:211], v[176:179], v[32:35]
	v_mfma_f32_16x16x32_bf16 v[28:31], v[216:219], v[176:179], v[28:31]
	v_mfma_f32_16x16x32_bf16 v[22:25], v[208:211], v[184:187], v[22:25]
	v_mfma_f32_16x16x32_bf16 v[18:21], v[216:219], v[184:187], v[18:21]
	v_mfma_f32_16x16x32_bf16 v[14:17], v[208:211], v[192:195], v[14:17]
	v_mfma_f32_16x16x32_bf16 v[10:13], v[216:219], v[192:195], v[10:13]
	v_mfma_f32_16x16x32_bf16 v[6:9], v[208:211], v[200:203], v[6:9]
	v_mfma_f32_16x16x32_bf16 v[2:5], v[216:219], v[200:203], v[2:5]
	s_barrier
	s_setprio 0
	s_add_i32 s24, 0, 0x18000
	s_add_u32 s0, s30, 0xb0000
	s_addc_u32 s1, s31, 0
	s_mov_b32 m0, s73
	ds_read_b128 v[172:175], v235 offset:32768
	ds_read_b128 v[176:179], v235 offset:33792
	ds_read_b128 v[180:183], v235 offset:34816
	ds_read_b128 v[184:187], v235 offset:35840
	ds_read_b128 v[188:191], v235 offset:36864
	ds_read_b128 v[192:195], v235 offset:37888
	ds_read_b128 v[196:199], v235 offset:38912
	ds_read_b128 v[200:203], v235 offset:39936
	global_load_lds_dwordx4 v144, s[0:1]
	s_mov_b32 m0, s81
	s_nop 0
	global_load_lds_dwordx4 v142, s[0:1]
	s_waitcnt vmcnt(10) lgkmcnt(8)
	s_setprio 1
	s_barrier
	s_waitcnt lgkmcnt(0)
	v_mfma_f32_16x16x32_bf16 v[136:139], v[100:103], v[172:175], v[136:139]
	v_mfma_f32_16x16x32_bf16 v[132:135], v[156:159], v[172:175], v[132:135]
	v_mfma_f32_16x16x32_bf16 v[128:131], v[100:103], v[180:183], v[128:131]
	v_mfma_f32_16x16x32_bf16 v[124:127], v[156:159], v[180:183], v[124:127]
	v_mfma_f32_16x16x32_bf16 v[120:123], v[100:103], v[188:191], v[120:123]
	v_mfma_f32_16x16x32_bf16 v[116:119], v[156:159], v[188:191], v[116:119]
	v_mfma_f32_16x16x32_bf16 v[112:115], v[100:103], v[196:199], v[112:115]
	v_mfma_f32_16x16x32_bf16 v[108:111], v[156:159], v[196:199], v[108:111]
	v_mfma_f32_16x16x32_bf16 v[136:139], v[104:107], v[176:179], v[136:139]
	v_mfma_f32_16x16x32_bf16 v[132:135], v[160:163], v[176:179], v[132:135]
	v_mfma_f32_16x16x32_bf16 v[128:131], v[104:107], v[184:187], v[128:131]
	v_mfma_f32_16x16x32_bf16 v[124:127], v[160:163], v[184:187], v[124:127]
	v_mfma_f32_16x16x32_bf16 v[120:123], v[104:107], v[192:195], v[120:123]
	v_mfma_f32_16x16x32_bf16 v[116:119], v[160:163], v[192:195], v[116:119]
	v_mfma_f32_16x16x32_bf16 v[112:115], v[104:107], v[200:203], v[112:115]
	v_mfma_f32_16x16x32_bf16 v[108:111], v[160:163], v[200:203], v[108:111]
	s_barrier
	s_setprio 0
	s_add_i32 s25, 0, 0x1c000
	s_add_i32 s0, s24, s68
	v_add_u32_e32 v166, s25, v233
	v_lshl_add_u64 v[164:165], v[164:165], 0, s[12:13]
	s_mov_b32 m0, s0
	ds_read_b128 v[204:207], v166
	ds_read_b128 v[208:211], v166 offset:1024
	ds_read_b128 v[212:215], v166 offset:2048
	ds_read_b128 v[216:219], v166 offset:3072
	global_load_lds_dwordx4 v[164:165], off
	v_lshl_add_u64 v[164:165], v[220:221], 0, s[12:13]
	s_add_i32 m0, s0, 0x2000
	s_nop 0
	global_load_lds_dwordx4 v[164:165], off
	s_waitcnt vmcnt(10)
	s_setprio 1
	s_barrier
	s_waitcnt lgkmcnt(0)
	v_mfma_f32_16x16x32_bf16 v[64:67], v[204:207], v[172:175], v[64:67]
	v_mfma_f32_16x16x32_bf16 v[60:63], v[212:215], v[172:175], v[60:63]
	v_mfma_f32_16x16x32_bf16 v[56:59], v[204:207], v[180:183], v[56:59]
	v_mfma_f32_16x16x32_bf16 v[52:55], v[212:215], v[180:183], v[52:55]
	v_mfma_f32_16x16x32_bf16 v[48:51], v[204:207], v[188:191], v[48:51]
	v_mfma_f32_16x16x32_bf16 v[44:47], v[212:215], v[188:191], v[44:47]
	v_mfma_f32_16x16x32_bf16 v[40:43], v[204:207], v[196:199], v[40:43]
	v_mfma_f32_16x16x32_bf16 v[36:39], v[212:215], v[196:199], v[36:39]
	v_mfma_f32_16x16x32_bf16 v[64:67], v[208:211], v[176:179], v[64:67]
	v_mfma_f32_16x16x32_bf16 v[60:63], v[216:219], v[176:179], v[60:63]
	v_mfma_f32_16x16x32_bf16 v[56:59], v[208:211], v[184:187], v[56:59]
	v_mfma_f32_16x16x32_bf16 v[52:55], v[216:219], v[184:187], v[52:55]
	v_mfma_f32_16x16x32_bf16 v[48:51], v[208:211], v[192:195], v[48:51]
	v_mfma_f32_16x16x32_bf16 v[44:47], v[216:219], v[192:195], v[44:47]
	v_mfma_f32_16x16x32_bf16 v[40:43], v[208:211], v[200:203], v[40:43]
	v_mfma_f32_16x16x32_bf16 v[36:39], v[216:219], v[200:203], v[36:39]
	s_barrier
	s_setprio 0
	s_mov_b32 m0, s21
	v_lshl_add_u64 v[164:165], v[222:223], 0, s[12:13]
	ds_read_b128 v[172:175], v235 offset:49152
	ds_read_b128 v[176:179], v235 offset:50176
	ds_read_b128 v[180:183], v235 offset:51200
	ds_read_b128 v[184:187], v235 offset:52224
	ds_read_b128 v[188:191], v235 offset:53248
	ds_read_b128 v[192:195], v235 offset:54272
	ds_read_b128 v[196:199], v235 offset:55296
	ds_read_b128 v[200:203], v235 offset:56320
	global_load_lds_dwordx4 v[164:165], off
	v_lshl_add_u64 v[164:165], v[224:225], 0, s[12:13]
	s_mov_b32 m0, s48
	s_nop 0
	global_load_lds_dwordx4 v[164:165], off
	s_waitcnt vmcnt(10)
	s_setprio 1
	s_barrier
	s_waitcnt lgkmcnt(0)
	v_mfma_f32_16x16x32_bf16 v[96:99], v[100:103], v[172:175], v[96:99]
	v_mfma_f32_16x16x32_bf16 v[92:95], v[156:159], v[172:175], v[92:95]
	v_mfma_f32_16x16x32_bf16 v[88:91], v[100:103], v[180:183], v[88:91]
	v_mfma_f32_16x16x32_bf16 v[84:87], v[156:159], v[180:183], v[84:87]
	v_mfma_f32_16x16x32_bf16 v[80:83], v[100:103], v[188:191], v[80:83]
	v_mfma_f32_16x16x32_bf16 v[76:79], v[156:159], v[188:191], v[76:79]
	v_mfma_f32_16x16x32_bf16 v[72:75], v[100:103], v[196:199], v[72:75]
	v_mfma_f32_16x16x32_bf16 v[68:71], v[156:159], v[196:199], v[68:71]
	v_mfma_f32_16x16x32_bf16 v[96:99], v[104:107], v[176:179], v[96:99]
	v_mfma_f32_16x16x32_bf16 v[92:95], v[160:163], v[176:179], v[92:95]
	v_mfma_f32_16x16x32_bf16 v[88:91], v[104:107], v[184:187], v[88:91]
	v_mfma_f32_16x16x32_bf16 v[84:87], v[160:163], v[184:187], v[84:87]
	v_mfma_f32_16x16x32_bf16 v[80:83], v[104:107], v[192:195], v[80:83]
	v_mfma_f32_16x16x32_bf16 v[76:79], v[160:163], v[192:195], v[76:79]
	v_mfma_f32_16x16x32_bf16 v[72:75], v[104:107], v[200:203], v[72:75]
	v_mfma_f32_16x16x32_bf16 v[68:71], v[160:163], v[200:203], v[68:71]
	s_barrier
	s_setprio 0
	s_add_u32 s0, s28, 0xb0080
	s_addc_u32 s1, s29, 0
	s_add_i32 s24, s25, s68
	s_mov_b32 m0, s24
	s_nop 0
	global_load_lds_dwordx4 v26, s[0:1]
	s_add_i32 m0, s24, 0x2000
	s_nop 0
	global_load_lds_dwordx4 v140, s[0:1]
	v_add_u32_e32 v160, 0x10000, v233
	ds_read_b128 v[100:103], v160
	ds_read_b128 v[104:107], v160 offset:1024
	ds_read_b128 v[156:159], v160 offset:2048
	ds_read_b128 v[160:163], v160 offset:3072
	s_add_i32 s52, s52, 2
	s_add_u32 s18, s18, 0x100
	s_addc_u32 s19, s19, 0
	s_mov_b64 s[24:25], s[26:27]
	s_cmp_gt_u32 s52, 41
	s_cbranch_scc1 .Lth__395
	s_add_u32 s26, s24, 0x100
	s_addc_u32 s27, s25, 0
	s_add_i32 s0, 0, 0x10000
	s_cmp_eq_u32 s52, 40
	s_cselect_b32 s31, s43, s27
	s_cselect_b32 s30, s42, s26
	s_cselect_b32 s29, s45, s19
	s_cselect_b32 s28, s44, s18
	s_cmp_gt_u32 s52, 41
.Lth__395:
	s_waitcnt vmcnt(10)
	s_setprio 1
	s_barrier
	v_mfma_f32_16x16x32_bf16 v[32:35], v[204:207], v[172:175], v[32:35]
	v_mfma_f32_16x16x32_bf16 v[28:31], v[212:215], v[172:175], v[28:31]
	v_mfma_f32_16x16x32_bf16 v[22:25], v[204:207], v[180:183], v[22:25]
	v_mfma_f32_16x16x32_bf16 v[18:21], v[212:215], v[180:183], v[18:21]
	v_mfma_f32_16x16x32_bf16 v[14:17], v[204:207], v[188:191], v[14:17]
	v_mfma_f32_16x16x32_bf16 v[10:13], v[212:215], v[188:191], v[10:13]
	v_mfma_f32_16x16x32_bf16 v[6:9], v[204:207], v[196:199], v[6:9]
	v_mfma_f32_16x16x32_bf16 v[2:5], v[212:215], v[196:199], v[2:5]
	v_mfma_f32_16x16x32_bf16 v[32:35], v[208:211], v[176:179], v[32:35]
	v_mfma_f32_16x16x32_bf16 v[28:31], v[216:219], v[176:179], v[28:31]
	v_mfma_f32_16x16x32_bf16 v[22:25], v[208:211], v[184:187], v[22:25]
	v_mfma_f32_16x16x32_bf16 v[18:21], v[216:219], v[184:187], v[18:21]
	v_mfma_f32_16x16x32_bf16 v[14:17], v[208:211], v[192:195], v[14:17]
	v_mfma_f32_16x16x32_bf16 v[10:13], v[216:219], v[192:195], v[10:13]
	v_mfma_f32_16x16x32_bf16 v[6:9], v[208:211], v[200:203], v[6:9]
	v_mfma_f32_16x16x32_bf16 v[2:5], v[216:219], v[200:203], v[2:5]
	s_barrier
	s_setprio 0
	s_cbranch_scc0 .LBB0_395
	s_waitcnt lgkmcnt(0)
	s_min_i32 s0, s22, 0x100
	s_ashr_i32 s0, s0, 5
	s_ashr_i32 s1, s0, 31
	s_add_i32 s18, s22, 0xffffff00
	s_cmpk_lt_i32 s22, 0x100
	s_cselect_b32 s18, s22, s18
	s_cselect_b32 s25, 0, s35
	s_cselect_b32 s24, 0, s34
	s_cselect_b32 s26, 0, s57
	s_cselect_b32 s27, 0, s58
	s_ashr_i32 s19, s18, 31
	s_add_u32 s24, s46, s24
	s_addc_u32 s25, s47, s25
	s_lshl_b64 s[18:19], s[18:19], 20
	v_lshl_add_u64 v[100:101], s[18:19], 0, v[146:147]
	s_add_u32 s18, s50, s26
	v_lshl_or_b32 v172, s23, 8, v234
	s_addc_u32 s19, s51, s27
	s_ashr_i32 s23, s22, 31
	v_lshl_add_u64 v[180:181], s[18:19], 0, v[100:101]
	s_lshl_b64 s[18:19], s[22:23], 19
	v_lshl_add_u64 v[184:185], v[148:149], 0, s[18:19]
	s_lshl_b64 s[52:53], s[22:23], 10
	s_mul_i32 s18, s0, 0x9000
	v_ashrrev_i32_e32 v173, 31, v172
	s_mul_hi_i32 s19, s0, 0x9000
	s_add_u32 s18, s36, s18
	s_addc_u32 s19, s37, s19
	v_lshlrev_b64 v[186:187], 2, v[172:173]
	v_lshl_add_u64 v[156:157], s[18:19], 0, v[186:187]
	v_lshl_add_u64 v[164:165], s[24:25], 0, v[100:101]
	global_load_dwordx4 v[100:103], v[156:157], off offset:16
	global_load_dwordx4 v[104:107], v[156:157], off
	s_lshl_b64 s[0:1], s[0:1], 12
	s_add_u32 s0, s59, s0
	s_addc_u32 s1, s20, s1
	v_lshl_add_u64 v[164:165], v[164:165], 0, v[186:187]
	s_mov_b32 s18, 0x20000
	s_waitcnt vmcnt(0)
	v_pk_mul_f32 v[178:179], v[102:103], 0.5 op_sel_hi:[1,0]
	v_pk_mul_f32 v[174:175], v[106:107], 0.5 op_sel_hi:[1,0]
	v_pk_mul_f32 v[176:177], v[104:105], 0.5 op_sel_hi:[1,0]
	v_pk_mul_f32 v[210:211], v[100:101], 0.5 op_sel_hi:[1,0]
	global_load_dwordx4 v[100:103], v[156:157], off offset:528
	global_load_dwordx4 v[104:107], v[156:157], off offset:512
	s_waitcnt vmcnt(0)
	v_pk_mul_f32 v[162:163], v[100:101], 0.5 op_sel_hi:[1,0]
	v_lshlrev_b64 v[100:101], 1, v[172:173]
	v_lshl_add_u64 v[182:183], v[180:181], 0, v[100:101]
	v_lshl_add_u64 v[180:181], v[184:185], 0, v[100:101]
	v_lshl_add_u64 v[184:185], s[0:1], 0, v[186:187]
	v_pk_mul_f32 v[156:157], v[106:107], 0.5 op_sel_hi:[1,0]
	v_pk_mul_f32 v[158:159], v[104:105], 0.5 op_sel_hi:[1,0]
	v_pk_mul_f32 v[160:161], v[102:103], 0.5 op_sel_hi:[1,0]
	global_load_dwordx4 v[100:103], v[184:185], off offset:16
	global_load_dwordx4 v[104:107], v[184:185], off
	global_load_dwordx4 v[188:191], v[164:165], off offset:16
	global_load_dwordx4 v[192:195], v[164:165], off
	v_add_co_u32_e32 v186, vcc, s65, v164
	s_mov_b64 s[0:1], 0x10000
	s_nop 0
	v_addc_co_u32_e32 v187, vcc, 0, v165, vcc
	v_lshl_add_u64 v[172:173], v[164:165], 0, s[0:1]
	global_load_dwordx4 v[196:199], v[186:187], off
	global_load_dwordx4 v[200:203], v[172:173], off offset:16
	s_mov_b32 s0, 0x8000
	s_waitcnt vmcnt(0)
	v_pk_fma_f32 v[134:135], v[134:135], v[178:179], v[190:191]
	v_pk_fma_f32 v[138:139], v[138:139], v[174:175], v[194:195]
	v_pk_fma_f32 v[136:137], v[136:137], v[176:177], v[192:193]
	v_pk_fma_f32 v[132:133], v[132:133], v[210:211], v[188:189]
	v_cvt_pk_bf16_f32 v188, v136, v137
	v_cvt_pk_bf16_f32 v189, v138, v139
	v_cvt_pk_bf16_f32 v190, v132, v133
	v_cvt_pk_bf16_f32 v191, v134, v135
	v_lshlrev_b32_e32 v138, 16, v188
	v_and_b32_e32 v139, 0xffff0000, v188
	v_lshlrev_b32_e32 v136, 16, v189
	v_and_b32_e32 v137, 0xffff0000, v189
	global_store_dwordx4 v[182:183], v[188:191], off offset:2048
	v_lshlrev_b32_e32 v134, 16, v190
	v_and_b32_e32 v135, 0xffff0000, v190
	v_lshlrev_b32_e32 v132, 16, v191
	v_and_b32_e32 v133, 0xffff0000, v191
	v_pk_mul_f32 v[172:173], v[106:107], v[136:137]
	v_pk_mul_f32 v[188:189], v[104:105], v[138:139]
	v_pk_mul_f32 v[192:193], v[102:103], v[132:133]
	v_pk_mul_f32 v[190:191], v[100:101], v[134:135]
	v_cvt_pk_bf16_f32 v188, v188, v189
	v_cvt_pk_bf16_f32 v189, v172, v173
	v_pk_fma_f32 v[130:131], v[130:131], v[174:175], v[198:199]
	v_pk_fma_f32 v[128:129], v[128:129], v[176:177], v[196:197]
	v_pk_fma_f32 v[172:173], v[126:127], v[178:179], v[202:203]
	v_pk_fma_f32 v[126:127], v[124:125], v[210:211], v[200:201]
	v_add_co_u32_e32 v202, vcc, s65, v182
	v_cvt_pk_bf16_f32 v190, v190, v191
	v_cvt_pk_bf16_f32 v191, v192, v193
	v_cvt_pk_bf16_f32 v124, v128, v129
	v_cvt_pk_bf16_f32 v125, v130, v131
	v_cvt_pk_bf16_f32 v126, v126, v127
	v_cvt_pk_bf16_f32 v127, v172, v173
	v_addc_co_u32_e32 v203, vcc, 0, v183, vcc
	global_store_dwordx4 v[180:181], v[188:191], off
	global_store_dwordx4 v[202:203], v[124:127], off offset:2048
	v_lshlrev_b32_e32 v128, 16, v124
	v_and_b32_e32 v129, 0xffff0000, v124
	v_lshlrev_b32_e32 v124, 16, v125
	v_and_b32_e32 v125, 0xffff0000, v125
	v_lshlrev_b32_e32 v130, 16, v126
	v_and_b32_e32 v131, 0xffff0000, v126
	v_lshlrev_b32_e32 v126, 16, v127
	v_and_b32_e32 v127, 0xffff0000, v127
	v_pk_mul_f32 v[172:173], v[106:107], v[124:125]
	v_pk_mul_f32 v[188:189], v[104:105], v[128:129]
	v_pk_mul_f32 v[192:193], v[102:103], v[126:127]
	v_pk_mul_f32 v[190:191], v[100:101], v[130:131]
	v_add_co_u32_e32 v220, vcc, s0, v180
	v_cvt_pk_bf16_f32 v188, v188, v189
	v_cvt_pk_bf16_f32 v189, v172, v173
	v_cvt_pk_bf16_f32 v190, v190, v191
	v_cvt_pk_bf16_f32 v191, v192, v193
	v_addc_co_u32_e32 v221, vcc, 0, v181, vcc
	global_store_dwordx4 v[220:221], v[188:191], off
	s_mov_b64 s[0:1], 0x20000
	v_lshl_add_u64 v[172:173], v[164:165], 0, s[0:1]
	v_add_co_u32_e32 v188, vcc, s18, v164
	s_mov_b64 s[0:1], 0x30000
	s_nop 0
	v_addc_co_u32_e32 v189, vcc, 0, v165, vcc
	global_load_dwordx4 v[192:195], v[188:189], off
	global_load_dwordx4 v[196:199], v[172:173], off offset:16
	v_lshl_add_u64 v[172:173], v[164:165], 0, s[0:1]
	s_mov_b32 s0, 0x30000
	v_add_co_u32_e32 v190, vcc, s0, v164
	s_waitcnt vmcnt(0)
	v_pk_fma_f32 v[120:121], v[120:121], v[176:177], v[192:193]
	v_addc_co_u32_e32 v191, vcc, 0, v165, vcc
	global_load_dwordx4 v[204:207], v[190:191], off
	global_load_dwordx4 v[212:215], v[172:173], off offset:16
	v_pk_fma_f32 v[122:123], v[122:123], v[174:175], v[194:195]
	v_pk_fma_f32 v[118:119], v[118:119], v[178:179], v[198:199]
	v_pk_fma_f32 v[116:117], v[116:117], v[210:211], v[196:197]
	v_cvt_pk_bf16_f32 v194, v120, v121
	v_add_co_u32_e32 v192, vcc, s18, v182
	v_cvt_pk_bf16_f32 v195, v122, v123
	v_cvt_pk_bf16_f32 v196, v116, v117
	v_cvt_pk_bf16_f32 v197, v118, v119
	v_addc_co_u32_e32 v193, vcc, 0, v183, vcc
	v_lshlrev_b32_e32 v122, 16, v194
	v_and_b32_e32 v123, 0xffff0000, v194
	global_store_dwordx4 v[192:193], v[194:197], off offset:2048
	v_lshlrev_b32_e32 v120, 16, v195
	v_and_b32_e32 v121, 0xffff0000, v195
	v_pk_mul_f32 v[194:195], v[104:105], v[122:123]
	v_lshlrev_b32_e32 v118, 16, v196
	v_and_b32_e32 v119, 0xffff0000, v196
	v_cvt_pk_bf16_f32 v196, v194, v195
	v_add_co_u32_e32 v194, vcc, s65, v180
	v_lshlrev_b32_e32 v116, 16, v197
	v_and_b32_e32 v117, 0xffff0000, v197
	v_pk_mul_f32 v[172:173], v[106:107], v[120:121]
	v_addc_co_u32_e32 v195, vcc, 0, v181, vcc
	v_pk_mul_f32 v[200:201], v[102:103], v[116:117]
	v_pk_mul_f32 v[198:199], v[100:101], v[118:119]
	v_cvt_pk_bf16_f32 v197, v172, v173
	v_cvt_pk_bf16_f32 v198, v198, v199
	v_cvt_pk_bf16_f32 v199, v200, v201
	global_store_dwordx4 v[194:195], v[196:199], off
	s_mov_b32 s18, 0x80000
	s_waitcnt vmcnt(0)
	v_pk_fma_f32 v[114:115], v[114:115], v[174:175], v[206:207]
	v_pk_fma_f32 v[112:113], v[112:113], v[176:177], v[204:205]
	v_pk_fma_f32 v[172:173], v[110:111], v[178:179], v[214:215]
	v_pk_fma_f32 v[110:111], v[108:109], v[210:211], v[212:213]
	v_add_co_u32_e32 v212, vcc, s0, v182
	v_cvt_pk_bf16_f32 v108, v112, v113
	v_cvt_pk_bf16_f32 v109, v114, v115
	v_cvt_pk_bf16_f32 v110, v110, v111
	v_cvt_pk_bf16_f32 v111, v172, v173
	v_addc_co_u32_e32 v213, vcc, 0, v183, vcc
	global_store_dwordx4 v[212:213], v[108:111], off offset:2048
	v_lshlrev_b32_e32 v112, 16, v108
	v_and_b32_e32 v113, 0xffff0000, v108
	v_lshlrev_b32_e32 v172, 16, v109
	v_and_b32_e32 v173, 0xffff0000, v109
	v_lshlrev_b32_e32 v114, 16, v110
	v_and_b32_e32 v115, 0xffff0000, v110
	v_lshlrev_b32_e32 v108, 16, v111
	v_and_b32_e32 v109, 0xffff0000, v111
	s_mov_b32 s0, 0x18000
	v_pk_mul_f32 v[110:111], v[106:107], v[172:173]
	v_pk_mul_f32 v[196:197], v[104:105], v[112:113]
	v_pk_mul_f32 v[200:201], v[102:103], v[108:109]
	v_pk_mul_f32 v[198:199], v[100:101], v[114:115]
	v_add_co_u32_e32 v222, vcc, s0, v180
	v_cvt_pk_bf16_f32 v196, v196, v197
	v_cvt_pk_bf16_f32 v197, v110, v111
	v_cvt_pk_bf16_f32 v198, v198, v199
	v_cvt_pk_bf16_f32 v199, v200, v201
	v_addc_co_u32_e32 v223, vcc, 0, v181, vcc
	global_store_dwordx4 v[222:223], v[196:199], off
	s_mov_b64 s[0:1], 0x80000
	v_lshl_add_u64 v[110:111], v[164:165], 0, s[0:1]
	v_add_co_u32_e32 v196, vcc, s18, v164
	s_mov_b64 s[0:1], 0x90000
	s_nop 0
	v_addc_co_u32_e32 v197, vcc, 0, v165, vcc
	global_load_dwordx4 v[204:207], v[196:197], off
	global_load_dwordx4 v[214:217], v[110:111], off offset:16
	v_lshl_add_u64 v[110:111], v[164:165], 0, s[0:1]
	s_mov_b32 s0, 0x90000
	v_add_co_u32_e32 v198, vcc, s0, v164
	s_mov_b32 s1, 0x40000
	s_nop 0
	v_addc_co_u32_e32 v199, vcc, 0, v165, vcc
	global_load_dwordx4 v[238:241], v[198:199], off
	global_load_dwordx4 v[242:245], v[110:111], off offset:16
	v_add_co_u32_e32 v200, vcc, s18, v182
	s_waitcnt vmcnt(0)
	v_pk_fma_f32 v[96:97], v[96:97], v[176:177], v[204:205]
	v_pk_fma_f32 v[98:99], v[98:99], v[174:175], v[206:207]
	v_pk_fma_f32 v[94:95], v[94:95], v[178:179], v[216:217]
	v_pk_fma_f32 v[92:93], v[92:93], v[210:211], v[214:215]
	v_cvt_pk_bf16_f32 v204, v96, v97
	v_cvt_pk_bf16_f32 v205, v98, v99
	v_cvt_pk_bf16_f32 v206, v92, v93
	v_cvt_pk_bf16_f32 v207, v94, v95
	v_addc_co_u32_e32 v201, vcc, 0, v183, vcc
	v_lshlrev_b32_e32 v98, 16, v204
	v_and_b32_e32 v99, 0xffff0000, v204
	global_store_dwordx4 v[200:201], v[204:207], off offset:2048
	v_lshlrev_b32_e32 v96, 16, v205
	v_and_b32_e32 v97, 0xffff0000, v205
	v_pk_mul_f32 v[204:205], v[104:105], v[98:99]
	v_lshlrev_b32_e32 v94, 16, v206
	v_and_b32_e32 v95, 0xffff0000, v206
	v_cvt_pk_bf16_f32 v206, v204, v205
	v_add_co_u32_e32 v204, vcc, s1, v180
	v_lshlrev_b32_e32 v92, 16, v207
	v_and_b32_e32 v93, 0xffff0000, v207
	v_pk_mul_f32 v[110:111], v[106:107], v[96:97]
	v_addc_co_u32_e32 v205, vcc, 0, v181, vcc
	v_pk_mul_f32 v[214:215], v[102:103], v[92:93]
	v_pk_mul_f32 v[208:209], v[100:101], v[94:95]
	v_cvt_pk_bf16_f32 v207, v110, v111
	v_pk_fma_f32 v[90:91], v[90:91], v[174:175], v[240:241]
	v_pk_fma_f32 v[88:89], v[88:89], v[176:177], v[238:239]
	v_pk_fma_f32 v[110:111], v[86:87], v[178:179], v[244:245]
	v_pk_fma_f32 v[86:87], v[84:85], v[210:211], v[242:243]
	v_add_co_u32_e32 v218, vcc, s0, v182
	v_cvt_pk_bf16_f32 v208, v208, v209
	v_cvt_pk_bf16_f32 v209, v214, v215
	v_cvt_pk_bf16_f32 v84, v88, v89
	v_cvt_pk_bf16_f32 v85, v90, v91
	v_cvt_pk_bf16_f32 v86, v86, v87
	v_cvt_pk_bf16_f32 v87, v110, v111
	v_addc_co_u32_e32 v219, vcc, 0, v183, vcc
	global_store_dwordx4 v[204:205], v[206:209], off
	global_store_dwordx4 v[218:219], v[84:87], off offset:2048
	v_lshlrev_b32_e32 v88, 16, v84
	v_and_b32_e32 v89, 0xffff0000, v84
	v_lshlrev_b32_e32 v110, 16, v85
	v_and_b32_e32 v111, 0xffff0000, v85
	v_lshlrev_b32_e32 v90, 16, v86
	v_and_b32_e32 v91, 0xffff0000, v86
	v_lshlrev_b32_e32 v84, 16, v87
	v_and_b32_e32 v85, 0xffff0000, v87
	s_mov_b32 s0, 0x48000
	v_pk_mul_f32 v[86:87], v[106:107], v[110:111]
	v_pk_mul_f32 v[206:207], v[104:105], v[88:89]
	v_pk_mul_f32 v[214:215], v[102:103], v[84:85]
	v_pk_mul_f32 v[208:209], v[100:101], v[90:91]
	v_add_co_u32_e32 v224, vcc, s0, v180
	v_cvt_pk_bf16_f32 v206, v206, v207
	v_cvt_pk_bf16_f32 v207, v86, v87
	v_cvt_pk_bf16_f32 v208, v208, v209
	v_cvt_pk_bf16_f32 v209, v214, v215
	v_addc_co_u32_e32 v225, vcc, 0, v181, vcc
	global_store_dwordx4 v[224:225], v[206:209], off
	s_mov_b64 s[0:1], 0xa0000
	v_lshl_add_u64 v[86:87], v[164:165], 0, s[0:1]
	v_add_co_u32_e32 v206, vcc, s76, v164
	s_mov_b64 s[0:1], 0xb0000
	s_nop 0
	v_addc_co_u32_e32 v207, vcc, 0, v165, vcc
	global_load_dwordx4 v[214:217], v[206:207], off
	global_load_dwordx4 v[238:241], v[86:87], off offset:16
	v_lshl_add_u64 v[86:87], v[164:165], 0, s[0:1]
	s_mov_b32 s0, 0xb0000
	v_add_co_u32_e32 v208, vcc, s0, v164
	s_waitcnt vmcnt(0)
	v_pk_fma_f32 v[80:81], v[80:81], v[176:177], v[214:215]
	v_addc_co_u32_e32 v209, vcc, 0, v165, vcc
	global_load_dwordx4 v[242:245], v[208:209], off
	global_load_dwordx4 v[246:249], v[86:87], off offset:16
	v_pk_fma_f32 v[82:83], v[82:83], v[174:175], v[216:217]
	v_pk_fma_f32 v[76:77], v[76:77], v[210:211], v[238:239]
	v_cvt_pk_bf16_f32 v238, v80, v81
	v_pk_fma_f32 v[78:79], v[78:79], v[178:179], v[240:241]
	v_cvt_pk_bf16_f32 v239, v82, v83
	v_add_co_u32_e32 v214, vcc, s76, v182
	v_lshlrev_b32_e32 v82, 16, v238
	v_and_b32_e32 v83, 0xffff0000, v238
	v_cvt_pk_bf16_f32 v240, v76, v77
	v_cvt_pk_bf16_f32 v241, v78, v79
	v_addc_co_u32_e32 v215, vcc, 0, v183, vcc
	v_lshlrev_b32_e32 v80, 16, v239
	v_and_b32_e32 v81, 0xffff0000, v239
	v_pk_mul_f32 v[216:217], v[104:105], v[82:83]
	global_store_dwordx4 v[214:215], v[238:241], off offset:2048
	v_pk_mul_f32 v[86:87], v[106:107], v[80:81]
	v_lshlrev_b32_e32 v78, 16, v240
	v_cvt_pk_bf16_f32 v238, v216, v217
	v_add_co_u32_e32 v216, vcc, s77, v180
	v_and_b32_e32 v79, 0xffff0000, v240
	v_lshlrev_b32_e32 v76, 16, v241
	v_and_b32_e32 v77, 0xffff0000, v241
	v_cvt_pk_bf16_f32 v239, v86, v87
	v_addc_co_u32_e32 v217, vcc, 0, v181, vcc
	v_pk_mul_f32 v[250:251], v[102:103], v[76:77]
	v_pk_mul_f32 v[240:241], v[100:101], v[78:79]
	s_waitcnt vmcnt(0)
	v_pk_fma_f32 v[74:75], v[74:75], v[174:175], v[244:245]
	v_pk_fma_f32 v[72:73], v[72:73], v[176:177], v[242:243]
	v_pk_fma_f32 v[86:87], v[70:71], v[178:179], v[248:249]
	v_pk_fma_f32 v[70:71], v[68:69], v[210:211], v[246:247]
	v_cvt_pk_bf16_f32 v68, v72, v73
	v_cvt_pk_bf16_f32 v69, v74, v75
	v_cvt_pk_bf16_f32 v70, v70, v71
	v_cvt_pk_bf16_f32 v71, v86, v87
	v_add_co_u32_e32 v210, vcc, s0, v182
	v_cvt_pk_bf16_f32 v240, v240, v241
	v_cvt_pk_bf16_f32 v241, v250, v251
	v_addc_co_u32_e32 v211, vcc, 0, v183, vcc
	v_lshlrev_b32_e32 v86, 16, v68
	v_and_b32_e32 v87, 0xffff0000, v68
	v_lshlrev_b32_e32 v178, 16, v69
	v_and_b32_e32 v179, 0xffff0000, v69
	v_lshlrev_b32_e32 v176, 16, v70
	v_and_b32_e32 v177, 0xffff0000, v70
	v_lshlrev_b32_e32 v174, 16, v71
	v_and_b32_e32 v175, 0xffff0000, v71
	s_mov_b32 s0, 0x58000
	global_store_dwordx4 v[216:217], v[238:241], off
	global_store_dwordx4 v[210:211], v[68:71], off offset:2048
	v_pk_mul_f32 v[72:73], v[102:103], v[174:175]
	v_pk_mul_f32 v[74:75], v[100:101], v[176:177]
	v_pk_mul_f32 v[70:71], v[106:107], v[178:179]
	v_pk_mul_f32 v[68:69], v[104:105], v[86:87]
	v_add_co_u32_e32 v100, vcc, s0, v180
	v_cvt_pk_bf16_f32 v68, v68, v69
	v_cvt_pk_bf16_f32 v69, v70, v71
	v_cvt_pk_bf16_f32 v70, v74, v75
	v_cvt_pk_bf16_f32 v71, v72, v73
	v_addc_co_u32_e32 v101, vcc, 0, v181, vcc
	global_store_dwordx4 v[100:101], v[68:71], off
	global_load_dwordx4 v[68:71], v[184:185], off offset:528
	s_nop 0
	global_load_dwordx4 v[72:75], v[184:185], off offset:512
	global_load_dwordx4 v[102:105], v[164:165], off offset:528
	global_load_dwordx4 v[238:241], v[164:165], off offset:512
	s_mov_b64 s[0:1], 0x10200
	v_lshl_add_u64 v[106:107], v[164:165], 0, s[0:1]
	global_load_dwordx4 v[184:187], v[186:187], off offset:512
	s_nop 0
	global_load_dwordx4 v[242:245], v[106:107], off offset:16
	s_mov_b64 s[0:1], 0x20200
	s_waitcnt vmcnt(0)
	v_pk_fma_f32 v[62:63], v[62:63], v[160:161], v[104:105]
	v_pk_fma_f32 v[66:67], v[66:67], v[156:157], v[240:241]
	v_pk_fma_f32 v[64:65], v[64:65], v[158:159], v[238:239]
	v_pk_fma_f32 v[60:61], v[60:61], v[162:163], v[102:103]
	v_cvt_pk_bf16_f32 v102, v64, v65
	v_cvt_pk_bf16_f32 v103, v66, v67
	v_cvt_pk_bf16_f32 v104, v60, v61
	v_cvt_pk_bf16_f32 v105, v62, v63
	v_lshlrev_b32_e32 v66, 16, v102
	v_and_b32_e32 v67, 0xffff0000, v102
	v_lshlrev_b32_e32 v64, 16, v103
	v_and_b32_e32 v65, 0xffff0000, v103
	v_lshlrev_b32_e32 v62, 16, v104
	v_and_b32_e32 v63, 0xffff0000, v104
	v_lshlrev_b32_e32 v60, 16, v105
	v_and_b32_e32 v61, 0xffff0000, v105
	global_store_dwordx4 v[182:183], v[102:105], off offset:2304
	v_pk_mul_f32 v[106:107], v[70:71], v[60:61]
	v_pk_mul_f32 v[182:183], v[68:69], v[62:63]
	v_pk_mul_f32 v[104:105], v[74:75], v[64:65]
	v_pk_mul_f32 v[102:103], v[72:73], v[66:67]
	v_pk_fma_f32 v[58:59], v[58:59], v[156:157], v[186:187]
	v_cvt_pk_bf16_f32 v102, v102, v103
	v_cvt_pk_bf16_f32 v103, v104, v105
	v_cvt_pk_bf16_f32 v104, v182, v183
	v_cvt_pk_bf16_f32 v105, v106, v107
	v_pk_fma_f32 v[56:57], v[56:57], v[158:159], v[184:185]
	v_pk_fma_f32 v[54:55], v[54:55], v[160:161], v[244:245]
	v_pk_fma_f32 v[52:53], v[52:53], v[162:163], v[242:243]
	global_store_dwordx4 v[180:181], v[102:105], off offset:256
	v_mul_f32_e32 v67, v67, v67
	v_mul_f32_e32 v65, v65, v65
	v_cvt_pk_bf16_f32 v102, v56, v57
	v_cvt_pk_bf16_f32 v103, v58, v59
	v_cvt_pk_bf16_f32 v104, v52, v53
	v_cvt_pk_bf16_f32 v105, v54, v55
	v_lshlrev_b32_e32 v58, 16, v102
	v_and_b32_e32 v59, 0xffff0000, v102
	v_lshlrev_b32_e32 v56, 16, v103
	v_and_b32_e32 v57, 0xffff0000, v103
	v_lshlrev_b32_e32 v54, 16, v104
	v_and_b32_e32 v55, 0xffff0000, v104
	v_lshlrev_b32_e32 v52, 16, v105
	v_and_b32_e32 v53, 0xffff0000, v105
	global_store_dwordx4 v[202:203], v[102:105], off offset:2304
	v_pk_mul_f32 v[106:107], v[70:71], v[52:53]
	v_pk_mul_f32 v[180:181], v[68:69], v[54:55]
	v_pk_mul_f32 v[104:105], v[74:75], v[56:57]
	v_pk_mul_f32 v[102:103], v[72:73], v[58:59]
	v_fmac_f32_e32 v67, v66, v66
	v_cvt_pk_bf16_f32 v102, v102, v103
	v_cvt_pk_bf16_f32 v103, v104, v105
	v_cvt_pk_bf16_f32 v104, v180, v181
	v_cvt_pk_bf16_f32 v105, v106, v107
	global_store_dwordx4 v[220:221], v[102:105], off offset:256
	v_lshl_add_u64 v[106:107], v[164:165], 0, s[0:1]
	global_load_dwordx4 v[102:105], v[188:189], off offset:512
	global_load_dwordx4 v[180:183], v[106:107], off offset:16
	s_mov_b64 s[0:1], 0x30200
	v_lshl_add_u64 v[106:107], v[164:165], 0, s[0:1]
	global_load_dwordx4 v[184:187], v[190:191], off offset:512
	s_nop 0
	global_load_dwordx4 v[188:191], v[106:107], off offset:16
	s_mov_b64 s[0:1], 0x80200
	v_fmac_f32_e32 v65, v64, v64
	v_mul_f32_e32 v63, v63, v63
	v_mul_f32_e32 v61, v61, v61
	v_add_f32_e32 v64, v67, v65
	v_fmac_f32_e32 v63, v62, v62
	v_fmac_f32_e32 v61, v60, v60
	v_add_f32_e32 v60, v63, v61
	s_waitcnt vmcnt(0)
	v_pk_fma_f32 v[50:51], v[50:51], v[156:157], v[104:105]
	v_pk_fma_f32 v[48:49], v[48:49], v[158:159], v[102:103]
	v_pk_fma_f32 v[46:47], v[46:47], v[160:161], v[182:183]
	v_pk_fma_f32 v[44:45], v[44:45], v[162:163], v[180:181]
	v_cvt_pk_bf16_f32 v102, v48, v49
	v_cvt_pk_bf16_f32 v103, v50, v51
	v_cvt_pk_bf16_f32 v104, v44, v45
	v_cvt_pk_bf16_f32 v105, v46, v47
	v_lshlrev_b32_e32 v50, 16, v102
	v_and_b32_e32 v51, 0xffff0000, v102
	v_lshlrev_b32_e32 v48, 16, v103
	v_and_b32_e32 v49, 0xffff0000, v103
	v_lshlrev_b32_e32 v46, 16, v104
	v_and_b32_e32 v47, 0xffff0000, v104
	v_lshlrev_b32_e32 v44, 16, v105
	v_and_b32_e32 v45, 0xffff0000, v105
	global_store_dwordx4 v[192:193], v[102:105], off offset:2304
	v_pk_mul_f32 v[106:107], v[70:71], v[44:45]
	v_pk_mul_f32 v[180:181], v[68:69], v[46:47]
	v_pk_mul_f32 v[104:105], v[74:75], v[48:49]
	v_pk_mul_f32 v[102:103], v[72:73], v[50:51]
	v_pk_fma_f32 v[42:43], v[42:43], v[156:157], v[186:187]
	v_cvt_pk_bf16_f32 v102, v102, v103
	v_cvt_pk_bf16_f32 v103, v104, v105
	v_cvt_pk_bf16_f32 v104, v180, v181
	v_cvt_pk_bf16_f32 v105, v106, v107
	v_pk_fma_f32 v[40:41], v[40:41], v[158:159], v[184:185]
	v_pk_fma_f32 v[38:39], v[38:39], v[160:161], v[190:191]
	v_pk_fma_f32 v[36:37], v[36:37], v[162:163], v[188:189]
	global_store_dwordx4 v[194:195], v[102:105], off offset:256
	s_nop 1
	v_cvt_pk_bf16_f32 v102, v40, v41
	v_cvt_pk_bf16_f32 v103, v42, v43
	v_cvt_pk_bf16_f32 v104, v36, v37
	v_cvt_pk_bf16_f32 v105, v38, v39
	v_lshlrev_b32_e32 v42, 16, v102
	v_and_b32_e32 v43, 0xffff0000, v102
	v_lshlrev_b32_e32 v40, 16, v103
	v_and_b32_e32 v41, 0xffff0000, v103
	v_lshlrev_b32_e32 v38, 16, v104
	v_and_b32_e32 v39, 0xffff0000, v104
	v_lshlrev_b32_e32 v36, 16, v105
	v_and_b32_e32 v37, 0xffff0000, v105
	global_store_dwordx4 v[212:213], v[102:105], off offset:2304
	v_pk_mul_f32 v[106:107], v[70:71], v[36:37]
	v_pk_mul_f32 v[180:181], v[68:69], v[38:39]
	v_pk_mul_f32 v[104:105], v[74:75], v[40:41]
	v_pk_mul_f32 v[102:103], v[72:73], v[42:43]
	s_nop 0
	v_cvt_pk_bf16_f32 v102, v102, v103
	v_cvt_pk_bf16_f32 v103, v104, v105
	v_cvt_pk_bf16_f32 v104, v180, v181
	v_cvt_pk_bf16_f32 v105, v106, v107
	global_store_dwordx4 v[222:223], v[102:105], off offset:256
	v_lshl_add_u64 v[106:107], v[164:165], 0, s[0:1]
	global_load_dwordx4 v[102:105], v[196:197], off offset:512
	global_load_dwordx4 v[180:183], v[106:107], off offset:16
	s_mov_b64 s[0:1], 0x90200
	v_lshl_add_u64 v[106:107], v[164:165], 0, s[0:1]
	global_load_dwordx4 v[184:187], v[198:199], off offset:512
	global_load_dwordx4 v[188:191], v[106:107], off offset:16
	s_mov_b64 s[0:1], 0xa0200
	s_waitcnt vmcnt(0)
	v_pk_fma_f32 v[34:35], v[34:35], v[156:157], v[104:105]
	v_pk_fma_f32 v[32:33], v[32:33], v[158:159], v[102:103]
	v_pk_fma_f32 v[30:31], v[30:31], v[160:161], v[182:183]
	v_pk_fma_f32 v[28:29], v[28:29], v[162:163], v[180:181]
	v_cvt_pk_bf16_f32 v102, v32, v33
	v_cvt_pk_bf16_f32 v103, v34, v35
	v_cvt_pk_bf16_f32 v104, v28, v29
	v_cvt_pk_bf16_f32 v105, v30, v31
	v_lshlrev_b32_e32 v34, 16, v102
	v_and_b32_e32 v35, 0xffff0000, v102
	v_lshlrev_b32_e32 v32, 16, v103
	v_and_b32_e32 v33, 0xffff0000, v103
	v_lshlrev_b32_e32 v30, 16, v104
	v_and_b32_e32 v31, 0xffff0000, v104
	v_lshlrev_b32_e32 v28, 16, v105
	v_and_b32_e32 v29, 0xffff0000, v105
	global_store_dwordx4 v[200:201], v[102:105], off offset:2304
	v_pk_mul_f32 v[106:107], v[70:71], v[28:29]
	v_pk_mul_f32 v[180:181], v[68:69], v[30:31]
	v_pk_mul_f32 v[104:105], v[74:75], v[32:33]
	v_pk_mul_f32 v[102:103], v[72:73], v[34:35]
	v_pk_fma_f32 v[24:25], v[24:25], v[156:157], v[186:187]
	v_cvt_pk_bf16_f32 v102, v102, v103
	v_cvt_pk_bf16_f32 v103, v104, v105
	v_cvt_pk_bf16_f32 v104, v180, v181
	v_cvt_pk_bf16_f32 v105, v106, v107
	v_pk_fma_f32 v[22:23], v[22:23], v[158:159], v[184:185]
	v_pk_fma_f32 v[20:21], v[20:21], v[160:161], v[190:191]
	v_pk_fma_f32 v[18:19], v[18:19], v[162:163], v[188:189]
	global_store_dwordx4 v[204:205], v[102:105], off offset:256
	s_nop 1
	v_cvt_pk_bf16_f32 v102, v22, v23
	v_cvt_pk_bf16_f32 v103, v24, v25
	v_cvt_pk_bf16_f32 v104, v18, v19
	v_cvt_pk_bf16_f32 v105, v20, v21
	v_lshlrev_b32_e32 v24, 16, v102
	v_and_b32_e32 v25, 0xffff0000, v102
	v_lshlrev_b32_e32 v22, 16, v103
	v_and_b32_e32 v23, 0xffff0000, v103
	v_lshlrev_b32_e32 v20, 16, v104
	v_and_b32_e32 v21, 0xffff0000, v104
	v_lshlrev_b32_e32 v18, 16, v105
	v_and_b32_e32 v19, 0xffff0000, v105
	global_store_dwordx4 v[218:219], v[102:105], off offset:2304
	v_pk_mul_f32 v[106:107], v[70:71], v[18:19]
	v_pk_mul_f32 v[180:181], v[68:69], v[20:21]
	v_pk_mul_f32 v[104:105], v[74:75], v[22:23]
	v_pk_mul_f32 v[102:103], v[72:73], v[24:25]
	s_nop 0
	v_cvt_pk_bf16_f32 v102, v102, v103
	v_cvt_pk_bf16_f32 v103, v104, v105
	v_cvt_pk_bf16_f32 v104, v180, v181
	v_cvt_pk_bf16_f32 v105, v106, v107
	global_store_dwordx4 v[224:225], v[102:105], off offset:256
	v_lshl_add_u64 v[106:107], v[164:165], 0, s[0:1]
	global_load_dwordx4 v[102:105], v[206:207], off offset:512
	global_load_dwordx4 v[180:183], v[106:107], off offset:16
	s_mov_b64 s[0:1], 0xb0200
	v_lshl_add_u64 v[106:107], v[164:165], 0, s[0:1]
	global_load_dwordx4 v[184:187], v[208:209], off offset:512
	global_load_dwordx4 v[188:191], v[106:107], off offset:16
	s_waitcnt vmcnt(0)
	v_pk_fma_f32 v[16:17], v[16:17], v[156:157], v[104:105]
	v_pk_fma_f32 v[14:15], v[14:15], v[158:159], v[102:103]
	v_pk_fma_f32 v[102:103], v[12:13], v[160:161], v[182:183]
	v_pk_fma_f32 v[12:13], v[10:11], v[162:163], v[180:181]
	v_cvt_pk_bf16_f32 v10, v14, v15
	v_cvt_pk_bf16_f32 v11, v16, v17
	v_cvt_pk_bf16_f32 v12, v12, v13
	v_cvt_pk_bf16_f32 v13, v102, v103
	v_lshlrev_b32_e32 v102, 16, v10
	v_and_b32_e32 v103, 0xffff0000, v10
	v_lshlrev_b32_e32 v16, 16, v11
	v_and_b32_e32 v17, 0xffff0000, v11
	global_store_dwordx4 v[214:215], v[10:13], off offset:2304
	v_lshlrev_b32_e32 v14, 16, v12
	v_and_b32_e32 v15, 0xffff0000, v12
	v_lshlrev_b32_e32 v12, 16, v13
	v_and_b32_e32 v13, 0xffff0000, v13
	v_pk_mul_f32 v[10:11], v[74:75], v[16:17]
	v_pk_mul_f32 v[104:105], v[72:73], v[102:103]
	v_pk_mul_f32 v[164:165], v[70:71], v[12:13]
	v_pk_mul_f32 v[106:107], v[68:69], v[14:15]
	v_cvt_pk_bf16_f32 v104, v104, v105
	v_cvt_pk_bf16_f32 v105, v10, v11
	v_pk_fma_f32 v[8:9], v[8:9], v[156:157], v[186:187]
	v_pk_fma_f32 v[6:7], v[6:7], v[158:159], v[184:185]
	v_pk_fma_f32 v[10:11], v[4:5], v[160:161], v[190:191]
	v_pk_fma_f32 v[4:5], v[2:3], v[162:163], v[188:189]
	v_cvt_pk_bf16_f32 v106, v106, v107
	v_cvt_pk_bf16_f32 v107, v164, v165
	v_cvt_pk_bf16_f32 v2, v6, v7
	v_cvt_pk_bf16_f32 v3, v8, v9
	v_cvt_pk_bf16_f32 v4, v4, v5
	v_cvt_pk_bf16_f32 v5, v10, v11
	global_store_dwordx4 v[216:217], v[104:107], off offset:256
	global_store_dwordx4 v[210:211], v[2:5], off offset:2304
	v_lshlrev_b32_e32 v10, 16, v2
	v_and_b32_e32 v11, 0xffff0000, v2
	v_lshlrev_b32_e32 v8, 16, v3
	v_and_b32_e32 v9, 0xffff0000, v3
	v_lshlrev_b32_e32 v6, 16, v4
	v_and_b32_e32 v7, 0xffff0000, v4
	v_lshlrev_b32_e32 v4, 16, v5
	v_and_b32_e32 v5, 0xffff0000, v5
	v_pk_mul_f32 v[2:3], v[74:75], v[8:9]
	v_pk_mul_f32 v[72:73], v[72:73], v[10:11]
	v_pk_mul_f32 v[74:75], v[70:71], v[4:5]
	v_pk_mul_f32 v[70:71], v[68:69], v[6:7]
	v_cvt_pk_bf16_f32 v68, v72, v73
	v_cvt_pk_bf16_f32 v69, v2, v3
	v_cvt_pk_bf16_f32 v70, v70, v71
	v_cvt_pk_bf16_f32 v71, v74, v75
	global_store_dwordx4 v[100:101], v[68:71], off offset:256
	v_mul_f32_e32 v72, v133, v133
	v_fmac_f32_e32 v72, v132, v132
	v_and_b32_e32 v69, 64, v227
	v_xor_b32_e32 v68, 16, v227
	v_add_u32_e32 v69, 64, v69
	v_cmp_lt_i32_e32 vcc, v68, v69
	v_xor_b32_e32 v70, 32, v227
	v_mul_f32_e32 v71, v137, v137
	v_cndmask_b32_e32 v68, v227, v68, vcc
	v_cmp_lt_i32_e32 vcc, v70, v69
	v_fmac_f32_e32 v71, v136, v136
	v_lshlrev_b32_e32 v68, 2, v68
	v_cndmask_b32_e32 v69, v227, v70, vcc
	v_mul_f32_e32 v70, v139, v139
	v_fmac_f32_e32 v70, v138, v138
	v_add_f32_e32 v70, v70, v71
	v_mul_f32_e32 v71, v135, v135
	v_fmac_f32_e32 v71, v134, v134
	v_add_f32_e32 v71, v71, v72
	v_add_f32_e32 v70, v70, v71
	v_add_f32_e32 v64, v70, v64
	v_add_f32_e32 v60, v64, v60
	ds_bpermute_b32 v61, v68, v60
	v_lshlrev_b32_e32 v69, 2, v69
	v_lshl_add_u64 v[2:3], v[150:151], 0, s[52:53]
	s_waitcnt lgkmcnt(0)
	v_add_f32_e32 v60, v60, v61
	ds_bpermute_b32 v61, v69, v60
	s_and_saveexec_b64 s[18:19], s[38:39]
	s_cbranch_execz .LBB0_398
	s_waitcnt lgkmcnt(0)
	v_add_f32_e32 v60, v60, v61
	global_atomic_add_f32 v[2:3], v60, off

.LBB0_478:
	s_ashr_i32 s49, s48, 31
	s_lshl_b64 s[0:1], s[48:49], 19
	s_add_u32 s52, s16, s0
	v_cmp_lt_i64_e32 vcc, s[26:27], v[170:171]
	s_addc_u32 s53, s17, s1
	s_and_b64 s[0:1], vcc, exec
	s_cselect_b32 s35, s53, s23
	s_cselect_b32 s40, s52, s22
	s_ashr_i32 s51, s50, 31
	s_lshl_b64 s[0:1], s[50:51], 19
	s_add_u32 s54, s20, s0
	s_addc_u32 s55, s21, s1
	s_and_b64 s[0:1], vcc, exec
	s_cselect_b32 s41, s55, s25
	s_cselect_b32 s49, s54, s24
	s_add_u32 s22, s22, 0x40080
	s_addc_u32 s23, s23, 0
	s_add_u32 s51, s24, 0x100
	v_mov_b32_e32 v2, 0
	s_addc_u32 s59, s25, 0
	s_mov_b32 s68, -2
	v_mov_b32_e32 v3, v2
	v_mov_b32_e32 v4, v2
	v_mov_b32_e32 v5, v2
	v_mov_b32_e32 v6, v2
	v_mov_b32_e32 v7, v2
	v_mov_b32_e32 v8, v2
	v_mov_b32_e32 v9, v2
	v_mov_b32_e32 v10, v2
	v_mov_b32_e32 v11, v2
	v_mov_b32_e32 v12, v2
	v_mov_b32_e32 v13, v2
	v_mov_b32_e32 v14, v2
	v_mov_b32_e32 v15, v2
	v_mov_b32_e32 v16, v2
	v_mov_b32_e32 v17, v2
	v_mov_b32_e32 v18, v2
	v_mov_b32_e32 v19, v2
	v_mov_b32_e32 v20, v2
	v_mov_b32_e32 v21, v2
	v_mov_b32_e32 v22, v2
	v_mov_b32_e32 v23, v2
	v_mov_b32_e32 v24, v2
	v_mov_b32_e32 v25, v2
	v_mov_b32_e32 v28, v2
	v_mov_b32_e32 v29, v2
	v_mov_b32_e32 v30, v2
	v_mov_b32_e32 v31, v2
	v_mov_b32_e32 v32, v2
	v_mov_b32_e32 v33, v2
	v_mov_b32_e32 v34, v2
	v_mov_b32_e32 v35, v2
	v_mov_b32_e32 v68, v2
	v_mov_b32_e32 v69, v2
	v_mov_b32_e32 v70, v2
	v_mov_b32_e32 v71, v2
	v_mov_b32_e32 v72, v2
	v_mov_b32_e32 v73, v2
	v_mov_b32_e32 v74, v2
	v_mov_b32_e32 v75, v2
	v_mov_b32_e32 v76, v2
	v_mov_b32_e32 v77, v2
	v_mov_b32_e32 v78, v2
	v_mov_b32_e32 v79, v2
	v_mov_b32_e32 v80, v2
	v_mov_b32_e32 v81, v2
	v_mov_b32_e32 v82, v2
	v_mov_b32_e32 v83, v2
	v_mov_b32_e32 v84, v2
	v_mov_b32_e32 v85, v2
	v_mov_b32_e32 v86, v2
	v_mov_b32_e32 v87, v2
	v_mov_b32_e32 v88, v2
	v_mov_b32_e32 v89, v2
	v_mov_b32_e32 v90, v2
	v_mov_b32_e32 v91, v2
	v_mov_b32_e32 v92, v2
	v_mov_b32_e32 v93, v2
	v_mov_b32_e32 v94, v2
	v_mov_b32_e32 v95, v2
	v_mov_b32_e32 v96, v2
	v_mov_b32_e32 v97, v2
	v_mov_b32_e32 v98, v2
	v_mov_b32_e32 v99, v2
	s_waitcnt vmcnt(0)
	v_mov_b32_e32 v36, v2
	v_mov_b32_e32 v37, v2
	v_mov_b32_e32 v38, v2
	v_mov_b32_e32 v39, v2
	v_mov_b32_e32 v40, v2
	v_mov_b32_e32 v41, v2
	v_mov_b32_e32 v42, v2
	v_mov_b32_e32 v43, v2
	v_mov_b32_e32 v44, v2
	v_mov_b32_e32 v45, v2
	v_mov_b32_e32 v46, v2
	v_mov_b32_e32 v47, v2
	v_mov_b32_e32 v48, v2
	v_mov_b32_e32 v49, v2
	v_mov_b32_e32 v50, v2
	v_mov_b32_e32 v51, v2
	v_mov_b32_e32 v52, v2
	v_mov_b32_e32 v53, v2
	v_mov_b32_e32 v54, v2
	v_mov_b32_e32 v55, v2
	v_mov_b32_e32 v56, v2
	v_mov_b32_e32 v57, v2
	v_mov_b32_e32 v58, v2
	v_mov_b32_e32 v59, v2
	v_mov_b32_e32 v60, v2
	v_mov_b32_e32 v61, v2
	v_mov_b32_e32 v62, v2
	v_mov_b32_e32 v63, v2
	v_mov_b32_e32 v64, v2
	v_mov_b32_e32 v65, v2
	v_mov_b32_e32 v66, v2
	v_mov_b32_e32 v67, v2
	v_mov_b32_e32 v108, v2
	v_mov_b32_e32 v109, v2
	v_mov_b32_e32 v110, v2
	v_mov_b32_e32 v111, v2
	v_mov_b32_e32 v112, v2
	v_mov_b32_e32 v113, v2
	v_mov_b32_e32 v114, v2
	v_mov_b32_e32 v115, v2
	v_mov_b32_e32 v116, v2
	v_mov_b32_e32 v117, v2
	v_mov_b32_e32 v118, v2
	v_mov_b32_e32 v119, v2
	v_mov_b32_e32 v120, v2
	v_mov_b32_e32 v121, v2
	v_mov_b32_e32 v122, v2
	v_mov_b32_e32 v123, v2
	v_mov_b32_e32 v124, v2
	v_mov_b32_e32 v125, v2
	v_mov_b32_e32 v126, v2
	v_mov_b32_e32 v127, v2
	v_mov_b32_e32 v128, v2
	v_mov_b32_e32 v129, v2
	v_mov_b32_e32 v130, v2
	v_mov_b32_e32 v131, v2
	v_mov_b32_e32 v132, v2
	v_mov_b32_e32 v133, v2
	v_mov_b32_e32 v134, v2
	v_mov_b32_e32 v135, v2
	v_mov_b32_e32 v136, v2
	v_mov_b32_e32 v137, v2
	v_mov_b32_e32 v138, v2
	v_mov_b32_e32 v139, v2
	v_add_u32_e32 v154, 0x10000, v163
	ds_read_b128 v[100:103], v154
	ds_read_b128 v[104:107], v154 offset:1024
	ds_read_b128 v[150:153], v154 offset:2048
	ds_read_b128 v[154:157], v154 offset:3072
	s_add_u32 s0, s22, 0xfffc0080
	s_addc_u32 s1, s23, -1
	s_add_i32 s69, 0, 0x10000
	s_cmp_eq_u32 s68, 12
	s_cselect_b32 s27, s35, s1
	s_cselect_b32 s26, s40, s0
	s_cselect_b32 s25, s41, s59
	s_cselect_b32 s24, s49, s51
.LBB0_479:
	s_add_i32 m0, s37, 0xc000
	ds_read_b128 v[158:161], v165
	ds_read_b128 v[172:175], v165 offset:1024
	ds_read_b128 v[176:179], v165 offset:2048
	ds_read_b128 v[180:183], v165 offset:3072
	ds_read_b128 v[184:187], v165 offset:4096
	ds_read_b128 v[188:191], v165 offset:5120
	ds_read_b128 v[192:195], v165 offset:6144
	ds_read_b128 v[196:199], v165 offset:7168
	global_load_lds_dwordx4 v146, s[22:23]
	v_lshl_add_u64 v[166:167], s[22:23], 0, v[148:149]
	s_add_i32 m0, s37, 0xe000
	s_nop 0
	global_load_lds_dwordx4 v[166:167], off
	s_waitcnt vmcnt(10) lgkmcnt(8)
	s_setprio 1
	s_barrier
	s_waitcnt lgkmcnt(0)
	v_mfma_f32_16x16x32_bf16 v[136:139], v[100:103], v[158:161], v[136:139]
	v_mfma_f32_16x16x32_bf16 v[132:135], v[150:153], v[158:161], v[132:135]
	v_mfma_f32_16x16x32_bf16 v[128:131], v[100:103], v[176:179], v[128:131]
	v_mfma_f32_16x16x32_bf16 v[124:127], v[150:153], v[176:179], v[124:127]
	v_mfma_f32_16x16x32_bf16 v[120:123], v[100:103], v[184:187], v[120:123]
	v_mfma_f32_16x16x32_bf16 v[116:119], v[150:153], v[184:187], v[116:119]
	v_mfma_f32_16x16x32_bf16 v[112:115], v[100:103], v[192:195], v[112:115]
	v_mfma_f32_16x16x32_bf16 v[108:111], v[150:153], v[192:195], v[108:111]
	v_mfma_f32_16x16x32_bf16 v[136:139], v[104:107], v[172:175], v[136:139]
	v_mfma_f32_16x16x32_bf16 v[132:135], v[154:157], v[172:175], v[132:135]
	v_mfma_f32_16x16x32_bf16 v[128:131], v[104:107], v[180:183], v[128:131]
	v_mfma_f32_16x16x32_bf16 v[124:127], v[154:157], v[180:183], v[124:127]
	v_mfma_f32_16x16x32_bf16 v[120:123], v[104:107], v[188:191], v[120:123]
	v_mfma_f32_16x16x32_bf16 v[116:119], v[154:157], v[188:191], v[116:119]
	v_mfma_f32_16x16x32_bf16 v[112:115], v[104:107], v[196:199], v[112:115]
	v_mfma_f32_16x16x32_bf16 v[108:111], v[154:157], v[196:199], v[108:111]
	s_barrier
	s_setprio 0
	s_add_i32 s72, 0, 0x14000
	v_add_u32_e32 v166, s72, v163
	s_add_i32 s0, s69, s36
	ds_read_b128 v[200:203], v166
	ds_read_b128 v[204:207], v166 offset:1024
	ds_read_b128 v[208:211], v166 offset:2048
	ds_read_b128 v[212:215], v166 offset:3072
	v_lshl_add_u64 v[166:167], s[24:25], 0, v[26:27]
	s_mov_b32 m0, s0
	v_lshl_add_u64 v[168:169], s[24:25], 0, v[140:141]
	global_load_lds_dwordx4 v[166:167], off
	s_add_i32 m0, s0, 0x2000
	s_nop 0
	global_load_lds_dwordx4 v[168:169], off
	s_waitcnt vmcnt(10)
	s_setprio 1
	s_barrier
	s_waitcnt lgkmcnt(0)
	v_mfma_f32_16x16x32_bf16 v[64:67], v[200:203], v[158:161], v[64:67]
	v_mfma_f32_16x16x32_bf16 v[60:63], v[208:211], v[158:161], v[60:63]
	v_mfma_f32_16x16x32_bf16 v[56:59], v[200:203], v[176:179], v[56:59]
	v_mfma_f32_16x16x32_bf16 v[52:55], v[208:211], v[176:179], v[52:55]
	v_mfma_f32_16x16x32_bf16 v[48:51], v[200:203], v[184:187], v[48:51]
	v_mfma_f32_16x16x32_bf16 v[44:47], v[208:211], v[184:187], v[44:47]
	v_mfma_f32_16x16x32_bf16 v[40:43], v[200:203], v[192:195], v[40:43]
	v_mfma_f32_16x16x32_bf16 v[36:39], v[208:211], v[192:195], v[36:39]
	v_mfma_f32_16x16x32_bf16 v[64:67], v[204:207], v[172:175], v[64:67]
	v_mfma_f32_16x16x32_bf16 v[60:63], v[212:215], v[172:175], v[60:63]
	v_mfma_f32_16x16x32_bf16 v[56:59], v[204:207], v[180:183], v[56:59]
	v_mfma_f32_16x16x32_bf16 v[52:55], v[212:215], v[180:183], v[52:55]
	v_mfma_f32_16x16x32_bf16 v[48:51], v[204:207], v[188:191], v[48:51]
	v_mfma_f32_16x16x32_bf16 v[44:47], v[212:215], v[188:191], v[44:47]
	v_mfma_f32_16x16x32_bf16 v[40:43], v[204:207], v[196:199], v[40:43]
	v_mfma_f32_16x16x32_bf16 v[36:39], v[212:215], v[196:199], v[36:39]
	s_barrier
	s_setprio 0
	s_mov_b32 m0, s37
	v_lshl_add_u64 v[216:217], s[26:27], 0, v[144:145]
	ds_read_b128 v[158:161], v165 offset:16384
	ds_read_b128 v[172:175], v165 offset:17408
	ds_read_b128 v[176:179], v165 offset:18432
	ds_read_b128 v[180:183], v165 offset:19456
	ds_read_b128 v[184:187], v165 offset:20480
	ds_read_b128 v[188:191], v165 offset:21504
	ds_read_b128 v[192:195], v165 offset:22528
	ds_read_b128 v[196:199], v165 offset:23552
	global_load_lds_dwordx4 v[216:217], off
	v_lshl_add_u64 v[218:219], s[26:27], 0, v[142:143]
	s_mov_b32 m0, s56
	s_nop 0
	global_load_lds_dwordx4 v[218:219], off
	s_waitcnt vmcnt(10)
	s_setprio 1
	s_barrier
	s_waitcnt lgkmcnt(0)
	v_mfma_f32_16x16x32_bf16 v[96:99], v[100:103], v[158:161], v[96:99]
	v_mfma_f32_16x16x32_bf16 v[92:95], v[150:153], v[158:161], v[92:95]
	v_mfma_f32_16x16x32_bf16 v[88:91], v[100:103], v[176:179], v[88:91]
	v_mfma_f32_16x16x32_bf16 v[84:87], v[150:153], v[176:179], v[84:87]
	v_mfma_f32_16x16x32_bf16 v[80:83], v[100:103], v[184:187], v[80:83]
	v_mfma_f32_16x16x32_bf16 v[76:79], v[150:153], v[184:187], v[76:79]
	v_mfma_f32_16x16x32_bf16 v[72:75], v[100:103], v[192:195], v[72:75]
	v_mfma_f32_16x16x32_bf16 v[68:71], v[150:153], v[192:195], v[68:71]
	v_mfma_f32_16x16x32_bf16 v[96:99], v[104:107], v[172:175], v[96:99]
	v_mfma_f32_16x16x32_bf16 v[92:95], v[154:157], v[172:175], v[92:95]
	v_mfma_f32_16x16x32_bf16 v[88:91], v[104:107], v[180:183], v[88:91]
	v_mfma_f32_16x16x32_bf16 v[84:87], v[154:157], v[180:183], v[84:87]
	v_mfma_f32_16x16x32_bf16 v[80:83], v[104:107], v[188:191], v[80:83]
	v_mfma_f32_16x16x32_bf16 v[76:79], v[154:157], v[188:191], v[76:79]
	v_mfma_f32_16x16x32_bf16 v[72:75], v[104:107], v[196:199], v[72:75]
	v_mfma_f32_16x16x32_bf16 v[68:71], v[154:157], v[196:199], v[68:71]
	s_barrier
	s_setprio 0
	s_add_u32 s0, s24, 0x40000
	s_addc_u32 s1, s25, 0
	s_add_i32 s69, s72, s36
	s_mov_b32 m0, s69
	s_nop 0
	global_load_lds_dwordx4 v26, s[0:1]
	s_add_i32 m0, s69, 0x2000
	s_nop 0
	global_load_lds_dwordx4 v140, s[0:1]
	v_add_u32_e32 v154, 0x18000, v163
	ds_read_b128 v[100:103], v154
	ds_read_b128 v[104:107], v154 offset:1024
	ds_read_b128 v[150:153], v154 offset:2048
	ds_read_b128 v[154:157], v154 offset:3072
	s_waitcnt vmcnt(10)
	s_setprio 1
	s_barrier
	v_mfma_f32_16x16x32_bf16 v[32:35], v[200:203], v[158:161], v[32:35]
	v_mfma_f32_16x16x32_bf16 v[28:31], v[208:211], v[158:161], v[28:31]
	v_mfma_f32_16x16x32_bf16 v[22:25], v[200:203], v[176:179], v[22:25]
	v_mfma_f32_16x16x32_bf16 v[18:21], v[208:211], v[176:179], v[18:21]
	v_mfma_f32_16x16x32_bf16 v[14:17], v[200:203], v[184:187], v[14:17]
	v_mfma_f32_16x16x32_bf16 v[10:13], v[208:211], v[184:187], v[10:13]
	v_mfma_f32_16x16x32_bf16 v[6:9], v[200:203], v[192:195], v[6:9]
	v_mfma_f32_16x16x32_bf16 v[2:5], v[208:211], v[192:195], v[2:5]
	v_mfma_f32_16x16x32_bf16 v[32:35], v[204:207], v[172:175], v[32:35]
	v_mfma_f32_16x16x32_bf16 v[28:31], v[212:215], v[172:175], v[28:31]
	v_mfma_f32_16x16x32_bf16 v[22:25], v[204:207], v[180:183], v[22:25]
	v_mfma_f32_16x16x32_bf16 v[18:21], v[212:215], v[180:183], v[18:21]
	v_mfma_f32_16x16x32_bf16 v[14:17], v[204:207], v[188:191], v[14:17]
	v_mfma_f32_16x16x32_bf16 v[10:13], v[212:215], v[188:191], v[10:13]
	v_mfma_f32_16x16x32_bf16 v[6:9], v[204:207], v[196:199], v[6:9]
	v_mfma_f32_16x16x32_bf16 v[2:5], v[212:215], v[196:199], v[2:5]
	s_barrier
	s_setprio 0
	s_add_i32 s69, 0, 0x18000
	s_add_u32 s0, s26, 0x40000
	s_addc_u32 s1, s27, 0
	s_mov_b32 m0, s57
	ds_read_b128 v[158:161], v165 offset:32768
	ds_read_b128 v[172:175], v165 offset:33792
	ds_read_b128 v[176:179], v165 offset:34816
	ds_read_b128 v[180:183], v165 offset:35840
	ds_read_b128 v[184:187], v165 offset:36864
	ds_read_b128 v[188:191], v165 offset:37888
	ds_read_b128 v[192:195], v165 offset:38912
	ds_read_b128 v[196:199], v165 offset:39936
	global_load_lds_dwordx4 v144, s[0:1]
	s_mov_b32 m0, s58
	s_nop 0
	global_load_lds_dwordx4 v142, s[0:1]
	s_waitcnt vmcnt(10) lgkmcnt(8)
	s_setprio 1
	s_barrier
	s_waitcnt lgkmcnt(0)
	v_mfma_f32_16x16x32_bf16 v[136:139], v[100:103], v[158:161], v[136:139]
	v_mfma_f32_16x16x32_bf16 v[132:135], v[150:153], v[158:161], v[132:135]
	v_mfma_f32_16x16x32_bf16 v[128:131], v[100:103], v[176:179], v[128:131]
	v_mfma_f32_16x16x32_bf16 v[124:127], v[150:153], v[176:179], v[124:127]
	v_mfma_f32_16x16x32_bf16 v[120:123], v[100:103], v[184:187], v[120:123]
	v_mfma_f32_16x16x32_bf16 v[116:119], v[150:153], v[184:187], v[116:119]
	v_mfma_f32_16x16x32_bf16 v[112:115], v[100:103], v[192:195], v[112:115]
	v_mfma_f32_16x16x32_bf16 v[108:111], v[150:153], v[192:195], v[108:111]
	v_mfma_f32_16x16x32_bf16 v[136:139], v[104:107], v[172:175], v[136:139]
	v_mfma_f32_16x16x32_bf16 v[132:135], v[154:157], v[172:175], v[132:135]
	v_mfma_f32_16x16x32_bf16 v[128:131], v[104:107], v[180:183], v[128:131]
	v_mfma_f32_16x16x32_bf16 v[124:127], v[154:157], v[180:183], v[124:127]
	v_mfma_f32_16x16x32_bf16 v[120:123], v[104:107], v[188:191], v[120:123]
	v_mfma_f32_16x16x32_bf16 v[116:119], v[154:157], v[188:191], v[116:119]
	v_mfma_f32_16x16x32_bf16 v[112:115], v[104:107], v[196:199], v[112:115]
	v_mfma_f32_16x16x32_bf16 v[108:111], v[154:157], v[196:199], v[108:111]
	s_barrier
	s_setprio 0
	s_add_i32 s26, 0, 0x1c000
	s_add_i32 s0, s69, s36
	v_add_u32_e32 v212, s26, v163
	v_lshl_add_u64 v[166:167], v[166:167], 0, s[12:13]
	s_mov_b32 m0, s0
	ds_read_b128 v[200:203], v212
	ds_read_b128 v[204:207], v212 offset:1024
	ds_read_b128 v[208:211], v212 offset:2048
	ds_read_b128 v[212:215], v212 offset:3072
	global_load_lds_dwordx4 v[166:167], off
	v_lshl_add_u64 v[166:167], v[168:169], 0, s[12:13]
	s_add_i32 m0, s0, 0x2000
	s_nop 0
	global_load_lds_dwordx4 v[166:167], off
	s_waitcnt vmcnt(10)
	s_setprio 1
	s_barrier
	s_waitcnt lgkmcnt(0)
	v_mfma_f32_16x16x32_bf16 v[64:67], v[200:203], v[158:161], v[64:67]
	v_mfma_f32_16x16x32_bf16 v[60:63], v[208:211], v[158:161], v[60:63]
	v_mfma_f32_16x16x32_bf16 v[56:59], v[200:203], v[176:179], v[56:59]
	v_mfma_f32_16x16x32_bf16 v[52:55], v[208:211], v[176:179], v[52:55]
	v_mfma_f32_16x16x32_bf16 v[48:51], v[200:203], v[184:187], v[48:51]
	v_mfma_f32_16x16x32_bf16 v[44:47], v[208:211], v[184:187], v[44:47]
	v_mfma_f32_16x16x32_bf16 v[40:43], v[200:203], v[192:195], v[40:43]
	v_mfma_f32_16x16x32_bf16 v[36:39], v[208:211], v[192:195], v[36:39]
	v_mfma_f32_16x16x32_bf16 v[64:67], v[204:207], v[172:175], v[64:67]
	v_mfma_f32_16x16x32_bf16 v[60:63], v[212:215], v[172:175], v[60:63]
	v_mfma_f32_16x16x32_bf16 v[56:59], v[204:207], v[180:183], v[56:59]
	v_mfma_f32_16x16x32_bf16 v[52:55], v[212:215], v[180:183], v[52:55]
	v_mfma_f32_16x16x32_bf16 v[48:51], v[204:207], v[188:191], v[48:51]
	v_mfma_f32_16x16x32_bf16 v[44:47], v[212:215], v[188:191], v[44:47]
	v_mfma_f32_16x16x32_bf16 v[40:43], v[204:207], v[196:199], v[40:43]
	v_mfma_f32_16x16x32_bf16 v[36:39], v[212:215], v[196:199], v[36:39]
	s_barrier
	s_setprio 0
	s_mov_b32 m0, s28
	v_lshl_add_u64 v[166:167], v[216:217], 0, s[12:13]
	ds_read_b128 v[158:161], v165 offset:49152
	ds_read_b128 v[172:175], v165 offset:50176
	ds_read_b128 v[176:179], v165 offset:51200
	ds_read_b128 v[180:183], v165 offset:52224
	ds_read_b128 v[184:187], v165 offset:53248
	ds_read_b128 v[188:191], v165 offset:54272
	ds_read_b128 v[192:195], v165 offset:55296
	ds_read_b128 v[196:199], v165 offset:56320
	global_load_lds_dwordx4 v[166:167], off
	v_lshl_add_u64 v[166:167], v[218:219], 0, s[12:13]
	s_mov_b32 m0, s29
	s_nop 0
	global_load_lds_dwordx4 v[166:167], off
	s_waitcnt vmcnt(10)
	s_setprio 1
	s_barrier
	s_waitcnt lgkmcnt(0)
	v_mfma_f32_16x16x32_bf16 v[96:99], v[100:103], v[158:161], v[96:99]
	v_mfma_f32_16x16x32_bf16 v[92:95], v[150:153], v[158:161], v[92:95]
	v_mfma_f32_16x16x32_bf16 v[88:91], v[100:103], v[176:179], v[88:91]
	v_mfma_f32_16x16x32_bf16 v[84:87], v[150:153], v[176:179], v[84:87]
	v_mfma_f32_16x16x32_bf16 v[80:83], v[100:103], v[184:187], v[80:83]
	v_mfma_f32_16x16x32_bf16 v[76:79], v[150:153], v[184:187], v[76:79]
	v_mfma_f32_16x16x32_bf16 v[72:75], v[100:103], v[192:195], v[72:75]
	v_mfma_f32_16x16x32_bf16 v[68:71], v[150:153], v[192:195], v[68:71]
	v_mfma_f32_16x16x32_bf16 v[96:99], v[104:107], v[172:175], v[96:99]
	v_mfma_f32_16x16x32_bf16 v[92:95], v[154:157], v[172:175], v[92:95]
	v_mfma_f32_16x16x32_bf16 v[88:91], v[104:107], v[180:183], v[88:91]
	v_mfma_f32_16x16x32_bf16 v[84:87], v[154:157], v[180:183], v[84:87]
	v_mfma_f32_16x16x32_bf16 v[80:83], v[104:107], v[188:191], v[80:83]
	v_mfma_f32_16x16x32_bf16 v[76:79], v[154:157], v[188:191], v[76:79]
	v_mfma_f32_16x16x32_bf16 v[72:75], v[104:107], v[196:199], v[72:75]
	v_mfma_f32_16x16x32_bf16 v[68:71], v[154:157], v[196:199], v[68:71]
	s_barrier
	s_setprio 0
	s_add_u32 s0, s24, 0x40080
	s_addc_u32 s1, s25, 0
	s_add_i32 s24, s26, s36
	s_mov_b32 m0, s24
	s_nop 0
	global_load_lds_dwordx4 v26, s[0:1]
	s_add_i32 m0, s24, 0x2000
	s_nop 0
	global_load_lds_dwordx4 v140, s[0:1]
	v_add_u32_e32 v154, 0x10000, v163
	ds_read_b128 v[100:103], v154
	ds_read_b128 v[104:107], v154 offset:1024
	ds_read_b128 v[150:153], v154 offset:2048
	ds_read_b128 v[154:157], v154 offset:3072
	s_add_i32 s68, s68, 2
	s_add_u32 s22, s22, 0x100
	s_addc_u32 s23, s23, 0
	s_add_u32 s51, s51, 0x100
	s_addc_u32 s59, s59, 0
	s_cmp_gt_u32 s68, 13
	s_cbranch_scc1 .Lth__479
	s_add_u32 s0, s22, 0xfffc0080
	s_addc_u32 s1, s23, -1
	s_add_i32 s69, 0, 0x10000
	s_cmp_eq_u32 s68, 12
	s_cselect_b32 s27, s35, s1
	s_cselect_b32 s26, s40, s0
	s_cselect_b32 s25, s41, s59
	s_cselect_b32 s24, s49, s51
	s_cmp_gt_u32 s68, 13
.Lth__479:
	s_waitcnt vmcnt(10)
	s_setprio 1
	s_barrier
	v_mfma_f32_16x16x32_bf16 v[32:35], v[200:203], v[158:161], v[32:35]
	v_mfma_f32_16x16x32_bf16 v[28:31], v[208:211], v[158:161], v[28:31]
	v_mfma_f32_16x16x32_bf16 v[22:25], v[200:203], v[176:179], v[22:25]
	v_mfma_f32_16x16x32_bf16 v[18:21], v[208:211], v[176:179], v[18:21]
	v_mfma_f32_16x16x32_bf16 v[14:17], v[200:203], v[184:187], v[14:17]
	v_mfma_f32_16x16x32_bf16 v[10:13], v[208:211], v[184:187], v[10:13]
	v_mfma_f32_16x16x32_bf16 v[6:9], v[200:203], v[192:195], v[6:9]
	v_mfma_f32_16x16x32_bf16 v[2:5], v[208:211], v[192:195], v[2:5]
	v_mfma_f32_16x16x32_bf16 v[32:35], v[204:207], v[172:175], v[32:35]
	v_mfma_f32_16x16x32_bf16 v[28:31], v[212:215], v[172:175], v[28:31]
	v_mfma_f32_16x16x32_bf16 v[22:25], v[204:207], v[180:183], v[22:25]
	v_mfma_f32_16x16x32_bf16 v[18:21], v[212:215], v[180:183], v[18:21]
	v_mfma_f32_16x16x32_bf16 v[14:17], v[204:207], v[188:191], v[14:17]
	v_mfma_f32_16x16x32_bf16 v[10:13], v[212:215], v[188:191], v[10:13]
	v_mfma_f32_16x16x32_bf16 v[6:9], v[204:207], v[196:199], v[6:9]
	v_mfma_f32_16x16x32_bf16 v[2:5], v[212:215], v[196:199], v[2:5]
	s_barrier
	s_setprio 0
	s_cbranch_scc0 .LBB0_479
	s_waitcnt lgkmcnt(0)
	s_cmpk_gt_i32 s34, 0xff
	s_mov_b64 s[22:23], 0xb000
	s_cbranch_scc1 .LBB0_482
	s_ashr_i32 s0, s34, 5
	s_mul_hi_i32 s23, s0, 0x1600
	s_mul_i32 s22, s0, 0x1600

.LBB0_886:
	s_lshl_b32 s0, s73, 21
	s_add_u32 s18, s53, s0
	s_addc_u32 s19, s54, 0
	s_ashr_i32 s45, s44, 31
	s_lshl_b64 s[0:1], s[44:45], 18
	s_add_u32 s48, s18, s0
	s_addc_u32 s49, s19, s1
	s_and_b64 s[0:1], s[38:39], exec
	s_cselect_b32 s18, s49, s25
	s_cselect_b32 s19, s48, s24
	s_add_u32 s45, s24, 0x100
	s_addc_u32 s50, s25, 0
	s_mov_b32 s51, -2
	v_add_u32_e32 v26, 0x10000, v191
	ds_read_b128 v[134:137], v26
	ds_read_b128 v[138:141], v26 offset:1024
	ds_read_b128 v[142:145], v26 offset:2048
	ds_read_b128 v[146:149], v26 offset:3072
	s_add_u32 s24, s22, 0x100
	s_addc_u32 s25, s23, 0
	s_add_i32 s0, 0, 0x10000
	s_cmp_eq_u32 s51, 4
	s_cselect_b32 s29, s47, s25
	s_cselect_b32 s28, s46, s24
	s_cselect_b32 s27, s18, s50
	s_cselect_b32 s26, s19, s45
.LBB0_887:
	s_add_i32 m0, s58, 0xc000
	ds_read_b128 v[150:153], v193
	ds_read_b128 v[154:157], v193 offset:1024
	ds_read_b128 v[158:161], v193 offset:2048
	ds_read_b128 v[162:165], v193 offset:3072
	ds_read_b128 v[184:187], v193 offset:4096
	ds_read_b128 v[194:197], v193 offset:5120
	ds_read_b128 v[198:201], v193 offset:6144
	ds_read_b128 v[202:205], v193 offset:7168
	global_load_lds_dwordx4 v180, s[22:23]
	s_add_i32 m0, s58, 0xe000
	s_nop 0
	global_load_lds_dwordx4 v182, s[22:23]
	s_waitcnt vmcnt(10) lgkmcnt(8)
	s_setprio 1
	s_barrier
	s_waitcnt lgkmcnt(0)
	v_mfma_f32_16x16x32_bf16 v[130:133], v[134:137], v[150:153], v[130:133]
	v_mfma_f32_16x16x32_bf16 v[126:129], v[142:145], v[150:153], v[126:129]
	v_mfma_f32_16x16x32_bf16 v[122:125], v[134:137], v[158:161], v[122:125]
	v_mfma_f32_16x16x32_bf16 v[118:121], v[142:145], v[158:161], v[118:121]
	v_mfma_f32_16x16x32_bf16 v[114:117], v[134:137], v[184:187], v[114:117]
	v_mfma_f32_16x16x32_bf16 v[110:113], v[142:145], v[184:187], v[110:113]
	v_mfma_f32_16x16x32_bf16 v[106:109], v[134:137], v[198:201], v[106:109]
	v_mfma_f32_16x16x32_bf16 v[102:105], v[142:145], v[198:201], v[102:105]
	v_mfma_f32_16x16x32_bf16 v[130:133], v[138:141], v[154:157], v[130:133]
	v_mfma_f32_16x16x32_bf16 v[126:129], v[146:149], v[154:157], v[126:129]
	v_mfma_f32_16x16x32_bf16 v[122:125], v[138:141], v[162:165], v[122:125]
	v_mfma_f32_16x16x32_bf16 v[118:121], v[146:149], v[162:165], v[118:121]
	v_mfma_f32_16x16x32_bf16 v[114:117], v[138:141], v[194:197], v[114:117]
	v_mfma_f32_16x16x32_bf16 v[110:113], v[146:149], v[194:197], v[110:113]
	v_mfma_f32_16x16x32_bf16 v[106:109], v[138:141], v[202:205], v[106:109]
	v_mfma_f32_16x16x32_bf16 v[102:105], v[146:149], v[202:205], v[102:105]
	s_barrier
	s_setprio 0
	s_add_i32 s22, 0, 0x14000
	s_add_i32 s0, s0, s55
	v_add_u32_e32 v26, s22, v191
	v_lshl_add_u64 v[166:167], s[26:27], 0, v[176:177]
	s_mov_b32 m0, s0
	ds_read_b128 v[206:209], v26
	ds_read_b128 v[210:213], v26 offset:1024
	ds_read_b128 v[214:217], v26 offset:2048
	ds_read_b128 v[218:221], v26 offset:3072
	global_load_lds_dwordx4 v[166:167], off
	v_lshl_add_u64 v[168:169], s[26:27], 0, v[172:173]
	s_add_i32 m0, s0, 0x2000
	s_nop 0
	global_load_lds_dwordx4 v[168:169], off
	s_waitcnt vmcnt(10)
	s_setprio 1
	s_barrier
	s_waitcnt lgkmcnt(0)
	v_mfma_f32_16x16x32_bf16 v[98:101], v[206:209], v[150:153], v[98:101]
	v_mfma_f32_16x16x32_bf16 v[94:97], v[214:217], v[150:153], v[94:97]
	v_mfma_f32_16x16x32_bf16 v[90:93], v[206:209], v[158:161], v[90:93]
	v_mfma_f32_16x16x32_bf16 v[86:89], v[214:217], v[158:161], v[86:89]
	v_mfma_f32_16x16x32_bf16 v[82:85], v[206:209], v[184:187], v[82:85]
	v_mfma_f32_16x16x32_bf16 v[78:81], v[214:217], v[184:187], v[78:81]
	v_mfma_f32_16x16x32_bf16 v[74:77], v[206:209], v[198:201], v[74:77]
	v_mfma_f32_16x16x32_bf16 v[70:73], v[214:217], v[198:201], v[70:73]
	v_mfma_f32_16x16x32_bf16 v[98:101], v[210:213], v[154:157], v[98:101]
	v_mfma_f32_16x16x32_bf16 v[94:97], v[218:221], v[154:157], v[94:97]
	v_mfma_f32_16x16x32_bf16 v[90:93], v[210:213], v[162:165], v[90:93]
	v_mfma_f32_16x16x32_bf16 v[86:89], v[218:221], v[162:165], v[86:89]
	v_mfma_f32_16x16x32_bf16 v[82:85], v[210:213], v[194:197], v[82:85]
	v_mfma_f32_16x16x32_bf16 v[78:81], v[218:221], v[194:197], v[78:81]
	v_mfma_f32_16x16x32_bf16 v[74:77], v[210:213], v[202:205], v[74:77]
	v_mfma_f32_16x16x32_bf16 v[70:73], v[218:221], v[202:205], v[70:73]
	s_barrier
	s_setprio 0
	s_mov_b32 m0, s58
	v_lshl_add_u64 v[188:189], s[28:29], 0, v[178:179]
	ds_read_b128 v[150:153], v193 offset:16384
	ds_read_b128 v[154:157], v193 offset:17408
	ds_read_b128 v[158:161], v193 offset:18432
	ds_read_b128 v[162:165], v193 offset:19456
	ds_read_b128 v[184:187], v193 offset:20480
	ds_read_b128 v[194:197], v193 offset:21504
	ds_read_b128 v[198:201], v193 offset:22528
	ds_read_b128 v[202:205], v193 offset:23552
	global_load_lds_dwordx4 v[188:189], off
	v_lshl_add_u64 v[222:223], s[28:29], 0, v[174:175]
	s_mov_b32 m0, s59
	s_nop 0
	global_load_lds_dwordx4 v[222:223], off
	s_waitcnt vmcnt(10)
	s_setprio 1
	s_barrier
	s_waitcnt lgkmcnt(0)
	v_mfma_f32_16x16x32_bf16 v[66:69], v[134:137], v[150:153], v[66:69]
	v_mfma_f32_16x16x32_bf16 v[62:65], v[142:145], v[150:153], v[62:65]
	v_mfma_f32_16x16x32_bf16 v[58:61], v[134:137], v[158:161], v[58:61]
	v_mfma_f32_16x16x32_bf16 v[54:57], v[142:145], v[158:161], v[54:57]
	v_mfma_f32_16x16x32_bf16 v[50:53], v[134:137], v[184:187], v[50:53]
	v_mfma_f32_16x16x32_bf16 v[46:49], v[142:145], v[184:187], v[46:49]
	v_mfma_f32_16x16x32_bf16 v[42:45], v[134:137], v[198:201], v[42:45]
	v_mfma_f32_16x16x32_bf16 v[38:41], v[142:145], v[198:201], v[38:41]
	v_mfma_f32_16x16x32_bf16 v[66:69], v[138:141], v[154:157], v[66:69]
	v_mfma_f32_16x16x32_bf16 v[62:65], v[146:149], v[154:157], v[62:65]
	v_mfma_f32_16x16x32_bf16 v[58:61], v[138:141], v[162:165], v[58:61]
	v_mfma_f32_16x16x32_bf16 v[54:57], v[146:149], v[162:165], v[54:57]
	v_mfma_f32_16x16x32_bf16 v[50:53], v[138:141], v[194:197], v[50:53]
	v_mfma_f32_16x16x32_bf16 v[46:49], v[146:149], v[194:197], v[46:49]
	v_mfma_f32_16x16x32_bf16 v[42:45], v[138:141], v[202:205], v[42:45]
	v_mfma_f32_16x16x32_bf16 v[38:41], v[146:149], v[202:205], v[38:41]
	s_barrier
	s_setprio 0
	s_add_u32 s0, s26, 0x20000
	s_addc_u32 s1, s27, 0
	s_add_i32 s22, s22, s55
	s_mov_b32 m0, s22
	s_nop 0
	global_load_lds_dwordx4 v176, s[0:1]
	s_add_i32 m0, s22, 0x2000
	s_nop 0
	global_load_lds_dwordx4 v172, s[0:1]
	v_add_u32_e32 v26, 0x18000, v191
	ds_read_b128 v[134:137], v26
	ds_read_b128 v[138:141], v26 offset:1024
	ds_read_b128 v[142:145], v26 offset:2048
	ds_read_b128 v[146:149], v26 offset:3072
	s_waitcnt vmcnt(10)
	s_setprio 1
	s_barrier
	v_mfma_f32_16x16x32_bf16 v[34:37], v[206:209], v[150:153], v[34:37]
	v_mfma_f32_16x16x32_bf16 v[28:31], v[214:217], v[150:153], v[30:33]
	v_mfma_f32_16x16x32_bf16 v[22:25], v[206:209], v[158:161], v[22:25]
	v_mfma_f32_16x16x32_bf16 v[18:21], v[214:217], v[158:161], v[18:21]
	v_mfma_f32_16x16x32_bf16 v[14:17], v[206:209], v[184:187], v[14:17]
	v_mfma_f32_16x16x32_bf16 v[10:13], v[214:217], v[184:187], v[10:13]
	v_mfma_f32_16x16x32_bf16 v[6:9], v[206:209], v[198:201], v[6:9]
	v_mfma_f32_16x16x32_bf16 v[2:5], v[214:217], v[198:201], v[2:5]
	v_mfma_f32_16x16x32_bf16 v[34:37], v[210:213], v[154:157], v[34:37]
	v_mfma_f32_16x16x32_bf16 v[28:31], v[218:221], v[154:157], v[28:31]
	v_mfma_f32_16x16x32_bf16 v[22:25], v[210:213], v[162:165], v[22:25]
	v_mfma_f32_16x16x32_bf16 v[18:21], v[218:221], v[162:165], v[18:21]
	v_mfma_f32_16x16x32_bf16 v[14:17], v[210:213], v[194:197], v[14:17]
	v_mfma_f32_16x16x32_bf16 v[10:13], v[218:221], v[194:197], v[10:13]
	v_mfma_f32_16x16x32_bf16 v[6:9], v[210:213], v[202:205], v[6:9]
	v_mfma_f32_16x16x32_bf16 v[2:5], v[218:221], v[202:205], v[2:5]
	s_barrier
	s_setprio 0
	s_add_i32 s22, 0, 0x18000
	s_add_u32 s0, s28, 0x140000
	s_addc_u32 s1, s29, 0
	s_mov_b32 m0, s68
	ds_read_b128 v[150:153], v193 offset:32768
	ds_read_b128 v[154:157], v193 offset:33792
	ds_read_b128 v[158:161], v193 offset:34816
	ds_read_b128 v[162:165], v193 offset:35840
	ds_read_b128 v[184:187], v193 offset:36864
	ds_read_b128 v[194:197], v193 offset:37888
	ds_read_b128 v[198:201], v193 offset:38912
	ds_read_b128 v[202:205], v193 offset:39936
	global_load_lds_dwordx4 v178, s[0:1]
	s_mov_b32 m0, s69
	s_nop 0
	global_load_lds_dwordx4 v174, s[0:1]
	s_waitcnt vmcnt(10) lgkmcnt(8)
	s_setprio 1
	s_barrier
	s_waitcnt lgkmcnt(0)
	v_mfma_f32_16x16x32_bf16 v[130:133], v[134:137], v[150:153], v[130:133]
	v_mfma_f32_16x16x32_bf16 v[126:129], v[142:145], v[150:153], v[126:129]
	v_mfma_f32_16x16x32_bf16 v[122:125], v[134:137], v[158:161], v[122:125]
	v_mfma_f32_16x16x32_bf16 v[118:121], v[142:145], v[158:161], v[118:121]
	v_mfma_f32_16x16x32_bf16 v[114:117], v[134:137], v[184:187], v[114:117]
	v_mfma_f32_16x16x32_bf16 v[110:113], v[142:145], v[184:187], v[110:113]
	v_mfma_f32_16x16x32_bf16 v[106:109], v[134:137], v[198:201], v[106:109]
	v_mfma_f32_16x16x32_bf16 v[102:105], v[142:145], v[198:201], v[102:105]
	v_mfma_f32_16x16x32_bf16 v[130:133], v[138:141], v[154:157], v[130:133]
	v_mfma_f32_16x16x32_bf16 v[126:129], v[146:149], v[154:157], v[126:129]
	v_mfma_f32_16x16x32_bf16 v[122:125], v[138:141], v[162:165], v[122:125]
	v_mfma_f32_16x16x32_bf16 v[118:121], v[146:149], v[162:165], v[118:121]
	v_mfma_f32_16x16x32_bf16 v[114:117], v[138:141], v[194:197], v[114:117]
	v_mfma_f32_16x16x32_bf16 v[110:113], v[146:149], v[194:197], v[110:113]
	v_mfma_f32_16x16x32_bf16 v[106:109], v[138:141], v[202:205], v[106:109]
	v_mfma_f32_16x16x32_bf16 v[102:105], v[146:149], v[202:205], v[102:105]
	s_barrier
	s_setprio 0
	s_add_i32 s23, 0, 0x1c000
	s_add_i32 s0, s22, s55
	v_add_u32_e32 v26, s23, v191
	v_lshl_add_u64 v[32:33], v[166:167], 0, s[12:13]
	s_mov_b32 m0, s0
	ds_read_b128 v[206:209], v26
	ds_read_b128 v[210:213], v26 offset:1024
	ds_read_b128 v[214:217], v26 offset:2048
	ds_read_b128 v[218:221], v26 offset:3072
	global_load_lds_dwordx4 v[32:33], off
	v_lshl_add_u64 v[32:33], v[168:169], 0, s[12:13]
	s_add_i32 m0, s0, 0x2000
	s_nop 0
	global_load_lds_dwordx4 v[32:33], off
	s_waitcnt vmcnt(10)
	s_setprio 1
	s_barrier
	s_waitcnt lgkmcnt(0)
	v_mfma_f32_16x16x32_bf16 v[98:101], v[206:209], v[150:153], v[98:101]
	v_mfma_f32_16x16x32_bf16 v[94:97], v[214:217], v[150:153], v[94:97]
	v_mfma_f32_16x16x32_bf16 v[90:93], v[206:209], v[158:161], v[90:93]
	v_mfma_f32_16x16x32_bf16 v[86:89], v[214:217], v[158:161], v[86:89]
	v_mfma_f32_16x16x32_bf16 v[82:85], v[206:209], v[184:187], v[82:85]
	v_mfma_f32_16x16x32_bf16 v[78:81], v[214:217], v[184:187], v[78:81]
	v_mfma_f32_16x16x32_bf16 v[74:77], v[206:209], v[198:201], v[74:77]
	v_mfma_f32_16x16x32_bf16 v[70:73], v[214:217], v[198:201], v[70:73]
	v_mfma_f32_16x16x32_bf16 v[98:101], v[210:213], v[154:157], v[98:101]
	v_mfma_f32_16x16x32_bf16 v[94:97], v[218:221], v[154:157], v[94:97]
	v_mfma_f32_16x16x32_bf16 v[90:93], v[210:213], v[162:165], v[90:93]
	v_mfma_f32_16x16x32_bf16 v[86:89], v[218:221], v[162:165], v[86:89]
	v_mfma_f32_16x16x32_bf16 v[82:85], v[210:213], v[194:197], v[82:85]
	v_mfma_f32_16x16x32_bf16 v[78:81], v[218:221], v[194:197], v[78:81]
	v_mfma_f32_16x16x32_bf16 v[74:77], v[210:213], v[202:205], v[74:77]
	v_mfma_f32_16x16x32_bf16 v[70:73], v[218:221], v[202:205], v[70:73]
	s_barrier
	s_setprio 0
	s_mov_b32 m0, s30
	v_lshl_add_u64 v[32:33], v[188:189], 0, s[12:13]
	ds_read_b128 v[150:153], v193 offset:49152
	ds_read_b128 v[154:157], v193 offset:50176
	ds_read_b128 v[158:161], v193 offset:51200
	ds_read_b128 v[162:165], v193 offset:52224
	ds_read_b128 v[184:187], v193 offset:53248
	ds_read_b128 v[194:197], v193 offset:54272
	ds_read_b128 v[198:201], v193 offset:55296
	ds_read_b128 v[202:205], v193 offset:56320
	global_load_lds_dwordx4 v[32:33], off
	v_lshl_add_u64 v[32:33], v[222:223], 0, s[12:13]
	s_mov_b32 m0, s34
	s_nop 0
	global_load_lds_dwordx4 v[32:33], off
	s_waitcnt vmcnt(10)
	s_setprio 1
	s_barrier
	s_waitcnt lgkmcnt(0)
	v_mfma_f32_16x16x32_bf16 v[66:69], v[134:137], v[150:153], v[66:69]
	v_mfma_f32_16x16x32_bf16 v[62:65], v[142:145], v[150:153], v[62:65]
	v_mfma_f32_16x16x32_bf16 v[58:61], v[134:137], v[158:161], v[58:61]
	v_mfma_f32_16x16x32_bf16 v[54:57], v[142:145], v[158:161], v[54:57]
	v_mfma_f32_16x16x32_bf16 v[50:53], v[134:137], v[184:187], v[50:53]
	v_mfma_f32_16x16x32_bf16 v[46:49], v[142:145], v[184:187], v[46:49]
	v_mfma_f32_16x16x32_bf16 v[42:45], v[134:137], v[198:201], v[42:45]
	v_mfma_f32_16x16x32_bf16 v[38:41], v[142:145], v[198:201], v[38:41]
	v_mfma_f32_16x16x32_bf16 v[66:69], v[138:141], v[154:157], v[66:69]
	v_mfma_f32_16x16x32_bf16 v[62:65], v[146:149], v[154:157], v[62:65]
	v_mfma_f32_16x16x32_bf16 v[58:61], v[138:141], v[162:165], v[58:61]
	v_mfma_f32_16x16x32_bf16 v[54:57], v[146:149], v[162:165], v[54:57]
	v_mfma_f32_16x16x32_bf16 v[50:53], v[138:141], v[194:197], v[50:53]
	v_mfma_f32_16x16x32_bf16 v[46:49], v[146:149], v[194:197], v[46:49]
	v_mfma_f32_16x16x32_bf16 v[42:45], v[138:141], v[202:205], v[42:45]
	v_mfma_f32_16x16x32_bf16 v[38:41], v[146:149], v[202:205], v[38:41]
	s_barrier
	s_setprio 0
	s_add_u32 s0, s26, 0x20080
	s_addc_u32 s1, s27, 0
	s_add_i32 s22, s23, s55
	s_mov_b32 m0, s22
	s_nop 0
	global_load_lds_dwordx4 v176, s[0:1]
	s_add_i32 m0, s22, 0x2000
	s_nop 0
	global_load_lds_dwordx4 v172, s[0:1]
	v_add_u32_e32 v26, 0x10000, v191
	ds_read_b128 v[134:137], v26
	ds_read_b128 v[138:141], v26 offset:1024
	ds_read_b128 v[142:145], v26 offset:2048
	ds_read_b128 v[146:149], v26 offset:3072
	s_add_i32 s51, s51, 2
	s_add_u32 s45, s45, 0x100
	s_addc_u32 s50, s50, 0
	s_mov_b64 s[22:23], s[24:25]
	s_cmp_gt_u32 s51, 5
	s_cbranch_scc1 .Lth__887
	s_add_u32 s24, s22, 0x100
	s_addc_u32 s25, s23, 0
	s_add_i32 s0, 0, 0x10000
	s_cmp_eq_u32 s51, 4
	s_cselect_b32 s29, s47, s25
	s_cselect_b32 s28, s46, s24
	s_cselect_b32 s27, s18, s50
	s_cselect_b32 s26, s19, s45
	s_cmp_gt_u32 s51, 5
.Lth__887:
	s_waitcnt vmcnt(10)
	s_setprio 1
	s_barrier
	v_mfma_f32_16x16x32_bf16 v[32:35], v[206:209], v[150:153], v[34:37]
	v_mfma_f32_16x16x32_bf16 v[28:31], v[214:217], v[150:153], v[28:31]
	v_mfma_f32_16x16x32_bf16 v[22:25], v[206:209], v[158:161], v[22:25]
	v_mfma_f32_16x16x32_bf16 v[18:21], v[214:217], v[158:161], v[18:21]
	v_mfma_f32_16x16x32_bf16 v[14:17], v[206:209], v[184:187], v[14:17]
	v_mfma_f32_16x16x32_bf16 v[10:13], v[214:217], v[184:187], v[10:13]
	v_mfma_f32_16x16x32_bf16 v[6:9], v[206:209], v[198:201], v[6:9]
	v_mfma_f32_16x16x32_bf16 v[2:5], v[214:217], v[198:201], v[2:5]
	v_mfma_f32_16x16x32_bf16 v[34:37], v[210:213], v[154:157], v[32:35]
	v_mfma_f32_16x16x32_bf16 v[30:33], v[218:221], v[154:157], v[28:31]
	v_mfma_f32_16x16x32_bf16 v[22:25], v[210:213], v[162:165], v[22:25]
	v_mfma_f32_16x16x32_bf16 v[18:21], v[218:221], v[162:165], v[18:21]
	v_mfma_f32_16x16x32_bf16 v[14:17], v[210:213], v[194:197], v[14:17]
	v_mfma_f32_16x16x32_bf16 v[10:13], v[218:221], v[194:197], v[10:13]
	v_mfma_f32_16x16x32_bf16 v[6:9], v[210:213], v[202:205], v[6:9]
	v_mfma_f32_16x16x32_bf16 v[2:5], v[218:221], v[202:205], v[2:5]
	s_barrier
	s_setprio 0
	s_cbranch_scc0 .LBB0_887
	s_waitcnt lgkmcnt(0)
	v_lshl_or_b32 v186, s17, 8, v192
	v_ashrrev_i32_e32 v187, 31, v186
	v_lshl_add_u32 v26, s16, 8, v190
	s_cmp_lg_u32 s81, 0
	v_lshl_add_u64 v[28:29], v[186:187], 1, s[40:41]
	s_cselect_b64 s[50:51], -1, 0
	s_cmp_eq_u32 s81, 0
	v_mad_i64_i32 v[184:185], s[0:1], v26, s78, v[28:29]
	v_or_b32_e32 v198, 16, v26
	v_or_b32_e32 v197, 32, v26
	v_or_b32_e32 v196, 48, v26
	v_add_u32_e32 v195, 0x80, v26
	v_add_u32_e32 v194, 0x90, v26
	s_cbranch_scc1 .LBB0_894
	v_add_co_u32_e32 v134, vcc, 0x2000, v184
	v_mad_i64_i32 v[166:167], s[0:1], v26, s78, 0
	s_nop 0
	v_addc_co_u32_e32 v135, vcc, 0, v185, vcc
	global_load_dwordx4 v[162:165], v[134:135], off
	global_load_dwordx4 v[158:161], v[134:135], off offset:256
	v_mad_i64_i32 v[134:135], s[0:1], v198, s78, v[28:29]
	v_add_co_u32_e32 v134, vcc, 0x2000, v134
	v_lshlrev_b64 v[186:187], 1, v[186:187]
	s_nop 0
	v_addc_co_u32_e32 v135, vcc, 0, v135, vcc
	global_load_dwordx4 v[154:157], v[134:135], off
	global_load_dwordx4 v[150:153], v[134:135], off offset:256
	v_mad_i64_i32 v[134:135], s[0:1], v197, s78, v[28:29]
	v_add_co_u32_e32 v134, vcc, 0x2000, v134
	s_movk_i32 s16, 0x2000
	s_nop 0
	v_addc_co_u32_e32 v135, vcc, 0, v135, vcc
	global_load_dwordx4 v[146:149], v[134:135], off
	global_load_dwordx4 v[142:145], v[134:135], off offset:256
	v_mad_i64_i32 v[134:135], s[0:1], v196, s78, v[28:29]
	v_add_co_u32_e32 v134, vcc, 0x2000, v134
	s_nop 1
	v_addc_co_u32_e32 v135, vcc, 0, v135, vcc
	global_load_dwordx4 v[138:141], v[134:135], off
	s_nop 0
	global_load_dwordx4 v[134:137], v[134:135], off offset:256
	s_waitcnt vmcnt(0)
	v_lshlrev_b32_e32 v168, 16, v162
	v_and_b32_e32 v162, 0xffff0000, v162
	v_mul_f32_e32 v162, 0xbfb8aa3b, v162
	v_exp_f32_e32 v162, v162
	v_mul_f32_e32 v168, 0xbfb8aa3b, v168
	v_exp_f32_e32 v168, v168
	v_add_f32_e32 v162, 1.0, v162
	v_rcp_f32_e32 v169, v162
	v_lshlrev_b32_e32 v162, 16, v163
	v_and_b32_e32 v163, 0xffff0000, v163
	v_mul_f32_e32 v162, 0xbfb8aa3b, v162
	v_mul_f32_e32 v163, 0xbfb8aa3b, v163
	v_exp_f32_e32 v162, v162
	v_exp_f32_e32 v163, v163
	v_add_f32_e32 v168, 1.0, v168
	v_rcp_f32_e32 v168, v168
	v_add_f32_e32 v162, 1.0, v162
	v_add_f32_e32 v163, 1.0, v163
	v_rcp_f32_e32 v162, v162
	v_rcp_f32_e32 v163, v163
	v_pk_mul_f32 v[168:169], v[130:131], v[168:169]
	v_pk_mul_f32 v[188:189], v[132:133], v[162:163]
	v_lshlrev_b32_e32 v162, 16, v164
	v_and_b32_e32 v163, 0xffff0000, v164
	v_mul_f32_e32 v162, 0xbfb8aa3b, v162
	v_mul_f32_e32 v163, 0xbfb8aa3b, v163
	v_exp_f32_e32 v162, v162
	v_exp_f32_e32 v163, v163
	v_add_f32_e32 v162, 1.0, v162
	v_add_f32_e32 v163, 1.0, v163
	v_rcp_f32_e32 v162, v162
	v_rcp_f32_e32 v163, v163
	s_nop 0
	v_pk_mul_f32 v[200:201], v[126:127], v[162:163]
	v_lshlrev_b32_e32 v162, 16, v165
	v_and_b32_e32 v163, 0xffff0000, v165
	v_mul_f32_e32 v162, 0xbfb8aa3b, v162
	v_mul_f32_e32 v163, 0xbfb8aa3b, v163
	v_exp_f32_e32 v162, v162
	v_exp_f32_e32 v163, v163
	v_cvt_pk_bf16_f32 v164, v200, v201
	v_add_f32_e32 v162, 1.0, v162
	v_add_f32_e32 v163, 1.0, v163
	v_rcp_f32_e32 v162, v162
	v_rcp_f32_e32 v163, v163
	s_nop 0
	v_pk_mul_f32 v[202:203], v[128:129], v[162:163]
	v_cvt_pk_bf16_f32 v163, v188, v189
	v_lshl_add_u64 v[188:189], s[42:43], 0, v[166:167]
	v_cvt_pk_bf16_f32 v162, v168, v169
	v_cvt_pk_bf16_f32 v165, v202, v203
	v_lshl_add_u64 v[188:189], v[188:189], 0, v[186:187]
	global_store_dwordx4 v[188:189], v[162:165], off
	s_nop 1
	v_lshlrev_b32_e32 v162, 16, v158
	v_and_b32_e32 v158, 0xffff0000, v158
	v_mul_f32_e32 v158, 0xbfb8aa3b, v158
	v_exp_f32_e32 v158, v158
	v_mul_f32_e32 v162, 0xbfb8aa3b, v162
	v_exp_f32_e32 v162, v162
	v_add_f32_e32 v158, 1.0, v158
	v_rcp_f32_e32 v163, v158
	v_lshlrev_b32_e32 v158, 16, v159
	v_and_b32_e32 v159, 0xffff0000, v159
	v_mul_f32_e32 v158, 0xbfb8aa3b, v158
	v_mul_f32_e32 v159, 0xbfb8aa3b, v159
	v_exp_f32_e32 v158, v158
	v_exp_f32_e32 v159, v159
	v_add_f32_e32 v162, 1.0, v162
	v_rcp_f32_e32 v162, v162
	v_add_f32_e32 v158, 1.0, v158
	v_add_f32_e32 v159, 1.0, v159
	v_rcp_f32_e32 v158, v158
	v_rcp_f32_e32 v159, v159
	v_pk_mul_f32 v[162:163], v[98:99], v[162:163]
	v_pk_mul_f32 v[164:165], v[100:101], v[158:159]
	v_lshlrev_b32_e32 v158, 16, v160
	v_and_b32_e32 v159, 0xffff0000, v160
	v_mul_f32_e32 v158, 0xbfb8aa3b, v158
	v_mul_f32_e32 v159, 0xbfb8aa3b, v159
	v_exp_f32_e32 v158, v158
	v_exp_f32_e32 v159, v159
	v_add_f32_e32 v158, 1.0, v158
	v_add_f32_e32 v159, 1.0, v159
	v_rcp_f32_e32 v158, v158
	v_rcp_f32_e32 v159, v159
	s_nop 0
	v_pk_mul_f32 v[166:167], v[94:95], v[158:159]
	v_lshlrev_b32_e32 v158, 16, v161
	v_and_b32_e32 v159, 0xffff0000, v161
	v_mul_f32_e32 v158, 0xbfb8aa3b, v158
	v_mul_f32_e32 v159, 0xbfb8aa3b, v159
	v_exp_f32_e32 v158, v158
	v_exp_f32_e32 v159, v159
	v_cvt_pk_bf16_f32 v160, v166, v167
	v_add_f32_e32 v158, 1.0, v158
	v_add_f32_e32 v159, 1.0, v159
	v_rcp_f32_e32 v158, v158
	v_rcp_f32_e32 v159, v159
	s_nop 0
	v_pk_mul_f32 v[168:169], v[96:97], v[158:159]
	v_cvt_pk_bf16_f32 v158, v162, v163
	v_cvt_pk_bf16_f32 v159, v164, v165
	v_cvt_pk_bf16_f32 v161, v168, v169
	global_store_dwordx4 v[188:189], v[158:161], off offset:256
	s_nop 1
	v_lshlrev_b32_e32 v158, 16, v154
	v_and_b32_e32 v154, 0xffff0000, v154
	v_mul_f32_e32 v154, 0xbfb8aa3b, v154
	v_exp_f32_e32 v154, v154
	v_mul_f32_e32 v158, 0xbfb8aa3b, v158
	v_exp_f32_e32 v158, v158
	v_add_f32_e32 v154, 1.0, v154
	v_rcp_f32_e32 v159, v154
	v_lshlrev_b32_e32 v154, 16, v155
	v_and_b32_e32 v155, 0xffff0000, v155
	v_mul_f32_e32 v154, 0xbfb8aa3b, v154
	v_mul_f32_e32 v155, 0xbfb8aa3b, v155
	v_exp_f32_e32 v154, v154
	v_exp_f32_e32 v155, v155
	v_add_f32_e32 v158, 1.0, v158
	v_rcp_f32_e32 v158, v158
	v_add_f32_e32 v154, 1.0, v154
	v_add_f32_e32 v155, 1.0, v155
	v_rcp_f32_e32 v154, v154
	v_rcp_f32_e32 v155, v155
	v_pk_mul_f32 v[158:159], v[122:123], v[158:159]
	v_pk_mul_f32 v[160:161], v[124:125], v[154:155]
	v_lshlrev_b32_e32 v154, 16, v156
	v_and_b32_e32 v155, 0xffff0000, v156
	v_mul_f32_e32 v154, 0xbfb8aa3b, v154
	v_mul_f32_e32 v155, 0xbfb8aa3b, v155
	v_exp_f32_e32 v154, v154
	v_exp_f32_e32 v155, v155
	v_add_f32_e32 v154, 1.0, v154
	v_add_f32_e32 v155, 1.0, v155
	v_rcp_f32_e32 v154, v154
	v_rcp_f32_e32 v155, v155
	s_nop 0
	v_pk_mul_f32 v[162:163], v[118:119], v[154:155]
	v_lshlrev_b32_e32 v154, 16, v157
	v_and_b32_e32 v155, 0xffff0000, v157
	v_mul_f32_e32 v154, 0xbfb8aa3b, v154
	v_mul_f32_e32 v155, 0xbfb8aa3b, v155
	v_exp_f32_e32 v154, v154
	v_exp_f32_e32 v155, v155
	v_cvt_pk_bf16_f32 v156, v162, v163
	v_mov_b64_e32 v[162:163], s[42:43]
	v_add_f32_e32 v154, 1.0, v154
	v_add_f32_e32 v155, 1.0, v155
	v_rcp_f32_e32 v154, v154
	v_rcp_f32_e32 v155, v155
	s_nop 0
	v_pk_mul_f32 v[164:165], v[120:121], v[154:155]
	v_cvt_pk_bf16_f32 v154, v158, v159
	v_mad_i64_i32 v[158:159], s[0:1], v198, s78, v[162:163]
	v_cvt_pk_bf16_f32 v155, v160, v161
	v_cvt_pk_bf16_f32 v157, v164, v165
	v_lshl_add_u64 v[158:159], v[158:159], 0, v[186:187]
	global_store_dwordx4 v[158:159], v[154:157], off
	s_nop 1
	v_lshlrev_b32_e32 v154, 16, v150
	v_and_b32_e32 v150, 0xffff0000, v150
	v_mul_f32_e32 v150, 0xbfb8aa3b, v150
	v_exp_f32_e32 v150, v150
	v_mul_f32_e32 v154, 0xbfb8aa3b, v154
	v_exp_f32_e32 v154, v154
	v_add_f32_e32 v150, 1.0, v150
	v_rcp_f32_e32 v155, v150
	v_lshlrev_b32_e32 v150, 16, v151
	v_and_b32_e32 v151, 0xffff0000, v151
	v_mul_f32_e32 v150, 0xbfb8aa3b, v150
	v_mul_f32_e32 v151, 0xbfb8aa3b, v151
	v_exp_f32_e32 v150, v150
	v_exp_f32_e32 v151, v151
	v_add_f32_e32 v154, 1.0, v154
	v_rcp_f32_e32 v154, v154
	v_add_f32_e32 v150, 1.0, v150
	v_add_f32_e32 v151, 1.0, v151
	v_rcp_f32_e32 v150, v150
	v_rcp_f32_e32 v151, v151
	v_pk_mul_f32 v[154:155], v[90:91], v[154:155]
	v_pk_mul_f32 v[156:157], v[92:93], v[150:151]
	v_lshlrev_b32_e32 v150, 16, v152
	v_and_b32_e32 v151, 0xffff0000, v152
	v_mul_f32_e32 v150, 0xbfb8aa3b, v150
	v_mul_f32_e32 v151, 0xbfb8aa3b, v151
	v_exp_f32_e32 v150, v150
	v_exp_f32_e32 v151, v151
	v_add_f32_e32 v150, 1.0, v150
	v_add_f32_e32 v151, 1.0, v151
	v_rcp_f32_e32 v150, v150
	v_rcp_f32_e32 v151, v151
	s_nop 0
	v_pk_mul_f32 v[160:161], v[86:87], v[150:151]
	v_lshlrev_b32_e32 v150, 16, v153
	v_and_b32_e32 v151, 0xffff0000, v153
	v_mul_f32_e32 v150, 0xbfb8aa3b, v150
	v_mul_f32_e32 v151, 0xbfb8aa3b, v151
	v_exp_f32_e32 v150, v150
	v_exp_f32_e32 v151, v151
	v_cvt_pk_bf16_f32 v152, v160, v161
	v_add_f32_e32 v150, 1.0, v150
	v_add_f32_e32 v151, 1.0, v151
	v_rcp_f32_e32 v150, v150
	v_rcp_f32_e32 v151, v151
	s_nop 0
	v_pk_mul_f32 v[164:165], v[88:89], v[150:151]
	v_cvt_pk_bf16_f32 v150, v154, v155
	v_cvt_pk_bf16_f32 v151, v156, v157
	v_cvt_pk_bf16_f32 v153, v164, v165
	global_store_dwordx4 v[158:159], v[150:153], off offset:256
	v_add_u32_e32 v165, 0xa0, v26
	v_add_u32_e32 v164, 0xb0, v26
	v_lshlrev_b32_e32 v150, 16, v146
	v_and_b32_e32 v146, 0xffff0000, v146
	v_mul_f32_e32 v146, 0xbfb8aa3b, v146
	v_exp_f32_e32 v146, v146
	v_mul_f32_e32 v150, 0xbfb8aa3b, v150
	v_exp_f32_e32 v150, v150
	v_add_f32_e32 v146, 1.0, v146
	v_rcp_f32_e32 v151, v146
	v_lshlrev_b32_e32 v146, 16, v147
	v_and_b32_e32 v147, 0xffff0000, v147
	v_mul_f32_e32 v146, 0xbfb8aa3b, v146
	v_mul_f32_e32 v147, 0xbfb8aa3b, v147
	v_exp_f32_e32 v146, v146
	v_exp_f32_e32 v147, v147
	v_add_f32_e32 v150, 1.0, v150
	v_rcp_f32_e32 v150, v150
	v_add_f32_e32 v146, 1.0, v146
	v_add_f32_e32 v147, 1.0, v147
	v_rcp_f32_e32 v146, v146
	v_rcp_f32_e32 v147, v147
	v_pk_mul_f32 v[150:151], v[114:115], v[150:151]
	v_pk_mul_f32 v[152:153], v[116:117], v[146:147]
	v_lshlrev_b32_e32 v146, 16, v148
	v_and_b32_e32 v147, 0xffff0000, v148
	v_mul_f32_e32 v146, 0xbfb8aa3b, v146
	v_mul_f32_e32 v147, 0xbfb8aa3b, v147
	v_exp_f32_e32 v146, v146
	v_exp_f32_e32 v147, v147
	v_add_f32_e32 v146, 1.0, v146
	v_add_f32_e32 v147, 1.0, v147
	v_rcp_f32_e32 v146, v146
	v_rcp_f32_e32 v147, v147
	s_nop 0
	v_pk_mul_f32 v[154:155], v[110:111], v[146:147]
	v_lshlrev_b32_e32 v146, 16, v149
	v_and_b32_e32 v147, 0xffff0000, v149
	v_mul_f32_e32 v146, 0xbfb8aa3b, v146
	v_mul_f32_e32 v147, 0xbfb8aa3b, v147
	v_exp_f32_e32 v146, v146
	v_exp_f32_e32 v147, v147
	v_cvt_pk_bf16_f32 v148, v154, v155
	v_add_f32_e32 v146, 1.0, v146
	v_add_f32_e32 v147, 1.0, v147
	v_rcp_f32_e32 v146, v146
	v_rcp_f32_e32 v147, v147
	s_nop 0
	v_pk_mul_f32 v[156:157], v[112:113], v[146:147]
	v_cvt_pk_bf16_f32 v146, v150, v151
	v_mad_i64_i32 v[150:151], s[0:1], v197, s78, v[162:163]
	v_cvt_pk_bf16_f32 v147, v152, v153
	v_cvt_pk_bf16_f32 v149, v156, v157
	v_lshl_add_u64 v[150:151], v[150:151], 0, v[186:187]
	global_store_dwordx4 v[150:151], v[146:149], off
	s_nop 1
	v_lshlrev_b32_e32 v146, 16, v142
	v_and_b32_e32 v142, 0xffff0000, v142
	v_mul_f32_e32 v142, 0xbfb8aa3b, v142
	v_exp_f32_e32 v142, v142
	v_mul_f32_e32 v146, 0xbfb8aa3b, v146
	v_exp_f32_e32 v146, v146
	v_add_f32_e32 v142, 1.0, v142
	v_rcp_f32_e32 v147, v142
	v_lshlrev_b32_e32 v142, 16, v143
	v_and_b32_e32 v143, 0xffff0000, v143
	v_mul_f32_e32 v142, 0xbfb8aa3b, v142
	v_mul_f32_e32 v143, 0xbfb8aa3b, v143
	v_exp_f32_e32 v142, v142
	v_exp_f32_e32 v143, v143
	v_add_f32_e32 v146, 1.0, v146
	v_rcp_f32_e32 v146, v146
	v_add_f32_e32 v142, 1.0, v142
	v_add_f32_e32 v143, 1.0, v143
	v_rcp_f32_e32 v142, v142
	v_rcp_f32_e32 v143, v143
	v_pk_mul_f32 v[146:147], v[82:83], v[146:147]
	v_pk_mul_f32 v[148:149], v[84:85], v[142:143]
	v_lshlrev_b32_e32 v142, 16, v144
	v_and_b32_e32 v143, 0xffff0000, v144
	v_mul_f32_e32 v142, 0xbfb8aa3b, v142
	v_mul_f32_e32 v143, 0xbfb8aa3b, v143
	v_exp_f32_e32 v142, v142
	v_exp_f32_e32 v143, v143
	v_add_f32_e32 v142, 1.0, v142
	v_add_f32_e32 v143, 1.0, v143
	v_rcp_f32_e32 v142, v142
	v_rcp_f32_e32 v143, v143
	s_nop 0
	v_pk_mul_f32 v[152:153], v[78:79], v[142:143]
	v_lshlrev_b32_e32 v142, 16, v145
	v_and_b32_e32 v143, 0xffff0000, v145
	v_mul_f32_e32 v142, 0xbfb8aa3b, v142
	v_mul_f32_e32 v143, 0xbfb8aa3b, v143
	v_exp_f32_e32 v142, v142
	v_exp_f32_e32 v143, v143
	v_cvt_pk_bf16_f32 v144, v152, v153
	v_add_f32_e32 v142, 1.0, v142
	v_add_f32_e32 v143, 1.0, v143
	v_rcp_f32_e32 v142, v142
	v_rcp_f32_e32 v143, v143
	s_nop 0
	v_pk_mul_f32 v[154:155], v[80:81], v[142:143]
	v_cvt_pk_bf16_f32 v142, v146, v147
	v_cvt_pk_bf16_f32 v143, v148, v149
	v_cvt_pk_bf16_f32 v145, v154, v155
	global_store_dwordx4 v[150:151], v[142:145], off offset:256
	s_nop 1
	v_lshlrev_b32_e32 v142, 16, v138
	v_and_b32_e32 v138, 0xffff0000, v138
	v_mul_f32_e32 v138, 0xbfb8aa3b, v138
	v_exp_f32_e32 v138, v138
	v_mul_f32_e32 v142, 0xbfb8aa3b, v142
	v_exp_f32_e32 v142, v142
	v_add_f32_e32 v138, 1.0, v138
	v_rcp_f32_e32 v143, v138
	v_lshlrev_b32_e32 v138, 16, v139
	v_and_b32_e32 v139, 0xffff0000, v139
	v_mul_f32_e32 v138, 0xbfb8aa3b, v138
	v_mul_f32_e32 v139, 0xbfb8aa3b, v139
	v_exp_f32_e32 v138, v138
	v_exp_f32_e32 v139, v139
	v_add_f32_e32 v142, 1.0, v142
	v_rcp_f32_e32 v142, v142
	v_add_f32_e32 v138, 1.0, v138
	v_add_f32_e32 v139, 1.0, v139
	v_rcp_f32_e32 v138, v138
	v_rcp_f32_e32 v139, v139
	v_pk_mul_f32 v[142:143], v[106:107], v[142:143]
	v_pk_mul_f32 v[144:145], v[108:109], v[138:139]
	v_lshlrev_b32_e32 v138, 16, v140
	v_and_b32_e32 v139, 0xffff0000, v140
	v_mul_f32_e32 v138, 0xbfb8aa3b, v138
	v_mul_f32_e32 v139, 0xbfb8aa3b, v139
	v_exp_f32_e32 v138, v138
	v_exp_f32_e32 v139, v139
	v_add_f32_e32 v138, 1.0, v138
	v_add_f32_e32 v139, 1.0, v139
	v_rcp_f32_e32 v138, v138
	v_rcp_f32_e32 v139, v139
	s_nop 0
	v_pk_mul_f32 v[146:147], v[102:103], v[138:139]
	v_lshlrev_b32_e32 v138, 16, v141
	v_and_b32_e32 v139, 0xffff0000, v141
	v_mul_f32_e32 v138, 0xbfb8aa3b, v138
	v_mul_f32_e32 v139, 0xbfb8aa3b, v139
	v_exp_f32_e32 v138, v138
	v_exp_f32_e32 v139, v139
	v_cvt_pk_bf16_f32 v140, v146, v147
	v_add_f32_e32 v138, 1.0, v138
	v_add_f32_e32 v139, 1.0, v139
	v_rcp_f32_e32 v138, v138
	v_rcp_f32_e32 v139, v139
	s_nop 0
	v_pk_mul_f32 v[148:149], v[104:105], v[138:139]
	v_cvt_pk_bf16_f32 v138, v142, v143
	v_mad_i64_i32 v[142:143], s[0:1], v196, s78, v[162:163]
	v_cvt_pk_bf16_f32 v139, v144, v145
	v_cvt_pk_bf16_f32 v141, v148, v149
	v_lshl_add_u64 v[142:143], v[142:143], 0, v[186:187]
	global_store_dwordx4 v[142:143], v[138:141], off
	s_nop 1
	v_lshlrev_b32_e32 v138, 16, v134
	v_and_b32_e32 v134, 0xffff0000, v134
	v_mul_f32_e32 v134, 0xbfb8aa3b, v134
	v_exp_f32_e32 v134, v134
	v_mul_f32_e32 v138, 0xbfb8aa3b, v138
	v_exp_f32_e32 v138, v138
	v_add_f32_e32 v134, 1.0, v134
	v_rcp_f32_e32 v139, v134
	v_lshlrev_b32_e32 v134, 16, v135
	v_and_b32_e32 v135, 0xffff0000, v135
	v_mul_f32_e32 v134, 0xbfb8aa3b, v134
	v_mul_f32_e32 v135, 0xbfb8aa3b, v135
	v_exp_f32_e32 v134, v134
	v_exp_f32_e32 v135, v135
	v_add_f32_e32 v138, 1.0, v138
	v_rcp_f32_e32 v138, v138
	v_add_f32_e32 v134, 1.0, v134
	v_add_f32_e32 v135, 1.0, v135
	v_rcp_f32_e32 v134, v134
	v_rcp_f32_e32 v135, v135
	v_pk_mul_f32 v[138:139], v[74:75], v[138:139]
	v_pk_mul_f32 v[140:141], v[76:77], v[134:135]
	v_lshlrev_b32_e32 v134, 16, v136
	v_and_b32_e32 v135, 0xffff0000, v136
	v_mul_f32_e32 v134, 0xbfb8aa3b, v134
	v_mul_f32_e32 v135, 0xbfb8aa3b, v135
	v_exp_f32_e32 v134, v134
	v_exp_f32_e32 v135, v135
	v_add_f32_e32 v134, 1.0, v134
	v_add_f32_e32 v135, 1.0, v135
	v_rcp_f32_e32 v134, v134
	v_rcp_f32_e32 v135, v135
	s_nop 0
	v_pk_mul_f32 v[144:145], v[70:71], v[134:135]
	v_lshlrev_b32_e32 v134, 16, v137
	v_and_b32_e32 v135, 0xffff0000, v137
	v_mul_f32_e32 v134, 0xbfb8aa3b, v134
	v_mul_f32_e32 v135, 0xbfb8aa3b, v135
	v_exp_f32_e32 v134, v134
	v_exp_f32_e32 v135, v135
	v_cvt_pk_bf16_f32 v136, v144, v145
	v_add_f32_e32 v134, 1.0, v134
	v_add_f32_e32 v135, 1.0, v135
	v_rcp_f32_e32 v134, v134
	v_rcp_f32_e32 v135, v135
	s_nop 0
	v_pk_mul_f32 v[146:147], v[72:73], v[134:135]
	v_cvt_pk_bf16_f32 v134, v138, v139
	v_cvt_pk_bf16_f32 v135, v140, v141
	v_cvt_pk_bf16_f32 v137, v146, v147
	global_store_dwordx4 v[142:143], v[134:137], off offset:256
	s_nop 1
	v_mad_i64_i32 v[134:135], s[0:1], v195, s78, v[28:29]
	v_add_co_u32_e32 v134, vcc, s16, v134
	s_nop 1
	v_addc_co_u32_e32 v135, vcc, 0, v135, vcc
	global_load_dwordx4 v[200:203], v[134:135], off
	global_load_dwordx4 v[158:161], v[134:135], off offset:256
	v_mad_i64_i32 v[134:135], s[0:1], v194, s78, v[28:29]
	v_add_co_u32_e32 v134, vcc, s16, v134
	s_waitcnt vmcnt(0)
	v_lshlrev_b32_e32 v199, 16, v203
	v_addc_co_u32_e32 v135, vcc, 0, v135, vcc
	global_load_dwordx4 v[154:157], v[134:135], off
	global_load_dwordx4 v[150:153], v[134:135], off offset:256
	v_mul_f32_e32 v199, 0xbfb8aa3b, v199
	v_exp_f32_e32 v199, v199
	v_lshlrev_b32_e32 v168, 16, v201
	v_and_b32_e32 v169, 0xffff0000, v201
	v_lshlrev_b32_e32 v166, 16, v200
	v_add_f32_e32 v199, 1.0, v199
	v_and_b32_e32 v167, 0xffff0000, v200
	v_mul_f32_e32 v168, 0xbfb8aa3b, v168
	v_mul_f32_e32 v169, 0xbfb8aa3b, v169
	v_rcp_f32_e32 v200, v199
	v_and_b32_e32 v199, 0xffff0000, v203
	v_exp_f32_e32 v168, v168
	v_exp_f32_e32 v169, v169
	v_mul_f32_e32 v199, 0xbfb8aa3b, v199
	v_exp_f32_e32 v199, v199
	v_add_f32_e32 v168, 1.0, v168
	v_add_f32_e32 v169, 1.0, v169
	v_rcp_f32_e32 v168, v168
	v_rcp_f32_e32 v169, v169
	v_add_f32_e32 v199, 1.0, v199
	v_rcp_f32_e32 v201, v199
	v_lshlrev_b32_e32 v188, 16, v202
	v_pk_mul_f32 v[168:169], v[68:69], v[168:169]
	v_and_b32_e32 v189, 0xffff0000, v202
	v_pk_mul_f32 v[204:205], v[64:65], v[200:201]
	v_cvt_pk_bf16_f32 v201, v168, v169
	v_lshlrev_b32_e32 v168, 16, v158
	v_and_b32_e32 v158, 0xffff0000, v158
	v_mul_f32_e32 v158, 0xbfb8aa3b, v158
	v_exp_f32_e32 v158, v158
	v_mul_f32_e32 v188, 0xbfb8aa3b, v188
	v_mul_f32_e32 v189, 0xbfb8aa3b, v189
	v_exp_f32_e32 v188, v188
	v_add_f32_e32 v158, 1.0, v158
	v_rcp_f32_e32 v169, v158
	v_lshlrev_b32_e32 v158, 16, v159
	v_and_b32_e32 v159, 0xffff0000, v159
	v_exp_f32_e32 v189, v189
	v_mul_f32_e32 v158, 0xbfb8aa3b, v158
	v_mul_f32_e32 v159, 0xbfb8aa3b, v159
	v_exp_f32_e32 v158, v158
	v_exp_f32_e32 v159, v159
	v_add_f32_e32 v188, 1.0, v188
	v_add_f32_e32 v189, 1.0, v189
	v_rcp_f32_e32 v188, v188
	v_rcp_f32_e32 v189, v189
	v_add_f32_e32 v158, 1.0, v158
	v_add_f32_e32 v159, 1.0, v159
	v_rcp_f32_e32 v158, v158
	v_rcp_f32_e32 v159, v159
	v_mul_f32_e32 v166, 0xbfb8aa3b, v166
	v_mul_f32_e32 v167, 0xbfb8aa3b, v167
	v_exp_f32_e32 v166, v166
	v_exp_f32_e32 v167, v167
	v_pk_mul_f32 v[188:189], v[62:63], v[188:189]
	v_mad_i64_i32 v[134:135], s[0:1], v165, s78, v[28:29]
	v_cvt_pk_bf16_f32 v202, v188, v189
	v_pk_mul_f32 v[188:189], v[36:37], v[158:159]
	v_lshlrev_b32_e32 v158, 16, v160
	v_and_b32_e32 v159, 0xffff0000, v160
	v_mul_f32_e32 v158, 0xbfb8aa3b, v158
	v_mul_f32_e32 v159, 0xbfb8aa3b, v159
	v_exp_f32_e32 v158, v158
	v_exp_f32_e32 v159, v159
	v_add_f32_e32 v166, 1.0, v166
	v_add_f32_e32 v167, 1.0, v167
	v_rcp_f32_e32 v166, v166
	v_rcp_f32_e32 v167, v167
	v_add_co_u32_e32 v134, vcc, s16, v134
	v_add_f32_e32 v158, 1.0, v158
	v_add_f32_e32 v159, 1.0, v159
	v_addc_co_u32_e32 v135, vcc, 0, v135, vcc
	v_rcp_f32_e32 v158, v158
	v_rcp_f32_e32 v159, v159
	global_load_dwordx4 v[146:149], v[134:135], off
	global_load_dwordx4 v[142:145], v[134:135], off offset:256
	v_mad_i64_i32 v[134:135], s[0:1], v164, s78, v[28:29]
	v_pk_mul_f32 v[166:167], v[66:67], v[166:167]
	v_add_co_u32_e32 v134, vcc, s16, v134
	v_cvt_pk_bf16_f32 v200, v166, v167
	v_mad_i64_i32 v[166:167], s[0:1], v195, s78, v[162:163]
	v_addc_co_u32_e32 v135, vcc, 0, v135, vcc
	v_cvt_pk_bf16_f32 v203, v204, v205
	v_lshl_add_u64 v[166:167], v[166:167], 0, v[186:187]
	global_load_dwordx4 v[138:141], v[134:135], off
	s_nop 0
	global_load_dwordx4 v[134:137], v[134:135], off offset:256
	v_mul_f32_e32 v168, 0xbfb8aa3b, v168
	global_store_dwordx4 v[166:167], v[200:203], off
	v_exp_f32_e32 v168, v168
	s_nop 0
	v_pk_mul_f32 v[200:201], v[30:31], v[158:159]
	v_lshlrev_b32_e32 v158, 16, v161
	v_and_b32_e32 v159, 0xffff0000, v161
	v_mul_f32_e32 v158, 0xbfb8aa3b, v158
	v_mul_f32_e32 v159, 0xbfb8aa3b, v159
	v_exp_f32_e32 v158, v158
	v_exp_f32_e32 v159, v159
	v_add_f32_e32 v168, 1.0, v168
	v_rcp_f32_e32 v168, v168
	v_add_f32_e32 v158, 1.0, v158
	v_add_f32_e32 v159, 1.0, v159
	v_rcp_f32_e32 v158, v158
	v_rcp_f32_e32 v159, v159
	v_pk_mul_f32 v[168:169], v[34:35], v[168:169]
	v_cvt_pk_bf16_f32 v160, v200, v201
	v_pk_mul_f32 v[202:203], v[32:33], v[158:159]
	v_cvt_pk_bf16_f32 v158, v168, v169
	v_cvt_pk_bf16_f32 v159, v188, v189
	v_cvt_pk_bf16_f32 v161, v202, v203
	global_store_dwordx4 v[166:167], v[158:161], off offset:256
	s_waitcnt vmcnt(0)
	s_nop 0
	v_lshlrev_b32_e32 v158, 16, v154
	v_and_b32_e32 v154, 0xffff0000, v154
	v_mul_f32_e32 v154, 0xbfb8aa3b, v154
	v_exp_f32_e32 v154, v154
	v_mul_f32_e32 v158, 0xbfb8aa3b, v158
	v_exp_f32_e32 v158, v158
	v_add_f32_e32 v154, 1.0, v154
	v_rcp_f32_e32 v159, v154
	v_lshlrev_b32_e32 v154, 16, v155
	v_and_b32_e32 v155, 0xffff0000, v155
	v_mul_f32_e32 v154, 0xbfb8aa3b, v154
	v_mul_f32_e32 v155, 0xbfb8aa3b, v155
	v_exp_f32_e32 v154, v154
	v_exp_f32_e32 v155, v155
	v_add_f32_e32 v158, 1.0, v158
	v_rcp_f32_e32 v158, v158
	v_add_f32_e32 v154, 1.0, v154
	v_add_f32_e32 v155, 1.0, v155
	v_rcp_f32_e32 v154, v154
	v_rcp_f32_e32 v155, v155
	v_pk_mul_f32 v[158:159], v[58:59], v[158:159]
	v_pk_mul_f32 v[160:161], v[60:61], v[154:155]
	v_lshlrev_b32_e32 v154, 16, v156
	v_and_b32_e32 v155, 0xffff0000, v156
	v_mul_f32_e32 v154, 0xbfb8aa3b, v154
	v_mul_f32_e32 v155, 0xbfb8aa3b, v155
	v_exp_f32_e32 v154, v154
	v_exp_f32_e32 v155, v155
	v_add_f32_e32 v154, 1.0, v154
	v_add_f32_e32 v155, 1.0, v155
	v_rcp_f32_e32 v154, v154
	v_rcp_f32_e32 v155, v155
	s_nop 0
	v_pk_mul_f32 v[166:167], v[54:55], v[154:155]
	v_lshlrev_b32_e32 v154, 16, v157
	v_and_b32_e32 v155, 0xffff0000, v157
	v_mul_f32_e32 v154, 0xbfb8aa3b, v154
	v_mul_f32_e32 v155, 0xbfb8aa3b, v155
	v_exp_f32_e32 v154, v154
	v_exp_f32_e32 v155, v155
	v_cvt_pk_bf16_f32 v156, v166, v167
	v_add_f32_e32 v154, 1.0, v154
	v_add_f32_e32 v155, 1.0, v155
	v_rcp_f32_e32 v154, v154
	v_rcp_f32_e32 v155, v155
	s_nop 0
	v_pk_mul_f32 v[168:169], v[56:57], v[154:155]
	v_cvt_pk_bf16_f32 v154, v158, v159
	v_mad_i64_i32 v[158:159], s[0:1], v194, s78, v[162:163]
	v_cvt_pk_bf16_f32 v155, v160, v161
	v_cvt_pk_bf16_f32 v157, v168, v169
	v_lshl_add_u64 v[158:159], v[158:159], 0, v[186:187]
	global_store_dwordx4 v[158:159], v[154:157], off
	s_nop 1
	v_lshlrev_b32_e32 v154, 16, v150
	v_and_b32_e32 v150, 0xffff0000, v150
	v_mul_f32_e32 v150, 0xbfb8aa3b, v150
	v_exp_f32_e32 v150, v150
	v_mul_f32_e32 v154, 0xbfb8aa3b, v154
	v_exp_f32_e32 v154, v154
	v_add_f32_e32 v150, 1.0, v150
	v_rcp_f32_e32 v155, v150
	v_lshlrev_b32_e32 v150, 16, v151
	v_and_b32_e32 v151, 0xffff0000, v151
	v_mul_f32_e32 v150, 0xbfb8aa3b, v150
	v_mul_f32_e32 v151, 0xbfb8aa3b, v151
	v_exp_f32_e32 v150, v150
	v_exp_f32_e32 v151, v151
	v_add_f32_e32 v154, 1.0, v154
	v_rcp_f32_e32 v154, v154
	v_add_f32_e32 v150, 1.0, v150
	v_add_f32_e32 v151, 1.0, v151
	v_rcp_f32_e32 v150, v150
	v_rcp_f32_e32 v151, v151
	v_pk_mul_f32 v[154:155], v[22:23], v[154:155]
	v_pk_mul_f32 v[156:157], v[24:25], v[150:151]
	v_lshlrev_b32_e32 v150, 16, v152
	v_and_b32_e32 v151, 0xffff0000, v152
	v_mul_f32_e32 v150, 0xbfb8aa3b, v150
	v_mul_f32_e32 v151, 0xbfb8aa3b, v151
	v_exp_f32_e32 v150, v150
	v_exp_f32_e32 v151, v151
	v_add_f32_e32 v150, 1.0, v150
	v_add_f32_e32 v151, 1.0, v151
	v_rcp_f32_e32 v150, v150
	v_rcp_f32_e32 v151, v151
	s_nop 0
	v_pk_mul_f32 v[160:161], v[18:19], v[150:151]
	v_lshlrev_b32_e32 v150, 16, v153
	v_and_b32_e32 v151, 0xffff0000, v153
	v_mul_f32_e32 v150, 0xbfb8aa3b, v150
	v_mul_f32_e32 v151, 0xbfb8aa3b, v151
	v_exp_f32_e32 v150, v150
	v_exp_f32_e32 v151, v151
	v_cvt_pk_bf16_f32 v152, v160, v161
	v_add_f32_e32 v150, 1.0, v150
	v_add_f32_e32 v151, 1.0, v151
	v_rcp_f32_e32 v150, v150
	v_rcp_f32_e32 v151, v151
	s_nop 0
	v_pk_mul_f32 v[166:167], v[20:21], v[150:151]
	v_cvt_pk_bf16_f32 v150, v154, v155
	v_cvt_pk_bf16_f32 v151, v156, v157
	v_cvt_pk_bf16_f32 v153, v166, v167
	global_store_dwordx4 v[158:159], v[150:153], off offset:256
	s_nop 1
	v_lshlrev_b32_e32 v150, 16, v146
	v_and_b32_e32 v146, 0xffff0000, v146
	v_mul_f32_e32 v146, 0xbfb8aa3b, v146
	v_exp_f32_e32 v146, v146
	v_mul_f32_e32 v150, 0xbfb8aa3b, v150
	v_exp_f32_e32 v150, v150
	v_add_f32_e32 v146, 1.0, v146
	v_rcp_f32_e32 v151, v146
	v_lshlrev_b32_e32 v146, 16, v147
	v_and_b32_e32 v147, 0xffff0000, v147
	v_mul_f32_e32 v146, 0xbfb8aa3b, v146
	v_mul_f32_e32 v147, 0xbfb8aa3b, v147
	v_exp_f32_e32 v146, v146
	v_exp_f32_e32 v147, v147
	v_add_f32_e32 v150, 1.0, v150
	v_rcp_f32_e32 v150, v150
	v_add_f32_e32 v146, 1.0, v146
	v_add_f32_e32 v147, 1.0, v147
	v_rcp_f32_e32 v146, v146
	v_rcp_f32_e32 v147, v147
	v_pk_mul_f32 v[150:151], v[50:51], v[150:151]
	v_pk_mul_f32 v[152:153], v[52:53], v[146:147]
	v_lshlrev_b32_e32 v146, 16, v148
	v_and_b32_e32 v147, 0xffff0000, v148
	v_mul_f32_e32 v146, 0xbfb8aa3b, v146
	v_mul_f32_e32 v147, 0xbfb8aa3b, v147
	v_exp_f32_e32 v146, v146
	v_exp_f32_e32 v147, v147
	v_add_f32_e32 v146, 1.0, v146
	v_add_f32_e32 v147, 1.0, v147
	v_rcp_f32_e32 v146, v146
	v_rcp_f32_e32 v147, v147
	s_nop 0
	v_pk_mul_f32 v[154:155], v[46:47], v[146:147]
	v_lshlrev_b32_e32 v146, 16, v149
	v_and_b32_e32 v147, 0xffff0000, v149
	v_mul_f32_e32 v146, 0xbfb8aa3b, v146
	v_mul_f32_e32 v147, 0xbfb8aa3b, v147
	v_exp_f32_e32 v146, v146
	v_exp_f32_e32 v147, v147
	v_cvt_pk_bf16_f32 v148, v154, v155
	v_add_f32_e32 v146, 1.0, v146
	v_add_f32_e32 v147, 1.0, v147
	v_rcp_f32_e32 v146, v146
	v_rcp_f32_e32 v147, v147
	s_nop 0
	v_pk_mul_f32 v[156:157], v[48:49], v[146:147]
	v_cvt_pk_bf16_f32 v146, v150, v151
	v_mad_i64_i32 v[150:151], s[0:1], v165, s78, v[162:163]
	v_cvt_pk_bf16_f32 v147, v152, v153
	v_cvt_pk_bf16_f32 v149, v156, v157
	v_lshl_add_u64 v[150:151], v[150:151], 0, v[186:187]
	global_store_dwordx4 v[150:151], v[146:149], off
	s_nop 1
	v_lshlrev_b32_e32 v146, 16, v142
	v_and_b32_e32 v142, 0xffff0000, v142
	v_mul_f32_e32 v142, 0xbfb8aa3b, v142
	v_exp_f32_e32 v142, v142
	v_mul_f32_e32 v146, 0xbfb8aa3b, v146
	v_exp_f32_e32 v146, v146
	v_add_f32_e32 v142, 1.0, v142
	v_rcp_f32_e32 v147, v142
	v_lshlrev_b32_e32 v142, 16, v143
	v_and_b32_e32 v143, 0xffff0000, v143
	v_mul_f32_e32 v142, 0xbfb8aa3b, v142
	v_mul_f32_e32 v143, 0xbfb8aa3b, v143
	v_exp_f32_e32 v142, v142
	v_exp_f32_e32 v143, v143
	v_add_f32_e32 v146, 1.0, v146
	v_rcp_f32_e32 v146, v146
	v_add_f32_e32 v142, 1.0, v142
	v_add_f32_e32 v143, 1.0, v143
	v_rcp_f32_e32 v142, v142
	v_rcp_f32_e32 v143, v143
	v_pk_mul_f32 v[146:147], v[14:15], v[146:147]
	v_pk_mul_f32 v[148:149], v[16:17], v[142:143]
	v_lshlrev_b32_e32 v142, 16, v144
	v_and_b32_e32 v143, 0xffff0000, v144
	v_mul_f32_e32 v142, 0xbfb8aa3b, v142
	v_mul_f32_e32 v143, 0xbfb8aa3b, v143
	v_exp_f32_e32 v142, v142
	v_exp_f32_e32 v143, v143
	v_add_f32_e32 v142, 1.0, v142
	v_add_f32_e32 v143, 1.0, v143
	v_rcp_f32_e32 v142, v142
	v_rcp_f32_e32 v143, v143
	s_nop 0
	v_pk_mul_f32 v[152:153], v[10:11], v[142:143]
	v_lshlrev_b32_e32 v142, 16, v145
	v_and_b32_e32 v143, 0xffff0000, v145
	v_mul_f32_e32 v142, 0xbfb8aa3b, v142
	v_mul_f32_e32 v143, 0xbfb8aa3b, v143
	v_exp_f32_e32 v142, v142
	v_exp_f32_e32 v143, v143
	v_cvt_pk_bf16_f32 v144, v152, v153
	v_add_f32_e32 v142, 1.0, v142
	v_add_f32_e32 v143, 1.0, v143
	v_rcp_f32_e32 v142, v142
	v_rcp_f32_e32 v143, v143
	s_nop 0
	v_pk_mul_f32 v[154:155], v[12:13], v[142:143]
	v_cvt_pk_bf16_f32 v142, v146, v147
	v_cvt_pk_bf16_f32 v143, v148, v149
	v_cvt_pk_bf16_f32 v145, v154, v155
	global_store_dwordx4 v[150:151], v[142:145], off offset:256
	s_nop 1
	v_lshlrev_b32_e32 v142, 16, v138
	v_and_b32_e32 v138, 0xffff0000, v138
	v_mul_f32_e32 v138, 0xbfb8aa3b, v138
	v_exp_f32_e32 v138, v138
	v_mul_f32_e32 v142, 0xbfb8aa3b, v142
	v_exp_f32_e32 v142, v142
	v_add_f32_e32 v138, 1.0, v138
	v_rcp_f32_e32 v143, v138
	v_lshlrev_b32_e32 v138, 16, v139
	v_and_b32_e32 v139, 0xffff0000, v139
	v_mul_f32_e32 v138, 0xbfb8aa3b, v138
	v_mul_f32_e32 v139, 0xbfb8aa3b, v139
	v_exp_f32_e32 v138, v138
	v_exp_f32_e32 v139, v139
	v_add_f32_e32 v142, 1.0, v142
	v_rcp_f32_e32 v142, v142
	v_add_f32_e32 v138, 1.0, v138
	v_add_f32_e32 v139, 1.0, v139
	v_rcp_f32_e32 v138, v138
	v_rcp_f32_e32 v139, v139
	v_pk_mul_f32 v[142:143], v[42:43], v[142:143]
	v_pk_mul_f32 v[144:145], v[44:45], v[138:139]
	v_lshlrev_b32_e32 v138, 16, v140
	v_and_b32_e32 v139, 0xffff0000, v140
	v_mul_f32_e32 v138, 0xbfb8aa3b, v138
	v_mul_f32_e32 v139, 0xbfb8aa3b, v139
	v_exp_f32_e32 v138, v138
	v_exp_f32_e32 v139, v139
	v_add_f32_e32 v138, 1.0, v138
	v_add_f32_e32 v139, 1.0, v139
	v_rcp_f32_e32 v138, v138
	v_rcp_f32_e32 v139, v139
	s_nop 0
	v_pk_mul_f32 v[146:147], v[38:39], v[138:139]
	v_lshlrev_b32_e32 v138, 16, v141
	v_and_b32_e32 v139, 0xffff0000, v141
	v_mul_f32_e32 v138, 0xbfb8aa3b, v138
	v_mul_f32_e32 v139, 0xbfb8aa3b, v139
	v_exp_f32_e32 v138, v138
	v_exp_f32_e32 v139, v139
	v_cvt_pk_bf16_f32 v140, v146, v147
	v_add_f32_e32 v138, 1.0, v138
	v_add_f32_e32 v139, 1.0, v139
	v_rcp_f32_e32 v138, v138
	v_rcp_f32_e32 v139, v139
	s_nop 0
	v_pk_mul_f32 v[148:149], v[40:41], v[138:139]
	v_cvt_pk_bf16_f32 v138, v142, v143
	v_mad_i64_i32 v[142:143], s[0:1], v164, s78, v[162:163]
	v_cvt_pk_bf16_f32 v139, v144, v145
	v_cvt_pk_bf16_f32 v141, v148, v149
	v_lshl_add_u64 v[142:143], v[142:143], 0, v[186:187]
	global_store_dwordx4 v[142:143], v[138:141], off
	s_nop 1
	v_lshlrev_b32_e32 v138, 16, v134
	v_and_b32_e32 v134, 0xffff0000, v134
	v_mul_f32_e32 v134, 0xbfb8aa3b, v134
	v_exp_f32_e32 v134, v134
	v_mul_f32_e32 v138, 0xbfb8aa3b, v138
	v_exp_f32_e32 v138, v138
	v_add_f32_e32 v134, 1.0, v134
	v_rcp_f32_e32 v139, v134
	v_lshlrev_b32_e32 v134, 16, v135
	v_and_b32_e32 v135, 0xffff0000, v135
	v_mul_f32_e32 v134, 0xbfb8aa3b, v134
	v_mul_f32_e32 v135, 0xbfb8aa3b, v135
	v_exp_f32_e32 v134, v134
	v_exp_f32_e32 v135, v135
	v_add_f32_e32 v138, 1.0, v138
	v_rcp_f32_e32 v138, v138
	v_add_f32_e32 v134, 1.0, v134
	v_add_f32_e32 v135, 1.0, v135
	v_rcp_f32_e32 v134, v134
	v_rcp_f32_e32 v135, v135
	v_pk_mul_f32 v[138:139], v[6:7], v[138:139]
	v_pk_mul_f32 v[140:141], v[8:9], v[134:135]
	v_lshlrev_b32_e32 v134, 16, v136
	v_and_b32_e32 v135, 0xffff0000, v136
	v_mul_f32_e32 v134, 0xbfb8aa3b, v134
	v_mul_f32_e32 v135, 0xbfb8aa3b, v135
	v_exp_f32_e32 v134, v134
	v_exp_f32_e32 v135, v135
	v_add_f32_e32 v134, 1.0, v134
	v_add_f32_e32 v135, 1.0, v135
	v_rcp_f32_e32 v134, v134
	v_rcp_f32_e32 v135, v135
	s_nop 0
	v_pk_mul_f32 v[144:145], v[2:3], v[134:135]
	v_lshlrev_b32_e32 v134, 16, v137
	v_and_b32_e32 v135, 0xffff0000, v137
	v_mul_f32_e32 v134, 0xbfb8aa3b, v134
	v_mul_f32_e32 v135, 0xbfb8aa3b, v135
	v_exp_f32_e32 v134, v134
	v_exp_f32_e32 v135, v135
	v_cvt_pk_bf16_f32 v136, v144, v145
	v_add_f32_e32 v134, 1.0, v134
	v_add_f32_e32 v135, 1.0, v135
	v_rcp_f32_e32 v134, v134
	v_rcp_f32_e32 v135, v135
	s_nop 0
	v_pk_mul_f32 v[146:147], v[4:5], v[134:135]
	v_cvt_pk_bf16_f32 v134, v138, v139
	v_cvt_pk_bf16_f32 v135, v140, v141
	v_cvt_pk_bf16_f32 v137, v146, v147
	global_store_dwordx4 v[142:143], v[134:137], off offset:256
	s_cbranch_execnz .LBB0_891

.LBB0_964:
	s_ashr_i32 s23, s22, 31
	s_lshl_b64 s[0:1], s[22:23], 19
	s_add_u32 s26, s50, s0
	s_addc_u32 s27, s51, s1
	s_and_b64 s[0:1], s[42:43], exec
	s_cselect_b32 s18, s27, s37
	s_cselect_b32 s19, s26, s36
	s_add_u32 s23, s36, 0x100
	v_mov_b32_e32 v2, 0
	s_addc_u32 s29, s37, 0
	s_mov_b32 s31, -2
	v_mov_b32_e32 v3, v2
	v_mov_b32_e32 v4, v2
	v_mov_b32_e32 v5, v2
	v_mov_b32_e32 v6, v2
	v_mov_b32_e32 v7, v2
	v_mov_b32_e32 v8, v2
	v_mov_b32_e32 v9, v2
	v_mov_b32_e32 v10, v2
	v_mov_b32_e32 v11, v2
	v_mov_b32_e32 v12, v2
	v_mov_b32_e32 v13, v2
	v_mov_b32_e32 v14, v2
	v_mov_b32_e32 v15, v2
	v_mov_b32_e32 v16, v2
	v_mov_b32_e32 v17, v2
	v_mov_b32_e32 v18, v2
	v_mov_b32_e32 v19, v2
	v_mov_b32_e32 v20, v2
	v_mov_b32_e32 v21, v2
	v_mov_b32_e32 v22, v2
	v_mov_b32_e32 v23, v2
	v_mov_b32_e32 v24, v2
	v_mov_b32_e32 v25, v2
	v_mov_b32_e32 v28, v2
	v_mov_b32_e32 v29, v2
	v_mov_b32_e32 v30, v2
	v_mov_b32_e32 v31, v2
	v_mov_b32_e32 v32, v2
	v_mov_b32_e32 v33, v2
	v_mov_b32_e32 v34, v2
	v_mov_b32_e32 v35, v2
	v_mov_b32_e32 v68, v2
	v_mov_b32_e32 v69, v2
	v_mov_b32_e32 v70, v2
	v_mov_b32_e32 v71, v2
	v_mov_b32_e32 v72, v2
	v_mov_b32_e32 v73, v2
	v_mov_b32_e32 v74, v2
	v_mov_b32_e32 v75, v2
	v_mov_b32_e32 v76, v2
	v_mov_b32_e32 v77, v2
	v_mov_b32_e32 v78, v2
	v_mov_b32_e32 v79, v2
	v_mov_b32_e32 v80, v2
	v_mov_b32_e32 v81, v2
	v_mov_b32_e32 v82, v2
	v_mov_b32_e32 v83, v2
	v_mov_b32_e32 v84, v2
	v_mov_b32_e32 v85, v2
	v_mov_b32_e32 v86, v2
	v_mov_b32_e32 v87, v2
	v_mov_b32_e32 v88, v2
	v_mov_b32_e32 v89, v2
	v_mov_b32_e32 v90, v2
	v_mov_b32_e32 v91, v2
	v_mov_b32_e32 v92, v2
	v_mov_b32_e32 v93, v2
	v_mov_b32_e32 v94, v2
	v_mov_b32_e32 v95, v2
	v_mov_b32_e32 v96, v2
	v_mov_b32_e32 v97, v2
	v_mov_b32_e32 v98, v2
	v_mov_b32_e32 v99, v2
	s_waitcnt vmcnt(0)
	v_mov_b32_e32 v36, v2
	v_mov_b32_e32 v37, v2
	v_mov_b32_e32 v38, v2
	v_mov_b32_e32 v39, v2
	v_mov_b32_e32 v40, v2
	v_mov_b32_e32 v41, v2
	v_mov_b32_e32 v42, v2
	v_mov_b32_e32 v43, v2
	v_mov_b32_e32 v44, v2
	v_mov_b32_e32 v45, v2
	v_mov_b32_e32 v46, v2
	v_mov_b32_e32 v47, v2
	v_mov_b32_e32 v48, v2
	v_mov_b32_e32 v49, v2
	v_mov_b32_e32 v50, v2
	v_mov_b32_e32 v51, v2
	v_mov_b32_e32 v52, v2
	v_mov_b32_e32 v53, v2
	v_mov_b32_e32 v54, v2
	v_mov_b32_e32 v55, v2
	v_mov_b32_e32 v56, v2
	v_mov_b32_e32 v57, v2
	v_mov_b32_e32 v58, v2
	v_mov_b32_e32 v59, v2
	v_mov_b32_e32 v60, v2
	v_mov_b32_e32 v61, v2
	v_mov_b32_e32 v62, v2
	v_mov_b32_e32 v63, v2
	v_mov_b32_e32 v64, v2
	v_mov_b32_e32 v65, v2
	v_mov_b32_e32 v66, v2
	v_mov_b32_e32 v67, v2
	v_mov_b32_e32 v108, v2
	v_mov_b32_e32 v109, v2
	v_mov_b32_e32 v110, v2
	v_mov_b32_e32 v111, v2
	v_mov_b32_e32 v112, v2
	v_mov_b32_e32 v113, v2
	v_mov_b32_e32 v114, v2
	v_mov_b32_e32 v115, v2
	v_mov_b32_e32 v116, v2
	v_mov_b32_e32 v117, v2
	v_mov_b32_e32 v118, v2
	v_mov_b32_e32 v119, v2
	v_mov_b32_e32 v120, v2
	v_mov_b32_e32 v121, v2
	v_mov_b32_e32 v122, v2
	v_mov_b32_e32 v123, v2
	v_mov_b32_e32 v124, v2
	v_mov_b32_e32 v125, v2
	v_mov_b32_e32 v126, v2
	v_mov_b32_e32 v127, v2
	v_mov_b32_e32 v128, v2
	v_mov_b32_e32 v129, v2
	v_mov_b32_e32 v130, v2
	v_mov_b32_e32 v131, v2
	v_mov_b32_e32 v132, v2
	v_mov_b32_e32 v133, v2
	v_mov_b32_e32 v134, v2
	v_mov_b32_e32 v135, v2
	v_mov_b32_e32 v136, v2
	v_mov_b32_e32 v137, v2
	v_mov_b32_e32 v138, v2
	v_mov_b32_e32 v139, v2
	v_add_u32_e32 v144, 0x10000, v222
	ds_read_b128 v[100:103], v144
	ds_read_b128 v[104:107], v144 offset:1024
	ds_read_b128 v[140:143], v144 offset:2048
	ds_read_b128 v[144:147], v144 offset:3072
	s_add_u32 s36, s34, 0x100
	s_addc_u32 s37, s35, 0
	s_add_i32 s0, 0, 0x10000
	s_cmp_eq_u32 s31, 12
	s_cselect_b32 s47, s25, s37
	s_cselect_b32 s46, s24, s36
	s_cselect_b32 s43, s18, s29
	s_cselect_b32 s42, s19, s23
.LBB0_965:
	s_add_i32 m0, s54, 0xc000
	ds_read_b128 v[148:151], v224
	ds_read_b128 v[152:155], v224 offset:1024
	ds_read_b128 v[178:181], v224 offset:2048
	ds_read_b128 v[182:185], v224 offset:3072
	ds_read_b128 v[186:189], v224 offset:4096
	ds_read_b128 v[190:193], v224 offset:5120
	ds_read_b128 v[194:197], v224 offset:6144
	ds_read_b128 v[198:201], v224 offset:7168
	global_load_lds_dwordx4 v174, s[34:35]
	v_lshl_add_u64 v[166:167], s[34:35], 0, v[176:177]
	s_add_i32 m0, s54, 0xe000
	s_nop 0
	global_load_lds_dwordx4 v[166:167], off
	s_waitcnt vmcnt(10) lgkmcnt(8)
	s_setprio 1
	s_barrier
	s_waitcnt lgkmcnt(0)
	v_mfma_f32_16x16x32_bf16 v[136:139], v[100:103], v[148:151], v[136:139]
	v_mfma_f32_16x16x32_bf16 v[132:135], v[140:143], v[148:151], v[132:135]
	v_mfma_f32_16x16x32_bf16 v[128:131], v[100:103], v[178:181], v[128:131]
	v_mfma_f32_16x16x32_bf16 v[124:127], v[140:143], v[178:181], v[124:127]
	v_mfma_f32_16x16x32_bf16 v[120:123], v[100:103], v[186:189], v[120:123]
	v_mfma_f32_16x16x32_bf16 v[116:119], v[140:143], v[186:189], v[116:119]
	v_mfma_f32_16x16x32_bf16 v[112:115], v[100:103], v[194:197], v[112:115]
	v_mfma_f32_16x16x32_bf16 v[108:111], v[140:143], v[194:197], v[108:111]
	v_mfma_f32_16x16x32_bf16 v[136:139], v[104:107], v[152:155], v[136:139]
	v_mfma_f32_16x16x32_bf16 v[132:135], v[144:147], v[152:155], v[132:135]
	v_mfma_f32_16x16x32_bf16 v[128:131], v[104:107], v[182:185], v[128:131]
	v_mfma_f32_16x16x32_bf16 v[124:127], v[144:147], v[182:185], v[124:127]
	v_mfma_f32_16x16x32_bf16 v[120:123], v[104:107], v[190:193], v[120:123]
	v_mfma_f32_16x16x32_bf16 v[116:119], v[144:147], v[190:193], v[116:119]
	v_mfma_f32_16x16x32_bf16 v[112:115], v[104:107], v[198:201], v[112:115]
	v_mfma_f32_16x16x32_bf16 v[108:111], v[144:147], v[198:201], v[108:111]
	s_barrier
	s_setprio 0
	s_add_i32 s34, 0, 0x14000
	v_add_u32_e32 v166, s34, v222
	s_add_i32 s0, s0, s53
	ds_read_b128 v[202:205], v166
	ds_read_b128 v[206:209], v166 offset:1024
	ds_read_b128 v[210:213], v166 offset:2048
	ds_read_b128 v[214:217], v166 offset:3072
	v_lshl_add_u64 v[166:167], s[42:43], 0, v[26:27]
	s_mov_b32 m0, s0
	v_lshl_add_u64 v[168:169], s[42:43], 0, v[160:161]
	global_load_lds_dwordx4 v[166:167], off
	s_add_i32 m0, s0, 0x2000
	s_nop 0
	global_load_lds_dwordx4 v[168:169], off
	s_waitcnt vmcnt(10)
	s_setprio 1
	s_barrier
	s_waitcnt lgkmcnt(0)
	v_mfma_f32_16x16x32_bf16 v[64:67], v[202:205], v[148:151], v[64:67]
	v_mfma_f32_16x16x32_bf16 v[60:63], v[210:213], v[148:151], v[60:63]
	v_mfma_f32_16x16x32_bf16 v[56:59], v[202:205], v[178:181], v[56:59]
	v_mfma_f32_16x16x32_bf16 v[52:55], v[210:213], v[178:181], v[52:55]
	v_mfma_f32_16x16x32_bf16 v[48:51], v[202:205], v[186:189], v[48:51]
	v_mfma_f32_16x16x32_bf16 v[44:47], v[210:213], v[186:189], v[44:47]
	v_mfma_f32_16x16x32_bf16 v[40:43], v[202:205], v[194:197], v[40:43]
	v_mfma_f32_16x16x32_bf16 v[36:39], v[210:213], v[194:197], v[36:39]
	v_mfma_f32_16x16x32_bf16 v[64:67], v[206:209], v[152:155], v[64:67]
	v_mfma_f32_16x16x32_bf16 v[60:63], v[214:217], v[152:155], v[60:63]
	v_mfma_f32_16x16x32_bf16 v[56:59], v[206:209], v[182:185], v[56:59]
	v_mfma_f32_16x16x32_bf16 v[52:55], v[214:217], v[182:185], v[52:55]
	v_mfma_f32_16x16x32_bf16 v[48:51], v[206:209], v[190:193], v[48:51]
	v_mfma_f32_16x16x32_bf16 v[44:47], v[214:217], v[190:193], v[44:47]
	v_mfma_f32_16x16x32_bf16 v[40:43], v[206:209], v[198:201], v[40:43]
	v_mfma_f32_16x16x32_bf16 v[36:39], v[214:217], v[198:201], v[36:39]
	s_barrier
	s_setprio 0
	s_mov_b32 m0, s54
	v_lshl_add_u64 v[218:219], s[46:47], 0, v[156:157]
	ds_read_b128 v[148:151], v224 offset:16384
	ds_read_b128 v[152:155], v224 offset:17408
	ds_read_b128 v[178:181], v224 offset:18432
	ds_read_b128 v[182:185], v224 offset:19456
	ds_read_b128 v[186:189], v224 offset:20480
	ds_read_b128 v[190:193], v224 offset:21504
	ds_read_b128 v[194:197], v224 offset:22528
	ds_read_b128 v[198:201], v224 offset:23552
	global_load_lds_dwordx4 v[218:219], off
	v_lshl_add_u64 v[220:221], s[46:47], 0, v[158:159]
	s_mov_b32 m0, s55
	s_nop 0
	global_load_lds_dwordx4 v[220:221], off
	s_waitcnt vmcnt(10)
	s_setprio 1
	s_barrier
	s_waitcnt lgkmcnt(0)
	v_mfma_f32_16x16x32_bf16 v[96:99], v[100:103], v[148:151], v[96:99]
	v_mfma_f32_16x16x32_bf16 v[92:95], v[140:143], v[148:151], v[92:95]
	v_mfma_f32_16x16x32_bf16 v[88:91], v[100:103], v[178:181], v[88:91]
	v_mfma_f32_16x16x32_bf16 v[84:87], v[140:143], v[178:181], v[84:87]
	v_mfma_f32_16x16x32_bf16 v[80:83], v[100:103], v[186:189], v[80:83]
	v_mfma_f32_16x16x32_bf16 v[76:79], v[140:143], v[186:189], v[76:79]
	v_mfma_f32_16x16x32_bf16 v[72:75], v[100:103], v[194:197], v[72:75]
	v_mfma_f32_16x16x32_bf16 v[68:71], v[140:143], v[194:197], v[68:71]
	v_mfma_f32_16x16x32_bf16 v[96:99], v[104:107], v[152:155], v[96:99]
	v_mfma_f32_16x16x32_bf16 v[92:95], v[144:147], v[152:155], v[92:95]
	v_mfma_f32_16x16x32_bf16 v[88:91], v[104:107], v[182:185], v[88:91]
	v_mfma_f32_16x16x32_bf16 v[84:87], v[144:147], v[182:185], v[84:87]
	v_mfma_f32_16x16x32_bf16 v[80:83], v[104:107], v[190:193], v[80:83]
	v_mfma_f32_16x16x32_bf16 v[76:79], v[144:147], v[190:193], v[76:79]
	v_mfma_f32_16x16x32_bf16 v[72:75], v[104:107], v[198:201], v[72:75]
	v_mfma_f32_16x16x32_bf16 v[68:71], v[144:147], v[198:201], v[68:71]
	s_barrier
	s_setprio 0
	s_add_u32 s0, s42, 0x40000
	s_addc_u32 s1, s43, 0
	s_add_i32 s34, s34, s53
	s_mov_b32 m0, s34
	s_nop 0
	global_load_lds_dwordx4 v26, s[0:1]
	s_add_i32 m0, s34, 0x2000
	s_nop 0
	global_load_lds_dwordx4 v160, s[0:1]
	v_add_u32_e32 v144, 0x18000, v222
	ds_read_b128 v[100:103], v144
	ds_read_b128 v[104:107], v144 offset:1024
	ds_read_b128 v[140:143], v144 offset:2048
	ds_read_b128 v[144:147], v144 offset:3072
	s_waitcnt vmcnt(10)
	s_setprio 1
	s_barrier
	v_mfma_f32_16x16x32_bf16 v[32:35], v[202:205], v[148:151], v[32:35]
	v_mfma_f32_16x16x32_bf16 v[28:31], v[210:213], v[148:151], v[28:31]
	v_mfma_f32_16x16x32_bf16 v[22:25], v[202:205], v[178:181], v[22:25]
	v_mfma_f32_16x16x32_bf16 v[18:21], v[210:213], v[178:181], v[18:21]
	v_mfma_f32_16x16x32_bf16 v[14:17], v[202:205], v[186:189], v[14:17]
	v_mfma_f32_16x16x32_bf16 v[10:13], v[210:213], v[186:189], v[10:13]
	v_mfma_f32_16x16x32_bf16 v[6:9], v[202:205], v[194:197], v[6:9]
	v_mfma_f32_16x16x32_bf16 v[2:5], v[210:213], v[194:197], v[2:5]
	v_mfma_f32_16x16x32_bf16 v[32:35], v[206:209], v[152:155], v[32:35]
	v_mfma_f32_16x16x32_bf16 v[28:31], v[214:217], v[152:155], v[28:31]
	v_mfma_f32_16x16x32_bf16 v[22:25], v[206:209], v[182:185], v[22:25]
	v_mfma_f32_16x16x32_bf16 v[18:21], v[214:217], v[182:185], v[18:21]
	v_mfma_f32_16x16x32_bf16 v[14:17], v[206:209], v[190:193], v[14:17]
	v_mfma_f32_16x16x32_bf16 v[10:13], v[214:217], v[190:193], v[10:13]
	v_mfma_f32_16x16x32_bf16 v[6:9], v[206:209], v[198:201], v[6:9]
	v_mfma_f32_16x16x32_bf16 v[2:5], v[214:217], v[198:201], v[2:5]
	s_barrier
	s_setprio 0
	s_add_i32 s34, 0, 0x18000
	s_add_u32 s0, s46, 0x140000
	s_addc_u32 s1, s47, 0
	s_mov_b32 m0, s56
	ds_read_b128 v[148:151], v224 offset:32768
	ds_read_b128 v[152:155], v224 offset:33792
	ds_read_b128 v[178:181], v224 offset:34816
	ds_read_b128 v[182:185], v224 offset:35840
	ds_read_b128 v[186:189], v224 offset:36864
	ds_read_b128 v[190:193], v224 offset:37888
	ds_read_b128 v[194:197], v224 offset:38912
	ds_read_b128 v[198:201], v224 offset:39936
	global_load_lds_dwordx4 v156, s[0:1]
	s_mov_b32 m0, s57
	s_nop 0
	global_load_lds_dwordx4 v158, s[0:1]
	s_waitcnt vmcnt(10) lgkmcnt(8)
	s_setprio 1
	s_barrier
	s_waitcnt lgkmcnt(0)
	v_mfma_f32_16x16x32_bf16 v[136:139], v[100:103], v[148:151], v[136:139]
	v_mfma_f32_16x16x32_bf16 v[132:135], v[140:143], v[148:151], v[132:135]
	v_mfma_f32_16x16x32_bf16 v[128:131], v[100:103], v[178:181], v[128:131]
	v_mfma_f32_16x16x32_bf16 v[124:127], v[140:143], v[178:181], v[124:127]
	v_mfma_f32_16x16x32_bf16 v[120:123], v[100:103], v[186:189], v[120:123]
	v_mfma_f32_16x16x32_bf16 v[116:119], v[140:143], v[186:189], v[116:119]
	v_mfma_f32_16x16x32_bf16 v[112:115], v[100:103], v[194:197], v[112:115]
	v_mfma_f32_16x16x32_bf16 v[108:111], v[140:143], v[194:197], v[108:111]
	v_mfma_f32_16x16x32_bf16 v[136:139], v[104:107], v[152:155], v[136:139]
	v_mfma_f32_16x16x32_bf16 v[132:135], v[144:147], v[152:155], v[132:135]
	v_mfma_f32_16x16x32_bf16 v[128:131], v[104:107], v[182:185], v[128:131]
	v_mfma_f32_16x16x32_bf16 v[124:127], v[144:147], v[182:185], v[124:127]
	v_mfma_f32_16x16x32_bf16 v[120:123], v[104:107], v[190:193], v[120:123]
	v_mfma_f32_16x16x32_bf16 v[116:119], v[144:147], v[190:193], v[116:119]
	v_mfma_f32_16x16x32_bf16 v[112:115], v[104:107], v[198:201], v[112:115]
	v_mfma_f32_16x16x32_bf16 v[108:111], v[144:147], v[198:201], v[108:111]
	s_barrier
	s_setprio 0
	s_add_i32 s35, 0, 0x1c000
	s_add_i32 s0, s34, s53
	v_add_u32_e32 v214, s35, v222
	v_lshl_add_u64 v[166:167], v[166:167], 0, s[12:13]
	s_mov_b32 m0, s0
	ds_read_b128 v[202:205], v214
	ds_read_b128 v[206:209], v214 offset:1024
	ds_read_b128 v[210:213], v214 offset:2048
	ds_read_b128 v[214:217], v214 offset:3072
	global_load_lds_dwordx4 v[166:167], off
	v_lshl_add_u64 v[166:167], v[168:169], 0, s[12:13]
	s_add_i32 m0, s0, 0x2000
	s_nop 0
	global_load_lds_dwordx4 v[166:167], off
	s_waitcnt vmcnt(10)
	s_setprio 1
	s_barrier
	s_waitcnt lgkmcnt(0)
	v_mfma_f32_16x16x32_bf16 v[64:67], v[202:205], v[148:151], v[64:67]
	v_mfma_f32_16x16x32_bf16 v[60:63], v[210:213], v[148:151], v[60:63]
	v_mfma_f32_16x16x32_bf16 v[56:59], v[202:205], v[178:181], v[56:59]
	v_mfma_f32_16x16x32_bf16 v[52:55], v[210:213], v[178:181], v[52:55]
	v_mfma_f32_16x16x32_bf16 v[48:51], v[202:205], v[186:189], v[48:51]
	v_mfma_f32_16x16x32_bf16 v[44:47], v[210:213], v[186:189], v[44:47]
	v_mfma_f32_16x16x32_bf16 v[40:43], v[202:205], v[194:197], v[40:43]
	v_mfma_f32_16x16x32_bf16 v[36:39], v[210:213], v[194:197], v[36:39]
	v_mfma_f32_16x16x32_bf16 v[64:67], v[206:209], v[152:155], v[64:67]
	v_mfma_f32_16x16x32_bf16 v[60:63], v[214:217], v[152:155], v[60:63]
	v_mfma_f32_16x16x32_bf16 v[56:59], v[206:209], v[182:185], v[56:59]
	v_mfma_f32_16x16x32_bf16 v[52:55], v[214:217], v[182:185], v[52:55]
	v_mfma_f32_16x16x32_bf16 v[48:51], v[206:209], v[190:193], v[48:51]
	v_mfma_f32_16x16x32_bf16 v[44:47], v[214:217], v[190:193], v[44:47]
	v_mfma_f32_16x16x32_bf16 v[40:43], v[206:209], v[198:201], v[40:43]
	v_mfma_f32_16x16x32_bf16 v[36:39], v[214:217], v[198:201], v[36:39]
	s_barrier
	s_setprio 0
	s_mov_b32 m0, s81
	v_lshl_add_u64 v[166:167], v[218:219], 0, s[12:13]
	ds_read_b128 v[148:151], v224 offset:49152
	ds_read_b128 v[152:155], v224 offset:50176
	ds_read_b128 v[178:181], v224 offset:51200
	ds_read_b128 v[182:185], v224 offset:52224
	ds_read_b128 v[186:189], v224 offset:53248
	ds_read_b128 v[190:193], v224 offset:54272
	ds_read_b128 v[194:197], v224 offset:55296
	ds_read_b128 v[198:201], v224 offset:56320
	global_load_lds_dwordx4 v[166:167], off
	v_lshl_add_u64 v[166:167], v[220:221], 0, s[12:13]
	s_mov_b32 m0, s17
	s_nop 0
	global_load_lds_dwordx4 v[166:167], off
	s_waitcnt vmcnt(10)
	s_setprio 1
	s_barrier
	s_waitcnt lgkmcnt(0)
	v_mfma_f32_16x16x32_bf16 v[96:99], v[100:103], v[148:151], v[96:99]
	v_mfma_f32_16x16x32_bf16 v[92:95], v[140:143], v[148:151], v[92:95]
	v_mfma_f32_16x16x32_bf16 v[88:91], v[100:103], v[178:181], v[88:91]
	v_mfma_f32_16x16x32_bf16 v[84:87], v[140:143], v[178:181], v[84:87]
	v_mfma_f32_16x16x32_bf16 v[80:83], v[100:103], v[186:189], v[80:83]
	v_mfma_f32_16x16x32_bf16 v[76:79], v[140:143], v[186:189], v[76:79]
	v_mfma_f32_16x16x32_bf16 v[72:75], v[100:103], v[194:197], v[72:75]
	v_mfma_f32_16x16x32_bf16 v[68:71], v[140:143], v[194:197], v[68:71]
	v_mfma_f32_16x16x32_bf16 v[96:99], v[104:107], v[152:155], v[96:99]
	v_mfma_f32_16x16x32_bf16 v[92:95], v[144:147], v[152:155], v[92:95]
	v_mfma_f32_16x16x32_bf16 v[88:91], v[104:107], v[182:185], v[88:91]
	v_mfma_f32_16x16x32_bf16 v[84:87], v[144:147], v[182:185], v[84:87]
	v_mfma_f32_16x16x32_bf16 v[80:83], v[104:107], v[190:193], v[80:83]
	v_mfma_f32_16x16x32_bf16 v[76:79], v[144:147], v[190:193], v[76:79]
	v_mfma_f32_16x16x32_bf16 v[72:75], v[104:107], v[198:201], v[72:75]
	v_mfma_f32_16x16x32_bf16 v[68:71], v[144:147], v[198:201], v[68:71]
	s_barrier
	s_setprio 0
	s_add_u32 s0, s42, 0x40080
	s_addc_u32 s1, s43, 0
	s_add_i32 s34, s35, s53
	s_mov_b32 m0, s34
	s_nop 0
	global_load_lds_dwordx4 v26, s[0:1]
	s_add_i32 m0, s34, 0x2000
	s_nop 0
	global_load_lds_dwordx4 v160, s[0:1]
	v_add_u32_e32 v144, 0x10000, v222
	ds_read_b128 v[100:103], v144
	ds_read_b128 v[104:107], v144 offset:1024
	ds_read_b128 v[140:143], v144 offset:2048
	ds_read_b128 v[144:147], v144 offset:3072
	s_add_i32 s31, s31, 2
	s_add_u32 s23, s23, 0x100
	s_addc_u32 s29, s29, 0
	s_mov_b64 s[34:35], s[36:37]
	s_cmp_gt_u32 s31, 13
	s_cbranch_scc1 .Lth__965
	s_add_u32 s36, s34, 0x100
	s_addc_u32 s37, s35, 0
	s_add_i32 s0, 0, 0x10000
	s_cmp_eq_u32 s31, 12
	s_cselect_b32 s47, s25, s37
	s_cselect_b32 s46, s24, s36
	s_cselect_b32 s43, s18, s29
	s_cselect_b32 s42, s19, s23
	s_cmp_gt_u32 s31, 13
.Lth__965:
	s_waitcnt vmcnt(10)
	s_setprio 1
	s_barrier
	v_mfma_f32_16x16x32_bf16 v[32:35], v[202:205], v[148:151], v[32:35]
	v_mfma_f32_16x16x32_bf16 v[28:31], v[210:213], v[148:151], v[28:31]
	v_mfma_f32_16x16x32_bf16 v[22:25], v[202:205], v[178:181], v[22:25]
	v_mfma_f32_16x16x32_bf16 v[18:21], v[210:213], v[178:181], v[18:21]
	v_mfma_f32_16x16x32_bf16 v[14:17], v[202:205], v[186:189], v[14:17]
	v_mfma_f32_16x16x32_bf16 v[10:13], v[210:213], v[186:189], v[10:13]
	v_mfma_f32_16x16x32_bf16 v[6:9], v[202:205], v[194:197], v[6:9]
	v_mfma_f32_16x16x32_bf16 v[2:5], v[210:213], v[194:197], v[2:5]
	v_mfma_f32_16x16x32_bf16 v[32:35], v[206:209], v[152:155], v[32:35]
	v_mfma_f32_16x16x32_bf16 v[28:31], v[214:217], v[152:155], v[28:31]
	v_mfma_f32_16x16x32_bf16 v[22:25], v[206:209], v[182:185], v[22:25]
	v_mfma_f32_16x16x32_bf16 v[18:21], v[214:217], v[182:185], v[18:21]
	v_mfma_f32_16x16x32_bf16 v[14:17], v[206:209], v[190:193], v[14:17]
	v_mfma_f32_16x16x32_bf16 v[10:13], v[214:217], v[190:193], v[10:13]
	v_mfma_f32_16x16x32_bf16 v[6:9], v[206:209], v[198:201], v[6:9]
	v_mfma_f32_16x16x32_bf16 v[2:5], v[214:217], v[198:201], v[2:5]
	s_barrier
	s_setprio 0
	s_cbranch_scc0 .LBB0_965
	s_waitcnt lgkmcnt(0)
	s_min_i32 s0, s28, 0x100
	s_ashr_i32 s0, s0, 5
	s_ashr_i32 s1, s0, 31
	s_add_i32 s18, s28, 0xffffff00
	s_cmpk_lt_i32 s28, 0x100
	s_cselect_b32 s18, s28, s18
	s_cselect_b32 s23, 0, s59
	s_cselect_b32 s29, 0, s58
	s_ashr_i32 s19, s18, 31
	s_lshl_b64 s[18:19], s[18:19], 19
	v_lshl_or_b32 v148, s30, 8, v223
	s_add_u32 s30, s44, s29
	s_addc_u32 s31, s45, s23
	s_ashr_i32 s29, s28, 31
	v_lshl_add_u64 v[100:101], s[18:19], 0, v[162:163]
	s_lshl_b64 s[18:19], s[28:29], 19
	v_lshl_add_u64 v[152:153], v[164:165], 0, s[18:19]
	s_lshl_b64 s[28:29], s[28:29], 10
	s_mul_i32 s18, s0, 0x9000
	s_mul_hi_i32 s19, s0, 0x9000
	s_add_u32 s18, s68, s18
	s_addc_u32 s19, s69, s19
	s_lshl_b64 s[0:1], s[0:1], 12
	v_ashrrev_i32_e32 v149, 31, v148
	s_add_u32 s0, s72, s0
	v_lshlrev_b64 v[154:155], 2, v[148:149]
	s_addc_u32 s1, s73, s1
	v_lshl_add_u64 v[150:151], v[100:101], 0, v[148:149]
	v_lshl_add_u64 v[104:105], s[18:19], 0, v[154:155]
	v_lshlrev_b64 v[168:169], 1, v[148:149]
	v_lshl_add_u64 v[180:181], s[0:1], 0, v[154:155]
	v_lshl_add_u64 v[166:167], v[100:101], 1, s[30:31]
	global_load_dwordx4 v[140:143], v[104:105], off offset:16
	global_load_dwordx4 v[144:147], v[104:105], off
	global_load_dwordx4 v[100:103], v[104:105], off offset:528
	s_nop 0
	global_load_dwordx4 v[104:107], v[104:105], off offset:512
	v_lshl_add_u64 v[196:197], v[150:151], 1, s[30:31]
	v_lshl_add_u64 v[178:179], v[152:153], 0, v[168:169]
	global_load_dwordx4 v[148:151], v[180:181], off offset:16
	global_load_dwordx4 v[152:155], v[180:181], off
	global_load_dwordx4 v[190:193], v[196:197], off offset:2048
	v_add_co_u32_e32 v210, vcc, s65, v196
	s_mov_b32 s1, 0x20000
	s_nop 0
	v_addc_co_u32_e32 v211, vcc, 0, v197, vcc
	global_load_dwordx4 v[198:201], v[210:211], off offset:2048
	v_add_co_u32_e32 v184, vcc, s1, v196
	s_mov_b32 s18, 0x30000
	s_nop 0
	v_addc_co_u32_e32 v185, vcc, 0, v197, vcc
	global_load_dwordx4 v[202:205], v[184:185], off offset:2048
	v_add_co_u32_e32 v188, vcc, s18, v196
	v_lshl_add_u64 v[182:183], v[166:167], 0, v[168:169]
	s_nop 0
	v_addc_co_u32_e32 v189, vcc, 0, v197, vcc
	global_load_dwordx4 v[206:209], v[188:189], off offset:2048
	s_mov_b32 s0, 0x8000
	s_mov_b32 s19, 0x80000
	s_mov_b32 s23, 0x90000
	s_waitcnt vmcnt(0)
	v_lshlrev_b32_e32 v166, 16, v190
	v_and_b32_e32 v167, 0xffff0000, v190
	v_lshlrev_b32_e32 v168, 16, v191
	v_and_b32_e32 v169, 0xffff0000, v191
	v_lshlrev_b32_e32 v186, 16, v192
	v_and_b32_e32 v187, 0xffff0000, v192
	v_lshlrev_b32_e32 v190, 16, v193
	v_and_b32_e32 v191, 0xffff0000, v193
	v_pk_fma_f32 v[138:139], v[138:139], v[146:147], v[168:169]
	v_pk_fma_f32 v[136:137], v[136:137], v[144:145], v[166:167]
	v_pk_fma_f32 v[134:135], v[134:135], v[142:143], v[190:191]
	v_pk_fma_f32 v[132:133], v[132:133], v[140:141], v[186:187]
	v_cvt_pk_bf16_f32 v190, v136, v137
	v_cvt_pk_bf16_f32 v191, v138, v139
	v_cvt_pk_bf16_f32 v192, v132, v133
	v_cvt_pk_bf16_f32 v193, v134, v135
	v_lshlrev_b32_e32 v138, 16, v190
	v_and_b32_e32 v139, 0xffff0000, v190
	v_lshlrev_b32_e32 v136, 16, v191
	v_and_b32_e32 v137, 0xffff0000, v191
	v_lshlrev_b32_e32 v134, 16, v192
	v_and_b32_e32 v135, 0xffff0000, v192
	v_lshlrev_b32_e32 v132, 16, v193
	v_and_b32_e32 v133, 0xffff0000, v193
	v_lshlrev_b32_e32 v212, 16, v200
	v_and_b32_e32 v213, 0xffff0000, v200
	v_lshlrev_b32_e32 v200, 16, v201
	v_and_b32_e32 v201, 0xffff0000, v201
	global_store_dwordx4 v[182:183], v[190:193], off offset:2048
	v_pk_mul_f32 v[166:167], v[154:155], v[136:137]
	v_pk_mul_f32 v[168:169], v[152:153], v[138:139]
	v_pk_mul_f32 v[186:187], v[150:151], v[132:133]
	v_pk_mul_f32 v[192:193], v[148:149], v[134:135]
	v_lshlrev_b32_e32 v194, 16, v198
	v_and_b32_e32 v195, 0xffff0000, v198
	v_lshlrev_b32_e32 v198, 16, v199
	v_and_b32_e32 v199, 0xffff0000, v199
	v_cvt_pk_bf16_f32 v190, v168, v169
	v_cvt_pk_bf16_f32 v191, v166, v167
	v_cvt_pk_bf16_f32 v192, v192, v193
	v_cvt_pk_bf16_f32 v193, v186, v187
	v_pk_fma_f32 v[126:127], v[126:127], v[142:143], v[200:201]
	v_pk_fma_f32 v[124:125], v[124:125], v[140:141], v[212:213]
	global_store_dwordx4 v[178:179], v[190:193], off
	v_pk_fma_f32 v[130:131], v[130:131], v[146:147], v[198:199]
	v_pk_fma_f32 v[128:129], v[128:129], v[144:145], v[194:195]
	v_cvt_pk_bf16_f32 v192, v124, v125
	v_cvt_pk_bf16_f32 v193, v126, v127
	v_add_co_u32_e32 v186, vcc, s65, v182
	v_cvt_pk_bf16_f32 v190, v128, v129
	v_cvt_pk_bf16_f32 v191, v130, v131
	v_addc_co_u32_e32 v187, vcc, 0, v183, vcc
	v_lshlrev_b32_e32 v126, 16, v192
	v_and_b32_e32 v127, 0xffff0000, v192
	v_lshlrev_b32_e32 v124, 16, v193
	v_and_b32_e32 v125, 0xffff0000, v193
	global_store_dwordx4 v[186:187], v[190:193], off offset:2048
	v_lshlrev_b32_e32 v130, 16, v190
	v_and_b32_e32 v131, 0xffff0000, v190
	v_lshlrev_b32_e32 v128, 16, v191
	v_and_b32_e32 v129, 0xffff0000, v191
	v_pk_mul_f32 v[190:191], v[150:151], v[124:125]
	v_pk_mul_f32 v[194:195], v[148:149], v[126:127]
	v_pk_mul_f32 v[166:167], v[154:155], v[128:129]
	v_pk_mul_f32 v[168:169], v[152:153], v[130:131]
	v_cvt_pk_bf16_f32 v194, v194, v195
	v_cvt_pk_bf16_f32 v195, v190, v191
	v_add_co_u32_e32 v190, vcc, s0, v178
	v_cvt_pk_bf16_f32 v192, v168, v169
	v_cvt_pk_bf16_f32 v193, v166, v167
	v_addc_co_u32_e32 v191, vcc, 0, v179, vcc
	global_store_dwordx4 v[190:191], v[192:195], off
	v_lshlrev_b32_e32 v198, 16, v204
	v_and_b32_e32 v199, 0xffff0000, v204
	v_add_co_u32_e32 v192, vcc, s19, v196
	v_lshlrev_b32_e32 v200, 16, v205
	s_nop 0
	v_addc_co_u32_e32 v193, vcc, 0, v197, vcc
	v_add_co_u32_e32 v194, vcc, s23, v196
	v_and_b32_e32 v201, 0xffff0000, v205
	global_load_dwordx4 v[212:215], v[192:193], off offset:2048
	v_addc_co_u32_e32 v195, vcc, 0, v197, vcc
	v_lshlrev_b32_e32 v166, 16, v202
	v_and_b32_e32 v167, 0xffff0000, v202
	v_lshlrev_b32_e32 v168, 16, v203
	v_and_b32_e32 v169, 0xffff0000, v203
	v_pk_fma_f32 v[118:119], v[118:119], v[142:143], v[200:201]
	v_pk_fma_f32 v[116:117], v[116:117], v[140:141], v[198:199]
	v_pk_fma_f32 v[122:123], v[122:123], v[146:147], v[168:169]
	v_pk_fma_f32 v[120:121], v[120:121], v[144:145], v[166:167]
	v_cvt_pk_bf16_f32 v202, v116, v117
	v_cvt_pk_bf16_f32 v203, v118, v119
	v_add_co_u32_e32 v198, vcc, s1, v182
	global_load_dwordx4 v[216:219], v[194:195], off offset:2048
	v_cvt_pk_bf16_f32 v200, v120, v121
	v_cvt_pk_bf16_f32 v201, v122, v123
	v_addc_co_u32_e32 v199, vcc, 0, v183, vcc
	v_lshlrev_b32_e32 v118, 16, v202
	v_and_b32_e32 v119, 0xffff0000, v202
	v_lshlrev_b32_e32 v116, 16, v203
	v_and_b32_e32 v117, 0xffff0000, v203
	global_store_dwordx4 v[198:199], v[200:203], off offset:2048
	v_lshlrev_b32_e32 v122, 16, v200
	v_and_b32_e32 v123, 0xffff0000, v200
	v_lshlrev_b32_e32 v120, 16, v201
	v_and_b32_e32 v121, 0xffff0000, v201
	v_pk_mul_f32 v[200:201], v[150:151], v[116:117]
	v_pk_mul_f32 v[204:205], v[148:149], v[118:119]
	v_lshlrev_b32_e32 v234, 16, v208
	v_and_b32_e32 v235, 0xffff0000, v208
	v_lshlrev_b32_e32 v208, 16, v209
	v_and_b32_e32 v209, 0xffff0000, v209
	v_pk_mul_f32 v[166:167], v[154:155], v[120:121]
	v_pk_mul_f32 v[168:169], v[152:153], v[122:123]
	v_cvt_pk_bf16_f32 v204, v204, v205
	v_cvt_pk_bf16_f32 v205, v200, v201
	v_add_co_u32_e32 v200, vcc, s65, v178
	v_lshlrev_b32_e32 v220, 16, v206
	v_and_b32_e32 v221, 0xffff0000, v206
	v_lshlrev_b32_e32 v206, 16, v207
	v_and_b32_e32 v207, 0xffff0000, v207
	v_cvt_pk_bf16_f32 v202, v168, v169
	v_cvt_pk_bf16_f32 v203, v166, v167
	v_addc_co_u32_e32 v201, vcc, 0, v179, vcc
	v_pk_fma_f32 v[110:111], v[110:111], v[142:143], v[208:209]
	v_pk_fma_f32 v[108:109], v[108:109], v[140:141], v[234:235]
	global_store_dwordx4 v[200:201], v[202:205], off
	v_pk_fma_f32 v[114:115], v[114:115], v[146:147], v[206:207]
	v_pk_fma_f32 v[112:113], v[112:113], v[144:145], v[220:221]
	v_cvt_pk_bf16_f32 v206, v108, v109
	v_cvt_pk_bf16_f32 v207, v110, v111
	v_add_co_u32_e32 v202, vcc, s18, v182
	v_cvt_pk_bf16_f32 v204, v112, v113
	v_cvt_pk_bf16_f32 v205, v114, v115
	v_addc_co_u32_e32 v203, vcc, 0, v183, vcc
	v_lshlrev_b32_e32 v110, 16, v206
	v_and_b32_e32 v111, 0xffff0000, v206
	v_lshlrev_b32_e32 v108, 16, v207
	v_and_b32_e32 v109, 0xffff0000, v207
	global_store_dwordx4 v[202:203], v[204:207], off offset:2048
	v_lshlrev_b32_e32 v114, 16, v204
	v_and_b32_e32 v115, 0xffff0000, v204
	v_lshlrev_b32_e32 v112, 16, v205
	v_and_b32_e32 v113, 0xffff0000, v205
	v_pk_mul_f32 v[204:205], v[150:151], v[108:109]
	v_pk_mul_f32 v[208:209], v[148:149], v[110:111]
	s_mov_b32 s0, 0x18000
	v_pk_mul_f32 v[166:167], v[154:155], v[112:113]
	v_pk_mul_f32 v[168:169], v[152:153], v[114:115]
	v_cvt_pk_bf16_f32 v208, v208, v209
	v_cvt_pk_bf16_f32 v209, v204, v205
	v_add_co_u32_e32 v204, vcc, s0, v178
	v_cvt_pk_bf16_f32 v206, v168, v169
	v_cvt_pk_bf16_f32 v207, v166, v167
	v_addc_co_u32_e32 v205, vcc, 0, v179, vcc
	global_store_dwordx4 v[204:205], v[206:209], off
	s_mov_b32 s0, 0xb0000
	s_waitcnt vmcnt(0)
	v_lshlrev_b32_e32 v166, 16, v212
	v_add_co_u32_e32 v206, vcc, s76, v196
	v_and_b32_e32 v167, 0xffff0000, v212
	s_nop 0
	v_addc_co_u32_e32 v207, vcc, 0, v197, vcc
	global_load_dwordx4 v[238:241], v[206:207], off offset:2048
	v_add_co_u32_e32 v208, vcc, s0, v196
	v_lshlrev_b32_e32 v168, 16, v213
	s_nop 0
	v_addc_co_u32_e32 v209, vcc, 0, v197, vcc
	global_load_dwordx4 v[242:245], v[208:209], off offset:2048
	v_and_b32_e32 v169, 0xffff0000, v213
	v_lshlrev_b32_e32 v212, 16, v214
	v_and_b32_e32 v213, 0xffff0000, v214
	v_lshlrev_b32_e32 v214, 16, v215
	v_and_b32_e32 v215, 0xffff0000, v215
	v_pk_fma_f32 v[94:95], v[94:95], v[142:143], v[214:215]
	v_pk_fma_f32 v[92:93], v[92:93], v[140:141], v[212:213]
	v_lshlrev_b32_e32 v220, 16, v216
	v_and_b32_e32 v221, 0xffff0000, v216
	v_lshlrev_b32_e32 v234, 16, v217
	v_and_b32_e32 v235, 0xffff0000, v217
	v_pk_fma_f32 v[98:99], v[98:99], v[146:147], v[168:169]
	v_pk_fma_f32 v[96:97], v[96:97], v[144:145], v[166:167]
	v_cvt_pk_bf16_f32 v216, v92, v93
	v_cvt_pk_bf16_f32 v217, v94, v95
	v_add_co_u32_e32 v212, vcc, s19, v182
	v_cvt_pk_bf16_f32 v214, v96, v97
	v_cvt_pk_bf16_f32 v215, v98, v99
	v_addc_co_u32_e32 v213, vcc, 0, v183, vcc
	v_lshlrev_b32_e32 v94, 16, v216
	v_and_b32_e32 v95, 0xffff0000, v216
	v_lshlrev_b32_e32 v92, 16, v217
	v_and_b32_e32 v93, 0xffff0000, v217
	v_lshlrev_b32_e32 v246, 16, v218
	v_and_b32_e32 v247, 0xffff0000, v218
	v_lshlrev_b32_e32 v248, 16, v219
	v_and_b32_e32 v249, 0xffff0000, v219
	global_store_dwordx4 v[212:213], v[214:217], off offset:2048
	v_lshlrev_b32_e32 v98, 16, v214
	v_and_b32_e32 v99, 0xffff0000, v214
	v_lshlrev_b32_e32 v96, 16, v215
	v_and_b32_e32 v97, 0xffff0000, v215
	v_pk_mul_f32 v[214:215], v[150:151], v[92:93]
	v_pk_mul_f32 v[218:219], v[148:149], v[94:95]
	s_mov_b32 s1, 0x40000
	v_pk_mul_f32 v[166:167], v[154:155], v[96:97]
	v_pk_mul_f32 v[168:169], v[152:153], v[98:99]
	v_cvt_pk_bf16_f32 v218, v218, v219
	v_cvt_pk_bf16_f32 v219, v214, v215
	v_add_co_u32_e32 v214, vcc, s1, v178
	v_cvt_pk_bf16_f32 v216, v168, v169
	v_cvt_pk_bf16_f32 v217, v166, v167
	v_addc_co_u32_e32 v215, vcc, 0, v179, vcc
	v_pk_fma_f32 v[86:87], v[86:87], v[142:143], v[248:249]
	global_store_dwordx4 v[214:215], v[216:219], off
	v_pk_fma_f32 v[90:91], v[90:91], v[146:147], v[234:235]
	v_pk_fma_f32 v[88:89], v[88:89], v[144:145], v[220:221]
	v_pk_fma_f32 v[84:85], v[84:85], v[140:141], v[246:247]
	v_cvt_pk_bf16_f32 v221, v86, v87
	v_add_co_u32_e32 v216, vcc, s23, v182
	v_cvt_pk_bf16_f32 v218, v88, v89
	v_cvt_pk_bf16_f32 v219, v90, v91
	v_cvt_pk_bf16_f32 v220, v84, v85
	v_addc_co_u32_e32 v217, vcc, 0, v183, vcc
	v_lshlrev_b32_e32 v84, 16, v221
	v_and_b32_e32 v85, 0xffff0000, v221
	global_store_dwordx4 v[216:217], v[218:221], off offset:2048
	v_lshlrev_b32_e32 v90, 16, v218
	v_and_b32_e32 v91, 0xffff0000, v218
	v_lshlrev_b32_e32 v88, 16, v219
	v_and_b32_e32 v89, 0xffff0000, v219
	v_lshlrev_b32_e32 v86, 16, v220
	v_and_b32_e32 v87, 0xffff0000, v220
	v_pk_mul_f32 v[218:219], v[150:151], v[84:85]
	s_mov_b32 s1, 0x48000
	v_pk_mul_f32 v[166:167], v[154:155], v[88:89]
	v_pk_mul_f32 v[168:169], v[152:153], v[90:91]
	v_pk_mul_f32 v[220:221], v[148:149], v[86:87]
	v_cvt_pk_bf16_f32 v249, v218, v219
	v_add_co_u32_e32 v218, vcc, s1, v178
	v_cvt_pk_bf16_f32 v246, v168, v169
	v_cvt_pk_bf16_f32 v247, v166, v167
	v_cvt_pk_bf16_f32 v248, v220, v221
	v_addc_co_u32_e32 v219, vcc, 0, v179, vcc
	global_store_dwordx4 v[218:219], v[246:249], off
	global_load_dwordx4 v[246:249], v[196:197], off offset:2304
	s_nop 0
	global_load_dwordx4 v[250:253], v[210:211], off offset:2304
	s_waitcnt vmcnt(0)
	v_lshlrev_b32_e32 v196, 16, v240
	v_and_b32_e32 v197, 0xffff0000, v240
	v_lshlrev_b32_e32 v210, 16, v241
	v_and_b32_e32 v211, 0xffff0000, v241
	v_lshlrev_b32_e32 v166, 16, v238
	v_and_b32_e32 v167, 0xffff0000, v238
	v_lshlrev_b32_e32 v168, 16, v239
	v_and_b32_e32 v169, 0xffff0000, v239
	v_pk_fma_f32 v[78:79], v[78:79], v[142:143], v[210:211]
	v_pk_fma_f32 v[76:77], v[76:77], v[140:141], v[196:197]
	v_pk_fma_f32 v[82:83], v[82:83], v[146:147], v[168:169]
	v_pk_fma_f32 v[80:81], v[80:81], v[144:145], v[166:167]
	v_cvt_pk_bf16_f32 v240, v76, v77
	v_cvt_pk_bf16_f32 v241, v78, v79
	v_add_co_u32_e32 v196, vcc, s76, v182
	v_cvt_pk_bf16_f32 v238, v80, v81
	v_cvt_pk_bf16_f32 v239, v82, v83
	v_addc_co_u32_e32 v197, vcc, 0, v183, vcc
	v_lshlrev_b32_e32 v78, 16, v240
	v_and_b32_e32 v79, 0xffff0000, v240
	v_lshlrev_b32_e32 v76, 16, v241
	v_and_b32_e32 v77, 0xffff0000, v241
	global_store_dwordx4 v[196:197], v[238:241], off offset:2048
	v_pk_mul_f32 v[210:211], v[150:151], v[76:77]
	v_lshlrev_b32_e32 v220, 16, v242
	v_pk_mul_f32 v[240:241], v[148:149], v[78:79]
	v_and_b32_e32 v221, 0xffff0000, v242
	v_lshlrev_b32_e32 v234, 16, v243
	v_and_b32_e32 v235, 0xffff0000, v243
	v_lshlrev_b32_e32 v242, 16, v244
	v_and_b32_e32 v243, 0xffff0000, v244
	v_lshlrev_b32_e32 v244, 16, v245
	v_and_b32_e32 v245, 0xffff0000, v245
	v_cvt_pk_bf16_f32 v240, v240, v241
	v_cvt_pk_bf16_f32 v241, v210, v211
	v_add_co_u32_e32 v210, vcc, s77, v178
	v_lshlrev_b32_e32 v82, 16, v238
	v_and_b32_e32 v83, 0xffff0000, v238
	v_lshlrev_b32_e32 v80, 16, v239
	v_and_b32_e32 v81, 0xffff0000, v239
	v_addc_co_u32_e32 v211, vcc, 0, v179, vcc
	v_pk_fma_f32 v[74:75], v[74:75], v[146:147], v[234:235]
	v_pk_fma_f32 v[72:73], v[72:73], v[144:145], v[220:221]
	v_pk_fma_f32 v[142:143], v[70:71], v[142:143], v[244:245]
	v_pk_fma_f32 v[70:71], v[68:69], v[140:141], v[242:243]
	v_pk_mul_f32 v[166:167], v[154:155], v[80:81]
	v_pk_mul_f32 v[168:169], v[152:153], v[82:83]
	v_cvt_pk_bf16_f32 v68, v72, v73
	v_cvt_pk_bf16_f32 v69, v74, v75
	v_cvt_pk_bf16_f32 v70, v70, v71
	v_cvt_pk_bf16_f32 v71, v142, v143
	v_add_co_u32_e32 v220, vcc, s0, v182
	v_cvt_pk_bf16_f32 v238, v168, v169
	v_cvt_pk_bf16_f32 v239, v166, v167
	v_addc_co_u32_e32 v221, vcc, 0, v183, vcc
	v_lshlrev_b32_e32 v146, 16, v68
	v_and_b32_e32 v147, 0xffff0000, v68
	v_lshlrev_b32_e32 v144, 16, v69
	v_and_b32_e32 v145, 0xffff0000, v69
	v_lshlrev_b32_e32 v142, 16, v70
	v_and_b32_e32 v143, 0xffff0000, v70
	v_lshlrev_b32_e32 v140, 16, v71
	v_and_b32_e32 v141, 0xffff0000, v71
	s_mov_b32 s0, 0x58000
	global_store_dwordx4 v[210:211], v[238:241], off
	global_store_dwordx4 v[220:221], v[68:71], off offset:2048
	v_pk_mul_f32 v[72:73], v[150:151], v[140:141]
	v_pk_mul_f32 v[74:75], v[148:149], v[142:143]
	v_pk_mul_f32 v[70:71], v[154:155], v[144:145]
	v_pk_mul_f32 v[68:69], v[152:153], v[146:147]
	v_add_co_u32_e32 v148, vcc, s0, v178
	v_cvt_pk_bf16_f32 v68, v68, v69
	v_cvt_pk_bf16_f32 v69, v70, v71
	v_cvt_pk_bf16_f32 v70, v74, v75
	v_cvt_pk_bf16_f32 v71, v72, v73
	v_addc_co_u32_e32 v149, vcc, 0, v179, vcc
	global_store_dwordx4 v[148:149], v[68:71], off
	global_load_dwordx4 v[150:153], v[184:185], off offset:2304
	global_load_dwordx4 v[238:241], v[188:189], off offset:2304
	s_nop 0
	global_load_dwordx4 v[68:71], v[180:181], off offset:528
	global_load_dwordx4 v[72:75], v[180:181], off offset:512
	v_lshlrev_b32_e32 v154, 16, v246
	v_and_b32_e32 v155, 0xffff0000, v246
	v_lshlrev_b32_e32 v166, 16, v247
	v_and_b32_e32 v167, 0xffff0000, v247
	v_lshlrev_b32_e32 v168, 16, v248
	v_and_b32_e32 v169, 0xffff0000, v248
	v_lshlrev_b32_e32 v180, 16, v249
	v_and_b32_e32 v181, 0xffff0000, v249
	v_pk_fma_f32 v[66:67], v[66:67], v[106:107], v[166:167]
	v_pk_fma_f32 v[64:65], v[64:65], v[104:105], v[154:155]
	v_pk_fma_f32 v[62:63], v[62:63], v[102:103], v[180:181]
	v_pk_fma_f32 v[60:61], v[60:61], v[100:101], v[168:169]
	v_cvt_pk_bf16_f32 v242, v64, v65
	v_cvt_pk_bf16_f32 v243, v66, v67
	v_cvt_pk_bf16_f32 v244, v60, v61
	v_cvt_pk_bf16_f32 v245, v62, v63
	v_lshlrev_b32_e32 v66, 16, v242
	v_and_b32_e32 v67, 0xffff0000, v242
	v_lshlrev_b32_e32 v64, 16, v243
	v_and_b32_e32 v65, 0xffff0000, v243
	v_lshlrev_b32_e32 v62, 16, v244
	v_and_b32_e32 v63, 0xffff0000, v244
	v_lshlrev_b32_e32 v60, 16, v245
	v_and_b32_e32 v61, 0xffff0000, v245
	v_lshlrev_b32_e32 v184, 16, v250
	v_and_b32_e32 v185, 0xffff0000, v250
	v_lshlrev_b32_e32 v188, 16, v251
	v_and_b32_e32 v189, 0xffff0000, v251
	v_lshlrev_b32_e32 v234, 16, v252
	v_and_b32_e32 v235, 0xffff0000, v252
	v_lshlrev_b32_e32 v246, 16, v253
	v_and_b32_e32 v247, 0xffff0000, v253
	global_store_dwordx4 v[182:183], v[242:245], off offset:2304
	v_pk_fma_f32 v[58:59], v[58:59], v[106:107], v[188:189]
	v_pk_fma_f32 v[56:57], v[56:57], v[104:105], v[184:185]
	v_pk_fma_f32 v[54:55], v[54:55], v[102:103], v[246:247]
	v_pk_fma_f32 v[52:53], v[52:53], v[100:101], v[234:235]
	s_waitcnt vmcnt(0)
	v_lshlrev_b32_e32 v188, 16, v240
	v_pk_mul_f32 v[168:169], v[70:71], v[60:61]
	v_pk_mul_f32 v[154:155], v[74:75], v[64:65]
	v_pk_mul_f32 v[166:167], v[72:73], v[66:67]
	v_pk_mul_f32 v[182:183], v[68:69], v[62:63]
	v_cvt_pk_bf16_f32 v180, v166, v167
	v_cvt_pk_bf16_f32 v181, v154, v155
	v_cvt_pk_bf16_f32 v182, v182, v183
	v_cvt_pk_bf16_f32 v183, v168, v169
	global_store_dwordx4 v[178:179], v[180:183], off offset:256
	v_cvt_pk_bf16_f32 v178, v56, v57
	v_cvt_pk_bf16_f32 v179, v58, v59
	v_cvt_pk_bf16_f32 v180, v52, v53
	v_cvt_pk_bf16_f32 v181, v54, v55
	v_lshlrev_b32_e32 v58, 16, v178
	v_and_b32_e32 v59, 0xffff0000, v178
	v_lshlrev_b32_e32 v56, 16, v179
	v_and_b32_e32 v57, 0xffff0000, v179
	v_lshlrev_b32_e32 v54, 16, v180
	v_and_b32_e32 v55, 0xffff0000, v180
	v_lshlrev_b32_e32 v52, 16, v181
	v_and_b32_e32 v53, 0xffff0000, v181
	global_store_dwordx4 v[186:187], v[178:181], off offset:2304
	v_pk_mul_f32 v[154:155], v[74:75], v[56:57]
	v_pk_mul_f32 v[166:167], v[72:73], v[58:59]
	v_pk_mul_f32 v[168:169], v[70:71], v[52:53]
	v_pk_mul_f32 v[180:181], v[68:69], v[54:55]
	v_cvt_pk_bf16_f32 v178, v166, v167
	v_cvt_pk_bf16_f32 v179, v154, v155
	v_cvt_pk_bf16_f32 v180, v180, v181
	v_cvt_pk_bf16_f32 v181, v168, v169
	v_lshlrev_b32_e32 v154, 16, v150
	v_and_b32_e32 v155, 0xffff0000, v150
	v_lshlrev_b32_e32 v150, 16, v151
	v_and_b32_e32 v151, 0xffff0000, v151
	v_lshlrev_b32_e32 v166, 16, v152
	v_and_b32_e32 v167, 0xffff0000, v152
	v_lshlrev_b32_e32 v152, 16, v153
	v_and_b32_e32 v153, 0xffff0000, v153
	global_store_dwordx4 v[190:191], v[178:181], off offset:256
	v_pk_fma_f32 v[50:51], v[50:51], v[106:107], v[150:151]
	v_pk_fma_f32 v[48:49], v[48:49], v[104:105], v[154:155]
	v_pk_fma_f32 v[46:47], v[46:47], v[102:103], v[152:153]
	v_pk_fma_f32 v[44:45], v[44:45], v[100:101], v[166:167]
	global_load_dwordx4 v[178:181], v[192:193], off offset:2304
	global_load_dwordx4 v[182:185], v[194:195], off offset:2304
	v_cvt_pk_bf16_f32 v150, v48, v49
	v_cvt_pk_bf16_f32 v151, v50, v51
	v_cvt_pk_bf16_f32 v152, v44, v45
	v_cvt_pk_bf16_f32 v153, v46, v47
	v_lshlrev_b32_e32 v50, 16, v150
	v_and_b32_e32 v51, 0xffff0000, v150
	v_lshlrev_b32_e32 v48, 16, v151
	v_and_b32_e32 v49, 0xffff0000, v151
	v_lshlrev_b32_e32 v46, 16, v152
	v_and_b32_e32 v47, 0xffff0000, v152
	v_lshlrev_b32_e32 v44, 16, v153
	v_and_b32_e32 v45, 0xffff0000, v153
	v_lshlrev_b32_e32 v168, 16, v238
	v_and_b32_e32 v169, 0xffff0000, v238
	v_lshlrev_b32_e32 v186, 16, v239
	v_and_b32_e32 v187, 0xffff0000, v239
	v_and_b32_e32 v189, 0xffff0000, v240
	v_lshlrev_b32_e32 v190, 16, v241
	v_and_b32_e32 v191, 0xffff0000, v241
	global_store_dwordx4 v[198:199], v[150:153], off offset:2304
	v_pk_mul_f32 v[154:155], v[70:71], v[44:45]
	v_pk_mul_f32 v[166:167], v[68:69], v[46:47]
	v_pk_mul_f32 v[152:153], v[74:75], v[48:49]
	v_pk_mul_f32 v[150:151], v[72:73], v[50:51]
	v_pk_fma_f32 v[42:43], v[42:43], v[106:107], v[186:187]
	v_cvt_pk_bf16_f32 v150, v150, v151
	v_cvt_pk_bf16_f32 v151, v152, v153
	v_cvt_pk_bf16_f32 v152, v166, v167
	v_cvt_pk_bf16_f32 v153, v154, v155
	v_pk_fma_f32 v[40:41], v[40:41], v[104:105], v[168:169]
	v_pk_fma_f32 v[38:39], v[38:39], v[102:103], v[190:191]
	v_pk_fma_f32 v[36:37], v[36:37], v[100:101], v[188:189]
	global_store_dwordx4 v[200:201], v[150:153], off offset:256
	v_mul_f32_e32 v67, v67, v67
	v_mul_f32_e32 v65, v65, v65
	v_cvt_pk_bf16_f32 v150, v40, v41
	v_cvt_pk_bf16_f32 v151, v42, v43
	v_cvt_pk_bf16_f32 v152, v36, v37
	v_cvt_pk_bf16_f32 v153, v38, v39
	v_lshlrev_b32_e32 v42, 16, v150
	v_and_b32_e32 v43, 0xffff0000, v150
	v_lshlrev_b32_e32 v40, 16, v151
	v_and_b32_e32 v41, 0xffff0000, v151
	v_lshlrev_b32_e32 v38, 16, v152
	v_and_b32_e32 v39, 0xffff0000, v152
	v_lshlrev_b32_e32 v36, 16, v153
	v_and_b32_e32 v37, 0xffff0000, v153
	global_store_dwordx4 v[202:203], v[150:153], off offset:2304
	v_pk_mul_f32 v[154:155], v[70:71], v[36:37]
	v_pk_mul_f32 v[166:167], v[68:69], v[38:39]
	v_pk_mul_f32 v[152:153], v[74:75], v[40:41]
	v_pk_mul_f32 v[150:151], v[72:73], v[42:43]
	v_fmac_f32_e32 v67, v66, v66
	v_cvt_pk_bf16_f32 v150, v150, v151
	v_cvt_pk_bf16_f32 v151, v152, v153
	v_cvt_pk_bf16_f32 v152, v166, v167
	v_cvt_pk_bf16_f32 v153, v154, v155
	global_store_dwordx4 v[204:205], v[150:153], off offset:256
	global_load_dwordx4 v[150:153], v[206:207], off offset:2304
	s_nop 0
	global_load_dwordx4 v[186:189], v[208:209], off offset:2304
	v_fmac_f32_e32 v65, v64, v64
	v_mul_f32_e32 v63, v63, v63
	v_mul_f32_e32 v61, v61, v61
	v_add_f32_e32 v64, v67, v65
	v_fmac_f32_e32 v63, v62, v62
	v_fmac_f32_e32 v61, v60, v60
	v_add_f32_e32 v60, v63, v61
	s_waitcnt vmcnt(0)
	v_lshlrev_b32_e32 v154, 16, v178
	v_and_b32_e32 v155, 0xffff0000, v178
	v_lshlrev_b32_e32 v166, 16, v179
	v_and_b32_e32 v167, 0xffff0000, v179
	v_lshlrev_b32_e32 v168, 16, v180
	v_and_b32_e32 v169, 0xffff0000, v180
	v_lshlrev_b32_e32 v178, 16, v181
	v_and_b32_e32 v179, 0xffff0000, v181
	v_pk_fma_f32 v[34:35], v[34:35], v[106:107], v[166:167]
	v_pk_fma_f32 v[32:33], v[32:33], v[104:105], v[154:155]
	v_pk_fma_f32 v[30:31], v[30:31], v[102:103], v[178:179]
	v_pk_fma_f32 v[28:29], v[28:29], v[100:101], v[168:169]
	v_cvt_pk_bf16_f32 v178, v32, v33
	v_cvt_pk_bf16_f32 v179, v34, v35
	v_cvt_pk_bf16_f32 v180, v28, v29
	v_cvt_pk_bf16_f32 v181, v30, v31
	v_lshlrev_b32_e32 v34, 16, v178
	v_and_b32_e32 v35, 0xffff0000, v178
	v_lshlrev_b32_e32 v32, 16, v179
	v_and_b32_e32 v33, 0xffff0000, v179
	v_lshlrev_b32_e32 v30, 16, v180
	v_and_b32_e32 v31, 0xffff0000, v180
	v_lshlrev_b32_e32 v28, 16, v181
	v_and_b32_e32 v29, 0xffff0000, v181
	v_lshlrev_b32_e32 v190, 16, v182
	v_and_b32_e32 v191, 0xffff0000, v182
	v_lshlrev_b32_e32 v182, 16, v183
	v_and_b32_e32 v183, 0xffff0000, v183
	global_store_dwordx4 v[212:213], v[178:181], off offset:2304
	v_pk_mul_f32 v[154:155], v[74:75], v[32:33]
	v_pk_mul_f32 v[166:167], v[72:73], v[34:35]
	v_pk_mul_f32 v[168:169], v[70:71], v[28:29]
	v_pk_mul_f32 v[180:181], v[68:69], v[30:31]
	v_lshlrev_b32_e32 v192, 16, v184
	v_and_b32_e32 v193, 0xffff0000, v184
	v_lshlrev_b32_e32 v184, 16, v185
	v_and_b32_e32 v185, 0xffff0000, v185
	v_cvt_pk_bf16_f32 v178, v166, v167
	v_cvt_pk_bf16_f32 v179, v154, v155
	v_cvt_pk_bf16_f32 v180, v180, v181
	v_cvt_pk_bf16_f32 v181, v168, v169
	v_pk_fma_f32 v[24:25], v[24:25], v[106:107], v[182:183]
	v_pk_fma_f32 v[22:23], v[22:23], v[104:105], v[190:191]
	global_store_dwordx4 v[214:215], v[178:181], off offset:256
	v_pk_fma_f32 v[20:21], v[20:21], v[102:103], v[184:185]
	v_pk_fma_f32 v[18:19], v[18:19], v[100:101], v[192:193]
	v_cvt_pk_bf16_f32 v178, v22, v23
	v_cvt_pk_bf16_f32 v179, v24, v25
	v_cvt_pk_bf16_f32 v180, v18, v19
	v_cvt_pk_bf16_f32 v181, v20, v21
	v_lshlrev_b32_e32 v24, 16, v178
	v_and_b32_e32 v25, 0xffff0000, v178
	v_lshlrev_b32_e32 v22, 16, v179
	v_and_b32_e32 v23, 0xffff0000, v179
	v_lshlrev_b32_e32 v20, 16, v180
	v_and_b32_e32 v21, 0xffff0000, v180
	v_lshlrev_b32_e32 v18, 16, v181
	v_and_b32_e32 v19, 0xffff0000, v181
	v_pk_mul_f32 v[154:155], v[74:75], v[22:23]
	v_pk_mul_f32 v[166:167], v[72:73], v[24:25]
	global_store_dwordx4 v[216:217], v[178:181], off offset:2304
	v_pk_mul_f32 v[168:169], v[70:71], v[18:19]
	v_lshlrev_b32_e32 v182, 16, v189
	v_pk_mul_f32 v[180:181], v[68:69], v[20:21]
	v_cvt_pk_bf16_f32 v178, v166, v167
	v_cvt_pk_bf16_f32 v179, v154, v155
	v_lshlrev_b32_e32 v154, 16, v150
	v_and_b32_e32 v155, 0xffff0000, v150
	v_lshlrev_b32_e32 v150, 16, v151
	v_and_b32_e32 v151, 0xffff0000, v151
	v_lshlrev_b32_e32 v166, 16, v152
	v_and_b32_e32 v167, 0xffff0000, v152
	v_lshlrev_b32_e32 v152, 16, v153
	v_and_b32_e32 v153, 0xffff0000, v153
	v_cvt_pk_bf16_f32 v180, v180, v181
	v_cvt_pk_bf16_f32 v181, v168, v169
	v_pk_fma_f32 v[16:17], v[16:17], v[106:107], v[150:151]
	v_pk_fma_f32 v[14:15], v[14:15], v[104:105], v[154:155]
	v_pk_fma_f32 v[12:13], v[12:13], v[102:103], v[152:153]
	v_pk_fma_f32 v[10:11], v[10:11], v[100:101], v[166:167]
	global_store_dwordx4 v[218:219], v[178:181], off offset:256
	v_lshlrev_b32_e32 v168, 16, v186
	v_and_b32_e32 v169, 0xffff0000, v186
	v_lshlrev_b32_e32 v178, 16, v187
	v_and_b32_e32 v179, 0xffff0000, v187
	v_lshlrev_b32_e32 v180, 16, v188
	v_and_b32_e32 v181, 0xffff0000, v188
	v_and_b32_e32 v183, 0xffff0000, v189
	v_cvt_pk_bf16_f32 v150, v14, v15
	v_cvt_pk_bf16_f32 v151, v16, v17
	v_cvt_pk_bf16_f32 v152, v10, v11
	v_cvt_pk_bf16_f32 v153, v12, v13
	v_lshlrev_b32_e32 v16, 16, v150
	v_and_b32_e32 v17, 0xffff0000, v150
	v_lshlrev_b32_e32 v14, 16, v151
	v_and_b32_e32 v15, 0xffff0000, v151
	v_lshlrev_b32_e32 v12, 16, v152
	v_and_b32_e32 v13, 0xffff0000, v152
	v_lshlrev_b32_e32 v10, 16, v153
	v_and_b32_e32 v11, 0xffff0000, v153
	v_pk_fma_f32 v[8:9], v[8:9], v[106:107], v[178:179]
	v_pk_fma_f32 v[6:7], v[6:7], v[104:105], v[168:169]
	v_pk_fma_f32 v[4:5], v[4:5], v[102:103], v[182:183]
	v_pk_fma_f32 v[2:3], v[2:3], v[100:101], v[180:181]
	global_store_dwordx4 v[196:197], v[150:153], off offset:2304
	v_pk_mul_f32 v[154:155], v[70:71], v[10:11]
	v_pk_mul_f32 v[166:167], v[68:69], v[12:13]
	v_pk_mul_f32 v[152:153], v[74:75], v[14:15]
	v_pk_mul_f32 v[150:151], v[72:73], v[16:17]
	v_cvt_pk_bf16_f32 v100, v6, v7
	v_cvt_pk_bf16_f32 v101, v8, v9
	v_cvt_pk_bf16_f32 v102, v2, v3
	v_cvt_pk_bf16_f32 v103, v4, v5
	v_cvt_pk_bf16_f32 v150, v150, v151
	v_cvt_pk_bf16_f32 v151, v152, v153
	v_cvt_pk_bf16_f32 v152, v166, v167
	v_cvt_pk_bf16_f32 v153, v154, v155
	v_lshlrev_b32_e32 v8, 16, v100
	v_and_b32_e32 v9, 0xffff0000, v100
	v_lshlrev_b32_e32 v6, 16, v101
	v_and_b32_e32 v7, 0xffff0000, v101
	v_lshlrev_b32_e32 v4, 16, v102
	v_and_b32_e32 v5, 0xffff0000, v102
	v_lshlrev_b32_e32 v2, 16, v103
	v_and_b32_e32 v3, 0xffff0000, v103
	global_store_dwordx4 v[210:211], v[150:153], off offset:256
	global_store_dwordx4 v[220:221], v[100:103], off offset:2304
	v_pk_mul_f32 v[74:75], v[74:75], v[6:7]
	v_pk_mul_f32 v[72:73], v[72:73], v[8:9]
	v_pk_mul_f32 v[100:101], v[70:71], v[2:3]
	v_pk_mul_f32 v[70:71], v[68:69], v[4:5]
	v_cvt_pk_bf16_f32 v68, v72, v73
	v_cvt_pk_bf16_f32 v69, v74, v75
	v_cvt_pk_bf16_f32 v70, v70, v71
	v_cvt_pk_bf16_f32 v71, v100, v101
	global_store_dwordx4 v[148:149], v[68:71], off offset:256
	v_xor_b32_e32 v72, 32, v227
	v_mul_f32_e32 v73, v137, v137
	v_and_b32_e32 v71, 64, v227
	v_xor_b32_e32 v70, 16, v227
	v_add_u32_e32 v71, 64, v71
	v_cmp_lt_i32_e32 vcc, v70, v71
	v_fmac_f32_e32 v73, v136, v136
	v_mul_f32_e32 v74, v133, v133
	v_cndmask_b32_e32 v70, v227, v70, vcc
	v_cmp_lt_i32_e32 vcc, v72, v71
	v_fmac_f32_e32 v74, v132, v132
	v_lshlrev_b32_e32 v70, 2, v70
	v_cndmask_b32_e32 v71, v227, v72, vcc
	v_mul_f32_e32 v72, v139, v139
	v_fmac_f32_e32 v72, v138, v138
	v_add_f32_e32 v72, v72, v73
	v_mul_f32_e32 v73, v135, v135
	v_fmac_f32_e32 v73, v134, v134
	v_add_f32_e32 v73, v73, v74
	v_add_f32_e32 v72, v72, v73
	v_add_f32_e32 v64, v72, v64
	v_add_f32_e32 v60, v60, v64
	ds_bpermute_b32 v61, v70, v60
	v_lshlrev_b32_e32 v71, 2, v71
	v_lshl_add_u64 v[68:69], v[172:173], 0, s[28:29]
	s_waitcnt lgkmcnt(0)
	v_add_f32_e32 v60, v60, v61
	ds_bpermute_b32 v61, v71, v60
	s_and_saveexec_b64 s[18:19], s[38:39]
	s_cbranch_execz .LBB0_968
	s_waitcnt lgkmcnt(0)
	v_add_f32_e32 v60, v60, v61
	global_atomic_add_f32 v[68:69], v60, off

.LBB0_1047:
	s_ashr_i32 s43, s42, 31
	s_lshl_b64 s[0:1], s[42:43], 19
	v_mov_b64_e32 v[2:3], s[10:11]
	s_add_u32 s46, s17, s0
	v_cmp_lt_i64_e32 vcc, s[28:29], v[2:3]
	s_addc_u32 s47, s50, s1
	s_and_b64 s[0:1], vcc, exec
	s_cselect_b32 s43, s47, s25
	s_cselect_b32 s69, s46, s24
	s_ashr_i32 s45, s44, 31
	s_lshl_b64 s[0:1], s[44:45], 19
	s_add_u32 s48, s51, s0
	s_addc_u32 s49, s53, s1
	s_and_b64 s[0:1], vcc, exec
	s_cselect_b32 s45, s49, s27
	s_cselect_b32 s72, s48, s26
	s_add_u32 s24, s24, 0x40080
	s_addc_u32 s25, s25, 0
	s_add_u32 s73, s26, 0x100
	v_mov_b32_e32 v2, 0
	s_addc_u32 s81, s27, 0
	s_mov_b32 s82, -2
	v_mov_b32_e32 v3, v2
	v_mov_b32_e32 v4, v2
	v_mov_b32_e32 v5, v2
	v_mov_b32_e32 v6, v2
	v_mov_b32_e32 v7, v2
	v_mov_b32_e32 v8, v2
	v_mov_b32_e32 v9, v2
	v_mov_b32_e32 v18, v2
	v_mov_b32_e32 v19, v2
	v_mov_b32_e32 v20, v2
	v_mov_b32_e32 v21, v2
	v_mov_b32_e32 v22, v2
	v_mov_b32_e32 v23, v2
	v_mov_b32_e32 v24, v2
	v_mov_b32_e32 v25, v2
	s_waitcnt vmcnt(0)
	v_mov_b32_e32 v36, v2
	v_mov_b32_e32 v37, v2
	v_mov_b32_e32 v38, v2
	v_mov_b32_e32 v39, v2
	v_mov_b32_e32 v40, v2
	v_mov_b32_e32 v41, v2
	v_mov_b32_e32 v42, v2
	v_mov_b32_e32 v43, v2
	v_mov_b32_e32 v52, v2
	v_mov_b32_e32 v53, v2
	v_mov_b32_e32 v54, v2
	v_mov_b32_e32 v55, v2
	v_mov_b32_e32 v56, v2
	v_mov_b32_e32 v57, v2
	v_mov_b32_e32 v58, v2
	v_mov_b32_e32 v59, v2
	v_mov_b32_e32 v10, v2
	v_mov_b32_e32 v11, v2
	v_mov_b32_e32 v12, v2
	v_mov_b32_e32 v13, v2
	v_mov_b32_e32 v14, v2
	v_mov_b32_e32 v15, v2
	v_mov_b32_e32 v16, v2
	v_mov_b32_e32 v17, v2
	v_mov_b32_e32 v28, v2
	v_mov_b32_e32 v29, v2
	v_mov_b32_e32 v30, v2
	v_mov_b32_e32 v31, v2
	v_mov_b32_e32 v32, v2
	v_mov_b32_e32 v33, v2
	v_mov_b32_e32 v34, v2
	v_mov_b32_e32 v35, v2
	v_mov_b32_e32 v44, v2
	v_mov_b32_e32 v45, v2
	v_mov_b32_e32 v46, v2
	v_mov_b32_e32 v47, v2
	v_mov_b32_e32 v48, v2
	v_mov_b32_e32 v49, v2
	v_mov_b32_e32 v50, v2
	v_mov_b32_e32 v51, v2
	v_mov_b32_e32 v60, v2
	v_mov_b32_e32 v61, v2
	v_mov_b32_e32 v62, v2
	v_mov_b32_e32 v63, v2
	v_mov_b32_e32 v64, v2
	v_mov_b32_e32 v65, v2
	v_mov_b32_e32 v66, v2
	v_mov_b32_e32 v67, v2
	v_mov_b32_e32 v84, v2
	v_mov_b32_e32 v85, v2
	v_mov_b32_e32 v86, v2
	v_mov_b32_e32 v87, v2
	v_mov_b32_e32 v88, v2
	v_mov_b32_e32 v89, v2
	v_mov_b32_e32 v90, v2
	v_mov_b32_e32 v91, v2
	v_mov_b32_e32 v100, v2
	v_mov_b32_e32 v101, v2
	v_mov_b32_e32 v102, v2
	v_mov_b32_e32 v103, v2
	v_mov_b32_e32 v104, v2
	v_mov_b32_e32 v105, v2
	v_mov_b32_e32 v106, v2
	v_mov_b32_e32 v107, v2
	v_mov_b32_e32 v116, v2
	v_mov_b32_e32 v117, v2
	v_mov_b32_e32 v118, v2
	v_mov_b32_e32 v119, v2
	v_mov_b32_e32 v120, v2
	v_mov_b32_e32 v121, v2
	v_mov_b32_e32 v122, v2
	v_mov_b32_e32 v123, v2
	v_mov_b32_e32 v132, v2
	v_mov_b32_e32 v133, v2
	v_mov_b32_e32 v134, v2
	v_mov_b32_e32 v135, v2
	v_mov_b32_e32 v136, v2
	v_mov_b32_e32 v137, v2
	v_mov_b32_e32 v138, v2
	v_mov_b32_e32 v139, v2
	v_mov_b32_e32 v92, v2
	v_mov_b32_e32 v93, v2
	v_mov_b32_e32 v94, v2
	v_mov_b32_e32 v95, v2
	v_mov_b32_e32 v96, v2
	v_mov_b32_e32 v97, v2
	v_mov_b32_e32 v98, v2
	v_mov_b32_e32 v99, v2
	v_mov_b32_e32 v108, v2
	v_mov_b32_e32 v109, v2
	v_mov_b32_e32 v110, v2
	v_mov_b32_e32 v111, v2
	v_mov_b32_e32 v112, v2
	v_mov_b32_e32 v113, v2
	v_mov_b32_e32 v114, v2
	v_mov_b32_e32 v115, v2
	v_mov_b32_e32 v124, v2
	v_mov_b32_e32 v125, v2
	v_mov_b32_e32 v126, v2
	v_mov_b32_e32 v127, v2
	v_mov_b32_e32 v128, v2
	v_mov_b32_e32 v129, v2
	v_mov_b32_e32 v130, v2
	v_mov_b32_e32 v131, v2
	v_mov_b32_e32 v140, v2
	v_mov_b32_e32 v141, v2
	v_mov_b32_e32 v142, v2
	v_mov_b32_e32 v143, v2
	v_mov_b32_e32 v144, v2
	v_mov_b32_e32 v145, v2
	v_mov_b32_e32 v146, v2
	v_mov_b32_e32 v147, v2
	v_add_u32_e32 v80, 0x10000, v163
	ds_read_b128 v[68:71], v80
	ds_read_b128 v[72:75], v80 offset:1024
	ds_read_b128 v[76:79], v80 offset:2048
	ds_read_b128 v[80:83], v80 offset:3072
	s_add_u32 s0, s24, 0xfffc0080
	s_addc_u32 s1, s25, -1
	s_add_i32 s83, 0, 0x10000
	s_cmp_eq_u32 s82, 12
	s_cselect_b32 s29, s43, s1
	s_cselect_b32 s28, s69, s0
	s_cselect_b32 s27, s45, s81
	s_cselect_b32 s26, s72, s73
.LBB0_1048:
	s_add_i32 m0, s23, 0xc000
	ds_read_b128 v[158:161], v165
	ds_read_b128 v[174:177], v165 offset:1024
	ds_read_b128 v[178:181], v165 offset:2048
	ds_read_b128 v[182:185], v165 offset:3072
	ds_read_b128 v[186:189], v165 offset:4096
	ds_read_b128 v[190:193], v165 offset:5120
	ds_read_b128 v[194:197], v165 offset:6144
	ds_read_b128 v[198:201], v165 offset:7168
	global_load_lds_dwordx4 v154, s[24:25]
	v_lshl_add_u64 v[166:167], s[24:25], 0, v[156:157]
	s_add_i32 m0, s23, 0xe000
	s_nop 0
	global_load_lds_dwordx4 v[166:167], off
	s_waitcnt vmcnt(10) lgkmcnt(8)
	s_setprio 1
	s_barrier
	s_waitcnt lgkmcnt(0)
	v_mfma_f32_16x16x32_bf16 v[144:147], v[68:71], v[158:161], v[144:147]
	v_mfma_f32_16x16x32_bf16 v[140:143], v[76:79], v[158:161], v[140:143]
	v_mfma_f32_16x16x32_bf16 v[128:131], v[68:71], v[178:181], v[128:131]
	v_mfma_f32_16x16x32_bf16 v[124:127], v[76:79], v[178:181], v[124:127]
	v_mfma_f32_16x16x32_bf16 v[112:115], v[68:71], v[186:189], v[112:115]
	v_mfma_f32_16x16x32_bf16 v[108:111], v[76:79], v[186:189], v[108:111]
	v_mfma_f32_16x16x32_bf16 v[96:99], v[68:71], v[194:197], v[96:99]
	v_mfma_f32_16x16x32_bf16 v[92:95], v[76:79], v[194:197], v[92:95]
	v_mfma_f32_16x16x32_bf16 v[144:147], v[72:75], v[174:177], v[144:147]
	v_mfma_f32_16x16x32_bf16 v[140:143], v[80:83], v[174:177], v[140:143]
	v_mfma_f32_16x16x32_bf16 v[128:131], v[72:75], v[182:185], v[128:131]
	v_mfma_f32_16x16x32_bf16 v[124:127], v[80:83], v[182:185], v[124:127]
	v_mfma_f32_16x16x32_bf16 v[112:115], v[72:75], v[190:193], v[112:115]
	v_mfma_f32_16x16x32_bf16 v[108:111], v[80:83], v[190:193], v[108:111]
	v_mfma_f32_16x16x32_bf16 v[96:99], v[72:75], v[198:201], v[96:99]
	v_mfma_f32_16x16x32_bf16 v[92:95], v[80:83], v[198:201], v[92:95]
	s_barrier
	s_setprio 0
	s_add_i32 s84, 0, 0x14000
	v_add_u32_e32 v166, s84, v163
	s_add_i32 s0, s83, s54
	ds_read_b128 v[202:205], v166
	ds_read_b128 v[206:209], v166 offset:1024
	ds_read_b128 v[210:213], v166 offset:2048
	ds_read_b128 v[214:217], v166 offset:3072
	v_lshl_add_u64 v[166:167], s[26:27], 0, v[26:27]
	s_mov_b32 m0, s0
	v_lshl_add_u64 v[168:169], s[26:27], 0, v[148:149]
	global_load_lds_dwordx4 v[166:167], off
	s_add_i32 m0, s0, 0x2000
	s_nop 0
	global_load_lds_dwordx4 v[168:169], off
	s_waitcnt vmcnt(10)
	s_setprio 1
	s_barrier
	s_waitcnt lgkmcnt(0)
	v_mfma_f32_16x16x32_bf16 v[136:139], v[202:205], v[158:161], v[136:139]
	v_mfma_f32_16x16x32_bf16 v[132:135], v[210:213], v[158:161], v[132:135]
	v_mfma_f32_16x16x32_bf16 v[120:123], v[202:205], v[178:181], v[120:123]
	v_mfma_f32_16x16x32_bf16 v[116:119], v[210:213], v[178:181], v[116:119]
	v_mfma_f32_16x16x32_bf16 v[104:107], v[202:205], v[186:189], v[104:107]
	v_mfma_f32_16x16x32_bf16 v[100:103], v[210:213], v[186:189], v[100:103]
	v_mfma_f32_16x16x32_bf16 v[88:91], v[202:205], v[194:197], v[88:91]
	v_mfma_f32_16x16x32_bf16 v[84:87], v[210:213], v[194:197], v[84:87]
	v_mfma_f32_16x16x32_bf16 v[136:139], v[206:209], v[174:177], v[136:139]
	v_mfma_f32_16x16x32_bf16 v[132:135], v[214:217], v[174:177], v[132:135]
	v_mfma_f32_16x16x32_bf16 v[120:123], v[206:209], v[182:185], v[120:123]
	v_mfma_f32_16x16x32_bf16 v[116:119], v[214:217], v[182:185], v[116:119]
	v_mfma_f32_16x16x32_bf16 v[104:107], v[206:209], v[190:193], v[104:107]
	v_mfma_f32_16x16x32_bf16 v[100:103], v[214:217], v[190:193], v[100:103]
	v_mfma_f32_16x16x32_bf16 v[88:91], v[206:209], v[198:201], v[88:91]
	v_mfma_f32_16x16x32_bf16 v[84:87], v[214:217], v[198:201], v[84:87]
	s_barrier
	s_setprio 0
	s_mov_b32 m0, s23
	v_lshl_add_u64 v[218:219], s[28:29], 0, v[152:153]
	ds_read_b128 v[158:161], v165 offset:16384
	ds_read_b128 v[174:177], v165 offset:17408
	ds_read_b128 v[178:181], v165 offset:18432
	ds_read_b128 v[182:185], v165 offset:19456
	ds_read_b128 v[186:189], v165 offset:20480
	ds_read_b128 v[190:193], v165 offset:21504
	ds_read_b128 v[194:197], v165 offset:22528
	ds_read_b128 v[198:201], v165 offset:23552
	global_load_lds_dwordx4 v[218:219], off
	v_lshl_add_u64 v[220:221], s[28:29], 0, v[150:151]
	s_mov_b32 m0, s57
	s_nop 0
	global_load_lds_dwordx4 v[220:221], off
	s_waitcnt vmcnt(10)
	s_setprio 1
	s_barrier
	s_waitcnt lgkmcnt(0)
	v_mfma_f32_16x16x32_bf16 v[64:67], v[68:71], v[158:161], v[64:67]
	v_mfma_f32_16x16x32_bf16 v[60:63], v[76:79], v[158:161], v[60:63]
	v_mfma_f32_16x16x32_bf16 v[48:51], v[68:71], v[178:181], v[48:51]
	v_mfma_f32_16x16x32_bf16 v[44:47], v[76:79], v[178:181], v[44:47]
	v_mfma_f32_16x16x32_bf16 v[32:35], v[68:71], v[186:189], v[32:35]
	v_mfma_f32_16x16x32_bf16 v[28:31], v[76:79], v[186:189], v[28:31]
	v_mfma_f32_16x16x32_bf16 v[14:17], v[68:71], v[194:197], v[14:17]
	v_mfma_f32_16x16x32_bf16 v[10:13], v[76:79], v[194:197], v[10:13]
	v_mfma_f32_16x16x32_bf16 v[64:67], v[72:75], v[174:177], v[64:67]
	v_mfma_f32_16x16x32_bf16 v[60:63], v[80:83], v[174:177], v[60:63]
	v_mfma_f32_16x16x32_bf16 v[48:51], v[72:75], v[182:185], v[48:51]
	v_mfma_f32_16x16x32_bf16 v[44:47], v[80:83], v[182:185], v[44:47]
	v_mfma_f32_16x16x32_bf16 v[32:35], v[72:75], v[190:193], v[32:35]
	v_mfma_f32_16x16x32_bf16 v[28:31], v[80:83], v[190:193], v[28:31]
	v_mfma_f32_16x16x32_bf16 v[14:17], v[72:75], v[198:201], v[14:17]
	v_mfma_f32_16x16x32_bf16 v[10:13], v[80:83], v[198:201], v[10:13]
	s_barrier
	s_setprio 0
	s_add_u32 s0, s26, 0x40000
	s_addc_u32 s1, s27, 0
	s_add_i32 s83, s84, s54
	s_mov_b32 m0, s83
	s_nop 0
	global_load_lds_dwordx4 v26, s[0:1]
	s_add_i32 m0, s83, 0x2000
	s_nop 0
	global_load_lds_dwordx4 v148, s[0:1]
	v_add_u32_e32 v80, 0x18000, v163
	ds_read_b128 v[68:71], v80
	ds_read_b128 v[72:75], v80 offset:1024
	ds_read_b128 v[76:79], v80 offset:2048
	ds_read_b128 v[80:83], v80 offset:3072
	s_waitcnt vmcnt(10)
	s_setprio 1
	s_barrier
	v_mfma_f32_16x16x32_bf16 v[56:59], v[202:205], v[158:161], v[56:59]
	v_mfma_f32_16x16x32_bf16 v[52:55], v[210:213], v[158:161], v[52:55]
	v_mfma_f32_16x16x32_bf16 v[40:43], v[202:205], v[178:181], v[40:43]
	v_mfma_f32_16x16x32_bf16 v[36:39], v[210:213], v[178:181], v[36:39]
	v_mfma_f32_16x16x32_bf16 v[22:25], v[202:205], v[186:189], v[22:25]
	v_mfma_f32_16x16x32_bf16 v[18:21], v[210:213], v[186:189], v[18:21]
	v_mfma_f32_16x16x32_bf16 v[6:9], v[202:205], v[194:197], v[6:9]
	v_mfma_f32_16x16x32_bf16 v[2:5], v[210:213], v[194:197], v[2:5]
	v_mfma_f32_16x16x32_bf16 v[56:59], v[206:209], v[174:177], v[56:59]
	v_mfma_f32_16x16x32_bf16 v[52:55], v[214:217], v[174:177], v[52:55]
	v_mfma_f32_16x16x32_bf16 v[40:43], v[206:209], v[182:185], v[40:43]
	v_mfma_f32_16x16x32_bf16 v[36:39], v[214:217], v[182:185], v[36:39]
	v_mfma_f32_16x16x32_bf16 v[22:25], v[206:209], v[190:193], v[22:25]
	v_mfma_f32_16x16x32_bf16 v[18:21], v[214:217], v[190:193], v[18:21]
	v_mfma_f32_16x16x32_bf16 v[6:9], v[206:209], v[198:201], v[6:9]
	v_mfma_f32_16x16x32_bf16 v[2:5], v[214:217], v[198:201], v[2:5]
	s_barrier
	s_setprio 0
	s_add_i32 s83, 0, 0x18000
	s_add_u32 s0, s28, 0x40000
	s_addc_u32 s1, s29, 0
	s_mov_b32 m0, s58
	ds_read_b128 v[158:161], v165 offset:32768
	ds_read_b128 v[174:177], v165 offset:33792
	ds_read_b128 v[178:181], v165 offset:34816
	ds_read_b128 v[182:185], v165 offset:35840
	ds_read_b128 v[186:189], v165 offset:36864
	ds_read_b128 v[190:193], v165 offset:37888
	ds_read_b128 v[194:197], v165 offset:38912
	ds_read_b128 v[198:201], v165 offset:39936
	global_load_lds_dwordx4 v152, s[0:1]
	s_mov_b32 m0, s59
	s_nop 0
	global_load_lds_dwordx4 v150, s[0:1]
	s_waitcnt vmcnt(10) lgkmcnt(8)
	s_setprio 1
	s_barrier
	s_waitcnt lgkmcnt(0)
	v_mfma_f32_16x16x32_bf16 v[144:147], v[68:71], v[158:161], v[144:147]
	v_mfma_f32_16x16x32_bf16 v[140:143], v[76:79], v[158:161], v[140:143]
	v_mfma_f32_16x16x32_bf16 v[128:131], v[68:71], v[178:181], v[128:131]
	v_mfma_f32_16x16x32_bf16 v[124:127], v[76:79], v[178:181], v[124:127]
	v_mfma_f32_16x16x32_bf16 v[112:115], v[68:71], v[186:189], v[112:115]
	v_mfma_f32_16x16x32_bf16 v[108:111], v[76:79], v[186:189], v[108:111]
	v_mfma_f32_16x16x32_bf16 v[96:99], v[68:71], v[194:197], v[96:99]
	v_mfma_f32_16x16x32_bf16 v[92:95], v[76:79], v[194:197], v[92:95]
	v_mfma_f32_16x16x32_bf16 v[144:147], v[72:75], v[174:177], v[144:147]
	v_mfma_f32_16x16x32_bf16 v[140:143], v[80:83], v[174:177], v[140:143]
	v_mfma_f32_16x16x32_bf16 v[128:131], v[72:75], v[182:185], v[128:131]
	v_mfma_f32_16x16x32_bf16 v[124:127], v[80:83], v[182:185], v[124:127]
	v_mfma_f32_16x16x32_bf16 v[112:115], v[72:75], v[190:193], v[112:115]
	v_mfma_f32_16x16x32_bf16 v[108:111], v[80:83], v[190:193], v[108:111]
	v_mfma_f32_16x16x32_bf16 v[96:99], v[72:75], v[198:201], v[96:99]
	v_mfma_f32_16x16x32_bf16 v[92:95], v[80:83], v[198:201], v[92:95]
	s_barrier
	s_setprio 0
	s_add_i32 s28, 0, 0x1c000
	s_add_i32 s0, s83, s54
	v_add_u32_e32 v173, s28, v163
	v_lshl_add_u64 v[166:167], v[166:167], 0, s[12:13]
	s_mov_b32 m0, s0
	ds_read_b128 v[202:205], v173
	ds_read_b128 v[206:209], v173 offset:1024
	ds_read_b128 v[210:213], v173 offset:2048
	ds_read_b128 v[214:217], v173 offset:3072
	global_load_lds_dwordx4 v[166:167], off
	v_lshl_add_u64 v[166:167], v[168:169], 0, s[12:13]
	s_add_i32 m0, s0, 0x2000
	s_nop 0
	global_load_lds_dwordx4 v[166:167], off
	s_waitcnt vmcnt(10)
	s_setprio 1
	s_barrier
	s_waitcnt lgkmcnt(0)
	v_mfma_f32_16x16x32_bf16 v[136:139], v[202:205], v[158:161], v[136:139]
	v_mfma_f32_16x16x32_bf16 v[132:135], v[210:213], v[158:161], v[132:135]
	v_mfma_f32_16x16x32_bf16 v[120:123], v[202:205], v[178:181], v[120:123]
	v_mfma_f32_16x16x32_bf16 v[116:119], v[210:213], v[178:181], v[116:119]
	v_mfma_f32_16x16x32_bf16 v[104:107], v[202:205], v[186:189], v[104:107]
	v_mfma_f32_16x16x32_bf16 v[100:103], v[210:213], v[186:189], v[100:103]
	v_mfma_f32_16x16x32_bf16 v[88:91], v[202:205], v[194:197], v[88:91]
	v_mfma_f32_16x16x32_bf16 v[84:87], v[210:213], v[194:197], v[84:87]
	v_mfma_f32_16x16x32_bf16 v[136:139], v[206:209], v[174:177], v[136:139]
	v_mfma_f32_16x16x32_bf16 v[132:135], v[214:217], v[174:177], v[132:135]
	v_mfma_f32_16x16x32_bf16 v[120:123], v[206:209], v[182:185], v[120:123]
	v_mfma_f32_16x16x32_bf16 v[116:119], v[214:217], v[182:185], v[116:119]
	v_mfma_f32_16x16x32_bf16 v[104:107], v[206:209], v[190:193], v[104:107]
	v_mfma_f32_16x16x32_bf16 v[100:103], v[214:217], v[190:193], v[100:103]
	v_mfma_f32_16x16x32_bf16 v[88:91], v[206:209], v[198:201], v[88:91]
	v_mfma_f32_16x16x32_bf16 v[84:87], v[214:217], v[198:201], v[84:87]
	s_barrier
	s_setprio 0
	s_mov_b32 m0, s34
	v_lshl_add_u64 v[166:167], v[218:219], 0, s[12:13]
	ds_read_b128 v[158:161], v165 offset:49152
	ds_read_b128 v[174:177], v165 offset:50176
	ds_read_b128 v[178:181], v165 offset:51200
	ds_read_b128 v[182:185], v165 offset:52224
	ds_read_b128 v[186:189], v165 offset:53248
	ds_read_b128 v[190:193], v165 offset:54272
	ds_read_b128 v[194:197], v165 offset:55296
	ds_read_b128 v[198:201], v165 offset:56320
	global_load_lds_dwordx4 v[166:167], off
	v_lshl_add_u64 v[166:167], v[220:221], 0, s[12:13]
	s_mov_b32 m0, s35
	s_nop 0
	global_load_lds_dwordx4 v[166:167], off
	s_waitcnt vmcnt(10)
	s_setprio 1
	s_barrier
	s_waitcnt lgkmcnt(0)
	v_mfma_f32_16x16x32_bf16 v[64:67], v[68:71], v[158:161], v[64:67]
	v_mfma_f32_16x16x32_bf16 v[60:63], v[76:79], v[158:161], v[60:63]
	v_mfma_f32_16x16x32_bf16 v[48:51], v[68:71], v[178:181], v[48:51]
	v_mfma_f32_16x16x32_bf16 v[44:47], v[76:79], v[178:181], v[44:47]
	v_mfma_f32_16x16x32_bf16 v[32:35], v[68:71], v[186:189], v[32:35]
	v_mfma_f32_16x16x32_bf16 v[28:31], v[76:79], v[186:189], v[28:31]
	v_mfma_f32_16x16x32_bf16 v[14:17], v[68:71], v[194:197], v[14:17]
	v_mfma_f32_16x16x32_bf16 v[10:13], v[76:79], v[194:197], v[10:13]
	v_mfma_f32_16x16x32_bf16 v[64:67], v[72:75], v[174:177], v[64:67]
	v_mfma_f32_16x16x32_bf16 v[60:63], v[80:83], v[174:177], v[60:63]
	v_mfma_f32_16x16x32_bf16 v[48:51], v[72:75], v[182:185], v[48:51]
	v_mfma_f32_16x16x32_bf16 v[44:47], v[80:83], v[182:185], v[44:47]
	v_mfma_f32_16x16x32_bf16 v[32:35], v[72:75], v[190:193], v[32:35]
	v_mfma_f32_16x16x32_bf16 v[28:31], v[80:83], v[190:193], v[28:31]
	v_mfma_f32_16x16x32_bf16 v[14:17], v[72:75], v[198:201], v[14:17]
	v_mfma_f32_16x16x32_bf16 v[10:13], v[80:83], v[198:201], v[10:13]
	s_barrier
	s_setprio 0
	s_add_u32 s0, s26, 0x40080
	s_addc_u32 s1, s27, 0
	s_add_i32 s26, s28, s54
	s_mov_b32 m0, s26
	s_nop 0
	global_load_lds_dwordx4 v26, s[0:1]
	s_add_i32 m0, s26, 0x2000
	s_nop 0
	global_load_lds_dwordx4 v148, s[0:1]
	v_add_u32_e32 v80, 0x10000, v163
	ds_read_b128 v[68:71], v80
	ds_read_b128 v[72:75], v80 offset:1024
	ds_read_b128 v[76:79], v80 offset:2048
	ds_read_b128 v[80:83], v80 offset:3072
	s_add_i32 s82, s82, 2
	s_add_u32 s24, s24, 0x100
	s_addc_u32 s25, s25, 0
	s_add_u32 s73, s73, 0x100
	s_addc_u32 s81, s81, 0
	s_cmp_gt_u32 s82, 13
	s_cbranch_scc1 .Lth__1048
	s_add_u32 s0, s24, 0xfffc0080
	s_addc_u32 s1, s25, -1
	s_add_i32 s83, 0, 0x10000
	s_cmp_eq_u32 s82, 12
	s_cselect_b32 s29, s43, s1
	s_cselect_b32 s28, s69, s0
	s_cselect_b32 s27, s45, s81
	s_cselect_b32 s26, s72, s73
	s_cmp_gt_u32 s82, 13
.Lth__1048:
	s_waitcnt vmcnt(10)
	s_setprio 1
	s_barrier
	v_mfma_f32_16x16x32_bf16 v[56:59], v[202:205], v[158:161], v[56:59]
	v_mfma_f32_16x16x32_bf16 v[52:55], v[210:213], v[158:161], v[52:55]
	v_mfma_f32_16x16x32_bf16 v[40:43], v[202:205], v[178:181], v[40:43]
	v_mfma_f32_16x16x32_bf16 v[36:39], v[210:213], v[178:181], v[36:39]
	v_mfma_f32_16x16x32_bf16 v[22:25], v[202:205], v[186:189], v[22:25]
	v_mfma_f32_16x16x32_bf16 v[18:21], v[210:213], v[186:189], v[18:21]
	v_mfma_f32_16x16x32_bf16 v[6:9], v[202:205], v[194:197], v[6:9]
	v_mfma_f32_16x16x32_bf16 v[2:5], v[210:213], v[194:197], v[2:5]
	v_mfma_f32_16x16x32_bf16 v[56:59], v[206:209], v[174:177], v[56:59]
	v_mfma_f32_16x16x32_bf16 v[52:55], v[214:217], v[174:177], v[52:55]
	v_mfma_f32_16x16x32_bf16 v[40:43], v[206:209], v[182:185], v[40:43]
	v_mfma_f32_16x16x32_bf16 v[36:39], v[214:217], v[182:185], v[36:39]
	v_mfma_f32_16x16x32_bf16 v[22:25], v[206:209], v[190:193], v[22:25]
	v_mfma_f32_16x16x32_bf16 v[18:21], v[214:217], v[190:193], v[18:21]
	v_mfma_f32_16x16x32_bf16 v[6:9], v[206:209], v[198:201], v[6:9]
	v_mfma_f32_16x16x32_bf16 v[2:5], v[214:217], v[198:201], v[2:5]
	s_barrier
	s_setprio 0
	s_cbranch_scc0 .LBB0_1048
	s_waitcnt lgkmcnt(0)
	v_readlane_b32 s82, v255, 51
	s_cmpk_gt_i32 s22, 0xff
	s_mov_b64 s[24:25], 0xb000
	v_readlane_b32 s83, v255, 52
	s_cbranch_scc1 .LBB0_1044
	s_ashr_i32 s0, s22, 5
	s_mul_hi_i32 s25, s0, 0x1600
	s_mul_i32 s24, s0, 0x1600
	s_branch .LBB0_1044

.LBB0_1121:
	s_add_u32 s68, s26, 0x100
	v_mov_b32_e32 v2, 0
	s_addc_u32 s69, s27, 0
	s_mov_b32 s72, -2
	v_mov_b32_e32 v3, v2
	v_mov_b32_e32 v4, v2
	v_mov_b32_e32 v5, v2
	v_mov_b32_e32 v6, v2
	v_mov_b32_e32 v7, v2
	v_mov_b32_e32 v8, v2
	v_mov_b32_e32 v9, v2
	v_mov_b32_e32 v10, v2
	v_mov_b32_e32 v11, v2
	v_mov_b32_e32 v12, v2
	v_mov_b32_e32 v13, v2
	v_mov_b32_e32 v14, v2
	v_mov_b32_e32 v15, v2
	v_mov_b32_e32 v16, v2
	v_mov_b32_e32 v17, v2
	v_mov_b32_e32 v18, v2
	v_mov_b32_e32 v19, v2
	v_mov_b32_e32 v20, v2
	v_mov_b32_e32 v21, v2
	v_mov_b32_e32 v22, v2
	v_mov_b32_e32 v23, v2
	v_mov_b32_e32 v24, v2
	v_mov_b32_e32 v25, v2
	v_mov_b32_e32 v28, v2
	v_mov_b32_e32 v29, v2
	v_mov_b32_e32 v30, v2
	v_mov_b32_e32 v31, v2
	v_mov_b32_e32 v32, v2
	v_mov_b32_e32 v33, v2
	v_mov_b32_e32 v34, v2
	v_mov_b32_e32 v35, v2
	v_mov_b32_e32 v64, v2
	v_mov_b32_e32 v65, v2
	v_mov_b32_e32 v66, v2
	v_mov_b32_e32 v67, v2
	v_mov_b32_e32 v72, v2
	v_mov_b32_e32 v73, v2
	v_mov_b32_e32 v74, v2
	v_mov_b32_e32 v75, v2
	v_mov_b32_e32 v76, v2
	v_mov_b32_e32 v77, v2
	v_mov_b32_e32 v78, v2
	v_mov_b32_e32 v79, v2
	v_mov_b32_e32 v80, v2
	v_mov_b32_e32 v81, v2
	v_mov_b32_e32 v82, v2
	v_mov_b32_e32 v83, v2
	v_mov_b32_e32 v84, v2
	v_mov_b32_e32 v85, v2
	v_mov_b32_e32 v86, v2
	v_mov_b32_e32 v87, v2
	v_mov_b32_e32 v88, v2
	v_mov_b32_e32 v89, v2
	v_mov_b32_e32 v90, v2
	v_mov_b32_e32 v91, v2
	v_mov_b32_e32 v92, v2
	v_mov_b32_e32 v93, v2
	v_mov_b32_e32 v94, v2
	v_mov_b32_e32 v95, v2
	v_mov_b32_e32 v96, v2
	v_mov_b32_e32 v97, v2
	v_mov_b32_e32 v98, v2
	v_mov_b32_e32 v99, v2
	s_waitcnt vmcnt(0)
	v_mov_b32_e32 v36, v2
	v_mov_b32_e32 v37, v2
	v_mov_b32_e32 v38, v2
	v_mov_b32_e32 v39, v2
	v_mov_b32_e32 v40, v2
	v_mov_b32_e32 v41, v2
	v_mov_b32_e32 v42, v2
	v_mov_b32_e32 v43, v2
	v_mov_b32_e32 v44, v2
	v_mov_b32_e32 v45, v2
	v_mov_b32_e32 v46, v2
	v_mov_b32_e32 v47, v2
	v_mov_b32_e32 v48, v2
	v_mov_b32_e32 v49, v2
	v_mov_b32_e32 v50, v2
	v_mov_b32_e32 v51, v2
	v_mov_b32_e32 v52, v2
	v_mov_b32_e32 v53, v2
	v_mov_b32_e32 v54, v2
	v_mov_b32_e32 v55, v2
	v_mov_b32_e32 v56, v2
	v_mov_b32_e32 v57, v2
	v_mov_b32_e32 v58, v2
	v_mov_b32_e32 v59, v2
	v_mov_b32_e32 v60, v2
	v_mov_b32_e32 v61, v2
	v_mov_b32_e32 v62, v2
	v_mov_b32_e32 v63, v2
	v_mov_b32_e32 v68, v2
	v_mov_b32_e32 v69, v2
	v_mov_b32_e32 v70, v2
	v_mov_b32_e32 v71, v2
	v_mov_b32_e32 v100, v2
	v_mov_b32_e32 v101, v2
	v_mov_b32_e32 v102, v2
	v_mov_b32_e32 v103, v2
	v_mov_b32_e32 v104, v2
	v_mov_b32_e32 v105, v2
	v_mov_b32_e32 v106, v2
	v_mov_b32_e32 v107, v2
	v_mov_b32_e32 v108, v2
	v_mov_b32_e32 v109, v2
	v_mov_b32_e32 v110, v2
	v_mov_b32_e32 v111, v2
	v_mov_b32_e32 v112, v2
	v_mov_b32_e32 v113, v2
	v_mov_b32_e32 v114, v2
	v_mov_b32_e32 v115, v2
	v_mov_b32_e32 v116, v2
	v_mov_b32_e32 v117, v2
	v_mov_b32_e32 v118, v2
	v_mov_b32_e32 v119, v2
	v_mov_b32_e32 v120, v2
	v_mov_b32_e32 v121, v2
	v_mov_b32_e32 v122, v2
	v_mov_b32_e32 v123, v2
	v_mov_b32_e32 v124, v2
	v_mov_b32_e32 v125, v2
	v_mov_b32_e32 v126, v2
	v_mov_b32_e32 v127, v2
	v_mov_b32_e32 v128, v2
	v_mov_b32_e32 v129, v2
	v_mov_b32_e32 v130, v2
	v_mov_b32_e32 v131, v2
	v_add_u32_e32 v158, 0x10000, v186
	ds_read_b128 v[132:135], v158
	ds_read_b128 v[136:139], v158 offset:1024
	ds_read_b128 v[154:157], v158 offset:2048
	ds_read_b128 v[158:161], v158 offset:3072
	s_add_u32 s26, s24, 0x100
	s_addc_u32 s27, s25, 0
	s_add_i32 s0, 0, 0x10000
	s_cmp_eq_u32 s72, 40
	s_cselect_b32 s31, s43, s27
	s_cselect_b32 s30, s42, s26
	s_cselect_b32 s29, s45, s69
	s_cselect_b32 s28, s44, s68
.LBB0_1122:
	s_add_i32 m0, s36, 0xc000
	ds_read_b128 v[162:165], v188
	ds_read_b128 v[172:175], v188 offset:1024
	ds_read_b128 v[176:179], v188 offset:2048
	ds_read_b128 v[180:183], v188 offset:3072
	ds_read_b128 v[190:193], v188 offset:4096
	ds_read_b128 v[194:197], v188 offset:5120
	ds_read_b128 v[198:201], v188 offset:6144
	ds_read_b128 v[202:205], v188 offset:7168
	global_load_lds_dwordx4 v150, s[24:25]
	v_lshl_add_u64 v[166:167], s[24:25], 0, v[152:153]
	s_add_i32 m0, s36, 0xe000
	s_nop 0
	global_load_lds_dwordx4 v[166:167], off
	s_waitcnt vmcnt(10) lgkmcnt(8)
	s_setprio 1
	s_barrier
	s_waitcnt lgkmcnt(0)
	v_mfma_f32_16x16x32_bf16 v[128:131], v[132:135], v[162:165], v[128:131]
	v_mfma_f32_16x16x32_bf16 v[124:127], v[154:157], v[162:165], v[124:127]
	v_mfma_f32_16x16x32_bf16 v[120:123], v[132:135], v[176:179], v[120:123]
	v_mfma_f32_16x16x32_bf16 v[116:119], v[154:157], v[176:179], v[116:119]
	v_mfma_f32_16x16x32_bf16 v[112:115], v[132:135], v[190:193], v[112:115]
	v_mfma_f32_16x16x32_bf16 v[108:111], v[154:157], v[190:193], v[108:111]
	v_mfma_f32_16x16x32_bf16 v[104:107], v[132:135], v[198:201], v[104:107]
	v_mfma_f32_16x16x32_bf16 v[100:103], v[154:157], v[198:201], v[100:103]
	v_mfma_f32_16x16x32_bf16 v[128:131], v[136:139], v[172:175], v[128:131]
	v_mfma_f32_16x16x32_bf16 v[124:127], v[158:161], v[172:175], v[124:127]
	v_mfma_f32_16x16x32_bf16 v[120:123], v[136:139], v[180:183], v[120:123]
	v_mfma_f32_16x16x32_bf16 v[116:119], v[158:161], v[180:183], v[116:119]
	v_mfma_f32_16x16x32_bf16 v[112:115], v[136:139], v[194:197], v[112:115]
	v_mfma_f32_16x16x32_bf16 v[108:111], v[158:161], v[194:197], v[108:111]
	v_mfma_f32_16x16x32_bf16 v[104:107], v[136:139], v[202:205], v[104:107]
	v_mfma_f32_16x16x32_bf16 v[100:103], v[158:161], v[202:205], v[100:103]
	s_barrier
	s_setprio 0
	s_add_i32 s24, 0, 0x14000
	v_add_u32_e32 v166, s24, v186
	s_add_i32 s0, s0, s17
	ds_read_b128 v[206:209], v166
	ds_read_b128 v[210:213], v166 offset:1024
	ds_read_b128 v[214:217], v166 offset:2048
	ds_read_b128 v[218:221], v166 offset:3072
	v_lshl_add_u64 v[166:167], s[28:29], 0, v[26:27]
	s_mov_b32 m0, s0
	v_lshl_add_u64 v[168:169], s[28:29], 0, v[144:145]
	global_load_lds_dwordx4 v[166:167], off
	s_add_i32 m0, s0, 0x2000
	s_nop 0
	global_load_lds_dwordx4 v[168:169], off
	s_waitcnt vmcnt(10)
	s_setprio 1
	s_barrier
	s_waitcnt lgkmcnt(0)
	v_mfma_f32_16x16x32_bf16 v[68:71], v[206:209], v[162:165], v[68:71]
	v_mfma_f32_16x16x32_bf16 v[60:63], v[214:217], v[162:165], v[60:63]
	v_mfma_f32_16x16x32_bf16 v[56:59], v[206:209], v[176:179], v[56:59]
	v_mfma_f32_16x16x32_bf16 v[52:55], v[214:217], v[176:179], v[52:55]
	v_mfma_f32_16x16x32_bf16 v[48:51], v[206:209], v[190:193], v[48:51]
	v_mfma_f32_16x16x32_bf16 v[44:47], v[214:217], v[190:193], v[44:47]
	v_mfma_f32_16x16x32_bf16 v[40:43], v[206:209], v[198:201], v[40:43]
	v_mfma_f32_16x16x32_bf16 v[36:39], v[214:217], v[198:201], v[36:39]
	v_mfma_f32_16x16x32_bf16 v[68:71], v[210:213], v[172:175], v[68:71]
	v_mfma_f32_16x16x32_bf16 v[60:63], v[218:221], v[172:175], v[60:63]
	v_mfma_f32_16x16x32_bf16 v[56:59], v[210:213], v[180:183], v[56:59]
	v_mfma_f32_16x16x32_bf16 v[52:55], v[218:221], v[180:183], v[52:55]
	v_mfma_f32_16x16x32_bf16 v[48:51], v[210:213], v[194:197], v[48:51]
	v_mfma_f32_16x16x32_bf16 v[44:47], v[218:221], v[194:197], v[44:47]
	v_mfma_f32_16x16x32_bf16 v[40:43], v[210:213], v[202:205], v[40:43]
	v_mfma_f32_16x16x32_bf16 v[36:39], v[218:221], v[202:205], v[36:39]
	s_barrier
	s_setprio 0
	s_mov_b32 m0, s36
	v_lshl_add_u64 v[184:185], s[30:31], 0, v[140:141]
	ds_read_b128 v[162:165], v188 offset:16384
	ds_read_b128 v[172:175], v188 offset:17408
	ds_read_b128 v[176:179], v188 offset:18432
	ds_read_b128 v[180:183], v188 offset:19456
	ds_read_b128 v[190:193], v188 offset:20480
	ds_read_b128 v[194:197], v188 offset:21504
	ds_read_b128 v[198:201], v188 offset:22528
	ds_read_b128 v[202:205], v188 offset:23552
	global_load_lds_dwordx4 v[184:185], off
	v_lshl_add_u64 v[222:223], s[30:31], 0, v[142:143]
	s_mov_b32 m0, s37
	s_nop 0
	global_load_lds_dwordx4 v[222:223], off
	s_waitcnt vmcnt(10)
	s_setprio 1
	s_barrier
	s_waitcnt lgkmcnt(0)
	v_mfma_f32_16x16x32_bf16 v[96:99], v[132:135], v[162:165], v[96:99]
	v_mfma_f32_16x16x32_bf16 v[92:95], v[154:157], v[162:165], v[92:95]
	v_mfma_f32_16x16x32_bf16 v[88:91], v[132:135], v[176:179], v[88:91]
	v_mfma_f32_16x16x32_bf16 v[84:87], v[154:157], v[176:179], v[84:87]
	v_mfma_f32_16x16x32_bf16 v[80:83], v[132:135], v[190:193], v[80:83]
	v_mfma_f32_16x16x32_bf16 v[76:79], v[154:157], v[190:193], v[76:79]
	v_mfma_f32_16x16x32_bf16 v[72:75], v[132:135], v[198:201], v[72:75]
	v_mfma_f32_16x16x32_bf16 v[64:67], v[154:157], v[198:201], v[64:67]
	v_mfma_f32_16x16x32_bf16 v[96:99], v[136:139], v[172:175], v[96:99]
	v_mfma_f32_16x16x32_bf16 v[92:95], v[158:161], v[172:175], v[92:95]
	v_mfma_f32_16x16x32_bf16 v[88:91], v[136:139], v[180:183], v[88:91]
	v_mfma_f32_16x16x32_bf16 v[84:87], v[158:161], v[180:183], v[84:87]
	v_mfma_f32_16x16x32_bf16 v[80:83], v[136:139], v[194:197], v[80:83]
	v_mfma_f32_16x16x32_bf16 v[76:79], v[158:161], v[194:197], v[76:79]
	v_mfma_f32_16x16x32_bf16 v[72:75], v[136:139], v[202:205], v[72:75]
	v_mfma_f32_16x16x32_bf16 v[64:67], v[158:161], v[202:205], v[64:67]
	s_barrier
	s_setprio 0
	s_add_u32 s0, s28, 0xb0000
	s_addc_u32 s1, s29, 0
	s_add_i32 s24, s24, s17
	s_mov_b32 m0, s24
	s_nop 0
	global_load_lds_dwordx4 v26, s[0:1]
	s_add_i32 m0, s24, 0x2000
	s_nop 0
	global_load_lds_dwordx4 v144, s[0:1]
	v_add_u32_e32 v158, 0x18000, v186
	ds_read_b128 v[132:135], v158
	ds_read_b128 v[136:139], v158 offset:1024
	ds_read_b128 v[154:157], v158 offset:2048
	ds_read_b128 v[158:161], v158 offset:3072
	s_waitcnt vmcnt(10)
	s_setprio 1
	s_barrier
	v_mfma_f32_16x16x32_bf16 v[32:35], v[206:209], v[162:165], v[32:35]
	v_mfma_f32_16x16x32_bf16 v[28:31], v[214:217], v[162:165], v[28:31]
	v_mfma_f32_16x16x32_bf16 v[22:25], v[206:209], v[176:179], v[22:25]
	v_mfma_f32_16x16x32_bf16 v[18:21], v[214:217], v[176:179], v[18:21]
	v_mfma_f32_16x16x32_bf16 v[14:17], v[206:209], v[190:193], v[14:17]
	v_mfma_f32_16x16x32_bf16 v[10:13], v[214:217], v[190:193], v[10:13]
	v_mfma_f32_16x16x32_bf16 v[6:9], v[206:209], v[198:201], v[6:9]
	v_mfma_f32_16x16x32_bf16 v[2:5], v[214:217], v[198:201], v[2:5]
	v_mfma_f32_16x16x32_bf16 v[32:35], v[210:213], v[172:175], v[32:35]
	v_mfma_f32_16x16x32_bf16 v[28:31], v[218:221], v[172:175], v[28:31]
	v_mfma_f32_16x16x32_bf16 v[22:25], v[210:213], v[180:183], v[22:25]
	v_mfma_f32_16x16x32_bf16 v[18:21], v[218:221], v[180:183], v[18:21]
	v_mfma_f32_16x16x32_bf16 v[14:17], v[210:213], v[194:197], v[14:17]
	v_mfma_f32_16x16x32_bf16 v[10:13], v[218:221], v[194:197], v[10:13]
	v_mfma_f32_16x16x32_bf16 v[6:9], v[210:213], v[202:205], v[6:9]
	v_mfma_f32_16x16x32_bf16 v[2:5], v[218:221], v[202:205], v[2:5]
	s_barrier
	s_setprio 0
	s_add_i32 s24, 0, 0x18000
	s_add_u32 s0, s30, 0xb0000
	s_addc_u32 s1, s31, 0
	s_mov_b32 m0, s52
	ds_read_b128 v[162:165], v188 offset:32768
	ds_read_b128 v[172:175], v188 offset:33792
	ds_read_b128 v[176:179], v188 offset:34816
	ds_read_b128 v[180:183], v188 offset:35840
	ds_read_b128 v[190:193], v188 offset:36864
	ds_read_b128 v[194:197], v188 offset:37888
	ds_read_b128 v[198:201], v188 offset:38912
	ds_read_b128 v[202:205], v188 offset:39936
	global_load_lds_dwordx4 v140, s[0:1]
	s_mov_b32 m0, s54
	s_nop 0
	global_load_lds_dwordx4 v142, s[0:1]
	s_waitcnt vmcnt(10) lgkmcnt(8)
	s_setprio 1
	s_barrier
	s_waitcnt lgkmcnt(0)
	v_mfma_f32_16x16x32_bf16 v[128:131], v[132:135], v[162:165], v[128:131]
	v_mfma_f32_16x16x32_bf16 v[124:127], v[154:157], v[162:165], v[124:127]
	v_mfma_f32_16x16x32_bf16 v[120:123], v[132:135], v[176:179], v[120:123]
	v_mfma_f32_16x16x32_bf16 v[116:119], v[154:157], v[176:179], v[116:119]
	v_mfma_f32_16x16x32_bf16 v[112:115], v[132:135], v[190:193], v[112:115]
	v_mfma_f32_16x16x32_bf16 v[108:111], v[154:157], v[190:193], v[108:111]
	v_mfma_f32_16x16x32_bf16 v[104:107], v[132:135], v[198:201], v[104:107]
	v_mfma_f32_16x16x32_bf16 v[100:103], v[154:157], v[198:201], v[100:103]
	v_mfma_f32_16x16x32_bf16 v[128:131], v[136:139], v[172:175], v[128:131]
	v_mfma_f32_16x16x32_bf16 v[124:127], v[158:161], v[172:175], v[124:127]
	v_mfma_f32_16x16x32_bf16 v[120:123], v[136:139], v[180:183], v[120:123]
	v_mfma_f32_16x16x32_bf16 v[116:119], v[158:161], v[180:183], v[116:119]
	v_mfma_f32_16x16x32_bf16 v[112:115], v[136:139], v[194:197], v[112:115]
	v_mfma_f32_16x16x32_bf16 v[108:111], v[158:161], v[194:197], v[108:111]
	v_mfma_f32_16x16x32_bf16 v[104:107], v[136:139], v[202:205], v[104:107]
	v_mfma_f32_16x16x32_bf16 v[100:103], v[158:161], v[202:205], v[100:103]
	s_barrier
	s_setprio 0
	s_add_i32 s25, 0, 0x1c000
	s_add_i32 s0, s24, s17
	v_add_u32_e32 v189, s25, v186
	v_lshl_add_u64 v[166:167], v[166:167], 0, s[12:13]
	s_mov_b32 m0, s0
	ds_read_b128 v[206:209], v189
	ds_read_b128 v[210:213], v189 offset:1024
	ds_read_b128 v[214:217], v189 offset:2048
	ds_read_b128 v[218:221], v189 offset:3072
	global_load_lds_dwordx4 v[166:167], off
	v_lshl_add_u64 v[166:167], v[168:169], 0, s[12:13]
	s_add_i32 m0, s0, 0x2000
	s_nop 0
	global_load_lds_dwordx4 v[166:167], off
	s_waitcnt vmcnt(10)
	s_setprio 1
	s_barrier
	s_waitcnt lgkmcnt(0)
	v_mfma_f32_16x16x32_bf16 v[68:71], v[206:209], v[162:165], v[68:71]
	v_mfma_f32_16x16x32_bf16 v[60:63], v[214:217], v[162:165], v[60:63]
	v_mfma_f32_16x16x32_bf16 v[56:59], v[206:209], v[176:179], v[56:59]
	v_mfma_f32_16x16x32_bf16 v[52:55], v[214:217], v[176:179], v[52:55]
	v_mfma_f32_16x16x32_bf16 v[48:51], v[206:209], v[190:193], v[48:51]
	v_mfma_f32_16x16x32_bf16 v[44:47], v[214:217], v[190:193], v[44:47]
	v_mfma_f32_16x16x32_bf16 v[40:43], v[206:209], v[198:201], v[40:43]
	v_mfma_f32_16x16x32_bf16 v[36:39], v[214:217], v[198:201], v[36:39]
	v_mfma_f32_16x16x32_bf16 v[68:71], v[210:213], v[172:175], v[68:71]
	v_mfma_f32_16x16x32_bf16 v[60:63], v[218:221], v[172:175], v[60:63]
	v_mfma_f32_16x16x32_bf16 v[56:59], v[210:213], v[180:183], v[56:59]
	v_mfma_f32_16x16x32_bf16 v[52:55], v[218:221], v[180:183], v[52:55]
	v_mfma_f32_16x16x32_bf16 v[48:51], v[210:213], v[194:197], v[48:51]
	v_mfma_f32_16x16x32_bf16 v[44:47], v[218:221], v[194:197], v[44:47]
	v_mfma_f32_16x16x32_bf16 v[40:43], v[210:213], v[202:205], v[40:43]
	v_mfma_f32_16x16x32_bf16 v[36:39], v[218:221], v[202:205], v[36:39]
	s_barrier
	s_setprio 0
	s_mov_b32 m0, s55
	v_lshl_add_u64 v[166:167], v[184:185], 0, s[12:13]
	ds_read_b128 v[162:165], v188 offset:49152
	ds_read_b128 v[172:175], v188 offset:50176
	ds_read_b128 v[176:179], v188 offset:51200
	ds_read_b128 v[180:183], v188 offset:52224
	ds_read_b128 v[190:193], v188 offset:53248
	ds_read_b128 v[194:197], v188 offset:54272
	ds_read_b128 v[198:201], v188 offset:55296
	ds_read_b128 v[202:205], v188 offset:56320
	global_load_lds_dwordx4 v[166:167], off
	v_lshl_add_u64 v[166:167], v[222:223], 0, s[12:13]
	s_mov_b32 m0, s56
	s_nop 0
	global_load_lds_dwordx4 v[166:167], off
	s_waitcnt vmcnt(10)
	s_setprio 1
	s_barrier
	s_waitcnt lgkmcnt(0)
	v_mfma_f32_16x16x32_bf16 v[96:99], v[132:135], v[162:165], v[96:99]
	v_mfma_f32_16x16x32_bf16 v[92:95], v[154:157], v[162:165], v[92:95]
	v_mfma_f32_16x16x32_bf16 v[88:91], v[132:135], v[176:179], v[88:91]
	v_mfma_f32_16x16x32_bf16 v[84:87], v[154:157], v[176:179], v[84:87]
	v_mfma_f32_16x16x32_bf16 v[80:83], v[132:135], v[190:193], v[80:83]
	v_mfma_f32_16x16x32_bf16 v[76:79], v[154:157], v[190:193], v[76:79]
	v_mfma_f32_16x16x32_bf16 v[72:75], v[132:135], v[198:201], v[72:75]
	v_mfma_f32_16x16x32_bf16 v[64:67], v[154:157], v[198:201], v[64:67]
	v_mfma_f32_16x16x32_bf16 v[96:99], v[136:139], v[172:175], v[96:99]
	v_mfma_f32_16x16x32_bf16 v[92:95], v[158:161], v[172:175], v[92:95]
	v_mfma_f32_16x16x32_bf16 v[88:91], v[136:139], v[180:183], v[88:91]
	v_mfma_f32_16x16x32_bf16 v[84:87], v[158:161], v[180:183], v[84:87]
	v_mfma_f32_16x16x32_bf16 v[80:83], v[136:139], v[194:197], v[80:83]
	v_mfma_f32_16x16x32_bf16 v[76:79], v[158:161], v[194:197], v[76:79]
	v_mfma_f32_16x16x32_bf16 v[72:75], v[136:139], v[202:205], v[72:75]
	v_mfma_f32_16x16x32_bf16 v[64:67], v[158:161], v[202:205], v[64:67]
	s_barrier
	s_setprio 0
	s_add_u32 s0, s28, 0xb0080
	s_addc_u32 s1, s29, 0
	s_add_i32 s24, s25, s17
	s_mov_b32 m0, s24
	s_nop 0
	global_load_lds_dwordx4 v26, s[0:1]
	s_add_i32 m0, s24, 0x2000
	s_nop 0
	global_load_lds_dwordx4 v144, s[0:1]
	v_add_u32_e32 v158, 0x10000, v186
	ds_read_b128 v[132:135], v158
	ds_read_b128 v[136:139], v158 offset:1024
	ds_read_b128 v[154:157], v158 offset:2048
	ds_read_b128 v[158:161], v158 offset:3072
	s_add_i32 s72, s72, 2
	s_add_u32 s68, s68, 0x100
	s_addc_u32 s69, s69, 0
	s_mov_b64 s[24:25], s[26:27]
	s_cmp_gt_u32 s72, 41
	s_cbranch_scc1 .Lth__1122
	s_add_u32 s26, s24, 0x100
	s_addc_u32 s27, s25, 0
	s_add_i32 s0, 0, 0x10000
	s_cmp_eq_u32 s72, 40
	s_cselect_b32 s31, s43, s27
	s_cselect_b32 s30, s42, s26
	s_cselect_b32 s29, s45, s69
	s_cselect_b32 s28, s44, s68
	s_cmp_gt_u32 s72, 41
.Lth__1122:
	s_waitcnt vmcnt(10)
	s_setprio 1
	s_barrier
	v_mfma_f32_16x16x32_bf16 v[32:35], v[206:209], v[162:165], v[32:35]
	v_mfma_f32_16x16x32_bf16 v[28:31], v[214:217], v[162:165], v[28:31]
	v_mfma_f32_16x16x32_bf16 v[22:25], v[206:209], v[176:179], v[22:25]
	v_mfma_f32_16x16x32_bf16 v[18:21], v[214:217], v[176:179], v[18:21]
	v_mfma_f32_16x16x32_bf16 v[14:17], v[206:209], v[190:193], v[14:17]
	v_mfma_f32_16x16x32_bf16 v[10:13], v[214:217], v[190:193], v[10:13]
	v_mfma_f32_16x16x32_bf16 v[6:9], v[206:209], v[198:201], v[6:9]
	v_mfma_f32_16x16x32_bf16 v[2:5], v[214:217], v[198:201], v[2:5]
	v_mfma_f32_16x16x32_bf16 v[32:35], v[210:213], v[172:175], v[32:35]
	v_mfma_f32_16x16x32_bf16 v[28:31], v[218:221], v[172:175], v[28:31]
	v_mfma_f32_16x16x32_bf16 v[22:25], v[210:213], v[180:183], v[22:25]
	v_mfma_f32_16x16x32_bf16 v[18:21], v[218:221], v[180:183], v[18:21]
	v_mfma_f32_16x16x32_bf16 v[14:17], v[210:213], v[194:197], v[14:17]
	v_mfma_f32_16x16x32_bf16 v[10:13], v[218:221], v[194:197], v[10:13]
	v_mfma_f32_16x16x32_bf16 v[6:9], v[210:213], v[202:205], v[6:9]
	v_mfma_f32_16x16x32_bf16 v[2:5], v[218:221], v[202:205], v[2:5]
	s_barrier
	s_setprio 0
	s_cbranch_scc0 .LBB0_1122
	s_waitcnt lgkmcnt(0)
	s_min_i32 s0, s22, 0x100
	s_ashr_i32 s26, s0, 5
	s_add_i32 s0, s22, 0xffffff00
	s_cmpk_lt_i32 s22, 0x100
	s_cselect_b32 s0, s22, s0
	s_cselect_b32 s25, 0, s51
	s_cselect_b32 s24, 0, s50
	s_ashr_i32 s1, s0, 31
	s_lshl_b64 s[0:1], s[0:1], 19
	s_add_u32 s24, s20, s24
	v_lshl_or_b32 v166, s23, 8, v187
	s_addc_u32 s25, s21, s25
	s_ashr_i32 s23, s22, 31
	v_lshl_add_u64 v[132:133], s[0:1], 0, v[146:147]
	s_lshl_b64 s[22:23], s[22:23], 10
	s_mul_hi_i32 s1, s26, 0x9000
	s_mul_i32 s26, s26, 0x9000
	s_add_u32 s0, s34, s26
	v_ashrrev_i32_e32 v167, 31, v166
	s_addc_u32 s1, s35, s1
	v_lshl_add_u64 v[154:155], v[166:167], 2, s[0:1]
	v_lshl_add_u64 v[168:169], v[132:133], 0, v[166:167]
	v_lshl_add_u64 v[176:177], v[132:133], 1, s[24:25]
	global_load_dwordx4 v[132:135], v[154:155], off offset:16
	global_load_dwordx4 v[136:139], v[154:155], off
	v_lshl_add_u64 v[182:183], v[168:169], 1, s[24:25]
	v_add_co_u32_e32 v184, vcc, s65, v182
	s_mov_b32 s0, 0x20000
	s_nop 0
	v_addc_co_u32_e32 v185, vcc, 0, v183, vcc
	v_add_co_u32_e32 v178, vcc, s0, v182
	s_mov_b32 s1, 0x30000
	s_nop 0
	v_addc_co_u32_e32 v179, vcc, 0, v183, vcc
	v_add_co_u32_e32 v180, vcc, s1, v182
	v_lshl_add_u64 v[176:177], v[166:167], 1, v[176:177]
	s_nop 0
	v_addc_co_u32_e32 v181, vcc, 0, v183, vcc
	s_mov_b32 s24, 0x80000
	s_mov_b32 s25, 0x90000
	s_waitcnt vmcnt(0)
	v_pk_mul_f32 v[164:165], v[134:135], 0.5 op_sel_hi:[1,0]
	v_pk_mul_f32 v[174:175], v[138:139], 0.5 op_sel_hi:[1,0]
	v_pk_mul_f32 v[172:173], v[136:137], 0.5 op_sel_hi:[1,0]
	v_pk_mul_f32 v[162:163], v[132:133], 0.5 op_sel_hi:[1,0]
	global_load_dwordx4 v[132:135], v[154:155], off offset:528
	global_load_dwordx4 v[136:139], v[154:155], off offset:512
	global_load_dwordx4 v[190:193], v[182:183], off offset:2048
	global_load_dwordx4 v[194:197], v[184:185], off offset:2048
	s_waitcnt vmcnt(0)
	v_pk_mul_f32 v[156:157], v[134:135], 0.5 op_sel_hi:[1,0]
	v_pk_mul_f32 v[160:161], v[138:139], 0.5 op_sel_hi:[1,0]
	v_pk_mul_f32 v[158:159], v[136:137], 0.5 op_sel_hi:[1,0]
	global_load_dwordx4 v[136:139], v[178:179], off offset:2048
	v_pk_mul_f32 v[154:155], v[132:133], 0.5 op_sel_hi:[1,0]
	global_load_dwordx4 v[132:135], v[180:181], off offset:2048
	v_lshlrev_b32_e32 v166, 16, v190
	v_and_b32_e32 v167, 0xffff0000, v190
	v_lshlrev_b32_e32 v168, 16, v191
	v_and_b32_e32 v169, 0xffff0000, v191
	v_lshlrev_b32_e32 v190, 16, v192
	v_and_b32_e32 v191, 0xffff0000, v192
	v_lshlrev_b32_e32 v192, 16, v193
	v_and_b32_e32 v193, 0xffff0000, v193
	v_pk_fma_f32 v[130:131], v[130:131], v[174:175], v[168:169]
	v_pk_fma_f32 v[128:129], v[128:129], v[172:173], v[166:167]
	v_pk_fma_f32 v[166:167], v[126:127], v[164:165], v[192:193]
	v_pk_fma_f32 v[126:127], v[124:125], v[162:163], v[190:191]
	v_lshlrev_b32_e32 v202, 16, v196
	v_and_b32_e32 v203, 0xffff0000, v196
	v_lshlrev_b32_e32 v204, 16, v197
	v_and_b32_e32 v205, 0xffff0000, v197
	v_cvt_pk_bf16_f32 v124, v128, v129
	v_cvt_pk_bf16_f32 v125, v130, v131
	v_cvt_pk_bf16_f32 v126, v126, v127
	v_cvt_pk_bf16_f32 v127, v166, v167
	v_lshlrev_b32_e32 v200, 16, v195
	v_and_b32_e32 v201, 0xffff0000, v195
	global_store_dwordx4 v[176:177], v[124:127], off offset:2048
	v_lshlrev_b32_e32 v193, 16, v124
	v_and_b32_e32 v196, 0xffff0000, v124
	v_lshlrev_b32_e32 v191, 16, v125
	v_and_b32_e32 v195, 0xffff0000, v125
	v_pk_fma_f32 v[124:125], v[118:119], v[164:165], v[204:205]
	v_pk_fma_f32 v[118:119], v[116:117], v[162:163], v[202:203]
	v_lshlrev_b32_e32 v198, 16, v194
	v_cvt_pk_bf16_f32 v118, v118, v119
	v_cvt_pk_bf16_f32 v119, v124, v125
	v_add_co_u32_e32 v124, vcc, s65, v176
	v_and_b32_e32 v199, 0xffff0000, v194
	s_nop 0
	v_addc_co_u32_e32 v125, vcc, 0, v177, vcc
	v_lshlrev_b32_e32 v190, 16, v126
	v_and_b32_e32 v194, 0xffff0000, v126
	v_add_co_u32_e32 v126, vcc, s24, v182
	v_lshlrev_b32_e32 v189, 16, v127
	v_and_b32_e32 v192, 0xffff0000, v127
	v_addc_co_u32_e32 v127, vcc, 0, v183, vcc
	v_add_co_u32_e32 v128, vcc, s25, v182
	v_pk_fma_f32 v[122:123], v[122:123], v[174:175], v[200:201]
	v_pk_fma_f32 v[120:121], v[120:121], v[172:173], v[198:199]
	v_addc_co_u32_e32 v129, vcc, 0, v183, vcc
	v_cvt_pk_bf16_f32 v116, v120, v121
	v_cvt_pk_bf16_f32 v117, v122, v123
	global_store_dwordx4 v[124:125], v[116:119], off offset:2048
	global_load_dwordx4 v[120:123], v[126:127], off offset:2048
	global_load_dwordx4 v[198:201], v[128:129], off offset:2048
	s_waitcnt vmcnt(0)
	v_lshlrev_b32_e32 v130, 16, v136
	v_and_b32_e32 v131, 0xffff0000, v136
	v_lshlrev_b32_e32 v166, 16, v138
	v_and_b32_e32 v167, 0xffff0000, v138
	v_lshlrev_b32_e32 v138, 16, v139
	v_and_b32_e32 v139, 0xffff0000, v139
	v_pk_fma_f32 v[112:113], v[112:113], v[172:173], v[130:131]
	v_pk_fma_f32 v[130:131], v[110:111], v[164:165], v[138:139]
	v_pk_fma_f32 v[110:111], v[108:109], v[162:163], v[166:167]
	v_lshlrev_b32_e32 v168, 16, v132
	v_cvt_pk_bf16_f32 v110, v110, v111
	v_cvt_pk_bf16_f32 v111, v130, v131
	v_add_co_u32_e32 v130, vcc, s0, v176
	v_and_b32_e32 v169, 0xffff0000, v132
	v_lshlrev_b32_e32 v132, 16, v133
	v_and_b32_e32 v133, 0xffff0000, v133
	v_addc_co_u32_e32 v131, vcc, 0, v177, vcc
	v_lshlrev_b32_e32 v136, 16, v137
	v_and_b32_e32 v137, 0xffff0000, v137
	v_lshlrev_b32_e32 v202, 16, v134
	v_and_b32_e32 v203, 0xffff0000, v134
	v_lshlrev_b32_e32 v134, 16, v135
	v_and_b32_e32 v135, 0xffff0000, v135
	v_pk_fma_f32 v[106:107], v[106:107], v[174:175], v[132:133]
	v_add_co_u32_e32 v132, vcc, s1, v176
	v_pk_fma_f32 v[114:115], v[114:115], v[174:175], v[136:137]
	v_cvt_pk_bf16_f32 v108, v112, v113
	v_pk_fma_f32 v[104:105], v[104:105], v[172:173], v[168:169]
	v_pk_fma_f32 v[112:113], v[102:103], v[164:165], v[134:135]
	v_pk_fma_f32 v[102:103], v[100:101], v[162:163], v[202:203]
	v_addc_co_u32_e32 v133, vcc, 0, v177, vcc
	v_cvt_pk_bf16_f32 v109, v114, v115
	v_cvt_pk_bf16_f32 v100, v104, v105
	v_cvt_pk_bf16_f32 v101, v106, v107
	v_cvt_pk_bf16_f32 v102, v102, v103
	v_cvt_pk_bf16_f32 v103, v112, v113
	v_add_co_u32_e32 v134, vcc, s76, v182
	global_store_dwordx4 v[130:131], v[108:111], off offset:2048
	global_store_dwordx4 v[132:133], v[100:103], off offset:2048
	v_addc_co_u32_e32 v135, vcc, 0, v183, vcc
	s_mov_b32 s0, 0xb0000
	global_load_dwordx4 v[112:115], v[134:135], off offset:2048
	v_add_co_u32_e32 v136, vcc, s0, v182
	v_lshlrev_b32_e32 v138, 16, v120
	s_nop 0
	v_addc_co_u32_e32 v137, vcc, 0, v183, vcc
	global_load_dwordx4 v[104:107], v[136:137], off offset:2048
	v_and_b32_e32 v139, 0xffff0000, v120
	v_lshlrev_b32_e32 v120, 16, v121
	v_and_b32_e32 v121, 0xffff0000, v121
	v_lshlrev_b32_e32 v166, 16, v122
	v_and_b32_e32 v167, 0xffff0000, v122
	v_lshlrev_b32_e32 v122, 16, v123
	v_and_b32_e32 v123, 0xffff0000, v123
	v_pk_fma_f32 v[96:97], v[96:97], v[172:173], v[138:139]
	v_lshlrev_b32_e32 v168, 16, v198
	v_and_b32_e32 v169, 0xffff0000, v198
	v_lshlrev_b32_e32 v198, 16, v199
	v_and_b32_e32 v199, 0xffff0000, v199
	v_pk_fma_f32 v[98:99], v[98:99], v[174:175], v[120:121]
	v_pk_fma_f32 v[120:121], v[94:95], v[164:165], v[122:123]
	v_pk_fma_f32 v[94:95], v[92:93], v[162:163], v[166:167]
	v_cvt_pk_bf16_f32 v92, v96, v97
	v_add_co_u32_e32 v96, vcc, s24, v176
	v_lshlrev_b32_e32 v202, 16, v200
	v_and_b32_e32 v203, 0xffff0000, v200
	v_lshlrev_b32_e32 v200, 16, v201
	v_and_b32_e32 v201, 0xffff0000, v201
	v_addc_co_u32_e32 v97, vcc, 0, v177, vcc
	v_pk_fma_f32 v[90:91], v[90:91], v[174:175], v[198:199]
	v_pk_fma_f32 v[88:89], v[88:89], v[172:173], v[168:169]
	v_cvt_pk_bf16_f32 v93, v98, v99
	v_pk_fma_f32 v[98:99], v[86:87], v[164:165], v[200:201]
	v_pk_fma_f32 v[86:87], v[84:85], v[162:163], v[202:203]
	v_cvt_pk_bf16_f32 v84, v88, v89
	v_cvt_pk_bf16_f32 v85, v90, v91
	v_add_co_u32_e32 v88, vcc, s25, v176
	v_cvt_pk_bf16_f32 v86, v86, v87
	v_cvt_pk_bf16_f32 v87, v98, v99
	v_addc_co_u32_e32 v89, vcc, 0, v177, vcc
	v_cvt_pk_bf16_f32 v94, v94, v95
	v_cvt_pk_bf16_f32 v95, v120, v121
	global_store_dwordx4 v[96:97], v[92:95], off offset:2048
	global_store_dwordx4 v[88:89], v[84:87], off offset:2048
	global_load_dwordx4 v[120:123], v[182:183], off offset:2304
	s_nop 0
	global_load_dwordx4 v[182:185], v[184:185], off offset:2304
	s_waitcnt vmcnt(0)
	v_lshlrev_b32_e32 v90, 16, v112
	v_and_b32_e32 v91, 0xffff0000, v112
	v_lshlrev_b32_e32 v98, 16, v113
	v_and_b32_e32 v99, 0xffff0000, v113
	v_lshlrev_b32_e32 v112, 16, v114
	v_and_b32_e32 v113, 0xffff0000, v114
	v_lshlrev_b32_e32 v114, 16, v115
	v_and_b32_e32 v115, 0xffff0000, v115
	v_pk_fma_f32 v[80:81], v[80:81], v[172:173], v[90:91]
	v_pk_fma_f32 v[90:91], v[78:79], v[164:165], v[114:115]
	v_pk_fma_f32 v[78:79], v[76:77], v[162:163], v[112:113]
	v_cvt_pk_bf16_f32 v76, v80, v81
	v_add_co_u32_e32 v80, vcc, s76, v176
	v_lshlrev_b32_e32 v138, 16, v104
	v_and_b32_e32 v139, 0xffff0000, v104
	v_lshlrev_b32_e32 v104, 16, v105
	v_and_b32_e32 v105, 0xffff0000, v105
	v_lshlrev_b32_e32 v166, 16, v106
	v_and_b32_e32 v167, 0xffff0000, v106
	v_lshlrev_b32_e32 v106, 16, v107
	v_and_b32_e32 v107, 0xffff0000, v107
	v_pk_fma_f32 v[82:83], v[82:83], v[174:175], v[98:99]
	v_addc_co_u32_e32 v81, vcc, 0, v177, vcc
	v_pk_fma_f32 v[72:73], v[72:73], v[172:173], v[138:139]
	v_cvt_pk_bf16_f32 v77, v82, v83
	v_pk_fma_f32 v[74:75], v[74:75], v[174:175], v[104:105]
	v_pk_fma_f32 v[82:83], v[66:67], v[164:165], v[106:107]
	v_pk_fma_f32 v[66:67], v[64:65], v[162:163], v[166:167]
	v_cvt_pk_bf16_f32 v64, v72, v73
	v_add_co_u32_e32 v72, vcc, s0, v176
	v_cvt_pk_bf16_f32 v78, v78, v79
	v_cvt_pk_bf16_f32 v79, v90, v91
	v_cvt_pk_bf16_f32 v65, v74, v75
	v_cvt_pk_bf16_f32 v66, v66, v67
	v_cvt_pk_bf16_f32 v67, v82, v83
	v_addc_co_u32_e32 v73, vcc, 0, v177, vcc
	global_store_dwordx4 v[80:81], v[76:79], off offset:2048
	global_store_dwordx4 v[72:73], v[64:67], off offset:2048
	global_load_dwordx4 v[104:107], v[178:179], off offset:2304
	global_load_dwordx4 v[112:115], v[180:181], off offset:2304
	v_lshlrev_b32_e32 v74, 16, v120
	v_and_b32_e32 v75, 0xffff0000, v120
	v_lshlrev_b32_e32 v82, 16, v121
	v_and_b32_e32 v83, 0xffff0000, v121
	v_lshlrev_b32_e32 v90, 16, v122
	v_and_b32_e32 v91, 0xffff0000, v122
	v_lshlrev_b32_e32 v98, 16, v123
	v_and_b32_e32 v99, 0xffff0000, v123
	v_pk_fma_f32 v[70:71], v[70:71], v[160:161], v[82:83]
	v_pk_fma_f32 v[68:69], v[68:69], v[158:159], v[74:75]
	v_pk_fma_f32 v[74:75], v[62:63], v[156:157], v[98:99]
	v_pk_fma_f32 v[62:63], v[60:61], v[154:155], v[90:91]
	v_lshlrev_b32_e32 v120, 16, v182
	v_and_b32_e32 v121, 0xffff0000, v182
	v_lshlrev_b32_e32 v122, 16, v183
	v_and_b32_e32 v123, 0xffff0000, v183
	v_lshlrev_b32_e32 v138, 16, v184
	v_and_b32_e32 v139, 0xffff0000, v184
	v_lshlrev_b32_e32 v162, 16, v185
	v_and_b32_e32 v163, 0xffff0000, v185
	v_cvt_pk_bf16_f32 v60, v68, v69
	v_cvt_pk_bf16_f32 v61, v70, v71
	v_cvt_pk_bf16_f32 v62, v62, v63
	v_cvt_pk_bf16_f32 v63, v74, v75
	global_store_dwordx4 v[176:177], v[60:63], off offset:2304
	v_lshlrev_b32_e32 v164, 16, v60
	v_and_b32_e32 v165, 0xffff0000, v60
	v_lshlrev_b32_e32 v166, 16, v61
	v_and_b32_e32 v167, 0xffff0000, v61
	v_pk_fma_f32 v[58:59], v[58:59], v[160:161], v[122:123]
	v_pk_fma_f32 v[56:57], v[56:57], v[158:159], v[120:121]
	v_pk_fma_f32 v[60:61], v[54:55], v[156:157], v[162:163]
	v_pk_fma_f32 v[54:55], v[52:53], v[154:155], v[138:139]
	v_cvt_pk_bf16_f32 v52, v56, v57
	v_cvt_pk_bf16_f32 v53, v58, v59
	v_cvt_pk_bf16_f32 v54, v54, v55
	v_cvt_pk_bf16_f32 v55, v60, v61
	global_store_dwordx4 v[124:125], v[52:55], off offset:2304
	v_lshlrev_b32_e32 v168, 16, v62
	v_and_b32_e32 v169, 0xffff0000, v62
	v_lshlrev_b32_e32 v172, 16, v63
	v_and_b32_e32 v173, 0xffff0000, v63
	global_load_dwordx4 v[56:59], v[126:127], off offset:2304
	global_load_dwordx4 v[60:63], v[128:129], off offset:2304
	s_waitcnt vmcnt(0)
	v_lshlrev_b32_e32 v68, 16, v104
	v_and_b32_e32 v69, 0xffff0000, v104
	v_lshlrev_b32_e32 v70, 16, v105
	v_and_b32_e32 v71, 0xffff0000, v105
	v_lshlrev_b32_e32 v74, 16, v106
	v_and_b32_e32 v75, 0xffff0000, v106
	v_lshlrev_b32_e32 v82, 16, v107
	v_and_b32_e32 v83, 0xffff0000, v107
	v_lshlrev_b32_e32 v90, 16, v112
	v_and_b32_e32 v91, 0xffff0000, v112
	v_lshlrev_b32_e32 v98, 16, v113
	v_and_b32_e32 v99, 0xffff0000, v113
	v_lshlrev_b32_e32 v104, 16, v114
	v_and_b32_e32 v105, 0xffff0000, v114
	v_lshlrev_b32_e32 v106, 16, v115
	v_and_b32_e32 v107, 0xffff0000, v115
	v_pk_fma_f32 v[48:49], v[48:49], v[158:159], v[68:69]
	v_pk_fma_f32 v[50:51], v[50:51], v[160:161], v[70:71]
	v_pk_fma_f32 v[68:69], v[46:47], v[156:157], v[82:83]
	v_pk_fma_f32 v[46:47], v[44:45], v[154:155], v[74:75]
	v_cvt_pk_bf16_f32 v44, v48, v49
	v_pk_fma_f32 v[42:43], v[42:43], v[160:161], v[98:99]
	v_pk_fma_f32 v[40:41], v[40:41], v[158:159], v[90:91]
	v_pk_fma_f32 v[48:49], v[38:39], v[156:157], v[106:107]
	v_pk_fma_f32 v[38:39], v[36:37], v[154:155], v[104:105]
	v_cvt_pk_bf16_f32 v45, v50, v51
	v_cvt_pk_bf16_f32 v46, v46, v47
	v_cvt_pk_bf16_f32 v47, v68, v69
	v_cvt_pk_bf16_f32 v36, v40, v41
	v_cvt_pk_bf16_f32 v37, v42, v43
	v_cvt_pk_bf16_f32 v38, v38, v39
	v_cvt_pk_bf16_f32 v39, v48, v49
	global_store_dwordx4 v[130:131], v[44:47], off offset:2304
	global_store_dwordx4 v[132:133], v[36:39], off offset:2304
	global_load_dwordx4 v[40:43], v[134:135], off offset:2304
	global_load_dwordx4 v[48:51], v[136:137], off offset:2304
	v_lshlrev_b32_e32 v68, 16, v56
	v_and_b32_e32 v69, 0xffff0000, v56
	v_lshlrev_b32_e32 v56, 16, v57
	v_and_b32_e32 v57, 0xffff0000, v57
	v_lshlrev_b32_e32 v70, 16, v58
	v_and_b32_e32 v71, 0xffff0000, v58
	v_lshlrev_b32_e32 v58, 16, v59
	v_and_b32_e32 v59, 0xffff0000, v59
	v_lshlrev_b32_e32 v74, 16, v60
	v_and_b32_e32 v75, 0xffff0000, v60
	v_lshlrev_b32_e32 v82, 16, v62
	v_and_b32_e32 v83, 0xffff0000, v62
	v_lshlrev_b32_e32 v62, 16, v63
	v_and_b32_e32 v63, 0xffff0000, v63
	v_pk_fma_f32 v[32:33], v[32:33], v[158:159], v[68:69]
	v_lshlrev_b32_e32 v60, 16, v61
	v_and_b32_e32 v61, 0xffff0000, v61
	v_pk_fma_f32 v[34:35], v[34:35], v[160:161], v[56:57]
	v_pk_fma_f32 v[56:57], v[30:31], v[156:157], v[58:59]
	v_pk_fma_f32 v[30:31], v[28:29], v[154:155], v[70:71]
	v_cvt_pk_bf16_f32 v28, v32, v33
	v_pk_fma_f32 v[22:23], v[22:23], v[158:159], v[74:75]
	v_pk_fma_f32 v[32:33], v[20:21], v[156:157], v[62:63]
	v_pk_fma_f32 v[20:21], v[18:19], v[154:155], v[82:83]
	v_cvt_pk_bf16_f32 v29, v34, v35
	v_pk_fma_f32 v[24:25], v[24:25], v[160:161], v[60:61]
	v_cvt_pk_bf16_f32 v18, v22, v23
	v_cvt_pk_bf16_f32 v20, v20, v21
	v_cvt_pk_bf16_f32 v21, v32, v33
	v_cvt_pk_bf16_f32 v19, v24, v25
	v_cvt_pk_bf16_f32 v30, v30, v31
	v_cvt_pk_bf16_f32 v31, v56, v57
	global_store_dwordx4 v[96:97], v[28:31], off offset:2304
	global_store_dwordx4 v[88:89], v[18:21], off offset:2304
	s_waitcnt vmcnt(0)
	v_lshlrev_b32_e32 v22, 16, v40
	v_and_b32_e32 v23, 0xffff0000, v40
	v_lshlrev_b32_e32 v32, 16, v42
	v_and_b32_e32 v33, 0xffff0000, v42
	v_lshlrev_b32_e32 v34, 16, v43
	v_and_b32_e32 v35, 0xffff0000, v43
	v_lshlrev_b32_e32 v42, 16, v49
	v_and_b32_e32 v43, 0xffff0000, v49
	v_lshlrev_b32_e32 v24, 16, v41
	v_and_b32_e32 v25, 0xffff0000, v41
	v_lshlrev_b32_e32 v40, 16, v48
	v_and_b32_e32 v41, 0xffff0000, v48
	v_lshlrev_b32_e32 v48, 16, v50
	v_and_b32_e32 v49, 0xffff0000, v50
	v_lshlrev_b32_e32 v50, 16, v51
	v_and_b32_e32 v51, 0xffff0000, v51
	v_pk_fma_f32 v[14:15], v[14:15], v[158:159], v[22:23]
	v_pk_fma_f32 v[8:9], v[8:9], v[160:161], v[42:43]
	v_pk_fma_f32 v[22:23], v[12:13], v[156:157], v[34:35]
	v_pk_fma_f32 v[12:13], v[10:11], v[154:155], v[32:33]
	v_cvt_pk_bf16_f32 v10, v14, v15
	v_pk_fma_f32 v[14:15], v[4:5], v[156:157], v[50:51]
	v_pk_fma_f32 v[4:5], v[2:3], v[154:155], v[48:49]
	v_cvt_pk_bf16_f32 v3, v8, v9
	v_and_b32_e32 v9, 64, v227
	v_xor_b32_e32 v8, 16, v227
	v_add_u32_e32 v9, 64, v9
	v_cvt_pk_bf16_f32 v4, v4, v5
	v_cvt_pk_bf16_f32 v5, v14, v15
	v_cmp_lt_i32_e32 vcc, v8, v9
	v_xor_b32_e32 v14, 32, v227
	v_mul_f32_e32 v15, v195, v195
	v_cndmask_b32_e32 v8, v227, v8, vcc
	v_cmp_lt_i32_e32 vcc, v14, v9
	v_pk_fma_f32 v[16:17], v[16:17], v[160:161], v[24:25]
	v_fmac_f32_e32 v15, v191, v191
	v_cndmask_b32_e32 v9, v227, v14, vcc
	v_mul_f32_e32 v14, v196, v196
	v_fmac_f32_e32 v14, v193, v193
	v_cvt_pk_bf16_f32 v11, v16, v17
	v_add_f32_e32 v14, v14, v15
	v_mul_f32_e32 v15, v194, v194
	v_mul_f32_e32 v16, v192, v192
	v_fmac_f32_e32 v15, v190, v190
	v_fmac_f32_e32 v16, v189, v189
	v_add_f32_e32 v15, v15, v16
	v_add_f32_e32 v14, v14, v15
	v_mul_f32_e32 v15, v165, v165
	v_mul_f32_e32 v16, v167, v167
	v_fmac_f32_e32 v15, v164, v164
	v_fmac_f32_e32 v16, v166, v166
	v_add_f32_e32 v15, v15, v16
	v_add_f32_e32 v14, v14, v15
	v_mul_f32_e32 v15, v169, v169
	v_mul_f32_e32 v16, v173, v173
	v_fmac_f32_e32 v15, v168, v168
	v_fmac_f32_e32 v16, v172, v172
	v_add_f32_e32 v15, v15, v16
	v_lshlrev_b32_e32 v8, 2, v8
	v_add_f32_e32 v14, v15, v14
	ds_bpermute_b32 v15, v8, v14
	v_lshlrev_b32_e32 v9, 2, v9
	v_pk_fma_f32 v[6:7], v[6:7], v[158:159], v[40:41]
	v_cvt_pk_bf16_f32 v12, v12, v13
	v_cvt_pk_bf16_f32 v13, v22, v23
	s_waitcnt lgkmcnt(0)
	v_add_f32_e32 v14, v14, v15
	ds_bpermute_b32 v15, v9, v14
	v_cvt_pk_bf16_f32 v2, v6, v7
	v_lshl_add_u64 v[6:7], v[148:149], 0, s[22:23]
	global_store_dwordx4 v[80:81], v[10:13], off offset:2304
	global_store_dwordx4 v[72:73], v[2:5], off offset:2304
	s_and_saveexec_b64 s[22:23], s[38:39]
	s_cbranch_execz .LBB0_1125
	s_waitcnt lgkmcnt(0)
	v_add_f32_e32 v14, v14, v15
	global_atomic_add_f32 v[6:7], v14, off

.LBB0_1155:
	s_add_u32 s44, s28, 0x100
	v_mov_b32_e32 v2, 0
	s_addc_u32 s45, s29, 0
	s_mov_b32 s81, -2
	v_mov_b32_e32 v3, v2
	v_mov_b32_e32 v4, v2
	v_mov_b32_e32 v5, v2
	v_mov_b32_e32 v6, v2
	v_mov_b32_e32 v7, v2
	v_mov_b32_e32 v8, v2
	v_mov_b32_e32 v9, v2
	v_mov_b32_e32 v10, v2
	v_mov_b32_e32 v11, v2
	v_mov_b32_e32 v12, v2
	v_mov_b32_e32 v13, v2
	v_mov_b32_e32 v14, v2
	v_mov_b32_e32 v15, v2
	v_mov_b32_e32 v16, v2
	v_mov_b32_e32 v17, v2
	v_mov_b32_e32 v18, v2
	v_mov_b32_e32 v19, v2
	v_mov_b32_e32 v20, v2
	v_mov_b32_e32 v21, v2
	v_mov_b32_e32 v22, v2
	v_mov_b32_e32 v23, v2
	v_mov_b32_e32 v24, v2
	v_mov_b32_e32 v25, v2
	v_mov_b32_e32 v28, v2
	v_mov_b32_e32 v29, v2
	v_mov_b32_e32 v30, v2
	v_mov_b32_e32 v31, v2
	v_mov_b32_e32 v32, v2
	v_mov_b32_e32 v33, v2
	v_mov_b32_e32 v34, v2
	v_mov_b32_e32 v35, v2
	v_mov_b32_e32 v68, v2
	v_mov_b32_e32 v69, v2
	v_mov_b32_e32 v70, v2
	v_mov_b32_e32 v71, v2
	v_mov_b32_e32 v72, v2
	v_mov_b32_e32 v73, v2
	v_mov_b32_e32 v74, v2
	v_mov_b32_e32 v75, v2
	v_mov_b32_e32 v76, v2
	v_mov_b32_e32 v77, v2
	v_mov_b32_e32 v78, v2
	v_mov_b32_e32 v79, v2
	v_mov_b32_e32 v80, v2
	v_mov_b32_e32 v81, v2
	v_mov_b32_e32 v82, v2
	v_mov_b32_e32 v83, v2
	v_mov_b32_e32 v84, v2
	v_mov_b32_e32 v85, v2
	v_mov_b32_e32 v86, v2
	v_mov_b32_e32 v87, v2
	v_mov_b32_e32 v88, v2
	v_mov_b32_e32 v89, v2
	v_mov_b32_e32 v90, v2
	v_mov_b32_e32 v91, v2
	v_mov_b32_e32 v92, v2
	v_mov_b32_e32 v93, v2
	v_mov_b32_e32 v94, v2
	v_mov_b32_e32 v95, v2
	v_mov_b32_e32 v96, v2
	v_mov_b32_e32 v97, v2
	v_mov_b32_e32 v98, v2
	v_mov_b32_e32 v99, v2
	s_waitcnt vmcnt(0)
	v_mov_b32_e32 v36, v2
	v_mov_b32_e32 v37, v2
	v_mov_b32_e32 v38, v2
	v_mov_b32_e32 v39, v2
	v_mov_b32_e32 v40, v2
	v_mov_b32_e32 v41, v2
	v_mov_b32_e32 v42, v2
	v_mov_b32_e32 v43, v2
	v_mov_b32_e32 v44, v2
	v_mov_b32_e32 v45, v2
	v_mov_b32_e32 v46, v2
	v_mov_b32_e32 v47, v2
	v_mov_b32_e32 v48, v2
	v_mov_b32_e32 v49, v2
	v_mov_b32_e32 v50, v2
	v_mov_b32_e32 v51, v2
	v_mov_b32_e32 v52, v2
	v_mov_b32_e32 v53, v2
	v_mov_b32_e32 v54, v2
	v_mov_b32_e32 v55, v2
	v_mov_b32_e32 v56, v2
	v_mov_b32_e32 v57, v2
	v_mov_b32_e32 v58, v2
	v_mov_b32_e32 v59, v2
	v_mov_b32_e32 v60, v2
	v_mov_b32_e32 v61, v2
	v_mov_b32_e32 v62, v2
	v_mov_b32_e32 v63, v2
	v_mov_b32_e32 v64, v2
	v_mov_b32_e32 v65, v2
	v_mov_b32_e32 v66, v2
	v_mov_b32_e32 v67, v2
	v_mov_b32_e32 v100, v2
	v_mov_b32_e32 v101, v2
	v_mov_b32_e32 v102, v2
	v_mov_b32_e32 v103, v2
	v_mov_b32_e32 v104, v2
	v_mov_b32_e32 v105, v2
	v_mov_b32_e32 v106, v2
	v_mov_b32_e32 v107, v2
	v_mov_b32_e32 v108, v2
	v_mov_b32_e32 v109, v2
	v_mov_b32_e32 v110, v2
	v_mov_b32_e32 v111, v2
	v_mov_b32_e32 v112, v2
	v_mov_b32_e32 v113, v2
	v_mov_b32_e32 v114, v2
	v_mov_b32_e32 v115, v2
	v_mov_b32_e32 v116, v2
	v_mov_b32_e32 v117, v2
	v_mov_b32_e32 v118, v2
	v_mov_b32_e32 v119, v2
	v_mov_b32_e32 v120, v2
	v_mov_b32_e32 v121, v2
	v_mov_b32_e32 v122, v2
	v_mov_b32_e32 v123, v2
	v_mov_b32_e32 v124, v2
	v_mov_b32_e32 v125, v2
	v_mov_b32_e32 v126, v2
	v_mov_b32_e32 v127, v2
	v_mov_b32_e32 v128, v2
	v_mov_b32_e32 v129, v2
	v_mov_b32_e32 v130, v2
	v_mov_b32_e32 v131, v2
	v_add_u32_e32 v160, 0x10000, v222
	ds_read_b128 v[132:135], v160
	ds_read_b128 v[136:139], v160 offset:1024
	ds_read_b128 v[156:159], v160 offset:2048
	ds_read_b128 v[160:163], v160 offset:3072
	s_add_u32 s28, s26, 0x100
	s_addc_u32 s29, s27, 0
	s_add_i32 s0, 0, 0x10000
	s_cmp_eq_u32 s81, 40
	s_cselect_b32 s35, s43, s29
	s_cselect_b32 s34, s42, s28
	s_cselect_b32 s31, s23, s45
	s_cselect_b32 s30, s22, s44
.LBB0_1156:
	s_add_i32 m0, s52, 0xc000
	ds_read_b128 v[172:175], v224
	ds_read_b128 v[176:179], v224 offset:1024
	ds_read_b128 v[180:183], v224 offset:2048
	ds_read_b128 v[184:187], v224 offset:3072
	ds_read_b128 v[188:191], v224 offset:4096
	ds_read_b128 v[192:195], v224 offset:5120
	ds_read_b128 v[196:199], v224 offset:6144
	ds_read_b128 v[200:203], v224 offset:7168
	global_load_lds_dwordx4 v152, s[26:27]
	v_lshl_add_u64 v[164:165], s[26:27], 0, v[154:155]
	s_add_i32 m0, s52, 0xe000
	s_nop 0
	global_load_lds_dwordx4 v[164:165], off
	s_waitcnt vmcnt(10) lgkmcnt(8)
	s_setprio 1
	s_barrier
	s_waitcnt lgkmcnt(0)
	v_mfma_f32_16x16x32_bf16 v[128:131], v[132:135], v[172:175], v[128:131]
	v_mfma_f32_16x16x32_bf16 v[124:127], v[156:159], v[172:175], v[124:127]
	v_mfma_f32_16x16x32_bf16 v[120:123], v[132:135], v[180:183], v[120:123]
	v_mfma_f32_16x16x32_bf16 v[116:119], v[156:159], v[180:183], v[116:119]
	v_mfma_f32_16x16x32_bf16 v[112:115], v[132:135], v[188:191], v[112:115]
	v_mfma_f32_16x16x32_bf16 v[108:111], v[156:159], v[188:191], v[108:111]
	v_mfma_f32_16x16x32_bf16 v[104:107], v[132:135], v[196:199], v[104:107]
	v_mfma_f32_16x16x32_bf16 v[100:103], v[156:159], v[196:199], v[100:103]
	v_mfma_f32_16x16x32_bf16 v[128:131], v[136:139], v[176:179], v[128:131]
	v_mfma_f32_16x16x32_bf16 v[124:127], v[160:163], v[176:179], v[124:127]
	v_mfma_f32_16x16x32_bf16 v[120:123], v[136:139], v[184:187], v[120:123]
	v_mfma_f32_16x16x32_bf16 v[116:119], v[160:163], v[184:187], v[116:119]
	v_mfma_f32_16x16x32_bf16 v[112:115], v[136:139], v[192:195], v[112:115]
	v_mfma_f32_16x16x32_bf16 v[108:111], v[160:163], v[192:195], v[108:111]
	v_mfma_f32_16x16x32_bf16 v[104:107], v[136:139], v[200:203], v[104:107]
	v_mfma_f32_16x16x32_bf16 v[100:103], v[160:163], v[200:203], v[100:103]
	s_barrier
	s_setprio 0
	s_add_i32 s26, 0, 0x14000
	v_add_u32_e32 v164, s26, v222
	s_add_i32 s0, s0, s17
	ds_read_b128 v[204:207], v164
	ds_read_b128 v[208:211], v164 offset:1024
	ds_read_b128 v[212:215], v164 offset:2048
	ds_read_b128 v[216:219], v164 offset:3072
	v_lshl_add_u64 v[164:165], s[30:31], 0, v[26:27]
	s_mov_b32 m0, s0
	v_lshl_add_u64 v[166:167], s[30:31], 0, v[144:145]
	global_load_lds_dwordx4 v[164:165], off
	s_add_i32 m0, s0, 0x2000
	s_nop 0
	global_load_lds_dwordx4 v[166:167], off
	s_waitcnt vmcnt(10)
	s_setprio 1
	s_barrier
	s_waitcnt lgkmcnt(0)
	v_mfma_f32_16x16x32_bf16 v[64:67], v[204:207], v[172:175], v[64:67]
	v_mfma_f32_16x16x32_bf16 v[60:63], v[212:215], v[172:175], v[60:63]
	v_mfma_f32_16x16x32_bf16 v[56:59], v[204:207], v[180:183], v[56:59]
	v_mfma_f32_16x16x32_bf16 v[52:55], v[212:215], v[180:183], v[52:55]
	v_mfma_f32_16x16x32_bf16 v[48:51], v[204:207], v[188:191], v[48:51]
	v_mfma_f32_16x16x32_bf16 v[44:47], v[212:215], v[188:191], v[44:47]
	v_mfma_f32_16x16x32_bf16 v[40:43], v[204:207], v[196:199], v[40:43]
	v_mfma_f32_16x16x32_bf16 v[36:39], v[212:215], v[196:199], v[36:39]
	v_mfma_f32_16x16x32_bf16 v[64:67], v[208:211], v[176:179], v[64:67]
	v_mfma_f32_16x16x32_bf16 v[60:63], v[216:219], v[176:179], v[60:63]
	v_mfma_f32_16x16x32_bf16 v[56:59], v[208:211], v[184:187], v[56:59]
	v_mfma_f32_16x16x32_bf16 v[52:55], v[216:219], v[184:187], v[52:55]
	v_mfma_f32_16x16x32_bf16 v[48:51], v[208:211], v[192:195], v[48:51]
	v_mfma_f32_16x16x32_bf16 v[44:47], v[216:219], v[192:195], v[44:47]
	v_mfma_f32_16x16x32_bf16 v[40:43], v[208:211], v[200:203], v[40:43]
	v_mfma_f32_16x16x32_bf16 v[36:39], v[216:219], v[200:203], v[36:39]
	s_barrier
	s_setprio 0
	s_mov_b32 m0, s52
	v_lshl_add_u64 v[168:169], s[34:35], 0, v[140:141]
	ds_read_b128 v[172:175], v224 offset:16384
	ds_read_b128 v[176:179], v224 offset:17408
	ds_read_b128 v[180:183], v224 offset:18432
	ds_read_b128 v[184:187], v224 offset:19456
	ds_read_b128 v[188:191], v224 offset:20480
	ds_read_b128 v[192:195], v224 offset:21504
	ds_read_b128 v[196:199], v224 offset:22528
	ds_read_b128 v[200:203], v224 offset:23552
	global_load_lds_dwordx4 v[168:169], off
	v_lshl_add_u64 v[220:221], s[34:35], 0, v[142:143]
	s_mov_b32 m0, s54
	s_nop 0
	global_load_lds_dwordx4 v[220:221], off
	s_waitcnt vmcnt(10)
	s_setprio 1
	s_barrier
	s_waitcnt lgkmcnt(0)
	v_mfma_f32_16x16x32_bf16 v[96:99], v[132:135], v[172:175], v[96:99]
	v_mfma_f32_16x16x32_bf16 v[92:95], v[156:159], v[172:175], v[92:95]
	v_mfma_f32_16x16x32_bf16 v[88:91], v[132:135], v[180:183], v[88:91]
	v_mfma_f32_16x16x32_bf16 v[84:87], v[156:159], v[180:183], v[84:87]
	v_mfma_f32_16x16x32_bf16 v[80:83], v[132:135], v[188:191], v[80:83]
	v_mfma_f32_16x16x32_bf16 v[76:79], v[156:159], v[188:191], v[76:79]
	v_mfma_f32_16x16x32_bf16 v[72:75], v[132:135], v[196:199], v[72:75]
	v_mfma_f32_16x16x32_bf16 v[68:71], v[156:159], v[196:199], v[68:71]
	v_mfma_f32_16x16x32_bf16 v[96:99], v[136:139], v[176:179], v[96:99]
	v_mfma_f32_16x16x32_bf16 v[92:95], v[160:163], v[176:179], v[92:95]
	v_mfma_f32_16x16x32_bf16 v[88:91], v[136:139], v[184:187], v[88:91]
	v_mfma_f32_16x16x32_bf16 v[84:87], v[160:163], v[184:187], v[84:87]
	v_mfma_f32_16x16x32_bf16 v[80:83], v[136:139], v[192:195], v[80:83]
	v_mfma_f32_16x16x32_bf16 v[76:79], v[160:163], v[192:195], v[76:79]
	v_mfma_f32_16x16x32_bf16 v[72:75], v[136:139], v[200:203], v[72:75]
	v_mfma_f32_16x16x32_bf16 v[68:71], v[160:163], v[200:203], v[68:71]
	s_barrier
	s_setprio 0
	s_add_u32 s0, s30, 0xb0000
	s_addc_u32 s1, s31, 0
	s_add_i32 s26, s26, s17
	s_mov_b32 m0, s26
	s_nop 0
	global_load_lds_dwordx4 v26, s[0:1]
	s_add_i32 m0, s26, 0x2000
	s_nop 0
	global_load_lds_dwordx4 v144, s[0:1]
	v_add_u32_e32 v160, 0x18000, v222
	ds_read_b128 v[132:135], v160
	ds_read_b128 v[136:139], v160 offset:1024
	ds_read_b128 v[156:159], v160 offset:2048
	ds_read_b128 v[160:163], v160 offset:3072
	s_waitcnt vmcnt(10)
	s_setprio 1
	s_barrier
	v_mfma_f32_16x16x32_bf16 v[32:35], v[204:207], v[172:175], v[32:35]
	v_mfma_f32_16x16x32_bf16 v[28:31], v[212:215], v[172:175], v[28:31]
	v_mfma_f32_16x16x32_bf16 v[22:25], v[204:207], v[180:183], v[22:25]
	v_mfma_f32_16x16x32_bf16 v[18:21], v[212:215], v[180:183], v[18:21]
	v_mfma_f32_16x16x32_bf16 v[14:17], v[204:207], v[188:191], v[14:17]
	v_mfma_f32_16x16x32_bf16 v[10:13], v[212:215], v[188:191], v[10:13]
	v_mfma_f32_16x16x32_bf16 v[6:9], v[204:207], v[196:199], v[6:9]
	v_mfma_f32_16x16x32_bf16 v[2:5], v[212:215], v[196:199], v[2:5]
	v_mfma_f32_16x16x32_bf16 v[32:35], v[208:211], v[176:179], v[32:35]
	v_mfma_f32_16x16x32_bf16 v[28:31], v[216:219], v[176:179], v[28:31]
	v_mfma_f32_16x16x32_bf16 v[22:25], v[208:211], v[184:187], v[22:25]
	v_mfma_f32_16x16x32_bf16 v[18:21], v[216:219], v[184:187], v[18:21]
	v_mfma_f32_16x16x32_bf16 v[14:17], v[208:211], v[192:195], v[14:17]
	v_mfma_f32_16x16x32_bf16 v[10:13], v[216:219], v[192:195], v[10:13]
	v_mfma_f32_16x16x32_bf16 v[6:9], v[208:211], v[200:203], v[6:9]
	v_mfma_f32_16x16x32_bf16 v[2:5], v[216:219], v[200:203], v[2:5]
	s_barrier
	s_setprio 0
	s_add_i32 s26, 0, 0x18000
	s_add_u32 s0, s34, 0xb0000
	s_addc_u32 s1, s35, 0
	s_mov_b32 m0, s55
	ds_read_b128 v[172:175], v224 offset:32768
	ds_read_b128 v[176:179], v224 offset:33792
	ds_read_b128 v[180:183], v224 offset:34816
	ds_read_b128 v[184:187], v224 offset:35840
	ds_read_b128 v[188:191], v224 offset:36864
	ds_read_b128 v[192:195], v224 offset:37888
	ds_read_b128 v[196:199], v224 offset:38912
	ds_read_b128 v[200:203], v224 offset:39936
	global_load_lds_dwordx4 v140, s[0:1]
	s_mov_b32 m0, s56
	s_nop 0
	global_load_lds_dwordx4 v142, s[0:1]
	s_waitcnt vmcnt(10) lgkmcnt(8)
	s_setprio 1
	s_barrier
	s_waitcnt lgkmcnt(0)
	v_mfma_f32_16x16x32_bf16 v[128:131], v[132:135], v[172:175], v[128:131]
	v_mfma_f32_16x16x32_bf16 v[124:127], v[156:159], v[172:175], v[124:127]
	v_mfma_f32_16x16x32_bf16 v[120:123], v[132:135], v[180:183], v[120:123]
	v_mfma_f32_16x16x32_bf16 v[116:119], v[156:159], v[180:183], v[116:119]
	v_mfma_f32_16x16x32_bf16 v[112:115], v[132:135], v[188:191], v[112:115]
	v_mfma_f32_16x16x32_bf16 v[108:111], v[156:159], v[188:191], v[108:111]
	v_mfma_f32_16x16x32_bf16 v[104:107], v[132:135], v[196:199], v[104:107]
	v_mfma_f32_16x16x32_bf16 v[100:103], v[156:159], v[196:199], v[100:103]
	v_mfma_f32_16x16x32_bf16 v[128:131], v[136:139], v[176:179], v[128:131]
	v_mfma_f32_16x16x32_bf16 v[124:127], v[160:163], v[176:179], v[124:127]
	v_mfma_f32_16x16x32_bf16 v[120:123], v[136:139], v[184:187], v[120:123]
	v_mfma_f32_16x16x32_bf16 v[116:119], v[160:163], v[184:187], v[116:119]
	v_mfma_f32_16x16x32_bf16 v[112:115], v[136:139], v[192:195], v[112:115]
	v_mfma_f32_16x16x32_bf16 v[108:111], v[160:163], v[192:195], v[108:111]
	v_mfma_f32_16x16x32_bf16 v[104:107], v[136:139], v[200:203], v[104:107]
	v_mfma_f32_16x16x32_bf16 v[100:103], v[160:163], v[200:203], v[100:103]
	s_barrier
	s_setprio 0
	s_add_i32 s27, 0, 0x1c000
	s_add_i32 s0, s26, s17
	v_add_u32_e32 v216, s27, v222
	v_lshl_add_u64 v[164:165], v[164:165], 0, s[12:13]
	s_mov_b32 m0, s0
	ds_read_b128 v[204:207], v216
	ds_read_b128 v[208:211], v216 offset:1024
	ds_read_b128 v[212:215], v216 offset:2048
	ds_read_b128 v[216:219], v216 offset:3072
	global_load_lds_dwordx4 v[164:165], off
	v_lshl_add_u64 v[164:165], v[166:167], 0, s[12:13]
	s_add_i32 m0, s0, 0x2000
	s_nop 0
	global_load_lds_dwordx4 v[164:165], off
	s_waitcnt vmcnt(10)
	s_setprio 1
	s_barrier
	s_waitcnt lgkmcnt(0)
	v_mfma_f32_16x16x32_bf16 v[64:67], v[204:207], v[172:175], v[64:67]
	v_mfma_f32_16x16x32_bf16 v[60:63], v[212:215], v[172:175], v[60:63]
	v_mfma_f32_16x16x32_bf16 v[56:59], v[204:207], v[180:183], v[56:59]
	v_mfma_f32_16x16x32_bf16 v[52:55], v[212:215], v[180:183], v[52:55]
	v_mfma_f32_16x16x32_bf16 v[48:51], v[204:207], v[188:191], v[48:51]
	v_mfma_f32_16x16x32_bf16 v[44:47], v[212:215], v[188:191], v[44:47]
	v_mfma_f32_16x16x32_bf16 v[40:43], v[204:207], v[196:199], v[40:43]
	v_mfma_f32_16x16x32_bf16 v[36:39], v[212:215], v[196:199], v[36:39]
	v_mfma_f32_16x16x32_bf16 v[64:67], v[208:211], v[176:179], v[64:67]
	v_mfma_f32_16x16x32_bf16 v[60:63], v[216:219], v[176:179], v[60:63]
	v_mfma_f32_16x16x32_bf16 v[56:59], v[208:211], v[184:187], v[56:59]
	v_mfma_f32_16x16x32_bf16 v[52:55], v[216:219], v[184:187], v[52:55]
	v_mfma_f32_16x16x32_bf16 v[48:51], v[208:211], v[192:195], v[48:51]
	v_mfma_f32_16x16x32_bf16 v[44:47], v[216:219], v[192:195], v[44:47]
	v_mfma_f32_16x16x32_bf16 v[40:43], v[208:211], v[200:203], v[40:43]
	v_mfma_f32_16x16x32_bf16 v[36:39], v[216:219], v[200:203], v[36:39]
	s_barrier
	s_setprio 0
	s_mov_b32 m0, s59
	v_lshl_add_u64 v[164:165], v[168:169], 0, s[12:13]
	ds_read_b128 v[172:175], v224 offset:49152
	ds_read_b128 v[176:179], v224 offset:50176
	ds_read_b128 v[180:183], v224 offset:51200
	ds_read_b128 v[184:187], v224 offset:52224
	ds_read_b128 v[188:191], v224 offset:53248
	ds_read_b128 v[192:195], v224 offset:54272
	ds_read_b128 v[196:199], v224 offset:55296
	ds_read_b128 v[200:203], v224 offset:56320
	global_load_lds_dwordx4 v[164:165], off
	v_lshl_add_u64 v[164:165], v[220:221], 0, s[12:13]
	s_mov_b32 m0, s68
	s_nop 0
	global_load_lds_dwordx4 v[164:165], off
	s_waitcnt vmcnt(10)
	s_setprio 1
	s_barrier
	s_waitcnt lgkmcnt(0)
	v_mfma_f32_16x16x32_bf16 v[96:99], v[132:135], v[172:175], v[96:99]
	v_mfma_f32_16x16x32_bf16 v[92:95], v[156:159], v[172:175], v[92:95]
	v_mfma_f32_16x16x32_bf16 v[88:91], v[132:135], v[180:183], v[88:91]
	v_mfma_f32_16x16x32_bf16 v[84:87], v[156:159], v[180:183], v[84:87]
	v_mfma_f32_16x16x32_bf16 v[80:83], v[132:135], v[188:191], v[80:83]
	v_mfma_f32_16x16x32_bf16 v[76:79], v[156:159], v[188:191], v[76:79]
	v_mfma_f32_16x16x32_bf16 v[72:75], v[132:135], v[196:199], v[72:75]
	v_mfma_f32_16x16x32_bf16 v[68:71], v[156:159], v[196:199], v[68:71]
	v_mfma_f32_16x16x32_bf16 v[96:99], v[136:139], v[176:179], v[96:99]
	v_mfma_f32_16x16x32_bf16 v[92:95], v[160:163], v[176:179], v[92:95]
	v_mfma_f32_16x16x32_bf16 v[88:91], v[136:139], v[184:187], v[88:91]
	v_mfma_f32_16x16x32_bf16 v[84:87], v[160:163], v[184:187], v[84:87]
	v_mfma_f32_16x16x32_bf16 v[80:83], v[136:139], v[192:195], v[80:83]
	v_mfma_f32_16x16x32_bf16 v[76:79], v[160:163], v[192:195], v[76:79]
	v_mfma_f32_16x16x32_bf16 v[72:75], v[136:139], v[200:203], v[72:75]
	v_mfma_f32_16x16x32_bf16 v[68:71], v[160:163], v[200:203], v[68:71]
	s_barrier
	s_setprio 0
	s_add_u32 s0, s30, 0xb0080
	s_addc_u32 s1, s31, 0
	s_add_i32 s26, s27, s17
	s_mov_b32 m0, s26
	s_nop 0
	global_load_lds_dwordx4 v26, s[0:1]
	s_add_i32 m0, s26, 0x2000
	s_nop 0
	global_load_lds_dwordx4 v144, s[0:1]
	v_add_u32_e32 v160, 0x10000, v222
	ds_read_b128 v[132:135], v160
	ds_read_b128 v[136:139], v160 offset:1024
	ds_read_b128 v[156:159], v160 offset:2048
	ds_read_b128 v[160:163], v160 offset:3072
	s_add_i32 s81, s81, 2
	s_add_u32 s44, s44, 0x100
	s_addc_u32 s45, s45, 0
	s_mov_b64 s[26:27], s[28:29]
	s_cmp_gt_u32 s81, 41
	s_cbranch_scc1 .Lth__1156
	s_add_u32 s28, s26, 0x100
	s_addc_u32 s29, s27, 0
	s_add_i32 s0, 0, 0x10000
	s_cmp_eq_u32 s81, 40
	s_cselect_b32 s35, s43, s29
	s_cselect_b32 s34, s42, s28
	s_cselect_b32 s31, s23, s45
	s_cselect_b32 s30, s22, s44
	s_cmp_gt_u32 s81, 41
.Lth__1156:
	s_waitcnt vmcnt(10)
	s_setprio 1
	s_barrier
	v_mfma_f32_16x16x32_bf16 v[32:35], v[204:207], v[172:175], v[32:35]
	v_mfma_f32_16x16x32_bf16 v[28:31], v[212:215], v[172:175], v[28:31]
	v_mfma_f32_16x16x32_bf16 v[22:25], v[204:207], v[180:183], v[22:25]
	v_mfma_f32_16x16x32_bf16 v[18:21], v[212:215], v[180:183], v[18:21]
	v_mfma_f32_16x16x32_bf16 v[14:17], v[204:207], v[188:191], v[14:17]
	v_mfma_f32_16x16x32_bf16 v[10:13], v[212:215], v[188:191], v[10:13]
	v_mfma_f32_16x16x32_bf16 v[6:9], v[204:207], v[196:199], v[6:9]
	v_mfma_f32_16x16x32_bf16 v[2:5], v[212:215], v[196:199], v[2:5]
	v_mfma_f32_16x16x32_bf16 v[32:35], v[208:211], v[176:179], v[32:35]
	v_mfma_f32_16x16x32_bf16 v[28:31], v[216:219], v[176:179], v[28:31]
	v_mfma_f32_16x16x32_bf16 v[22:25], v[208:211], v[184:187], v[22:25]
	v_mfma_f32_16x16x32_bf16 v[18:21], v[216:219], v[184:187], v[18:21]
	v_mfma_f32_16x16x32_bf16 v[14:17], v[208:211], v[192:195], v[14:17]
	v_mfma_f32_16x16x32_bf16 v[10:13], v[216:219], v[192:195], v[10:13]
	v_mfma_f32_16x16x32_bf16 v[6:9], v[208:211], v[200:203], v[6:9]
	v_mfma_f32_16x16x32_bf16 v[2:5], v[216:219], v[200:203], v[2:5]
	s_barrier
	s_setprio 0
	s_cbranch_scc0 .LBB0_1156
	s_waitcnt lgkmcnt(0)
	s_min_i32 s0, s24, 0x100
	s_ashr_i32 s0, s0, 5
	s_ashr_i32 s1, s0, 31
	s_add_i32 s26, s24, 0xffffff00
	s_cmpk_lt_i32 s24, 0x100
	s_cselect_b32 s26, s24, s26
	s_cselect_b32 s28, 0, s51
	s_cselect_b32 s29, 0, s50
	s_ashr_i32 s27, s26, 31
	s_lshl_b64 s[26:27], s[26:27], 19
	v_lshl_add_u64 v[132:133], s[26:27], 0, v[146:147]
	s_add_u32 s26, s20, s29
	v_lshl_or_b32 v166, s25, 8, v223
	s_addc_u32 s27, s21, s28
	s_ashr_i32 s25, s24, 31
	s_lshl_b64 s[28:29], s[24:25], 19
	v_lshl_add_u64 v[178:179], v[148:149], 0, s[28:29]
	s_lshl_b64 s[24:25], s[24:25], 10
	s_mul_i32 s28, s0, 0x9000
	v_ashrrev_i32_e32 v167, 31, v166
	s_mul_hi_i32 s29, s0, 0x9000
	s_add_u32 s28, s36, s28
	s_addc_u32 s29, s37, s29
	v_lshlrev_b64 v[180:181], 2, v[166:167]
	v_lshl_add_u64 v[156:157], s[28:29], 0, v[180:181]
	v_lshl_add_u64 v[168:169], v[132:133], 0, v[166:167]
	v_lshl_add_u64 v[182:183], v[132:133], 1, s[26:27]
	global_load_dwordx4 v[132:135], v[156:157], off offset:16
	global_load_dwordx4 v[136:139], v[156:157], off
	s_lshl_b64 s[0:1], s[0:1], 12
	s_add_u32 s28, s57, s0
	s_addc_u32 s29, s58, s1
	v_lshl_add_u64 v[180:181], s[28:29], 0, v[180:181]
	v_lshl_add_u64 v[196:197], v[168:169], 1, s[26:27]
	v_add_co_u32_e32 v210, vcc, s65, v196
	s_mov_b32 s1, 0x20000
	s_nop 0
	v_addc_co_u32_e32 v211, vcc, 0, v197, vcc
	v_add_co_u32_e32 v184, vcc, s1, v196
	s_mov_b32 s26, 0x30000
	s_nop 0
	v_addc_co_u32_e32 v185, vcc, 0, v197, vcc
	v_add_co_u32_e32 v188, vcc, s26, v196
	v_lshlrev_b64 v[166:167], 1, v[166:167]
	s_nop 0
	v_addc_co_u32_e32 v189, vcc, 0, v197, vcc
	v_lshl_add_u64 v[178:179], v[178:179], 0, v[166:167]
	v_lshl_add_u64 v[182:183], v[182:183], 0, v[166:167]
	s_mov_b32 s0, 0x8000
	s_mov_b32 s27, 0x80000
	s_mov_b32 s28, 0x90000
	s_waitcnt vmcnt(0)
	v_pk_mul_f32 v[172:173], v[134:135], 0.5 op_sel_hi:[1,0]
	v_pk_mul_f32 v[176:177], v[138:139], 0.5 op_sel_hi:[1,0]
	v_pk_mul_f32 v[174:175], v[136:137], 0.5 op_sel_hi:[1,0]
	v_pk_mul_f32 v[164:165], v[132:133], 0.5 op_sel_hi:[1,0]
	global_load_dwordx4 v[132:135], v[156:157], off offset:528
	global_load_dwordx4 v[136:139], v[156:157], off offset:512
	s_waitcnt vmcnt(0)
	v_pk_mul_f32 v[158:159], v[134:135], 0.5 op_sel_hi:[1,0]
	v_pk_mul_f32 v[162:163], v[138:139], 0.5 op_sel_hi:[1,0]
	v_pk_mul_f32 v[160:161], v[136:137], 0.5 op_sel_hi:[1,0]
	v_pk_mul_f32 v[156:157], v[132:133], 0.5 op_sel_hi:[1,0]
	global_load_dwordx4 v[132:135], v[180:181], off offset:16
	global_load_dwordx4 v[136:139], v[180:181], off
	global_load_dwordx4 v[190:193], v[196:197], off offset:2048
	global_load_dwordx4 v[198:201], v[210:211], off offset:2048
	global_load_dwordx4 v[202:205], v[184:185], off offset:2048
	global_load_dwordx4 v[206:209], v[188:189], off offset:2048
	s_waitcnt vmcnt(0)
	v_lshlrev_b32_e32 v166, 16, v190
	v_and_b32_e32 v167, 0xffff0000, v190
	v_lshlrev_b32_e32 v168, 16, v191
	v_and_b32_e32 v169, 0xffff0000, v191
	v_lshlrev_b32_e32 v186, 16, v192
	v_and_b32_e32 v187, 0xffff0000, v192
	v_lshlrev_b32_e32 v190, 16, v193
	v_and_b32_e32 v191, 0xffff0000, v193
	v_pk_fma_f32 v[130:131], v[130:131], v[176:177], v[168:169]
	v_pk_fma_f32 v[128:129], v[128:129], v[174:175], v[166:167]
	v_pk_fma_f32 v[126:127], v[126:127], v[172:173], v[190:191]
	v_pk_fma_f32 v[124:125], v[124:125], v[164:165], v[186:187]
	v_cvt_pk_bf16_f32 v190, v128, v129
	v_cvt_pk_bf16_f32 v191, v130, v131
	v_cvt_pk_bf16_f32 v192, v124, v125
	v_cvt_pk_bf16_f32 v193, v126, v127
	v_lshlrev_b32_e32 v130, 16, v190
	v_and_b32_e32 v131, 0xffff0000, v190
	v_lshlrev_b32_e32 v128, 16, v191
	v_and_b32_e32 v129, 0xffff0000, v191
	v_lshlrev_b32_e32 v126, 16, v192
	v_and_b32_e32 v127, 0xffff0000, v192
	v_lshlrev_b32_e32 v124, 16, v193
	v_and_b32_e32 v125, 0xffff0000, v193
	v_lshlrev_b32_e32 v212, 16, v200
	v_and_b32_e32 v213, 0xffff0000, v200
	v_lshlrev_b32_e32 v200, 16, v201
	v_and_b32_e32 v201, 0xffff0000, v201
	global_store_dwordx4 v[182:183], v[190:193], off offset:2048
	v_pk_mul_f32 v[166:167], v[138:139], v[128:129]
	v_pk_mul_f32 v[168:169], v[136:137], v[130:131]
	v_pk_mul_f32 v[186:187], v[134:135], v[124:125]
	v_pk_mul_f32 v[192:193], v[132:133], v[126:127]
	v_lshlrev_b32_e32 v194, 16, v198
	v_and_b32_e32 v195, 0xffff0000, v198
	v_lshlrev_b32_e32 v198, 16, v199
	v_and_b32_e32 v199, 0xffff0000, v199
	v_cvt_pk_bf16_f32 v190, v168, v169
	v_cvt_pk_bf16_f32 v191, v166, v167
	v_cvt_pk_bf16_f32 v192, v192, v193
	v_cvt_pk_bf16_f32 v193, v186, v187
	v_pk_fma_f32 v[118:119], v[118:119], v[172:173], v[200:201]
	v_pk_fma_f32 v[116:117], v[116:117], v[164:165], v[212:213]
	global_store_dwordx4 v[178:179], v[190:193], off
	v_pk_fma_f32 v[122:123], v[122:123], v[176:177], v[198:199]
	v_pk_fma_f32 v[120:121], v[120:121], v[174:175], v[194:195]
	v_cvt_pk_bf16_f32 v192, v116, v117
	v_cvt_pk_bf16_f32 v193, v118, v119
	v_add_co_u32_e32 v186, vcc, s65, v182
	v_cvt_pk_bf16_f32 v190, v120, v121
	v_cvt_pk_bf16_f32 v191, v122, v123
	v_addc_co_u32_e32 v187, vcc, 0, v183, vcc
	v_lshlrev_b32_e32 v118, 16, v192
	v_and_b32_e32 v119, 0xffff0000, v192
	v_lshlrev_b32_e32 v116, 16, v193
	v_and_b32_e32 v117, 0xffff0000, v193
	global_store_dwordx4 v[186:187], v[190:193], off offset:2048
	v_lshlrev_b32_e32 v122, 16, v190
	v_and_b32_e32 v123, 0xffff0000, v190
	v_lshlrev_b32_e32 v120, 16, v191
	v_and_b32_e32 v121, 0xffff0000, v191
	v_pk_mul_f32 v[190:191], v[134:135], v[116:117]
	v_pk_mul_f32 v[194:195], v[132:133], v[118:119]
	v_pk_mul_f32 v[166:167], v[138:139], v[120:121]
	v_pk_mul_f32 v[168:169], v[136:137], v[122:123]
	v_cvt_pk_bf16_f32 v194, v194, v195
	v_cvt_pk_bf16_f32 v195, v190, v191
	v_add_co_u32_e32 v190, vcc, s0, v178
	v_cvt_pk_bf16_f32 v192, v168, v169
	v_cvt_pk_bf16_f32 v193, v166, v167
	v_addc_co_u32_e32 v191, vcc, 0, v179, vcc
	global_store_dwordx4 v[190:191], v[192:195], off
	v_lshlrev_b32_e32 v198, 16, v204
	v_and_b32_e32 v199, 0xffff0000, v204
	v_add_co_u32_e32 v192, vcc, s27, v196
	v_lshlrev_b32_e32 v200, 16, v205
	s_nop 0
	v_addc_co_u32_e32 v193, vcc, 0, v197, vcc
	v_add_co_u32_e32 v194, vcc, s28, v196
	v_and_b32_e32 v201, 0xffff0000, v205
	global_load_dwordx4 v[212:215], v[192:193], off offset:2048
	v_addc_co_u32_e32 v195, vcc, 0, v197, vcc
	v_lshlrev_b32_e32 v166, 16, v202
	v_and_b32_e32 v167, 0xffff0000, v202
	v_lshlrev_b32_e32 v168, 16, v203
	v_and_b32_e32 v169, 0xffff0000, v203
	v_pk_fma_f32 v[110:111], v[110:111], v[172:173], v[200:201]
	v_pk_fma_f32 v[108:109], v[108:109], v[164:165], v[198:199]
	v_pk_fma_f32 v[114:115], v[114:115], v[176:177], v[168:169]
	v_pk_fma_f32 v[112:113], v[112:113], v[174:175], v[166:167]
	v_cvt_pk_bf16_f32 v202, v108, v109
	v_cvt_pk_bf16_f32 v203, v110, v111
	v_add_co_u32_e32 v198, vcc, s1, v182
	global_load_dwordx4 v[216:219], v[194:195], off offset:2048
	v_cvt_pk_bf16_f32 v200, v112, v113
	v_cvt_pk_bf16_f32 v201, v114, v115
	v_addc_co_u32_e32 v199, vcc, 0, v183, vcc
	v_lshlrev_b32_e32 v110, 16, v202
	v_and_b32_e32 v111, 0xffff0000, v202
	v_lshlrev_b32_e32 v108, 16, v203
	v_and_b32_e32 v109, 0xffff0000, v203
	global_store_dwordx4 v[198:199], v[200:203], off offset:2048
	v_lshlrev_b32_e32 v114, 16, v200
	v_and_b32_e32 v115, 0xffff0000, v200
	v_lshlrev_b32_e32 v112, 16, v201
	v_and_b32_e32 v113, 0xffff0000, v201
	v_pk_mul_f32 v[200:201], v[134:135], v[108:109]
	v_pk_mul_f32 v[204:205], v[132:133], v[110:111]
	v_lshlrev_b32_e32 v234, 16, v208
	v_and_b32_e32 v235, 0xffff0000, v208
	v_lshlrev_b32_e32 v208, 16, v209
	v_and_b32_e32 v209, 0xffff0000, v209
	v_pk_mul_f32 v[166:167], v[138:139], v[112:113]
	v_pk_mul_f32 v[168:169], v[136:137], v[114:115]
	v_cvt_pk_bf16_f32 v204, v204, v205
	v_cvt_pk_bf16_f32 v205, v200, v201
	v_add_co_u32_e32 v200, vcc, s65, v178
	v_lshlrev_b32_e32 v220, 16, v206
	v_and_b32_e32 v221, 0xffff0000, v206
	v_lshlrev_b32_e32 v206, 16, v207
	v_and_b32_e32 v207, 0xffff0000, v207
	v_cvt_pk_bf16_f32 v202, v168, v169
	v_cvt_pk_bf16_f32 v203, v166, v167
	v_addc_co_u32_e32 v201, vcc, 0, v179, vcc
	v_pk_fma_f32 v[102:103], v[102:103], v[172:173], v[208:209]
	v_pk_fma_f32 v[100:101], v[100:101], v[164:165], v[234:235]
	global_store_dwordx4 v[200:201], v[202:205], off
	v_pk_fma_f32 v[106:107], v[106:107], v[176:177], v[206:207]
	v_pk_fma_f32 v[104:105], v[104:105], v[174:175], v[220:221]
	v_cvt_pk_bf16_f32 v206, v100, v101
	v_cvt_pk_bf16_f32 v207, v102, v103
	v_add_co_u32_e32 v202, vcc, s26, v182
	v_cvt_pk_bf16_f32 v204, v104, v105
	v_cvt_pk_bf16_f32 v205, v106, v107
	v_addc_co_u32_e32 v203, vcc, 0, v183, vcc
	v_lshlrev_b32_e32 v102, 16, v206
	v_and_b32_e32 v103, 0xffff0000, v206
	v_lshlrev_b32_e32 v100, 16, v207
	v_and_b32_e32 v101, 0xffff0000, v207
	global_store_dwordx4 v[202:203], v[204:207], off offset:2048
	v_lshlrev_b32_e32 v106, 16, v204
	v_and_b32_e32 v107, 0xffff0000, v204
	v_lshlrev_b32_e32 v104, 16, v205
	v_and_b32_e32 v105, 0xffff0000, v205
	v_pk_mul_f32 v[204:205], v[134:135], v[100:101]
	v_pk_mul_f32 v[208:209], v[132:133], v[102:103]
	s_mov_b32 s0, 0x18000
	v_pk_mul_f32 v[166:167], v[138:139], v[104:105]
	v_pk_mul_f32 v[168:169], v[136:137], v[106:107]
	v_cvt_pk_bf16_f32 v208, v208, v209
	v_cvt_pk_bf16_f32 v209, v204, v205
	v_add_co_u32_e32 v204, vcc, s0, v178
	v_cvt_pk_bf16_f32 v206, v168, v169
	v_cvt_pk_bf16_f32 v207, v166, v167
	v_addc_co_u32_e32 v205, vcc, 0, v179, vcc
	global_store_dwordx4 v[204:205], v[206:209], off
	s_mov_b32 s0, 0xb0000
	s_waitcnt vmcnt(0)
	v_lshlrev_b32_e32 v166, 16, v212
	v_add_co_u32_e32 v206, vcc, s76, v196
	v_and_b32_e32 v167, 0xffff0000, v212
	s_nop 0
	v_addc_co_u32_e32 v207, vcc, 0, v197, vcc
	global_load_dwordx4 v[238:241], v[206:207], off offset:2048
	v_add_co_u32_e32 v208, vcc, s0, v196
	v_lshlrev_b32_e32 v168, 16, v213
	s_nop 0
	v_addc_co_u32_e32 v209, vcc, 0, v197, vcc
	global_load_dwordx4 v[242:245], v[208:209], off offset:2048
	v_and_b32_e32 v169, 0xffff0000, v213
	v_lshlrev_b32_e32 v212, 16, v214
	v_and_b32_e32 v213, 0xffff0000, v214
	v_lshlrev_b32_e32 v214, 16, v215
	v_and_b32_e32 v215, 0xffff0000, v215
	v_pk_fma_f32 v[94:95], v[94:95], v[172:173], v[214:215]
	v_pk_fma_f32 v[92:93], v[92:93], v[164:165], v[212:213]
	v_lshlrev_b32_e32 v220, 16, v216
	v_and_b32_e32 v221, 0xffff0000, v216
	v_lshlrev_b32_e32 v234, 16, v217
	v_and_b32_e32 v235, 0xffff0000, v217
	v_pk_fma_f32 v[98:99], v[98:99], v[176:177], v[168:169]
	v_pk_fma_f32 v[96:97], v[96:97], v[174:175], v[166:167]
	v_cvt_pk_bf16_f32 v216, v92, v93
	v_cvt_pk_bf16_f32 v217, v94, v95
	v_add_co_u32_e32 v212, vcc, s27, v182
	v_cvt_pk_bf16_f32 v214, v96, v97
	v_cvt_pk_bf16_f32 v215, v98, v99
	v_addc_co_u32_e32 v213, vcc, 0, v183, vcc
	v_lshlrev_b32_e32 v94, 16, v216
	v_and_b32_e32 v95, 0xffff0000, v216
	v_lshlrev_b32_e32 v92, 16, v217
	v_and_b32_e32 v93, 0xffff0000, v217
	v_lshlrev_b32_e32 v246, 16, v218
	v_and_b32_e32 v247, 0xffff0000, v218
	v_lshlrev_b32_e32 v248, 16, v219
	v_and_b32_e32 v249, 0xffff0000, v219
	global_store_dwordx4 v[212:213], v[214:217], off offset:2048
	v_lshlrev_b32_e32 v98, 16, v214
	v_and_b32_e32 v99, 0xffff0000, v214
	v_lshlrev_b32_e32 v96, 16, v215
	v_and_b32_e32 v97, 0xffff0000, v215
	v_pk_mul_f32 v[214:215], v[134:135], v[92:93]
	v_pk_mul_f32 v[218:219], v[132:133], v[94:95]
	s_mov_b32 s1, 0x40000
	v_pk_mul_f32 v[166:167], v[138:139], v[96:97]
	v_pk_mul_f32 v[168:169], v[136:137], v[98:99]
	v_cvt_pk_bf16_f32 v218, v218, v219
	v_cvt_pk_bf16_f32 v219, v214, v215
	v_add_co_u32_e32 v214, vcc, s1, v178
	v_cvt_pk_bf16_f32 v216, v168, v169
	v_cvt_pk_bf16_f32 v217, v166, v167
	v_addc_co_u32_e32 v215, vcc, 0, v179, vcc
	v_pk_fma_f32 v[86:87], v[86:87], v[172:173], v[248:249]
	global_store_dwordx4 v[214:215], v[216:219], off
	v_pk_fma_f32 v[90:91], v[90:91], v[176:177], v[234:235]
	v_pk_fma_f32 v[88:89], v[88:89], v[174:175], v[220:221]
	v_pk_fma_f32 v[84:85], v[84:85], v[164:165], v[246:247]
	v_cvt_pk_bf16_f32 v221, v86, v87
	v_add_co_u32_e32 v216, vcc, s28, v182
	v_cvt_pk_bf16_f32 v218, v88, v89
	v_cvt_pk_bf16_f32 v219, v90, v91
	v_cvt_pk_bf16_f32 v220, v84, v85
	v_addc_co_u32_e32 v217, vcc, 0, v183, vcc
	v_lshlrev_b32_e32 v84, 16, v221
	v_and_b32_e32 v85, 0xffff0000, v221
	global_store_dwordx4 v[216:217], v[218:221], off offset:2048
	v_lshlrev_b32_e32 v90, 16, v218
	v_and_b32_e32 v91, 0xffff0000, v218
	v_lshlrev_b32_e32 v88, 16, v219
	v_and_b32_e32 v89, 0xffff0000, v219
	v_lshlrev_b32_e32 v86, 16, v220
	v_and_b32_e32 v87, 0xffff0000, v220
	v_pk_mul_f32 v[218:219], v[134:135], v[84:85]
	s_mov_b32 s1, 0x48000
	v_pk_mul_f32 v[166:167], v[138:139], v[88:89]
	v_pk_mul_f32 v[168:169], v[136:137], v[90:91]
	v_pk_mul_f32 v[220:221], v[132:133], v[86:87]
	v_cvt_pk_bf16_f32 v249, v218, v219
	v_add_co_u32_e32 v218, vcc, s1, v178
	v_cvt_pk_bf16_f32 v246, v168, v169
	v_cvt_pk_bf16_f32 v247, v166, v167
	v_cvt_pk_bf16_f32 v248, v220, v221
	v_addc_co_u32_e32 v219, vcc, 0, v179, vcc
	global_store_dwordx4 v[218:219], v[246:249], off
	global_load_dwordx4 v[246:249], v[196:197], off offset:2304
	s_nop 0
	global_load_dwordx4 v[250:253], v[210:211], off offset:2304
	s_waitcnt vmcnt(0)
	v_lshlrev_b32_e32 v196, 16, v240
	v_and_b32_e32 v197, 0xffff0000, v240
	v_lshlrev_b32_e32 v210, 16, v241
	v_and_b32_e32 v211, 0xffff0000, v241
	v_lshlrev_b32_e32 v166, 16, v238
	v_and_b32_e32 v167, 0xffff0000, v238
	v_lshlrev_b32_e32 v168, 16, v239
	v_and_b32_e32 v169, 0xffff0000, v239
	v_pk_fma_f32 v[78:79], v[78:79], v[172:173], v[210:211]
	v_pk_fma_f32 v[76:77], v[76:77], v[164:165], v[196:197]
	v_pk_fma_f32 v[82:83], v[82:83], v[176:177], v[168:169]
	v_pk_fma_f32 v[80:81], v[80:81], v[174:175], v[166:167]
	v_cvt_pk_bf16_f32 v240, v76, v77
	v_cvt_pk_bf16_f32 v241, v78, v79
	v_add_co_u32_e32 v196, vcc, s76, v182
	v_cvt_pk_bf16_f32 v238, v80, v81
	v_cvt_pk_bf16_f32 v239, v82, v83
	v_addc_co_u32_e32 v197, vcc, 0, v183, vcc
	v_lshlrev_b32_e32 v78, 16, v240
	v_and_b32_e32 v79, 0xffff0000, v240
	v_lshlrev_b32_e32 v76, 16, v241
	v_and_b32_e32 v77, 0xffff0000, v241
	global_store_dwordx4 v[196:197], v[238:241], off offset:2048
	v_lshlrev_b32_e32 v80, 16, v239
	v_and_b32_e32 v81, 0xffff0000, v239
	v_pk_mul_f32 v[210:211], v[134:135], v[76:77]
	v_pk_mul_f32 v[240:241], v[132:133], v[78:79]
	v_lshlrev_b32_e32 v220, 16, v242
	v_and_b32_e32 v221, 0xffff0000, v242
	v_lshlrev_b32_e32 v234, 16, v243
	v_and_b32_e32 v235, 0xffff0000, v243
	v_lshlrev_b32_e32 v242, 16, v244
	v_and_b32_e32 v243, 0xffff0000, v244
	v_lshlrev_b32_e32 v244, 16, v245
	v_and_b32_e32 v245, 0xffff0000, v245
	v_pk_mul_f32 v[166:167], v[138:139], v[80:81]
	v_cvt_pk_bf16_f32 v240, v240, v241
	v_cvt_pk_bf16_f32 v241, v210, v211
	v_add_co_u32_e32 v210, vcc, s77, v178
	v_lshlrev_b32_e32 v82, 16, v238
	v_and_b32_e32 v83, 0xffff0000, v238
	v_cvt_pk_bf16_f32 v239, v166, v167
	v_addc_co_u32_e32 v211, vcc, 0, v179, vcc
	v_pk_fma_f32 v[74:75], v[74:75], v[176:177], v[234:235]
	v_pk_fma_f32 v[72:73], v[72:73], v[174:175], v[220:221]
	v_pk_fma_f32 v[166:167], v[70:71], v[172:173], v[244:245]
	v_pk_fma_f32 v[70:71], v[68:69], v[164:165], v[242:243]
	v_pk_mul_f32 v[168:169], v[136:137], v[82:83]
	v_cvt_pk_bf16_f32 v68, v72, v73
	v_cvt_pk_bf16_f32 v69, v74, v75
	v_cvt_pk_bf16_f32 v70, v70, v71
	v_cvt_pk_bf16_f32 v71, v166, v167
	v_add_co_u32_e32 v220, vcc, s0, v182
	v_cvt_pk_bf16_f32 v238, v168, v169
	s_nop 0
	v_addc_co_u32_e32 v221, vcc, 0, v183, vcc
	v_lshlrev_b32_e32 v176, 16, v68
	v_and_b32_e32 v177, 0xffff0000, v68
	v_lshlrev_b32_e32 v174, 16, v69
	v_and_b32_e32 v175, 0xffff0000, v69
	v_lshlrev_b32_e32 v172, 16, v70
	v_and_b32_e32 v173, 0xffff0000, v70
	v_lshlrev_b32_e32 v164, 16, v71
	v_and_b32_e32 v165, 0xffff0000, v71
	s_mov_b32 s0, 0x58000
	global_store_dwordx4 v[210:211], v[238:241], off
	global_store_dwordx4 v[220:221], v[68:71], off offset:2048
	v_pk_mul_f32 v[72:73], v[134:135], v[164:165]
	v_pk_mul_f32 v[74:75], v[132:133], v[172:173]
	v_pk_mul_f32 v[70:71], v[138:139], v[174:175]
	v_pk_mul_f32 v[68:69], v[136:137], v[176:177]
	v_add_co_u32_e32 v132, vcc, s0, v178
	v_cvt_pk_bf16_f32 v68, v68, v69
	v_cvt_pk_bf16_f32 v69, v70, v71
	v_cvt_pk_bf16_f32 v70, v74, v75
	v_cvt_pk_bf16_f32 v71, v72, v73
	v_addc_co_u32_e32 v133, vcc, 0, v179, vcc
	global_store_dwordx4 v[132:133], v[68:71], off
	global_load_dwordx4 v[134:137], v[184:185], off offset:2304
	global_load_dwordx4 v[238:241], v[188:189], off offset:2304
	s_nop 0
	global_load_dwordx4 v[68:71], v[180:181], off offset:528
	global_load_dwordx4 v[72:75], v[180:181], off offset:512
	v_lshlrev_b32_e32 v138, 16, v246
	v_and_b32_e32 v139, 0xffff0000, v246
	v_lshlrev_b32_e32 v166, 16, v247
	v_and_b32_e32 v167, 0xffff0000, v247
	v_lshlrev_b32_e32 v168, 16, v248
	v_and_b32_e32 v169, 0xffff0000, v248
	v_lshlrev_b32_e32 v180, 16, v249
	v_and_b32_e32 v181, 0xffff0000, v249
	v_pk_fma_f32 v[66:67], v[66:67], v[162:163], v[166:167]
	v_pk_fma_f32 v[64:65], v[64:65], v[160:161], v[138:139]
	v_pk_fma_f32 v[62:63], v[62:63], v[158:159], v[180:181]
	v_pk_fma_f32 v[60:61], v[60:61], v[156:157], v[168:169]
	v_cvt_pk_bf16_f32 v242, v64, v65
	v_cvt_pk_bf16_f32 v243, v66, v67
	v_cvt_pk_bf16_f32 v244, v60, v61
	v_cvt_pk_bf16_f32 v245, v62, v63
	v_lshlrev_b32_e32 v66, 16, v242
	v_and_b32_e32 v67, 0xffff0000, v242
	v_lshlrev_b32_e32 v64, 16, v243
	v_and_b32_e32 v65, 0xffff0000, v243
	v_lshlrev_b32_e32 v62, 16, v244
	v_and_b32_e32 v63, 0xffff0000, v244
	v_lshlrev_b32_e32 v60, 16, v245
	v_and_b32_e32 v61, 0xffff0000, v245
	v_lshlrev_b32_e32 v184, 16, v250
	v_and_b32_e32 v185, 0xffff0000, v250
	v_lshlrev_b32_e32 v188, 16, v251
	v_and_b32_e32 v189, 0xffff0000, v251
	v_lshlrev_b32_e32 v234, 16, v252
	v_and_b32_e32 v235, 0xffff0000, v252
	v_lshlrev_b32_e32 v246, 16, v253
	v_and_b32_e32 v247, 0xffff0000, v253
	global_store_dwordx4 v[182:183], v[242:245], off offset:2304
	v_pk_fma_f32 v[58:59], v[58:59], v[162:163], v[188:189]
	v_pk_fma_f32 v[56:57], v[56:57], v[160:161], v[184:185]
	v_pk_fma_f32 v[54:55], v[54:55], v[158:159], v[246:247]
	v_pk_fma_f32 v[52:53], v[52:53], v[156:157], v[234:235]
	s_waitcnt vmcnt(0)
	v_lshlrev_b32_e32 v188, 16, v240
	v_pk_mul_f32 v[168:169], v[70:71], v[60:61]
	v_pk_mul_f32 v[138:139], v[74:75], v[64:65]
	v_pk_mul_f32 v[166:167], v[72:73], v[66:67]
	v_pk_mul_f32 v[182:183], v[68:69], v[62:63]
	v_cvt_pk_bf16_f32 v180, v166, v167
	v_cvt_pk_bf16_f32 v181, v138, v139
	v_cvt_pk_bf16_f32 v182, v182, v183
	v_cvt_pk_bf16_f32 v183, v168, v169
	global_store_dwordx4 v[178:179], v[180:183], off offset:256
	v_cvt_pk_bf16_f32 v178, v56, v57
	v_cvt_pk_bf16_f32 v179, v58, v59
	v_cvt_pk_bf16_f32 v180, v52, v53
	v_cvt_pk_bf16_f32 v181, v54, v55
	v_lshlrev_b32_e32 v58, 16, v178
	v_and_b32_e32 v59, 0xffff0000, v178
	v_lshlrev_b32_e32 v56, 16, v179
	v_and_b32_e32 v57, 0xffff0000, v179
	v_lshlrev_b32_e32 v54, 16, v180
	v_and_b32_e32 v55, 0xffff0000, v180
	v_lshlrev_b32_e32 v52, 16, v181
	v_and_b32_e32 v53, 0xffff0000, v181
	global_store_dwordx4 v[186:187], v[178:181], off offset:2304
	v_pk_mul_f32 v[138:139], v[74:75], v[56:57]
	v_pk_mul_f32 v[166:167], v[72:73], v[58:59]
	v_pk_mul_f32 v[168:169], v[70:71], v[52:53]
	v_pk_mul_f32 v[180:181], v[68:69], v[54:55]
	v_cvt_pk_bf16_f32 v178, v166, v167
	v_cvt_pk_bf16_f32 v179, v138, v139
	v_cvt_pk_bf16_f32 v180, v180, v181
	v_cvt_pk_bf16_f32 v181, v168, v169
	v_lshlrev_b32_e32 v138, 16, v134
	v_and_b32_e32 v139, 0xffff0000, v134
	v_lshlrev_b32_e32 v134, 16, v135
	v_and_b32_e32 v135, 0xffff0000, v135
	v_lshlrev_b32_e32 v166, 16, v136
	v_and_b32_e32 v167, 0xffff0000, v136
	v_lshlrev_b32_e32 v136, 16, v137
	v_and_b32_e32 v137, 0xffff0000, v137
	global_store_dwordx4 v[190:191], v[178:181], off offset:256
	v_pk_fma_f32 v[50:51], v[50:51], v[162:163], v[134:135]
	v_pk_fma_f32 v[48:49], v[48:49], v[160:161], v[138:139]
	v_pk_fma_f32 v[46:47], v[46:47], v[158:159], v[136:137]
	v_pk_fma_f32 v[44:45], v[44:45], v[156:157], v[166:167]
	global_load_dwordx4 v[178:181], v[192:193], off offset:2304
	global_load_dwordx4 v[182:185], v[194:195], off offset:2304
	v_cvt_pk_bf16_f32 v134, v48, v49
	v_cvt_pk_bf16_f32 v135, v50, v51
	v_cvt_pk_bf16_f32 v136, v44, v45
	v_cvt_pk_bf16_f32 v137, v46, v47
	v_lshlrev_b32_e32 v50, 16, v134
	v_and_b32_e32 v51, 0xffff0000, v134
	v_lshlrev_b32_e32 v48, 16, v135
	v_and_b32_e32 v49, 0xffff0000, v135
	v_lshlrev_b32_e32 v46, 16, v136
	v_and_b32_e32 v47, 0xffff0000, v136
	v_lshlrev_b32_e32 v44, 16, v137
	v_and_b32_e32 v45, 0xffff0000, v137
	v_lshlrev_b32_e32 v168, 16, v238
	v_and_b32_e32 v169, 0xffff0000, v238
	v_lshlrev_b32_e32 v186, 16, v239
	v_and_b32_e32 v187, 0xffff0000, v239
	v_and_b32_e32 v189, 0xffff0000, v240
	v_lshlrev_b32_e32 v190, 16, v241
	v_and_b32_e32 v191, 0xffff0000, v241
	global_store_dwordx4 v[198:199], v[134:137], off offset:2304
	v_pk_mul_f32 v[138:139], v[70:71], v[44:45]
	v_pk_mul_f32 v[166:167], v[68:69], v[46:47]
	v_pk_mul_f32 v[136:137], v[74:75], v[48:49]
	v_pk_mul_f32 v[134:135], v[72:73], v[50:51]
	v_pk_fma_f32 v[42:43], v[42:43], v[162:163], v[186:187]
	v_cvt_pk_bf16_f32 v134, v134, v135
	v_cvt_pk_bf16_f32 v135, v136, v137
	v_cvt_pk_bf16_f32 v136, v166, v167
	v_cvt_pk_bf16_f32 v137, v138, v139
	v_pk_fma_f32 v[40:41], v[40:41], v[160:161], v[168:169]
	v_pk_fma_f32 v[38:39], v[38:39], v[158:159], v[190:191]
	v_pk_fma_f32 v[36:37], v[36:37], v[156:157], v[188:189]
	global_store_dwordx4 v[200:201], v[134:137], off offset:256
	v_mul_f32_e32 v67, v67, v67
	v_mul_f32_e32 v65, v65, v65
	v_cvt_pk_bf16_f32 v134, v40, v41
	v_cvt_pk_bf16_f32 v135, v42, v43
	v_cvt_pk_bf16_f32 v136, v36, v37
	v_cvt_pk_bf16_f32 v137, v38, v39
	v_lshlrev_b32_e32 v42, 16, v134
	v_and_b32_e32 v43, 0xffff0000, v134
	v_lshlrev_b32_e32 v40, 16, v135
	v_and_b32_e32 v41, 0xffff0000, v135
	v_lshlrev_b32_e32 v38, 16, v136
	v_and_b32_e32 v39, 0xffff0000, v136
	v_lshlrev_b32_e32 v36, 16, v137
	v_and_b32_e32 v37, 0xffff0000, v137
	global_store_dwordx4 v[202:203], v[134:137], off offset:2304
	v_pk_mul_f32 v[138:139], v[70:71], v[36:37]
	v_pk_mul_f32 v[166:167], v[68:69], v[38:39]
	v_pk_mul_f32 v[136:137], v[74:75], v[40:41]
	v_pk_mul_f32 v[134:135], v[72:73], v[42:43]
	v_fmac_f32_e32 v67, v66, v66
	v_cvt_pk_bf16_f32 v134, v134, v135
	v_cvt_pk_bf16_f32 v135, v136, v137
	v_cvt_pk_bf16_f32 v136, v166, v167
	v_cvt_pk_bf16_f32 v137, v138, v139
	global_store_dwordx4 v[204:205], v[134:137], off offset:256
	global_load_dwordx4 v[134:137], v[206:207], off offset:2304
	s_nop 0
	global_load_dwordx4 v[186:189], v[208:209], off offset:2304
	v_fmac_f32_e32 v65, v64, v64
	v_mul_f32_e32 v63, v63, v63
	v_mul_f32_e32 v61, v61, v61
	v_add_f32_e32 v64, v67, v65
	v_fmac_f32_e32 v63, v62, v62
	v_fmac_f32_e32 v61, v60, v60
	v_add_f32_e32 v60, v63, v61
	s_waitcnt vmcnt(0)
	v_lshlrev_b32_e32 v138, 16, v178
	v_and_b32_e32 v139, 0xffff0000, v178
	v_lshlrev_b32_e32 v166, 16, v179
	v_and_b32_e32 v167, 0xffff0000, v179
	v_lshlrev_b32_e32 v168, 16, v180
	v_and_b32_e32 v169, 0xffff0000, v180
	v_lshlrev_b32_e32 v178, 16, v181
	v_and_b32_e32 v179, 0xffff0000, v181
	v_pk_fma_f32 v[34:35], v[34:35], v[162:163], v[166:167]
	v_pk_fma_f32 v[32:33], v[32:33], v[160:161], v[138:139]
	v_pk_fma_f32 v[30:31], v[30:31], v[158:159], v[178:179]
	v_pk_fma_f32 v[28:29], v[28:29], v[156:157], v[168:169]
	v_cvt_pk_bf16_f32 v178, v32, v33
	v_cvt_pk_bf16_f32 v179, v34, v35
	v_cvt_pk_bf16_f32 v180, v28, v29
	v_cvt_pk_bf16_f32 v181, v30, v31
	v_lshlrev_b32_e32 v34, 16, v178
	v_and_b32_e32 v35, 0xffff0000, v178
	v_lshlrev_b32_e32 v32, 16, v179
	v_and_b32_e32 v33, 0xffff0000, v179
	v_lshlrev_b32_e32 v30, 16, v180
	v_and_b32_e32 v31, 0xffff0000, v180
	v_lshlrev_b32_e32 v28, 16, v181
	v_and_b32_e32 v29, 0xffff0000, v181
	v_lshlrev_b32_e32 v190, 16, v182
	v_and_b32_e32 v191, 0xffff0000, v182
	v_lshlrev_b32_e32 v182, 16, v183
	v_and_b32_e32 v183, 0xffff0000, v183
	global_store_dwordx4 v[212:213], v[178:181], off offset:2304
	v_pk_mul_f32 v[138:139], v[74:75], v[32:33]
	v_pk_mul_f32 v[166:167], v[72:73], v[34:35]
	v_pk_mul_f32 v[168:169], v[70:71], v[28:29]
	v_pk_mul_f32 v[180:181], v[68:69], v[30:31]
	v_cvt_pk_bf16_f32 v178, v166, v167
	v_cvt_pk_bf16_f32 v179, v138, v139
	v_cvt_pk_bf16_f32 v180, v180, v181
	v_cvt_pk_bf16_f32 v181, v168, v169
	v_pk_fma_f32 v[24:25], v[24:25], v[162:163], v[182:183]
	v_pk_fma_f32 v[22:23], v[22:23], v[160:161], v[190:191]
	v_lshlrev_b32_e32 v192, 16, v184
	v_and_b32_e32 v193, 0xffff0000, v184
	v_lshlrev_b32_e32 v184, 16, v185
	v_and_b32_e32 v185, 0xffff0000, v185
	global_store_dwordx4 v[214:215], v[178:181], off offset:256
	v_pk_fma_f32 v[20:21], v[20:21], v[158:159], v[184:185]
	v_pk_fma_f32 v[18:19], v[18:19], v[156:157], v[192:193]
	v_cvt_pk_bf16_f32 v178, v22, v23
	v_cvt_pk_bf16_f32 v179, v24, v25
	v_lshlrev_b32_e32 v24, 16, v178
	v_and_b32_e32 v25, 0xffff0000, v178
	v_lshlrev_b32_e32 v22, 16, v179
	v_and_b32_e32 v23, 0xffff0000, v179
	v_cvt_pk_bf16_f32 v180, v18, v19
	v_cvt_pk_bf16_f32 v181, v20, v21
	v_pk_mul_f32 v[138:139], v[74:75], v[22:23]
	v_pk_mul_f32 v[166:167], v[72:73], v[24:25]
	global_store_dwordx4 v[216:217], v[178:181], off offset:2304
	v_lshlrev_b32_e32 v20, 16, v180
	v_and_b32_e32 v21, 0xffff0000, v180
	v_cvt_pk_bf16_f32 v178, v166, v167
	v_cvt_pk_bf16_f32 v179, v138, v139
	v_lshlrev_b32_e32 v138, 16, v134
	v_and_b32_e32 v139, 0xffff0000, v134
	v_lshlrev_b32_e32 v134, 16, v135
	v_and_b32_e32 v135, 0xffff0000, v135
	v_lshlrev_b32_e32 v166, 16, v136
	v_and_b32_e32 v167, 0xffff0000, v136
	v_lshlrev_b32_e32 v136, 16, v137
	v_and_b32_e32 v137, 0xffff0000, v137
	v_lshlrev_b32_e32 v18, 16, v181
	v_and_b32_e32 v19, 0xffff0000, v181
	v_pk_fma_f32 v[16:17], v[16:17], v[162:163], v[134:135]
	v_pk_fma_f32 v[14:15], v[14:15], v[160:161], v[138:139]
	v_pk_fma_f32 v[12:13], v[12:13], v[158:159], v[136:137]
	v_pk_fma_f32 v[10:11], v[10:11], v[156:157], v[166:167]
	v_pk_mul_f32 v[168:169], v[70:71], v[18:19]
	v_pk_mul_f32 v[180:181], v[68:69], v[20:21]
	v_cvt_pk_bf16_f32 v134, v14, v15
	v_cvt_pk_bf16_f32 v135, v16, v17
	v_cvt_pk_bf16_f32 v136, v10, v11
	v_cvt_pk_bf16_f32 v137, v12, v13
	v_cvt_pk_bf16_f32 v180, v180, v181
	v_cvt_pk_bf16_f32 v181, v168, v169
	v_lshlrev_b32_e32 v16, 16, v134
	v_and_b32_e32 v17, 0xffff0000, v134
	v_lshlrev_b32_e32 v14, 16, v135
	v_and_b32_e32 v15, 0xffff0000, v135
	v_lshlrev_b32_e32 v12, 16, v136
	v_and_b32_e32 v13, 0xffff0000, v136
	v_lshlrev_b32_e32 v10, 16, v137
	v_and_b32_e32 v11, 0xffff0000, v137
	global_store_dwordx4 v[218:219], v[178:181], off offset:256
	v_lshlrev_b32_e32 v168, 16, v186
	v_and_b32_e32 v169, 0xffff0000, v186
	v_lshlrev_b32_e32 v178, 16, v187
	v_and_b32_e32 v179, 0xffff0000, v187
	v_lshlrev_b32_e32 v180, 16, v188
	v_and_b32_e32 v181, 0xffff0000, v188
	v_lshlrev_b32_e32 v182, 16, v189
	v_and_b32_e32 v183, 0xffff0000, v189
	global_store_dwordx4 v[196:197], v[134:137], off offset:2304
	v_pk_mul_f32 v[138:139], v[70:71], v[10:11]
	v_pk_mul_f32 v[166:167], v[68:69], v[12:13]
	v_pk_mul_f32 v[136:137], v[74:75], v[14:15]
	v_pk_mul_f32 v[134:135], v[72:73], v[16:17]
	v_pk_fma_f32 v[8:9], v[8:9], v[162:163], v[178:179]
	v_cvt_pk_bf16_f32 v134, v134, v135
	v_cvt_pk_bf16_f32 v135, v136, v137
	v_cvt_pk_bf16_f32 v136, v166, v167
	v_cvt_pk_bf16_f32 v137, v138, v139
	v_pk_fma_f32 v[6:7], v[6:7], v[160:161], v[168:169]
	v_pk_fma_f32 v[4:5], v[4:5], v[158:159], v[182:183]
	v_pk_fma_f32 v[2:3], v[2:3], v[156:157], v[180:181]
	global_store_dwordx4 v[210:211], v[134:137], off offset:256
	s_nop 1
	v_cvt_pk_bf16_f32 v134, v6, v7
	v_cvt_pk_bf16_f32 v135, v8, v9
	v_cvt_pk_bf16_f32 v136, v2, v3
	v_cvt_pk_bf16_f32 v137, v4, v5
	v_lshlrev_b32_e32 v8, 16, v134
	v_and_b32_e32 v9, 0xffff0000, v134
	v_lshlrev_b32_e32 v6, 16, v135
	v_and_b32_e32 v7, 0xffff0000, v135
	v_lshlrev_b32_e32 v4, 16, v136
	v_and_b32_e32 v5, 0xffff0000, v136
	v_lshlrev_b32_e32 v2, 16, v137
	v_and_b32_e32 v3, 0xffff0000, v137
	global_store_dwordx4 v[220:221], v[134:137], off offset:2304
	v_pk_mul_f32 v[74:75], v[74:75], v[6:7]
	v_pk_mul_f32 v[72:73], v[72:73], v[8:9]
	v_pk_mul_f32 v[134:135], v[70:71], v[2:3]
	v_pk_mul_f32 v[70:71], v[68:69], v[4:5]
	v_cvt_pk_bf16_f32 v68, v72, v73
	v_cvt_pk_bf16_f32 v69, v74, v75
	v_cvt_pk_bf16_f32 v70, v70, v71
	v_cvt_pk_bf16_f32 v71, v134, v135
	global_store_dwordx4 v[132:133], v[68:71], off offset:256
	v_xor_b32_e32 v72, 32, v227
	v_mul_f32_e32 v73, v129, v129
	v_and_b32_e32 v71, 64, v227
	v_xor_b32_e32 v70, 16, v227
	v_add_u32_e32 v71, 64, v71
	v_cmp_lt_i32_e32 vcc, v70, v71
	v_fmac_f32_e32 v73, v128, v128
	v_mul_f32_e32 v74, v125, v125
	v_cndmask_b32_e32 v70, v227, v70, vcc
	v_cmp_lt_i32_e32 vcc, v72, v71
	v_fmac_f32_e32 v74, v124, v124
	v_lshlrev_b32_e32 v70, 2, v70
	v_cndmask_b32_e32 v71, v227, v72, vcc
	v_mul_f32_e32 v72, v131, v131
	v_fmac_f32_e32 v72, v130, v130
	v_add_f32_e32 v72, v72, v73
	v_mul_f32_e32 v73, v127, v127
	v_fmac_f32_e32 v73, v126, v126
	v_add_f32_e32 v73, v73, v74
	v_add_f32_e32 v72, v72, v73
	v_add_f32_e32 v64, v72, v64
	v_add_f32_e32 v60, v60, v64
	ds_bpermute_b32 v61, v70, v60
	v_lshlrev_b32_e32 v71, 2, v71
	v_lshl_add_u64 v[68:69], v[150:151], 0, s[24:25]
	s_waitcnt lgkmcnt(0)
	v_add_f32_e32 v60, v60, v61
	ds_bpermute_b32 v61, v71, v60
	s_and_saveexec_b64 s[24:25], s[38:39]
	s_cbranch_execz .LBB0_1159
	s_waitcnt lgkmcnt(0)
	v_add_f32_e32 v60, v60, v61
	global_atomic_add_f32 v[68:69], v60, off
